# blanket s_nop pads around the inline-asm bf16 convert blocks removed (one wait state kept only behind a transcendental producer)
# baseline (speedup 1.0000x reference)
.LBB0_169:
	s_ashr_i32 s77, s76, 31
	s_add_i32 s4, s76, 0xffffe000
	s_and_b64 s[0:1], exec, s[16:17]
	s_cselect_b32 s1, s77, 0
	s_cselect_b32 s0, s76, s4
	s_lshl_b64 s[0:1], s[0:1], 13
	v_lshl_add_u64 v[60:61], v[60:61], 0, s[0:1]
	s_lshl_b64 s[0:1], s[76:77], 2
	v_lshl_add_u64 v[60:61], v[60:61], 0, v[70:71]
	s_add_u32 s0, s46, s0
	flat_load_dwordx4 v[64:67], v[60:61]
	v_lshl_add_u64 v[60:61], v[62:63], 0, v[70:71]
	s_addc_u32 s1, s47, s1
	v_lshl_add_u64 v[92:93], v[92:93], 2, s[46:47]
	flat_load_dwordx4 v[60:63], v[60:61]
	s_waitcnt vmcnt(0)
	v_cndmask_b32_e64 v97, v13, v5, s[12:13]
	global_load_dword v94, v89, s[0:1]
	v_cndmask_b32_e64 v96, v12, v4, s[12:13]
	global_load_dword v92, v[92:93], off
	v_cndmask_b32_e64 v99, v15, v7, s[12:13]
	v_cndmask_b32_e64 v98, v14, v6, s[12:13]
	v_pk_add_f32 v[98:99], v[98:99], 1.0 op_sel_hi:[1,0]
	v_pk_add_f32 v[96:97], v[96:97], 1.0 op_sel_hi:[1,0]
	s_waitcnt lgkmcnt(0)
	v_pk_mul_f32 v[98:99], v[2:3], v[98:99]
	v_pk_mul_f32 v[96:97], v[0:1], v[96:97]
	v_cndmask_b32_e64 v101, v17, v9, s[12:13]
	v_cndmask_b32_e64 v100, v16, v8, s[12:13]
	v_cndmask_b32_e64 v103, v19, v11, s[12:13]
	v_cndmask_b32_e64 v102, v18, v10, s[12:13]
	v_pk_mul_f32 v[46:47], v[46:47], v[84:85] op_sel_hi:[1,0]
	v_pk_mul_f32 v[44:45], v[44:45], v[84:85] op_sel_hi:[1,0]
	v_pk_mul_f32 v[50:51], v[50:51], v[86:87] op_sel_hi:[1,0]
	v_pk_mul_f32 v[48:49], v[48:49], v[86:87] op_sel_hi:[1,0]
	v_pk_fma_f32 v[44:45], v[96:97], v[44:45], v[100:101]
	v_pk_fma_f32 v[46:47], v[98:99], v[46:47], v[102:103]
	v_pk_fma_f32 v[50:51], v[98:99], v[50:51], v[102:103]
	v_pk_fma_f32 v[48:49], v[96:97], v[48:49], v[100:101]
	v_cndmask_b32_e64 v46, 0, v46, s[68:69]
	v_cndmask_b32_e64 v47, 0, v47, s[68:69]
	v_cndmask_b32_e64 v44, 0, v44, s[68:69]
	v_cndmask_b32_e64 v45, 0, v45, s[68:69]
	v_sub_f32_e32 v45, v45, v49
	v_sub_f32_e32 v44, v44, v48
	v_sub_f32_e32 v47, v47, v51
	v_sub_f32_e32 v46, v46, v50
	v_pk_fma_f32 v[96:97], v[46:47], v[22:23], v[50:51]
	v_pk_fma_f32 v[98:99], v[44:45], v[20:21], v[48:49]
	s_lshl_b64 s[0:1], s[66:67], 12
	v_cvt_pk_bf16_f32 v98, v98, v99
	v_cvt_pk_bf16_f32 v99, v96, v97
	v_lshl_add_u64 v[96:97], v[72:73], 0, s[0:1]
	global_store_dwordx2 v[96:97], v[98:99], off
	v_pk_fma_f32 v[96:97], v[46:47], v[26:27], v[50:51]
	v_pk_fma_f32 v[98:99], v[44:45], v[24:25], v[48:49]
	s_andn2_b64 vcc, exec, s[72:73]
	v_cvt_pk_bf16_f32 v98, v98, v99
	v_cvt_pk_bf16_f32 v99, v96, v97
	v_lshl_add_u64 v[96:97], v[74:75], 0, s[0:1]
	global_store_dwordx2 v[96:97], v[98:99], off
	v_pk_fma_f32 v[96:97], v[46:47], v[30:31], v[50:51]
	v_pk_fma_f32 v[98:99], v[44:45], v[28:29], v[48:49]
	s_nop 0
	v_cvt_pk_bf16_f32 v98, v98, v99
	v_cvt_pk_bf16_f32 v99, v96, v97
	v_lshl_add_u64 v[96:97], v[76:77], 0, s[0:1]
	global_store_dwordx2 v[96:97], v[98:99], off
	v_pk_fma_f32 v[96:97], v[46:47], v[34:35], v[50:51]
	v_pk_fma_f32 v[98:99], v[44:45], v[32:33], v[48:49]
	s_nop 0
	v_cvt_pk_bf16_f32 v98, v98, v99
	v_cvt_pk_bf16_f32 v99, v96, v97
	v_lshl_add_u64 v[96:97], v[78:79], 0, s[0:1]
	global_store_dwordx2 v[96:97], v[98:99], off
	v_pk_fma_f32 v[96:97], v[46:47], v[38:39], v[50:51]
	v_pk_fma_f32 v[98:99], v[44:45], v[36:37], v[48:49]
	v_pk_fma_f32 v[46:47], v[46:47], v[42:43], v[50:51]
	v_cvt_pk_bf16_f32 v98, v98, v99
	v_cvt_pk_bf16_f32 v99, v96, v97
	v_lshl_add_u64 v[96:97], v[80:81], 0, s[0:1]
	v_pk_fma_f32 v[44:45], v[44:45], v[40:41], v[48:49]
	global_store_dwordx2 v[96:97], v[98:99], off
	v_cvt_pk_bf16_f32 v44, v44, v45
	v_cvt_pk_bf16_f32 v45, v46, v47
	v_lshl_add_u64 v[46:47], v[82:83], 0, s[0:1]
	global_store_dwordx2 v[46:47], v[44:45], off
	s_cbranch_vccnz .LBB0_171
	v_cndmask_b32_e64 v45, v13, v5, s[14:15]
	v_cndmask_b32_e64 v44, v12, v4, s[14:15]
	v_cndmask_b32_e64 v47, v15, v7, s[14:15]
	v_cndmask_b32_e64 v46, v14, v6, s[14:15]
	v_pk_add_f32 v[46:47], v[46:47], 1.0 op_sel_hi:[1,0]
	v_pk_add_f32 v[44:45], v[44:45], 1.0 op_sel_hi:[1,0]
	v_pk_mul_f32 v[46:47], v[2:3], v[46:47]
	v_pk_mul_f32 v[44:45], v[0:1], v[44:45]
	v_cndmask_b32_e64 v49, v17, v9, s[14:15]
	v_cndmask_b32_e64 v48, v16, v8, s[14:15]
	v_cndmask_b32_e64 v51, v19, v11, s[14:15]
	v_cndmask_b32_e64 v50, v18, v10, s[14:15]
	v_pk_mul_f32 v[58:59], v[58:59], v[90:91] op_sel_hi:[1,0]
	v_pk_mul_f32 v[56:57], v[56:57], v[90:91] op_sel_hi:[1,0]
	v_pk_mul_f32 v[54:55], v[54:55], v[88:89] op_sel_hi:[1,0]
	v_pk_mul_f32 v[52:53], v[52:53], v[88:89] op_sel_hi:[1,0]
	v_pk_fma_f32 v[58:59], v[46:47], v[58:59], v[50:51]
	v_pk_fma_f32 v[56:57], v[44:45], v[56:57], v[48:49]
	v_pk_fma_f32 v[44:45], v[44:45], v[52:53], v[48:49]
	v_pk_fma_f32 v[46:47], v[46:47], v[54:55], v[50:51]
	v_cndmask_b32_e64 v44, 0, v44, s[74:75]
	v_cndmask_b32_e64 v46, 0, v46, s[74:75]
	v_cndmask_b32_e64 v47, 0, v47, s[74:75]
	v_cndmask_b32_e64 v45, 0, v45, s[74:75]
	v_sub_f32_e32 v45, v45, v57
	v_sub_f32_e32 v44, v44, v56
	v_sub_f32_e32 v47, v47, v59
	v_sub_f32_e32 v46, v46, v58
	v_pk_fma_f32 v[48:49], v[46:47], v[22:23], v[58:59]
	v_pk_fma_f32 v[50:51], v[44:45], v[20:21], v[56:57]
	s_lshl_b64 s[0:1], s[70:71], 12
	v_cvt_pk_bf16_f32 v50, v50, v51
	v_cvt_pk_bf16_f32 v51, v48, v49
	v_lshl_add_u64 v[48:49], v[72:73], 0, s[0:1]
	global_store_dwordx2 v[48:49], v[50:51], off
	v_pk_fma_f32 v[48:49], v[46:47], v[26:27], v[58:59]
	v_pk_fma_f32 v[50:51], v[44:45], v[24:25], v[56:57]
	s_nop 0
	v_cvt_pk_bf16_f32 v50, v50, v51
	v_cvt_pk_bf16_f32 v51, v48, v49
	v_lshl_add_u64 v[48:49], v[74:75], 0, s[0:1]
	global_store_dwordx2 v[48:49], v[50:51], off
	v_pk_fma_f32 v[48:49], v[46:47], v[30:31], v[58:59]
	v_pk_fma_f32 v[50:51], v[44:45], v[28:29], v[56:57]
	s_nop 0
	v_cvt_pk_bf16_f32 v50, v50, v51
	v_cvt_pk_bf16_f32 v51, v48, v49
	v_lshl_add_u64 v[48:49], v[76:77], 0, s[0:1]
	global_store_dwordx2 v[48:49], v[50:51], off
	v_pk_fma_f32 v[48:49], v[46:47], v[34:35], v[58:59]
	v_pk_fma_f32 v[50:51], v[44:45], v[32:33], v[56:57]
	s_nop 0
	v_cvt_pk_bf16_f32 v50, v50, v51
	v_cvt_pk_bf16_f32 v51, v48, v49
	v_lshl_add_u64 v[48:49], v[78:79], 0, s[0:1]
	global_store_dwordx2 v[48:49], v[50:51], off
	v_pk_fma_f32 v[48:49], v[46:47], v[38:39], v[58:59]
	v_pk_fma_f32 v[50:51], v[44:45], v[36:37], v[56:57]
	v_pk_fma_f32 v[46:47], v[46:47], v[42:43], v[58:59]
	v_cvt_pk_bf16_f32 v50, v50, v51
	v_cvt_pk_bf16_f32 v51, v48, v49
	v_lshl_add_u64 v[48:49], v[80:81], 0, s[0:1]
	v_pk_fma_f32 v[44:45], v[44:45], v[40:41], v[56:57]
	global_store_dwordx2 v[48:49], v[50:51], off
	v_cvt_pk_bf16_f32 v44, v44, v45
	v_cvt_pk_bf16_f32 v45, v46, v47
	v_lshl_add_u64 v[46:47], v[82:83], 0, s[0:1]
	global_store_dwordx2 v[46:47], v[44:45], off
	s_andn2_b64 vcc, exec, s[78:79]
	s_cbranch_vccnz .LBB0_102
	s_branch .LBB0_172

.LBB0_172:
	v_cndmask_b32_e64 v45, v13, v5, s[16:17]
	v_cndmask_b32_e64 v44, v12, v4, s[16:17]
	v_cndmask_b32_e64 v47, v15, v7, s[16:17]
	v_cndmask_b32_e64 v46, v14, v6, s[16:17]
	v_pk_add_f32 v[46:47], v[46:47], 1.0 op_sel_hi:[1,0]
	v_pk_add_f32 v[44:45], v[44:45], 1.0 op_sel_hi:[1,0]
	v_pk_mul_f32 v[46:47], v[2:3], v[46:47]
	v_pk_mul_f32 v[44:45], v[0:1], v[44:45]
	v_cndmask_b32_e64 v49, v17, v9, s[16:17]
	v_cndmask_b32_e64 v48, v16, v8, s[16:17]
	v_cndmask_b32_e64 v51, v19, v11, s[16:17]
	v_cndmask_b32_e64 v50, v18, v10, s[16:17]
	s_waitcnt vmcnt(7)
	v_pk_mul_f32 v[52:53], v[66:67], v[94:95] op_sel_hi:[1,0]
	v_pk_mul_f32 v[54:55], v[64:65], v[94:95] op_sel_hi:[1,0]
	s_waitcnt vmcnt(6)
	v_pk_mul_f32 v[56:57], v[62:63], v[92:93] op_sel_hi:[1,0]
	v_pk_mul_f32 v[58:59], v[60:61], v[92:93] op_sel_hi:[1,0]
	v_pk_fma_f32 v[52:53], v[46:47], v[52:53], v[50:51]
	v_pk_fma_f32 v[54:55], v[44:45], v[54:55], v[48:49]
	v_pk_fma_f32 v[44:45], v[44:45], v[58:59], v[48:49]
	v_pk_fma_f32 v[46:47], v[46:47], v[56:57], v[50:51]
	v_cndmask_b32_e64 v44, 0, v44, s[80:81]
	v_cndmask_b32_e64 v46, 0, v46, s[80:81]
	v_cndmask_b32_e64 v47, 0, v47, s[80:81]
	v_cndmask_b32_e64 v45, 0, v45, s[80:81]
	v_sub_f32_e32 v45, v45, v55
	v_sub_f32_e32 v44, v44, v54
	v_sub_f32_e32 v47, v47, v53
	v_sub_f32_e32 v46, v46, v52
	v_pk_fma_f32 v[48:49], v[46:47], v[22:23], v[52:53]
	v_pk_fma_f32 v[50:51], v[44:45], v[20:21], v[54:55]
	s_lshl_b64 s[0:1], s[76:77], 12
	v_cvt_pk_bf16_f32 v50, v50, v51
	v_cvt_pk_bf16_f32 v51, v48, v49
	v_lshl_add_u64 v[48:49], v[72:73], 0, s[0:1]
	global_store_dwordx2 v[48:49], v[50:51], off
	v_pk_fma_f32 v[48:49], v[46:47], v[26:27], v[52:53]
	v_pk_fma_f32 v[50:51], v[44:45], v[24:25], v[54:55]
	s_nop 0
	v_cvt_pk_bf16_f32 v50, v50, v51
	v_cvt_pk_bf16_f32 v51, v48, v49
	v_lshl_add_u64 v[48:49], v[74:75], 0, s[0:1]
	global_store_dwordx2 v[48:49], v[50:51], off
	v_pk_fma_f32 v[48:49], v[46:47], v[30:31], v[52:53]
	v_pk_fma_f32 v[50:51], v[44:45], v[28:29], v[54:55]
	s_nop 0
	v_cvt_pk_bf16_f32 v50, v50, v51
	v_cvt_pk_bf16_f32 v51, v48, v49
	v_lshl_add_u64 v[48:49], v[76:77], 0, s[0:1]
	global_store_dwordx2 v[48:49], v[50:51], off
	v_pk_fma_f32 v[48:49], v[46:47], v[34:35], v[52:53]
	v_pk_fma_f32 v[50:51], v[44:45], v[32:33], v[54:55]
	s_nop 0
	v_cvt_pk_bf16_f32 v50, v50, v51
	v_cvt_pk_bf16_f32 v51, v48, v49
	v_lshl_add_u64 v[48:49], v[78:79], 0, s[0:1]
	global_store_dwordx2 v[48:49], v[50:51], off
	v_pk_fma_f32 v[48:49], v[46:47], v[38:39], v[52:53]
	v_pk_fma_f32 v[50:51], v[44:45], v[36:37], v[54:55]
	v_pk_fma_f32 v[46:47], v[46:47], v[42:43], v[52:53]
	v_cvt_pk_bf16_f32 v50, v50, v51
	v_cvt_pk_bf16_f32 v51, v48, v49
	v_lshl_add_u64 v[48:49], v[80:81], 0, s[0:1]
	v_pk_fma_f32 v[44:45], v[44:45], v[40:41], v[54:55]
	global_store_dwordx2 v[48:49], v[50:51], off
	v_cvt_pk_bf16_f32 v44, v44, v45
	v_cvt_pk_bf16_f32 v45, v46, v47
	v_lshl_add_u64 v[46:47], v[82:83], 0, s[0:1]
	global_store_dwordx2 v[46:47], v[44:45], off
	s_branch .LBB0_102

.LBB0_214:
	s_cmpk_gt_i32 s4, 0x7ff
	s_mov_b64 s[0:1], -1
	s_cbranch_scc0 .LBB0_240
	s_cmpk_gt_u32 s4, 0xfff
	s_cbranch_scc0 .LBB0_237
	s_cmpk_gt_u32 s4, 0x17ff
	s_cbranch_scc0 .LBB0_234
	s_cmpk_gt_u32 s4, 0x185f
	s_cbranch_scc0 .LBB0_231
	s_cmpk_gt_u32 s4, 0x18bf
	s_cbranch_scc0 .LBB0_228
	s_cmpk_gt_u32 s4, 0x191f
	s_cbranch_scc0 .LBB0_225
	s_cmpk_gt_u32 s4, 0x197f
	s_cbranch_scc0 .LBB0_222
	v_readlane_b32 s0, v255, 10
	v_readlane_b32 s1, v255, 11
	s_and_b32 s11, s16, 0x7c0
	v_bitop3_b32 v19, s11, v4, v11 bitop3:0xde
	v_mov_b64_e32 v[20:21], s[0:1]
	flat_load_dwordx2 v[20:21], v[20:21] offset:176 sc0 sc1
	s_waitcnt vmcnt(0)
	s_and_b32 s10, s14, 0xe0
	v_mov_b32_e32 v23, v1
	v_lshlrev_b32_e32 v22, 10, v19
	s_lshl_b32 s6, s10, 2
	s_waitcnt lgkmcnt(0)
	v_readfirstlane_b32 s1, v21
	v_readfirstlane_b32 s0, v20
	s_nop 1
	v_lshl_add_u64 v[20:21], s[0:1], 0, v[22:23]
	v_lshl_add_u64 v[20:21], v[20:21], 0, s[6:7]
	v_lshl_add_u64 v[20:21], v[20:21], 0, v[0:1]
	v_add_co_u32_e32 v22, vcc, s23, v20
	s_or_b32 s0, s10, 0x1a00
	s_nop 0
	v_addc_co_u32_e32 v23, vcc, 0, v21, vcc
	v_add_co_u32_e32 v24, vcc, s24, v20
	s_xor_b32 s1, s11, 0x400
	s_nop 0
	v_addc_co_u32_e32 v25, vcc, 0, v21, vcc
	v_add_co_u32_e32 v26, vcc, s25, v20
	s_lshl_b32 s6, s1, 1
	s_nop 0
	v_addc_co_u32_e32 v27, vcc, 0, v21, vcc
	v_add_co_u32_e32 v28, vcc, s28, v20
	s_nop 1
	v_addc_co_u32_e32 v29, vcc, 0, v21, vcc
	v_add_co_u32_e32 v30, vcc, s29, v20
	s_nop 1
	v_addc_co_u32_e32 v31, vcc, 0, v21, vcc
	v_add_co_u32_e32 v32, vcc, s33, v20
	s_nop 1
	v_addc_co_u32_e32 v33, vcc, 0, v21, vcc
	v_add_co_u32_e32 v34, vcc, s36, v20
	s_nop 1
	v_addc_co_u32_e32 v35, vcc, 0, v21, vcc
	v_add_co_u32_e32 v36, vcc, s37, v20
	s_nop 1
	v_addc_co_u32_e32 v37, vcc, 0, v21, vcc
	v_add_co_u32_e32 v38, vcc, s40, v20
	s_nop 1
	v_addc_co_u32_e32 v39, vcc, 0, v21, vcc
	v_add_co_u32_e32 v40, vcc, s41, v20
	s_nop 1
	v_addc_co_u32_e32 v41, vcc, 0, v21, vcc
	v_add_co_u32_e32 v42, vcc, s42, v20
	s_nop 1
	v_addc_co_u32_e32 v43, vcc, 0, v21, vcc
	v_add_co_u32_e32 v44, vcc, s43, v20
	flat_load_dword v19, v[20:21] nt
	flat_load_dword v46, v[20:21] offset:2048 nt
	flat_load_dword v47, v[22:23] nt
	flat_load_dword v48, v[22:23] offset:2048 nt
	flat_load_dword v49, v[24:25] nt
	flat_load_dword v50, v[24:25] offset:2048 nt
	flat_load_dword v51, v[26:27] nt
	s_nop 0
	flat_load_dword v26, v[26:27] offset:2048 nt
	s_nop 0
	flat_load_dword v27, v[28:29] nt
	s_nop 0
	flat_load_dword v28, v[28:29] offset:2048 nt
	s_nop 0
	flat_load_dword v29, v[30:31] nt
	s_nop 0
	flat_load_dword v30, v[30:31] offset:2048 nt
	s_nop 0
	flat_load_dword v31, v[32:33] nt
	s_nop 0
	flat_load_dword v32, v[32:33] offset:2048 nt
	s_nop 0
	flat_load_dword v33, v[34:35] nt
	s_nop 0
	flat_load_dword v34, v[34:35] offset:2048 nt
	s_nop 0
	flat_load_dword v35, v[36:37] nt
	s_nop 0
	flat_load_dword v36, v[36:37] offset:2048 nt
	s_nop 0
	flat_load_dword v37, v[38:39] nt
	s_nop 0
	flat_load_dword v38, v[38:39] offset:2048 nt
	s_nop 0
	flat_load_dword v39, v[40:41] nt
	s_nop 0
	flat_load_dword v40, v[40:41] offset:2048 nt
	s_nop 0
	flat_load_dword v41, v[42:43] nt
	s_nop 0
	flat_load_dword v42, v[42:43] offset:2048 nt
	v_addc_co_u32_e32 v45, vcc, 0, v21, vcc
	v_add_co_u32_e32 v22, vcc, s44, v20
	s_nop 1
	v_addc_co_u32_e32 v23, vcc, 0, v21, vcc
	v_add_co_u32_e32 v24, vcc, s45, v20
	s_nop 1
	v_addc_co_u32_e32 v25, vcc, 0, v21, vcc
	v_add_co_u32_e32 v20, vcc, s46, v20
	s_nop 1
	v_addc_co_u32_e32 v21, vcc, 0, v21, vcc
	flat_load_dword v43, v[44:45] nt
	s_nop 0
	flat_load_dword v44, v[44:45] offset:2048 nt
	s_nop 0
	flat_load_dword v45, v[22:23] nt
	s_nop 0
	flat_load_dword v22, v[22:23] offset:2048 nt
	s_nop 0
	flat_load_dword v23, v[24:25] nt
	s_nop 0
	flat_load_dword v24, v[24:25] offset:2048 nt
	s_nop 0
	flat_load_dword v25, v[20:21] nt
	s_nop 0
	flat_load_dword v20, v[20:21] offset:2048 nt
	s_waitcnt vmcnt(0) lgkmcnt(0)
	ds_write2_b32 v5, v19, v46 offset1:66
	ds_write2_b32 v5, v47, v48 offset0:132 offset1:198
	ds_write2_b32 v12, v49, v50 offset0:8 offset1:74
	ds_write2_b32 v12, v51, v26 offset0:140 offset1:206
	ds_write2_b32 v13, v27, v28 offset0:16 offset1:82
	ds_write2_b32 v13, v29, v30 offset0:148 offset1:214
	ds_write2_b32 v14, v31, v32 offset0:24 offset1:90
	ds_write2_b32 v14, v33, v34 offset0:156 offset1:222
	ds_write2_b32 v15, v35, v36 offset0:32 offset1:98
	ds_write2_b32 v15, v37, v38 offset0:164 offset1:230
	ds_write2_b32 v16, v39, v40 offset0:40 offset1:106
	ds_write2_b32 v16, v41, v42 offset0:172 offset1:238
	ds_write2_b32 v17, v43, v44 offset0:48 offset1:114
	ds_write2_b32 v17, v45, v22 offset0:180 offset1:246
	ds_write2_b32 v18, v23, v24 offset0:56 offset1:122
	ds_write2_b32 v18, v25, v20 offset0:188 offset1:254
	s_waitcnt lgkmcnt(0)
	ds_read2_b32 v[20:21], v7 offset1:33
	s_waitcnt lgkmcnt(0)
	v_cvt_pk_bf16_f32 v20, v20, v21
	ds_read2_b32 v[22:23], v7 offset0:66 offset1:99
	v_or_b32_e32 v19, s0, v6
	s_waitcnt lgkmcnt(0)
	v_cvt_pk_bf16_f32 v21, v22, v23
	ds_read2_b32 v[22:23], v7 offset0:132 offset1:165
	v_mov_b32_e32 v25, v1
	v_lshlrev_b32_e32 v24, 12, v19
	v_lshl_add_u64 v[28:29], v[2:3], 0, s[6:7]
	s_waitcnt lgkmcnt(0)
	v_cvt_pk_bf16_f32 v22, v22, v23
	ds_read2_b32 v[26:27], v7 offset0:198 offset1:231
	s_waitcnt lgkmcnt(0)
	v_cvt_pk_bf16_f32 v23, v26, v27
	v_lshl_add_u64 v[24:25], v[28:29], 0, v[24:25]
	ds_read2_b32 v[26:27], v7 offset0:8 offset1:41
	global_store_dwordx4 v[24:25], v[20:23], off
	v_or_b32_e32 v19, s0, v8
	s_waitcnt lgkmcnt(0)
	v_cvt_pk_bf16_f32 v20, v26, v27
	ds_read2_b32 v[22:23], v7 offset0:74 offset1:107
	s_waitcnt lgkmcnt(0)
	v_cvt_pk_bf16_f32 v21, v22, v23
	ds_read2_b32 v[22:23], v7 offset0:140 offset1:173
	v_mov_b32_e32 v27, v1
	v_lshlrev_b32_e32 v26, 12, v19
	s_waitcnt lgkmcnt(0)
	v_cvt_pk_bf16_f32 v22, v22, v23
	ds_read2_b32 v[24:25], v7 offset0:206 offset1:239
	s_waitcnt lgkmcnt(0)
	v_cvt_pk_bf16_f32 v23, v24, v25
	v_lshl_add_u64 v[26:27], v[28:29], 0, v[26:27]
	ds_read2_b32 v[24:25], v7 offset0:16 offset1:49
	global_store_dwordx4 v[26:27], v[20:23], off
	v_or_b32_e32 v19, s0, v9
	v_mov_b32_e32 v27, v1
	s_waitcnt lgkmcnt(0)
	v_cvt_pk_bf16_f32 v20, v24, v25
	ds_read2_b32 v[22:23], v7 offset0:82 offset1:115
	s_waitcnt lgkmcnt(0)
	v_cvt_pk_bf16_f32 v21, v22, v23
	ds_read2_b32 v[22:23], v7 offset0:148 offset1:181
	v_lshlrev_b32_e32 v26, 12, v19
	s_waitcnt lgkmcnt(0)
	v_cvt_pk_bf16_f32 v22, v22, v23
	ds_read2_b32 v[24:25], v7 offset0:214 offset1:247
	s_waitcnt lgkmcnt(0)
	v_cvt_pk_bf16_f32 v23, v24, v25
	v_lshl_add_u64 v[26:27], v[28:29], 0, v[26:27]
	ds_read2_b32 v[24:25], v7 offset0:24 offset1:57
	global_store_dwordx4 v[26:27], v[20:23], off
	v_or_b32_e32 v19, s0, v10
	v_mov_b32_e32 v27, v1
	s_waitcnt lgkmcnt(0)
	v_cvt_pk_bf16_f32 v20, v24, v25
	ds_read2_b32 v[22:23], v7 offset0:90 offset1:123
	s_waitcnt lgkmcnt(0)
	v_cvt_pk_bf16_f32 v21, v22, v23
	ds_read2_b32 v[22:23], v7 offset0:156 offset1:189
	s_waitcnt lgkmcnt(0)
	v_cvt_pk_bf16_f32 v22, v22, v23
	ds_read2_b32 v[24:25], v7 offset0:222 offset1:255
	v_lshlrev_b32_e32 v26, 12, v19
	s_waitcnt lgkmcnt(0)
	v_cvt_pk_bf16_f32 v23, v24, v25
	v_lshl_add_u64 v[24:25], v[28:29], 0, v[26:27]
	global_store_dwordx4 v[24:25], v[20:23], off
	s_waitcnt lgkmcnt(0)
	s_mov_b64 s[0:1], 0
.LBB0_222:
	s_andn2_b64 vcc, exec, s[0:1]
	s_cbranch_vccnz .LBB0_224
	v_readlane_b32 s0, v255, 10
	v_readlane_b32 s1, v255, 11
	v_mov_b32_e32 v23, v1
	s_nop 0
	v_mov_b64_e32 v[20:21], s[0:1]
	flat_load_dwordx2 v[20:21], v[20:21] offset:160 sc0 sc1
	s_waitcnt vmcnt(0)
	s_add_i32 s0, s4, 0xffe0
	s_and_b32 s1, s0, 0xff
	s_mulk_i32 s1, 0xab
	s_bfe_u32 s10, s1, 0x70009
	s_mul_i32 s1, s10, 3
	v_lshl_or_b32 v19, s10, 6, v4
	s_sub_i32 s0, s0, s1
	v_mul_u32_u24_e32 v19, 0x60, v19
	s_lshl_b32 s0, s0, 5
	v_lshlrev_b32_e32 v22, 2, v19
	s_and_b32 s11, s0, 0xe0
	s_lshl_b32 s6, s11, 2
	s_addk_i32 s11, 0x1960
	s_waitcnt lgkmcnt(0)
	v_readfirstlane_b32 s1, v21
	v_readfirstlane_b32 s0, v20
	s_nop 1
	v_lshl_add_u64 v[20:21], s[0:1], 0, v[22:23]
	v_lshl_add_u64 v[20:21], v[20:21], 0, s[6:7]
	v_lshl_add_u64 v[20:21], v[20:21], 0, v[0:1]
	v_add_co_u32_e32 v24, vcc, s47, v20
	v_lshl_add_u64 v[22:23], v[20:21], 0, s[8:9]
	s_nop 0
	v_addc_co_u32_e32 v25, vcc, 0, v21, vcc
	v_add_co_u32_e32 v26, vcc, s48, v20
	s_lshl_b32 s6, s10, 7
	s_nop 0
	v_addc_co_u32_e32 v27, vcc, 0, v21, vcc
	v_add_co_u32_e32 v28, vcc, s49, v20
	s_nop 1
	v_addc_co_u32_e32 v29, vcc, 0, v21, vcc
	v_add_co_u32_e32 v30, vcc, s50, v20
	s_nop 1
	v_addc_co_u32_e32 v31, vcc, 0, v21, vcc
	v_add_co_u32_e32 v32, vcc, s51, v20
	s_nop 1
	v_addc_co_u32_e32 v33, vcc, 0, v21, vcc
	v_add_co_u32_e32 v20, vcc, s52, v20
	s_nop 1
	v_addc_co_u32_e32 v21, vcc, 0, v21, vcc
	flat_load_dword v19, v[24:25] nt
	s_nop 0
	flat_load_dword v24, v[22:23] offset:768 nt
	flat_load_dword v25, v[22:23] offset:1536 nt
	flat_load_dword v34, v[22:23] offset:2304 nt
	flat_load_dword v35, v[22:23] offset:3072 nt
	flat_load_dword v36, v[26:27] offset:512 nt
	flat_load_dword v37, v[26:27] offset:1280 nt
	s_nop 0
	flat_load_dword v22, v[22:23] offset:3840 nt
	s_nop 0
	flat_load_dword v23, v[26:27] offset:2048 nt
	flat_load_dword v38, v[26:27] offset:2816 nt
	s_nop 0
	flat_load_dword v26, v[26:27] offset:3584 nt
	s_nop 0
	flat_load_dword v27, v[28:29] offset:256 nt
	flat_load_dword v39, v[28:29] offset:1024 nt
	flat_load_dword v40, v[28:29] offset:1792 nt
	flat_load_dword v41, v[28:29] offset:2560 nt
	s_nop 0
	flat_load_dword v28, v[28:29] offset:3328 nt
	s_nop 0
	flat_load_dword v29, v[30:31] nt
	flat_load_dword v42, v[30:31] offset:768 nt
	flat_load_dword v43, v[30:31] offset:1536 nt
	flat_load_dword v44, v[30:31] offset:2304 nt
	flat_load_dword v45, v[30:31] offset:3072 nt
	s_nop 0
	flat_load_dword v30, v[30:31] offset:3840 nt
	s_nop 0
	flat_load_dword v31, v[32:33] offset:512 nt
	flat_load_dword v46, v[32:33] offset:1280 nt
	flat_load_dword v47, v[32:33] offset:2048 nt
	flat_load_dword v48, v[32:33] offset:2816 nt
	s_nop 0
	flat_load_dword v32, v[32:33] offset:3584 nt
	s_nop 0
	flat_load_dword v33, v[20:21] offset:256 nt
	flat_load_dword v49, v[20:21] offset:1024 nt
	flat_load_dword v50, v[20:21] offset:1792 nt
	flat_load_dword v51, v[20:21] offset:2560 nt
	s_nop 0
	flat_load_dword v20, v[20:21] offset:3328 nt
	s_waitcnt vmcnt(0) lgkmcnt(0)
	ds_write2_b32 v5, v19, v24 offset1:66
	ds_write2_b32 v5, v25, v34 offset0:132 offset1:198
	ds_write2_b32 v12, v35, v22 offset0:8 offset1:74
	ds_write2_b32 v12, v36, v37 offset0:140 offset1:206
	ds_write2_b32 v13, v23, v38 offset0:16 offset1:82
	ds_write2_b32 v13, v26, v27 offset0:148 offset1:214
	ds_write2_b32 v14, v39, v40 offset0:24 offset1:90
	ds_write2_b32 v14, v41, v28 offset0:156 offset1:222
	ds_write2_b32 v15, v29, v42 offset0:32 offset1:98
	ds_write2_b32 v15, v43, v44 offset0:164 offset1:230
	ds_write2_b32 v16, v45, v30 offset0:40 offset1:106
	ds_write2_b32 v16, v31, v46 offset0:172 offset1:238
	ds_write2_b32 v17, v47, v48 offset0:48 offset1:114
	ds_write2_b32 v17, v32, v33 offset0:180 offset1:246
	ds_write2_b32 v18, v49, v50 offset0:56 offset1:122
	ds_write2_b32 v18, v51, v20 offset0:188 offset1:254
	s_waitcnt lgkmcnt(0)
	ds_read2_b32 v[20:21], v7 offset1:33
	s_waitcnt lgkmcnt(0)
	v_cvt_pk_bf16_f32 v20, v20, v21
	ds_read2_b32 v[22:23], v7 offset0:66 offset1:99
	v_or_b32_e32 v19, s11, v6
	s_waitcnt lgkmcnt(0)
	v_cvt_pk_bf16_f32 v21, v22, v23
	ds_read2_b32 v[22:23], v7 offset0:132 offset1:165
	v_mov_b32_e32 v27, v1
	v_lshlrev_b32_e32 v26, 12, v19
	v_lshl_add_u64 v[28:29], v[2:3], 0, s[6:7]
	s_waitcnt lgkmcnt(0)
	v_cvt_pk_bf16_f32 v22, v22, v23
	ds_read2_b32 v[24:25], v7 offset0:198 offset1:231
	s_waitcnt lgkmcnt(0)
	v_cvt_pk_bf16_f32 v23, v24, v25
	v_lshl_add_u64 v[26:27], v[28:29], 0, v[26:27]
	ds_read2_b32 v[24:25], v7 offset0:8 offset1:41
	global_store_dwordx4 v[26:27], v[20:23], off
	v_or_b32_e32 v19, s11, v8
	v_mov_b32_e32 v27, v1
	s_waitcnt lgkmcnt(0)
	v_cvt_pk_bf16_f32 v20, v24, v25
	ds_read2_b32 v[22:23], v7 offset0:74 offset1:107
	s_waitcnt lgkmcnt(0)
	v_cvt_pk_bf16_f32 v21, v22, v23
	ds_read2_b32 v[22:23], v7 offset0:140 offset1:173
	v_lshlrev_b32_e32 v26, 12, v19
	s_waitcnt lgkmcnt(0)
	v_cvt_pk_bf16_f32 v22, v22, v23
	ds_read2_b32 v[24:25], v7 offset0:206 offset1:239
	s_waitcnt lgkmcnt(0)
	v_cvt_pk_bf16_f32 v23, v24, v25
	v_lshl_add_u64 v[26:27], v[28:29], 0, v[26:27]
	ds_read2_b32 v[24:25], v7 offset0:16 offset1:49
	global_store_dwordx4 v[26:27], v[20:23], off
	v_or_b32_e32 v19, s11, v9
	v_mov_b32_e32 v27, v1
	s_waitcnt lgkmcnt(0)
	v_cvt_pk_bf16_f32 v20, v24, v25
	ds_read2_b32 v[22:23], v7 offset0:82 offset1:115
	s_waitcnt lgkmcnt(0)
	v_cvt_pk_bf16_f32 v21, v22, v23
	ds_read2_b32 v[22:23], v7 offset0:148 offset1:181
	v_lshlrev_b32_e32 v26, 12, v19
	s_waitcnt lgkmcnt(0)
	v_cvt_pk_bf16_f32 v22, v22, v23
	ds_read2_b32 v[24:25], v7 offset0:214 offset1:247
	s_waitcnt lgkmcnt(0)
	v_cvt_pk_bf16_f32 v23, v24, v25
	v_lshl_add_u64 v[26:27], v[28:29], 0, v[26:27]
	ds_read2_b32 v[24:25], v7 offset0:24 offset1:57
	global_store_dwordx4 v[26:27], v[20:23], off
	v_or_b32_e32 v19, s11, v10
	v_mov_b32_e32 v27, v1
	s_waitcnt lgkmcnt(0)
	v_cvt_pk_bf16_f32 v20, v24, v25
	ds_read2_b32 v[22:23], v7 offset0:90 offset1:123
	s_waitcnt lgkmcnt(0)
	v_cvt_pk_bf16_f32 v21, v22, v23
	ds_read2_b32 v[22:23], v7 offset0:156 offset1:189
	s_waitcnt lgkmcnt(0)
	v_cvt_pk_bf16_f32 v22, v22, v23
	ds_read2_b32 v[24:25], v7 offset0:222 offset1:255
	v_lshlrev_b32_e32 v26, 12, v19
	s_waitcnt lgkmcnt(0)
	v_cvt_pk_bf16_f32 v23, v24, v25
	v_lshl_add_u64 v[24:25], v[28:29], 0, v[26:27]
	global_store_dwordx4 v[24:25], v[20:23], off
	s_waitcnt lgkmcnt(0)

.LBB0_225:
	s_andn2_b64 vcc, exec, s[0:1]
	s_cbranch_vccnz .LBB0_227
	v_readlane_b32 s0, v255, 10
	v_readlane_b32 s1, v255, 11
	v_mov_b32_e32 v23, v1
	s_nop 0
	v_mov_b64_e32 v[20:21], s[0:1]
	flat_load_dwordx2 v[20:21], v[20:21] offset:160 sc0 sc1
	s_waitcnt vmcnt(0)
	s_add_i32 s0, s4, 64
	s_and_b32 s1, s0, 0xff
	s_mulk_i32 s1, 0xab
	s_bfe_u32 s10, s1, 0x70009
	s_mul_i32 s1, s10, 3
	v_lshl_or_b32 v19, s10, 6, v4
	s_sub_i32 s0, s0, s1
	v_mul_u32_u24_e32 v19, 0x60, v19
	s_lshl_b32 s0, s0, 5
	v_lshlrev_b32_e32 v22, 2, v19
	s_and_b32 s11, s0, 0xe0
	s_lshl_b32 s6, s11, 2
	s_waitcnt lgkmcnt(0)
	v_readfirstlane_b32 s1, v21
	v_readfirstlane_b32 s0, v20
	s_nop 1
	v_lshl_add_u64 v[20:21], s[0:1], 0, v[22:23]
	v_lshl_add_u64 v[20:21], v[20:21], 0, s[6:7]
	v_lshl_add_u64 v[20:21], v[20:21], 0, v[0:1]
	v_add_co_u32_e32 v22, vcc, s23, v20
	s_or_b32 s0, s11, 0x1900
	s_nop 0
	v_addc_co_u32_e32 v23, vcc, 0, v21, vcc
	v_add_co_u32_e32 v24, vcc, s24, v20
	s_lshl_b32 s6, s10, 7
	s_nop 0
	v_addc_co_u32_e32 v25, vcc, 0, v21, vcc
	v_add_co_u32_e32 v26, vcc, s25, v20
	s_nop 1
	v_addc_co_u32_e32 v27, vcc, 0, v21, vcc
	v_add_co_u32_e32 v28, vcc, s28, v20
	s_nop 1
	v_addc_co_u32_e32 v29, vcc, 0, v21, vcc
	v_add_co_u32_e32 v30, vcc, s29, v20
	s_nop 1
	v_addc_co_u32_e32 v31, vcc, 0, v21, vcc
	flat_load_dword v19, v[20:21] nt
	flat_load_dword v32, v[20:21] offset:768 nt
	flat_load_dword v33, v[20:21] offset:1536 nt
	flat_load_dword v34, v[20:21] offset:2304 nt
	flat_load_dword v35, v[20:21] offset:3072 nt
	s_nop 0
	flat_load_dword v20, v[20:21] offset:3840 nt
	s_nop 0
	flat_load_dword v21, v[22:23] offset:512 nt
	flat_load_dword v36, v[22:23] offset:1280 nt
	flat_load_dword v37, v[22:23] offset:2048 nt
	flat_load_dword v38, v[22:23] offset:2816 nt
	s_nop 0
	flat_load_dword v22, v[22:23] offset:3584 nt
	s_nop 0
	flat_load_dword v23, v[24:25] offset:256 nt
	flat_load_dword v39, v[24:25] offset:1024 nt
	flat_load_dword v40, v[24:25] offset:1792 nt
	flat_load_dword v41, v[24:25] offset:2560 nt
	s_nop 0
	flat_load_dword v24, v[24:25] offset:3328 nt
	s_nop 0
	flat_load_dword v25, v[26:27] nt
	flat_load_dword v42, v[26:27] offset:768 nt
	flat_load_dword v43, v[26:27] offset:1536 nt
	flat_load_dword v44, v[26:27] offset:2304 nt
	flat_load_dword v45, v[26:27] offset:3072 nt
	s_nop 0
	flat_load_dword v26, v[26:27] offset:3840 nt
	s_nop 0
	flat_load_dword v27, v[28:29] offset:512 nt
	flat_load_dword v46, v[28:29] offset:1280 nt
	flat_load_dword v47, v[28:29] offset:2048 nt
	flat_load_dword v48, v[28:29] offset:2816 nt
	s_nop 0
	flat_load_dword v28, v[28:29] offset:3584 nt
	s_nop 0
	flat_load_dword v29, v[30:31] offset:256 nt
	flat_load_dword v49, v[30:31] offset:1024 nt
	flat_load_dword v50, v[30:31] offset:1792 nt
	flat_load_dword v51, v[30:31] offset:2560 nt
	s_nop 0
	flat_load_dword v30, v[30:31] offset:3328 nt
	s_waitcnt vmcnt(0) lgkmcnt(0)
	ds_write2_b32 v5, v19, v32 offset1:66
	ds_write2_b32 v5, v33, v34 offset0:132 offset1:198
	ds_write2_b32 v12, v35, v20 offset0:8 offset1:74
	ds_write2_b32 v12, v21, v36 offset0:140 offset1:206
	ds_write2_b32 v13, v37, v38 offset0:16 offset1:82
	ds_write2_b32 v13, v22, v23 offset0:148 offset1:214
	ds_write2_b32 v14, v39, v40 offset0:24 offset1:90
	ds_write2_b32 v14, v41, v24 offset0:156 offset1:222
	ds_write2_b32 v15, v25, v42 offset0:32 offset1:98
	ds_write2_b32 v15, v43, v44 offset0:164 offset1:230
	ds_write2_b32 v16, v45, v26 offset0:40 offset1:106
	ds_write2_b32 v16, v27, v46 offset0:172 offset1:238
	ds_write2_b32 v17, v47, v48 offset0:48 offset1:114
	ds_write2_b32 v17, v28, v29 offset0:180 offset1:246
	ds_write2_b32 v18, v49, v50 offset0:56 offset1:122
	ds_write2_b32 v18, v51, v30 offset0:188 offset1:254
	s_waitcnt lgkmcnt(0)
	ds_read2_b32 v[20:21], v7 offset1:33
	s_waitcnt lgkmcnt(0)
	v_cvt_pk_bf16_f32 v20, v20, v21
	ds_read2_b32 v[22:23], v7 offset0:66 offset1:99
	v_or_b32_e32 v19, s0, v6
	s_waitcnt lgkmcnt(0)
	v_cvt_pk_bf16_f32 v21, v22, v23
	ds_read2_b32 v[22:23], v7 offset0:132 offset1:165
	v_mov_b32_e32 v27, v1
	v_lshlrev_b32_e32 v26, 12, v19
	v_lshl_add_u64 v[28:29], v[2:3], 0, s[6:7]
	s_waitcnt lgkmcnt(0)
	v_cvt_pk_bf16_f32 v22, v22, v23
	ds_read2_b32 v[24:25], v7 offset0:198 offset1:231
	s_waitcnt lgkmcnt(0)
	v_cvt_pk_bf16_f32 v23, v24, v25
	v_lshl_add_u64 v[26:27], v[28:29], 0, v[26:27]
	ds_read2_b32 v[24:25], v7 offset0:8 offset1:41
	global_store_dwordx4 v[26:27], v[20:23], off
	v_or_b32_e32 v19, s0, v8
	v_mov_b32_e32 v27, v1
	s_waitcnt lgkmcnt(0)
	v_cvt_pk_bf16_f32 v20, v24, v25
	ds_read2_b32 v[22:23], v7 offset0:74 offset1:107
	s_waitcnt lgkmcnt(0)
	v_cvt_pk_bf16_f32 v21, v22, v23
	ds_read2_b32 v[22:23], v7 offset0:140 offset1:173
	v_lshlrev_b32_e32 v26, 12, v19
	s_waitcnt lgkmcnt(0)
	v_cvt_pk_bf16_f32 v22, v22, v23
	ds_read2_b32 v[24:25], v7 offset0:206 offset1:239
	s_waitcnt lgkmcnt(0)
	v_cvt_pk_bf16_f32 v23, v24, v25
	v_lshl_add_u64 v[26:27], v[28:29], 0, v[26:27]
	ds_read2_b32 v[24:25], v7 offset0:16 offset1:49
	global_store_dwordx4 v[26:27], v[20:23], off
	v_or_b32_e32 v19, s0, v9
	v_mov_b32_e32 v27, v1
	s_waitcnt lgkmcnt(0)
	v_cvt_pk_bf16_f32 v20, v24, v25
	ds_read2_b32 v[22:23], v7 offset0:82 offset1:115
	s_waitcnt lgkmcnt(0)
	v_cvt_pk_bf16_f32 v21, v22, v23
	ds_read2_b32 v[22:23], v7 offset0:148 offset1:181
	v_lshlrev_b32_e32 v26, 12, v19
	s_waitcnt lgkmcnt(0)
	v_cvt_pk_bf16_f32 v22, v22, v23
	ds_read2_b32 v[24:25], v7 offset0:214 offset1:247
	s_waitcnt lgkmcnt(0)
	v_cvt_pk_bf16_f32 v23, v24, v25
	v_lshl_add_u64 v[26:27], v[28:29], 0, v[26:27]
	ds_read2_b32 v[24:25], v7 offset0:24 offset1:57
	global_store_dwordx4 v[26:27], v[20:23], off
	v_or_b32_e32 v19, s0, v10
	v_mov_b32_e32 v27, v1
	s_waitcnt lgkmcnt(0)
	v_cvt_pk_bf16_f32 v20, v24, v25
	ds_read2_b32 v[22:23], v7 offset0:90 offset1:123
	s_waitcnt lgkmcnt(0)
	v_cvt_pk_bf16_f32 v21, v22, v23
	ds_read2_b32 v[22:23], v7 offset0:156 offset1:189
	s_waitcnt lgkmcnt(0)
	v_cvt_pk_bf16_f32 v22, v22, v23
	ds_read2_b32 v[24:25], v7 offset0:222 offset1:255
	v_lshlrev_b32_e32 v26, 12, v19
	s_waitcnt lgkmcnt(0)
	v_cvt_pk_bf16_f32 v23, v24, v25
	v_lshl_add_u64 v[24:25], v[28:29], 0, v[26:27]
	global_store_dwordx4 v[24:25], v[20:23], off
	s_waitcnt lgkmcnt(0)

.LBB0_228:
	s_andn2_b64 vcc, exec, s[0:1]
	s_cbranch_vccnz .LBB0_230
	v_readlane_b32 s0, v255, 10
	v_readlane_b32 s1, v255, 11
	v_mov_b32_e32 v23, v1
	s_nop 0
	v_mov_b64_e32 v[20:21], s[0:1]
	flat_load_dwordx2 v[20:21], v[20:21] offset:136 sc0 sc1
	s_waitcnt vmcnt(0)
	s_add_i32 s0, s4, 0xffa0
	s_and_b32 s1, s0, 0xff
	s_mulk_i32 s1, 0xab
	s_bfe_u32 s10, s1, 0x70009
	s_mul_i32 s1, s10, 3
	v_lshl_or_b32 v19, s10, 6, v4
	s_sub_i32 s0, s0, s1
	v_mul_u32_u24_e32 v19, 0x60, v19
	s_lshl_b32 s0, s0, 5
	v_lshlrev_b32_e32 v22, 2, v19
	s_and_b32 s11, s0, 0xe0
	s_lshl_b32 s6, s11, 2
	s_addk_i32 s11, 0x1860
	s_waitcnt lgkmcnt(0)
	v_readfirstlane_b32 s1, v21
	v_readfirstlane_b32 s0, v20
	s_nop 1
	v_lshl_add_u64 v[20:21], s[0:1], 0, v[22:23]
	v_lshl_add_u64 v[20:21], v[20:21], 0, s[6:7]
	v_lshl_add_u64 v[20:21], v[20:21], 0, v[0:1]
	v_add_co_u32_e32 v24, vcc, s47, v20
	v_lshl_add_u64 v[22:23], v[20:21], 0, s[8:9]
	s_nop 0
	v_addc_co_u32_e32 v25, vcc, 0, v21, vcc
	v_add_co_u32_e32 v26, vcc, s48, v20
	s_lshl_b32 s6, s10, 7
	s_nop 0
	v_addc_co_u32_e32 v27, vcc, 0, v21, vcc
	v_add_co_u32_e32 v28, vcc, s49, v20
	s_nop 1
	v_addc_co_u32_e32 v29, vcc, 0, v21, vcc
	v_add_co_u32_e32 v30, vcc, s50, v20
	s_nop 1
	v_addc_co_u32_e32 v31, vcc, 0, v21, vcc
	v_add_co_u32_e32 v32, vcc, s51, v20
	s_nop 1
	v_addc_co_u32_e32 v33, vcc, 0, v21, vcc
	v_add_co_u32_e32 v20, vcc, s52, v20
	s_nop 1
	v_addc_co_u32_e32 v21, vcc, 0, v21, vcc
	flat_load_dword v19, v[24:25] nt
	s_nop 0
	flat_load_dword v24, v[22:23] offset:768 nt
	flat_load_dword v25, v[22:23] offset:1536 nt
	flat_load_dword v34, v[22:23] offset:2304 nt
	flat_load_dword v35, v[22:23] offset:3072 nt
	flat_load_dword v36, v[26:27] offset:512 nt
	flat_load_dword v37, v[26:27] offset:1280 nt
	s_nop 0
	flat_load_dword v22, v[22:23] offset:3840 nt
	s_nop 0
	flat_load_dword v23, v[26:27] offset:2048 nt
	flat_load_dword v38, v[26:27] offset:2816 nt
	s_nop 0
	flat_load_dword v26, v[26:27] offset:3584 nt
	s_nop 0
	flat_load_dword v27, v[28:29] offset:256 nt
	flat_load_dword v39, v[28:29] offset:1024 nt
	flat_load_dword v40, v[28:29] offset:1792 nt
	flat_load_dword v41, v[28:29] offset:2560 nt
	s_nop 0
	flat_load_dword v28, v[28:29] offset:3328 nt
	s_nop 0
	flat_load_dword v29, v[30:31] nt
	flat_load_dword v42, v[30:31] offset:768 nt
	flat_load_dword v43, v[30:31] offset:1536 nt
	flat_load_dword v44, v[30:31] offset:2304 nt
	flat_load_dword v45, v[30:31] offset:3072 nt
	s_nop 0
	flat_load_dword v30, v[30:31] offset:3840 nt
	s_nop 0
	flat_load_dword v31, v[32:33] offset:512 nt
	flat_load_dword v46, v[32:33] offset:1280 nt
	flat_load_dword v47, v[32:33] offset:2048 nt
	flat_load_dword v48, v[32:33] offset:2816 nt
	s_nop 0
	flat_load_dword v32, v[32:33] offset:3584 nt
	s_nop 0
	flat_load_dword v33, v[20:21] offset:256 nt
	flat_load_dword v49, v[20:21] offset:1024 nt
	flat_load_dword v50, v[20:21] offset:1792 nt
	flat_load_dword v51, v[20:21] offset:2560 nt
	s_nop 0
	flat_load_dword v20, v[20:21] offset:3328 nt
	s_waitcnt vmcnt(0) lgkmcnt(0)
	ds_write2_b32 v5, v19, v24 offset1:66
	ds_write2_b32 v5, v25, v34 offset0:132 offset1:198
	ds_write2_b32 v12, v35, v22 offset0:8 offset1:74
	ds_write2_b32 v12, v36, v37 offset0:140 offset1:206
	ds_write2_b32 v13, v23, v38 offset0:16 offset1:82
	ds_write2_b32 v13, v26, v27 offset0:148 offset1:214
	ds_write2_b32 v14, v39, v40 offset0:24 offset1:90
	ds_write2_b32 v14, v41, v28 offset0:156 offset1:222
	ds_write2_b32 v15, v29, v42 offset0:32 offset1:98
	ds_write2_b32 v15, v43, v44 offset0:164 offset1:230
	ds_write2_b32 v16, v45, v30 offset0:40 offset1:106
	ds_write2_b32 v16, v31, v46 offset0:172 offset1:238
	ds_write2_b32 v17, v47, v48 offset0:48 offset1:114
	ds_write2_b32 v17, v32, v33 offset0:180 offset1:246
	ds_write2_b32 v18, v49, v50 offset0:56 offset1:122
	ds_write2_b32 v18, v51, v20 offset0:188 offset1:254
	s_waitcnt lgkmcnt(0)
	ds_read2_b32 v[20:21], v7 offset1:33
	s_waitcnt lgkmcnt(0)
	v_cvt_pk_bf16_f32 v20, v20, v21
	ds_read2_b32 v[22:23], v7 offset0:66 offset1:99
	v_or_b32_e32 v19, s11, v6
	s_waitcnt lgkmcnt(0)
	v_cvt_pk_bf16_f32 v21, v22, v23
	ds_read2_b32 v[22:23], v7 offset0:132 offset1:165
	v_mov_b32_e32 v27, v1
	v_lshlrev_b32_e32 v26, 12, v19
	v_lshl_add_u64 v[28:29], v[2:3], 0, s[6:7]
	s_waitcnt lgkmcnt(0)
	v_cvt_pk_bf16_f32 v22, v22, v23
	ds_read2_b32 v[24:25], v7 offset0:198 offset1:231
	s_waitcnt lgkmcnt(0)
	v_cvt_pk_bf16_f32 v23, v24, v25
	v_lshl_add_u64 v[26:27], v[28:29], 0, v[26:27]
	ds_read2_b32 v[24:25], v7 offset0:8 offset1:41
	global_store_dwordx4 v[26:27], v[20:23], off
	v_or_b32_e32 v19, s11, v8
	v_mov_b32_e32 v27, v1
	s_waitcnt lgkmcnt(0)
	v_cvt_pk_bf16_f32 v20, v24, v25
	ds_read2_b32 v[22:23], v7 offset0:74 offset1:107
	s_waitcnt lgkmcnt(0)
	v_cvt_pk_bf16_f32 v21, v22, v23
	ds_read2_b32 v[22:23], v7 offset0:140 offset1:173
	v_lshlrev_b32_e32 v26, 12, v19
	s_waitcnt lgkmcnt(0)
	v_cvt_pk_bf16_f32 v22, v22, v23
	ds_read2_b32 v[24:25], v7 offset0:206 offset1:239
	s_waitcnt lgkmcnt(0)
	v_cvt_pk_bf16_f32 v23, v24, v25
	v_lshl_add_u64 v[26:27], v[28:29], 0, v[26:27]
	ds_read2_b32 v[24:25], v7 offset0:16 offset1:49
	global_store_dwordx4 v[26:27], v[20:23], off
	v_or_b32_e32 v19, s11, v9
	v_mov_b32_e32 v27, v1
	s_waitcnt lgkmcnt(0)
	v_cvt_pk_bf16_f32 v20, v24, v25
	ds_read2_b32 v[22:23], v7 offset0:82 offset1:115
	s_waitcnt lgkmcnt(0)
	v_cvt_pk_bf16_f32 v21, v22, v23
	ds_read2_b32 v[22:23], v7 offset0:148 offset1:181
	v_lshlrev_b32_e32 v26, 12, v19
	s_waitcnt lgkmcnt(0)
	v_cvt_pk_bf16_f32 v22, v22, v23
	ds_read2_b32 v[24:25], v7 offset0:214 offset1:247
	s_waitcnt lgkmcnt(0)
	v_cvt_pk_bf16_f32 v23, v24, v25
	v_lshl_add_u64 v[26:27], v[28:29], 0, v[26:27]
	ds_read2_b32 v[24:25], v7 offset0:24 offset1:57
	global_store_dwordx4 v[26:27], v[20:23], off
	v_or_b32_e32 v19, s11, v10
	v_mov_b32_e32 v27, v1
	s_waitcnt lgkmcnt(0)
	v_cvt_pk_bf16_f32 v20, v24, v25
	ds_read2_b32 v[22:23], v7 offset0:90 offset1:123
	s_waitcnt lgkmcnt(0)
	v_cvt_pk_bf16_f32 v21, v22, v23
	ds_read2_b32 v[22:23], v7 offset0:156 offset1:189
	s_waitcnt lgkmcnt(0)
	v_cvt_pk_bf16_f32 v22, v22, v23
	ds_read2_b32 v[24:25], v7 offset0:222 offset1:255
	v_lshlrev_b32_e32 v26, 12, v19
	s_waitcnt lgkmcnt(0)
	v_cvt_pk_bf16_f32 v23, v24, v25
	v_lshl_add_u64 v[24:25], v[28:29], 0, v[26:27]
	global_store_dwordx4 v[24:25], v[20:23], off
	s_waitcnt lgkmcnt(0)

.LBB0_231:
	s_andn2_b64 vcc, exec, s[0:1]
	s_cbranch_vccnz .LBB0_233
	v_readlane_b32 s0, v255, 10
	v_readlane_b32 s1, v255, 11
	v_mov_b32_e32 v23, v1
	s_nop 0
	v_mov_b64_e32 v[20:21], s[0:1]
	flat_load_dwordx2 v[20:21], v[20:21] offset:136 sc0 sc1
	s_waitcnt vmcnt(0)
	s_and_b32 s0, s4, 0xff
	s_mulk_i32 s0, 0xab
	s_lshr_b32 s10, s0, 9
	s_mul_i32 s0, s10, 3
	v_lshl_or_b32 v19, s10, 6, v4
	s_sub_i32 s0, s4, s0
	v_mul_u32_u24_e32 v19, 0x60, v19
	s_lshl_b32 s0, s0, 5
	v_lshlrev_b32_e32 v22, 2, v19
	s_and_b32 s11, s0, 0xe0
	s_lshl_b32 s6, s11, 2
	s_waitcnt lgkmcnt(0)
	v_readfirstlane_b32 s1, v21
	v_readfirstlane_b32 s0, v20
	s_nop 1
	v_lshl_add_u64 v[20:21], s[0:1], 0, v[22:23]
	v_lshl_add_u64 v[20:21], v[20:21], 0, s[6:7]
	v_lshl_add_u64 v[20:21], v[20:21], 0, v[0:1]
	v_add_co_u32_e32 v22, vcc, s23, v20
	s_or_b32 s0, s11, 0x1800
	s_nop 0
	v_addc_co_u32_e32 v23, vcc, 0, v21, vcc
	v_add_co_u32_e32 v24, vcc, s24, v20
	s_lshl_b32 s6, s10, 7
	s_nop 0
	v_addc_co_u32_e32 v25, vcc, 0, v21, vcc
	v_add_co_u32_e32 v26, vcc, s25, v20
	s_nop 1
	v_addc_co_u32_e32 v27, vcc, 0, v21, vcc
	v_add_co_u32_e32 v28, vcc, s28, v20
	s_nop 1
	v_addc_co_u32_e32 v29, vcc, 0, v21, vcc
	v_add_co_u32_e32 v30, vcc, s29, v20
	s_nop 1
	v_addc_co_u32_e32 v31, vcc, 0, v21, vcc
	flat_load_dword v19, v[20:21] nt
	flat_load_dword v32, v[20:21] offset:768 nt
	flat_load_dword v33, v[20:21] offset:1536 nt
	flat_load_dword v34, v[20:21] offset:2304 nt
	flat_load_dword v35, v[20:21] offset:3072 nt
	s_nop 0
	flat_load_dword v20, v[20:21] offset:3840 nt
	s_nop 0
	flat_load_dword v21, v[22:23] offset:512 nt
	flat_load_dword v36, v[22:23] offset:1280 nt
	flat_load_dword v37, v[22:23] offset:2048 nt
	flat_load_dword v38, v[22:23] offset:2816 nt
	s_nop 0
	flat_load_dword v22, v[22:23] offset:3584 nt
	s_nop 0
	flat_load_dword v23, v[24:25] offset:256 nt
	flat_load_dword v39, v[24:25] offset:1024 nt
	flat_load_dword v40, v[24:25] offset:1792 nt
	flat_load_dword v41, v[24:25] offset:2560 nt
	s_nop 0
	flat_load_dword v24, v[24:25] offset:3328 nt
	s_nop 0
	flat_load_dword v25, v[26:27] nt
	flat_load_dword v42, v[26:27] offset:768 nt
	flat_load_dword v43, v[26:27] offset:1536 nt
	flat_load_dword v44, v[26:27] offset:2304 nt
	flat_load_dword v45, v[26:27] offset:3072 nt
	s_nop 0
	flat_load_dword v26, v[26:27] offset:3840 nt
	s_nop 0
	flat_load_dword v27, v[28:29] offset:512 nt
	flat_load_dword v46, v[28:29] offset:1280 nt
	flat_load_dword v47, v[28:29] offset:2048 nt
	flat_load_dword v48, v[28:29] offset:2816 nt
	s_nop 0
	flat_load_dword v28, v[28:29] offset:3584 nt
	s_nop 0
	flat_load_dword v29, v[30:31] offset:256 nt
	flat_load_dword v49, v[30:31] offset:1024 nt
	flat_load_dword v50, v[30:31] offset:1792 nt
	flat_load_dword v51, v[30:31] offset:2560 nt
	s_nop 0
	flat_load_dword v30, v[30:31] offset:3328 nt
	s_waitcnt vmcnt(0) lgkmcnt(0)
	ds_write2_b32 v5, v19, v32 offset1:66
	ds_write2_b32 v5, v33, v34 offset0:132 offset1:198
	ds_write2_b32 v12, v35, v20 offset0:8 offset1:74
	ds_write2_b32 v12, v21, v36 offset0:140 offset1:206
	ds_write2_b32 v13, v37, v38 offset0:16 offset1:82
	ds_write2_b32 v13, v22, v23 offset0:148 offset1:214
	ds_write2_b32 v14, v39, v40 offset0:24 offset1:90
	ds_write2_b32 v14, v41, v24 offset0:156 offset1:222
	ds_write2_b32 v15, v25, v42 offset0:32 offset1:98
	ds_write2_b32 v15, v43, v44 offset0:164 offset1:230
	ds_write2_b32 v16, v45, v26 offset0:40 offset1:106
	ds_write2_b32 v16, v27, v46 offset0:172 offset1:238
	ds_write2_b32 v17, v47, v48 offset0:48 offset1:114
	ds_write2_b32 v17, v28, v29 offset0:180 offset1:246
	ds_write2_b32 v18, v49, v50 offset0:56 offset1:122
	ds_write2_b32 v18, v51, v30 offset0:188 offset1:254
	s_waitcnt lgkmcnt(0)
	ds_read2_b32 v[20:21], v7 offset1:33
	s_waitcnt lgkmcnt(0)
	v_cvt_pk_bf16_f32 v20, v20, v21
	ds_read2_b32 v[22:23], v7 offset0:66 offset1:99
	v_or_b32_e32 v19, s0, v6
	s_waitcnt lgkmcnt(0)
	v_cvt_pk_bf16_f32 v21, v22, v23
	ds_read2_b32 v[22:23], v7 offset0:132 offset1:165
	v_mov_b32_e32 v27, v1
	v_lshlrev_b32_e32 v26, 12, v19
	v_lshl_add_u64 v[28:29], v[2:3], 0, s[6:7]
	s_waitcnt lgkmcnt(0)
	v_cvt_pk_bf16_f32 v22, v22, v23
	ds_read2_b32 v[24:25], v7 offset0:198 offset1:231
	s_waitcnt lgkmcnt(0)
	v_cvt_pk_bf16_f32 v23, v24, v25
	v_lshl_add_u64 v[26:27], v[28:29], 0, v[26:27]
	ds_read2_b32 v[24:25], v7 offset0:8 offset1:41
	global_store_dwordx4 v[26:27], v[20:23], off
	v_or_b32_e32 v19, s0, v8
	v_mov_b32_e32 v27, v1
	s_waitcnt lgkmcnt(0)
	v_cvt_pk_bf16_f32 v20, v24, v25
	ds_read2_b32 v[22:23], v7 offset0:74 offset1:107
	s_waitcnt lgkmcnt(0)
	v_cvt_pk_bf16_f32 v21, v22, v23
	ds_read2_b32 v[22:23], v7 offset0:140 offset1:173
	v_lshlrev_b32_e32 v26, 12, v19
	s_waitcnt lgkmcnt(0)
	v_cvt_pk_bf16_f32 v22, v22, v23
	ds_read2_b32 v[24:25], v7 offset0:206 offset1:239
	s_waitcnt lgkmcnt(0)
	v_cvt_pk_bf16_f32 v23, v24, v25
	v_lshl_add_u64 v[26:27], v[28:29], 0, v[26:27]
	ds_read2_b32 v[24:25], v7 offset0:16 offset1:49
	global_store_dwordx4 v[26:27], v[20:23], off
	v_or_b32_e32 v19, s0, v9
	v_mov_b32_e32 v27, v1
	s_waitcnt lgkmcnt(0)
	v_cvt_pk_bf16_f32 v20, v24, v25
	ds_read2_b32 v[22:23], v7 offset0:82 offset1:115
	s_waitcnt lgkmcnt(0)
	v_cvt_pk_bf16_f32 v21, v22, v23
	ds_read2_b32 v[22:23], v7 offset0:148 offset1:181
	v_lshlrev_b32_e32 v26, 12, v19
	s_waitcnt lgkmcnt(0)
	v_cvt_pk_bf16_f32 v22, v22, v23
	ds_read2_b32 v[24:25], v7 offset0:214 offset1:247
	s_waitcnt lgkmcnt(0)
	v_cvt_pk_bf16_f32 v23, v24, v25
	v_lshl_add_u64 v[26:27], v[28:29], 0, v[26:27]
	ds_read2_b32 v[24:25], v7 offset0:24 offset1:57
	global_store_dwordx4 v[26:27], v[20:23], off
	v_or_b32_e32 v19, s0, v10
	v_mov_b32_e32 v27, v1
	s_waitcnt lgkmcnt(0)
	v_cvt_pk_bf16_f32 v20, v24, v25
	ds_read2_b32 v[22:23], v7 offset0:90 offset1:123
	s_waitcnt lgkmcnt(0)
	v_cvt_pk_bf16_f32 v21, v22, v23
	ds_read2_b32 v[22:23], v7 offset0:156 offset1:189
	s_waitcnt lgkmcnt(0)
	v_cvt_pk_bf16_f32 v22, v22, v23
	ds_read2_b32 v[24:25], v7 offset0:222 offset1:255
	v_lshlrev_b32_e32 v26, 12, v19
	s_waitcnt lgkmcnt(0)
	v_cvt_pk_bf16_f32 v23, v24, v25
	v_lshl_add_u64 v[24:25], v[28:29], 0, v[26:27]
	global_store_dwordx4 v[24:25], v[20:23], off
	s_waitcnt lgkmcnt(0)

.LBB0_234:
	s_andn2_b64 vcc, exec, s[0:1]
	s_cbranch_vccnz .LBB0_236
	v_readlane_b32 s0, v255, 10
	v_readlane_b32 s1, v255, 11
	v_mov_b32_e32 v23, v1
	s_nop 0
	v_mov_b64_e32 v[20:21], s[0:1]
	flat_load_dwordx2 v[20:21], v[20:21] offset:112 sc0 sc1
	s_waitcnt vmcnt(0)
	s_add_i32 s1, s4, 0xf000
	s_and_b32 s1, s1, 0xffc0
	v_or_b32_e32 v19, s1, v4
	s_and_b32 s0, s14, 0x7e0
	v_lshlrev_b32_e32 v22, 13, v19
	s_lshl_b32 s6, s0, 2
	s_bitset1_b32 s0, 12
	s_waitcnt lgkmcnt(0)
	v_readfirstlane_b32 s11, v21
	v_readfirstlane_b32 s10, v20
	s_nop 1
	v_lshl_add_u64 v[20:21], s[10:11], 0, v[22:23]
	v_lshl_add_u64 v[20:21], v[20:21], 0, s[6:7]
	v_lshl_add_u64 v[20:21], v[20:21], 0, v[0:1]
	v_add_co_u32_e32 v22, vcc, s28, v20
	s_lshl_b32 s6, s1, 1
	s_nop 0
	v_addc_co_u32_e32 v23, vcc, 0, v21, vcc
	v_add_co_u32_e32 v24, vcc, s37, v20
	s_nop 1
	v_addc_co_u32_e32 v25, vcc, 0, v21, vcc
	v_add_co_u32_e32 v26, vcc, s43, v20
	s_nop 1
	v_addc_co_u32_e32 v27, vcc, 0, v21, vcc
	v_add_co_u32_e32 v28, vcc, s53, v20
	s_nop 1
	v_addc_co_u32_e32 v29, vcc, 0, v21, vcc
	v_add_co_u32_e32 v30, vcc, s54, v20
	s_nop 1
	v_addc_co_u32_e32 v31, vcc, 0, v21, vcc
	v_add_co_u32_e32 v32, vcc, s55, v20
	s_nop 1
	v_addc_co_u32_e32 v33, vcc, 0, v21, vcc
	v_add_co_u32_e32 v34, vcc, s56, v20
	s_nop 1
	v_addc_co_u32_e32 v35, vcc, 0, v21, vcc
	v_add_co_u32_e32 v36, vcc, s57, v20
	s_nop 1
	v_addc_co_u32_e32 v37, vcc, 0, v21, vcc
	v_add_co_u32_e32 v38, vcc, s58, v20
	s_nop 1
	v_addc_co_u32_e32 v39, vcc, 0, v21, vcc
	v_add_co_u32_e32 v40, vcc, s59, v20
	s_nop 1
	v_addc_co_u32_e32 v41, vcc, 0, v21, vcc
	v_add_co_u32_e32 v42, vcc, s60, v20
	s_nop 1
	v_addc_co_u32_e32 v43, vcc, 0, v21, vcc
	v_add_co_u32_e32 v44, vcc, s61, v20
	s_nop 1
	v_addc_co_u32_e32 v45, vcc, 0, v21, vcc
	v_add_co_u32_e32 v46, vcc, s62, v20
	s_nop 1
	v_addc_co_u32_e32 v47, vcc, 0, v21, vcc
	v_add_co_u32_e32 v48, vcc, s63, v20
	s_nop 1
	v_addc_co_u32_e32 v49, vcc, 0, v21, vcc
	v_add_co_u32_e32 v50, vcc, s64, v20
	s_nop 1
	v_addc_co_u32_e32 v51, vcc, 0, v21, vcc
	flat_load_dword v19, v[20:21] nt
	flat_load_dword v52, v[22:23] nt
	flat_load_dword v53, v[24:25] nt
	flat_load_dword v54, v[26:27] nt
	flat_load_dword v55, v[28:29] nt
	flat_load_dword v56, v[30:31] nt
	flat_load_dword v57, v[32:33] nt
	flat_load_dword v58, v[34:35] nt
	flat_load_dword v59, v[36:37] nt
	s_nop 0
	flat_load_dword v38, v[38:39] nt
	s_nop 0
	flat_load_dword v39, v[40:41] nt
	s_nop 0
	flat_load_dword v40, v[42:43] nt
	flat_load_dword v41, v[44:45] nt
	s_nop 0
	flat_load_dword v42, v[46:47] nt
	flat_load_dword v43, v[48:49] nt
	flat_load_dword v44, v[50:51] nt
	v_add_co_u32_e32 v22, vcc, s65, v20
	s_nop 1
	v_addc_co_u32_e32 v23, vcc, 0, v21, vcc
	v_add_co_u32_e32 v24, vcc, s66, v20
	s_nop 1
	v_addc_co_u32_e32 v25, vcc, 0, v21, vcc
	v_add_co_u32_e32 v26, vcc, s67, v20
	s_nop 1
	v_addc_co_u32_e32 v27, vcc, 0, v21, vcc
	v_add_co_u32_e32 v28, vcc, s68, v20
	s_nop 1
	v_addc_co_u32_e32 v29, vcc, 0, v21, vcc
	v_add_co_u32_e32 v30, vcc, s69, v20
	s_nop 1
	v_addc_co_u32_e32 v31, vcc, 0, v21, vcc
	v_add_co_u32_e32 v32, vcc, s70, v20
	s_nop 1
	v_addc_co_u32_e32 v33, vcc, 0, v21, vcc
	v_add_co_u32_e32 v34, vcc, s71, v20
	s_nop 1
	v_addc_co_u32_e32 v35, vcc, 0, v21, vcc
	v_add_co_u32_e32 v36, vcc, s72, v20
	s_nop 1
	v_addc_co_u32_e32 v37, vcc, 0, v21, vcc
	flat_load_dword v45, v[22:23] nt
	flat_load_dword v46, v[24:25] nt
	flat_load_dword v47, v[26:27] nt
	flat_load_dword v48, v[28:29] nt
	flat_load_dword v49, v[30:31] nt
	flat_load_dword v50, v[32:33] nt
	flat_load_dword v51, v[34:35] nt
	s_nop 0
	flat_load_dword v36, v[36:37] nt
	v_add_co_u32_e32 v22, vcc, s73, v20
	s_nop 1
	v_addc_co_u32_e32 v23, vcc, 0, v21, vcc
	v_add_co_u32_e32 v24, vcc, s74, v20
	s_nop 1
	v_addc_co_u32_e32 v25, vcc, 0, v21, vcc
	v_add_co_u32_e32 v26, vcc, s75, v20
	s_nop 1
	v_addc_co_u32_e32 v27, vcc, 0, v21, vcc
	v_add_co_u32_e32 v28, vcc, s76, v20
	s_nop 1
	v_addc_co_u32_e32 v29, vcc, 0, v21, vcc
	v_add_co_u32_e32 v30, vcc, s77, v20
	s_nop 1
	v_addc_co_u32_e32 v31, vcc, 0, v21, vcc
	v_add_co_u32_e32 v32, vcc, s78, v20
	s_nop 1
	v_addc_co_u32_e32 v33, vcc, 0, v21, vcc
	v_add_co_u32_e32 v34, vcc, s79, v20
	s_nop 1
	v_addc_co_u32_e32 v35, vcc, 0, v21, vcc
	v_add_co_u32_e32 v20, vcc, s80, v20
	s_nop 1
	v_addc_co_u32_e32 v21, vcc, 0, v21, vcc
	flat_load_dword v22, v[22:23] nt
	s_nop 0
	flat_load_dword v23, v[24:25] nt
	s_nop 0
	flat_load_dword v24, v[26:27] nt
	flat_load_dword v25, v[28:29] nt
	s_nop 0
	flat_load_dword v26, v[30:31] nt
	flat_load_dword v27, v[32:33] nt
	flat_load_dword v28, v[34:35] nt
	s_nop 0
	flat_load_dword v20, v[20:21] nt
	s_waitcnt vmcnt(0) lgkmcnt(0)
	ds_write2_b32 v5, v19, v52 offset1:66
	ds_write2_b32 v5, v53, v54 offset0:132 offset1:198
	ds_write2_b32 v12, v55, v56 offset0:8 offset1:74
	ds_write2_b32 v12, v57, v58 offset0:140 offset1:206
	ds_write2_b32 v13, v59, v38 offset0:16 offset1:82
	ds_write2_b32 v13, v39, v40 offset0:148 offset1:214
	ds_write2_b32 v14, v41, v42 offset0:24 offset1:90
	ds_write2_b32 v14, v43, v44 offset0:156 offset1:222
	ds_write2_b32 v15, v45, v46 offset0:32 offset1:98
	ds_write2_b32 v15, v47, v48 offset0:164 offset1:230
	ds_write2_b32 v16, v49, v50 offset0:40 offset1:106
	ds_write2_b32 v16, v51, v36 offset0:172 offset1:238
	ds_write2_b32 v17, v22, v23 offset0:48 offset1:114
	ds_write2_b32 v17, v24, v25 offset0:180 offset1:246
	ds_write2_b32 v18, v26, v27 offset0:56 offset1:122
	ds_write2_b32 v18, v28, v20 offset0:188 offset1:254
	s_waitcnt lgkmcnt(0)
	ds_read2_b32 v[20:21], v7 offset1:33
	s_waitcnt lgkmcnt(0)
	v_cvt_pk_bf16_f32 v20, v20, v21
	ds_read2_b32 v[22:23], v7 offset0:66 offset1:99
	v_or_b32_e32 v19, s0, v6
	s_waitcnt lgkmcnt(0)
	v_cvt_pk_bf16_f32 v21, v22, v23
	ds_read2_b32 v[22:23], v7 offset0:132 offset1:165
	v_lshl_add_u64 v[26:27], v[2:3], 0, s[6:7]
	v_lshlrev_b32_e32 v28, 12, v19
	v_mov_b32_e32 v29, v1
	s_waitcnt lgkmcnt(0)
	v_cvt_pk_bf16_f32 v22, v22, v23
	ds_read2_b32 v[24:25], v7 offset0:198 offset1:231
	s_waitcnt lgkmcnt(0)
	v_cvt_pk_bf16_f32 v23, v24, v25
	v_lshl_add_u64 v[28:29], v[26:27], 0, v[28:29]
	ds_read2_b32 v[24:25], v7 offset0:8 offset1:41
	global_store_dwordx4 v[28:29], v[20:23], off
	v_or_b32_e32 v19, s0, v8
	v_lshlrev_b32_e32 v28, 12, v19
	s_waitcnt lgkmcnt(0)
	v_cvt_pk_bf16_f32 v20, v24, v25
	ds_read2_b32 v[22:23], v7 offset0:74 offset1:107
	s_waitcnt lgkmcnt(0)
	v_cvt_pk_bf16_f32 v21, v22, v23
	ds_read2_b32 v[22:23], v7 offset0:140 offset1:173
	v_mov_b32_e32 v29, v1
	s_waitcnt lgkmcnt(0)
	v_cvt_pk_bf16_f32 v22, v22, v23
	ds_read2_b32 v[24:25], v7 offset0:206 offset1:239
	s_waitcnt lgkmcnt(0)
	v_cvt_pk_bf16_f32 v23, v24, v25
	v_lshl_add_u64 v[28:29], v[26:27], 0, v[28:29]
	ds_read2_b32 v[24:25], v7 offset0:16 offset1:49
	global_store_dwordx4 v[28:29], v[20:23], off
	v_or_b32_e32 v19, s0, v9
	v_mov_b32_e32 v29, v1
	s_waitcnt lgkmcnt(0)
	v_cvt_pk_bf16_f32 v20, v24, v25
	ds_read2_b32 v[22:23], v7 offset0:82 offset1:115
	s_waitcnt lgkmcnt(0)
	v_cvt_pk_bf16_f32 v21, v22, v23
	ds_read2_b32 v[22:23], v7 offset0:148 offset1:181
	v_lshlrev_b32_e32 v28, 12, v19
	s_waitcnt lgkmcnt(0)
	v_cvt_pk_bf16_f32 v22, v22, v23
	ds_read2_b32 v[24:25], v7 offset0:214 offset1:247
	s_waitcnt lgkmcnt(0)
	v_cvt_pk_bf16_f32 v23, v24, v25
	v_lshl_add_u64 v[28:29], v[26:27], 0, v[28:29]
	ds_read2_b32 v[24:25], v7 offset0:24 offset1:57
	global_store_dwordx4 v[28:29], v[20:23], off
	v_or_b32_e32 v19, s0, v10
	v_mov_b32_e32 v29, v1
	s_waitcnt lgkmcnt(0)
	v_cvt_pk_bf16_f32 v20, v24, v25
	ds_read2_b32 v[22:23], v7 offset0:90 offset1:123
	s_waitcnt lgkmcnt(0)
	v_cvt_pk_bf16_f32 v21, v22, v23
	ds_read2_b32 v[22:23], v7 offset0:156 offset1:189
	s_waitcnt lgkmcnt(0)
	v_cvt_pk_bf16_f32 v22, v22, v23
	ds_read2_b32 v[24:25], v7 offset0:222 offset1:255
	v_lshlrev_b32_e32 v28, 12, v19
	s_waitcnt lgkmcnt(0)
	v_cvt_pk_bf16_f32 v23, v24, v25
	v_lshl_add_u64 v[24:25], v[26:27], 0, v[28:29]
	global_store_dwordx4 v[24:25], v[20:23], off
	s_waitcnt lgkmcnt(0)

.LBB0_237:
	s_andn2_b64 vcc, exec, s[0:1]
	s_cbranch_vccnz .LBB0_239
	v_readlane_b32 s0, v255, 10
	v_readlane_b32 s1, v255, 11
	v_mov_b32_e32 v23, v1
	s_nop 0
	v_mov_b64_e32 v[20:21], s[0:1]
	flat_load_dwordx2 v[20:21], v[20:21] offset:104 sc0 sc1
	s_waitcnt vmcnt(0)
	s_add_i32 s1, s4, 0xf800
	s_and_b32 s1, s1, 0xffc0
	v_or_b32_e32 v19, s1, v4
	s_and_b32 s0, s14, 0x7e0
	v_lshlrev_b32_e32 v22, 13, v19
	s_lshl_b32 s6, s0, 2
	s_bitset1_b32 s0, 11
	s_waitcnt lgkmcnt(0)
	v_readfirstlane_b32 s11, v21
	v_readfirstlane_b32 s10, v20
	s_nop 1
	v_lshl_add_u64 v[20:21], s[10:11], 0, v[22:23]
	v_lshl_add_u64 v[20:21], v[20:21], 0, s[6:7]
	v_lshl_add_u64 v[20:21], v[20:21], 0, v[0:1]
	v_add_co_u32_e32 v22, vcc, s28, v20
	s_lshl_b32 s6, s1, 1
	s_nop 0
	v_addc_co_u32_e32 v23, vcc, 0, v21, vcc
	v_add_co_u32_e32 v24, vcc, s37, v20
	s_nop 1
	v_addc_co_u32_e32 v25, vcc, 0, v21, vcc
	v_add_co_u32_e32 v26, vcc, s43, v20
	s_nop 1
	v_addc_co_u32_e32 v27, vcc, 0, v21, vcc
	v_add_co_u32_e32 v28, vcc, s53, v20
	s_nop 1
	v_addc_co_u32_e32 v29, vcc, 0, v21, vcc
	v_add_co_u32_e32 v30, vcc, s54, v20
	s_nop 1
	v_addc_co_u32_e32 v31, vcc, 0, v21, vcc
	v_add_co_u32_e32 v32, vcc, s55, v20
	s_nop 1
	v_addc_co_u32_e32 v33, vcc, 0, v21, vcc
	v_add_co_u32_e32 v34, vcc, s56, v20
	s_nop 1
	v_addc_co_u32_e32 v35, vcc, 0, v21, vcc
	v_add_co_u32_e32 v36, vcc, s57, v20
	s_nop 1
	v_addc_co_u32_e32 v37, vcc, 0, v21, vcc
	v_add_co_u32_e32 v38, vcc, s58, v20
	s_nop 1
	v_addc_co_u32_e32 v39, vcc, 0, v21, vcc
	v_add_co_u32_e32 v40, vcc, s59, v20
	s_nop 1
	v_addc_co_u32_e32 v41, vcc, 0, v21, vcc
	v_add_co_u32_e32 v42, vcc, s60, v20
	s_nop 1
	v_addc_co_u32_e32 v43, vcc, 0, v21, vcc
	v_add_co_u32_e32 v44, vcc, s61, v20
	s_nop 1
	v_addc_co_u32_e32 v45, vcc, 0, v21, vcc
	v_add_co_u32_e32 v46, vcc, s62, v20
	s_nop 1
	v_addc_co_u32_e32 v47, vcc, 0, v21, vcc
	v_add_co_u32_e32 v48, vcc, s63, v20
	s_nop 1
	v_addc_co_u32_e32 v49, vcc, 0, v21, vcc
	v_add_co_u32_e32 v50, vcc, s64, v20
	s_nop 1
	v_addc_co_u32_e32 v51, vcc, 0, v21, vcc
	flat_load_dword v19, v[20:21] nt
	flat_load_dword v52, v[22:23] nt
	flat_load_dword v53, v[24:25] nt
	flat_load_dword v54, v[26:27] nt
	flat_load_dword v55, v[28:29] nt
	flat_load_dword v56, v[30:31] nt
	flat_load_dword v57, v[32:33] nt
	flat_load_dword v58, v[34:35] nt
	flat_load_dword v59, v[36:37] nt
	s_nop 0
	flat_load_dword v38, v[38:39] nt
	s_nop 0
	flat_load_dword v39, v[40:41] nt
	s_nop 0
	flat_load_dword v40, v[42:43] nt
	flat_load_dword v41, v[44:45] nt
	s_nop 0
	flat_load_dword v42, v[46:47] nt
	flat_load_dword v43, v[48:49] nt
	flat_load_dword v44, v[50:51] nt
	v_add_co_u32_e32 v22, vcc, s65, v20
	s_nop 1
	v_addc_co_u32_e32 v23, vcc, 0, v21, vcc
	v_add_co_u32_e32 v24, vcc, s66, v20
	s_nop 1
	v_addc_co_u32_e32 v25, vcc, 0, v21, vcc
	v_add_co_u32_e32 v26, vcc, s67, v20
	s_nop 1
	v_addc_co_u32_e32 v27, vcc, 0, v21, vcc
	v_add_co_u32_e32 v28, vcc, s68, v20
	s_nop 1
	v_addc_co_u32_e32 v29, vcc, 0, v21, vcc
	v_add_co_u32_e32 v30, vcc, s69, v20
	s_nop 1
	v_addc_co_u32_e32 v31, vcc, 0, v21, vcc
	v_add_co_u32_e32 v32, vcc, s70, v20
	s_nop 1
	v_addc_co_u32_e32 v33, vcc, 0, v21, vcc
	v_add_co_u32_e32 v34, vcc, s71, v20
	s_nop 1
	v_addc_co_u32_e32 v35, vcc, 0, v21, vcc
	v_add_co_u32_e32 v36, vcc, s72, v20
	s_nop 1
	v_addc_co_u32_e32 v37, vcc, 0, v21, vcc
	flat_load_dword v45, v[22:23] nt
	flat_load_dword v46, v[24:25] nt
	flat_load_dword v47, v[26:27] nt
	flat_load_dword v48, v[28:29] nt
	flat_load_dword v49, v[30:31] nt
	flat_load_dword v50, v[32:33] nt
	flat_load_dword v51, v[34:35] nt
	s_nop 0
	flat_load_dword v36, v[36:37] nt
	v_add_co_u32_e32 v22, vcc, s73, v20
	s_nop 1
	v_addc_co_u32_e32 v23, vcc, 0, v21, vcc
	v_add_co_u32_e32 v24, vcc, s74, v20
	s_nop 1
	v_addc_co_u32_e32 v25, vcc, 0, v21, vcc
	v_add_co_u32_e32 v26, vcc, s75, v20
	s_nop 1
	v_addc_co_u32_e32 v27, vcc, 0, v21, vcc
	v_add_co_u32_e32 v28, vcc, s76, v20
	s_nop 1
	v_addc_co_u32_e32 v29, vcc, 0, v21, vcc
	v_add_co_u32_e32 v30, vcc, s77, v20
	s_nop 1
	v_addc_co_u32_e32 v31, vcc, 0, v21, vcc
	v_add_co_u32_e32 v32, vcc, s78, v20
	s_nop 1
	v_addc_co_u32_e32 v33, vcc, 0, v21, vcc
	v_add_co_u32_e32 v34, vcc, s79, v20
	s_nop 1
	v_addc_co_u32_e32 v35, vcc, 0, v21, vcc
	v_add_co_u32_e32 v20, vcc, s80, v20
	s_nop 1
	v_addc_co_u32_e32 v21, vcc, 0, v21, vcc
	flat_load_dword v22, v[22:23] nt
	s_nop 0
	flat_load_dword v23, v[24:25] nt
	s_nop 0
	flat_load_dword v24, v[26:27] nt
	flat_load_dword v25, v[28:29] nt
	s_nop 0
	flat_load_dword v26, v[30:31] nt
	flat_load_dword v27, v[32:33] nt
	flat_load_dword v28, v[34:35] nt
	s_nop 0
	flat_load_dword v20, v[20:21] nt
	s_waitcnt vmcnt(0) lgkmcnt(0)
	ds_write2_b32 v5, v19, v52 offset1:66
	ds_write2_b32 v5, v53, v54 offset0:132 offset1:198
	ds_write2_b32 v12, v55, v56 offset0:8 offset1:74
	ds_write2_b32 v12, v57, v58 offset0:140 offset1:206
	ds_write2_b32 v13, v59, v38 offset0:16 offset1:82
	ds_write2_b32 v13, v39, v40 offset0:148 offset1:214
	ds_write2_b32 v14, v41, v42 offset0:24 offset1:90
	ds_write2_b32 v14, v43, v44 offset0:156 offset1:222
	ds_write2_b32 v15, v45, v46 offset0:32 offset1:98
	ds_write2_b32 v15, v47, v48 offset0:164 offset1:230
	ds_write2_b32 v16, v49, v50 offset0:40 offset1:106
	ds_write2_b32 v16, v51, v36 offset0:172 offset1:238
	ds_write2_b32 v17, v22, v23 offset0:48 offset1:114
	ds_write2_b32 v17, v24, v25 offset0:180 offset1:246
	ds_write2_b32 v18, v26, v27 offset0:56 offset1:122
	ds_write2_b32 v18, v28, v20 offset0:188 offset1:254
	s_waitcnt lgkmcnt(0)
	ds_read2_b32 v[20:21], v7 offset1:33
	s_waitcnt lgkmcnt(0)
	v_cvt_pk_bf16_f32 v20, v20, v21
	ds_read2_b32 v[22:23], v7 offset0:66 offset1:99
	v_or_b32_e32 v19, s0, v6
	s_waitcnt lgkmcnt(0)
	v_cvt_pk_bf16_f32 v21, v22, v23
	ds_read2_b32 v[22:23], v7 offset0:132 offset1:165
	v_lshl_add_u64 v[26:27], v[2:3], 0, s[6:7]
	v_lshlrev_b32_e32 v28, 12, v19
	v_mov_b32_e32 v29, v1
	s_waitcnt lgkmcnt(0)
	v_cvt_pk_bf16_f32 v22, v22, v23
	ds_read2_b32 v[24:25], v7 offset0:198 offset1:231
	s_waitcnt lgkmcnt(0)
	v_cvt_pk_bf16_f32 v23, v24, v25
	v_lshl_add_u64 v[28:29], v[26:27], 0, v[28:29]
	ds_read2_b32 v[24:25], v7 offset0:8 offset1:41
	global_store_dwordx4 v[28:29], v[20:23], off
	v_or_b32_e32 v19, s0, v8
	v_lshlrev_b32_e32 v28, 12, v19
	s_waitcnt lgkmcnt(0)
	v_cvt_pk_bf16_f32 v20, v24, v25
	ds_read2_b32 v[22:23], v7 offset0:74 offset1:107
	s_waitcnt lgkmcnt(0)
	v_cvt_pk_bf16_f32 v21, v22, v23
	ds_read2_b32 v[22:23], v7 offset0:140 offset1:173
	v_mov_b32_e32 v29, v1
	s_waitcnt lgkmcnt(0)
	v_cvt_pk_bf16_f32 v22, v22, v23
	ds_read2_b32 v[24:25], v7 offset0:206 offset1:239
	s_waitcnt lgkmcnt(0)
	v_cvt_pk_bf16_f32 v23, v24, v25
	v_lshl_add_u64 v[28:29], v[26:27], 0, v[28:29]
	ds_read2_b32 v[24:25], v7 offset0:16 offset1:49
	global_store_dwordx4 v[28:29], v[20:23], off
	v_or_b32_e32 v19, s0, v9
	v_mov_b32_e32 v29, v1
	s_waitcnt lgkmcnt(0)
	v_cvt_pk_bf16_f32 v20, v24, v25
	ds_read2_b32 v[22:23], v7 offset0:82 offset1:115
	s_waitcnt lgkmcnt(0)
	v_cvt_pk_bf16_f32 v21, v22, v23
	ds_read2_b32 v[22:23], v7 offset0:148 offset1:181
	v_lshlrev_b32_e32 v28, 12, v19
	s_waitcnt lgkmcnt(0)
	v_cvt_pk_bf16_f32 v22, v22, v23
	ds_read2_b32 v[24:25], v7 offset0:214 offset1:247
	s_waitcnt lgkmcnt(0)
	v_cvt_pk_bf16_f32 v23, v24, v25
	v_lshl_add_u64 v[28:29], v[26:27], 0, v[28:29]
	ds_read2_b32 v[24:25], v7 offset0:24 offset1:57
	global_store_dwordx4 v[28:29], v[20:23], off
	v_or_b32_e32 v19, s0, v10
	v_mov_b32_e32 v29, v1
	s_waitcnt lgkmcnt(0)
	v_cvt_pk_bf16_f32 v20, v24, v25
	ds_read2_b32 v[22:23], v7 offset0:90 offset1:123
	s_waitcnt lgkmcnt(0)
	v_cvt_pk_bf16_f32 v21, v22, v23
	ds_read2_b32 v[22:23], v7 offset0:156 offset1:189
	s_waitcnt lgkmcnt(0)
	v_cvt_pk_bf16_f32 v22, v22, v23
	ds_read2_b32 v[24:25], v7 offset0:222 offset1:255
	v_lshlrev_b32_e32 v28, 12, v19
	s_waitcnt lgkmcnt(0)
	v_cvt_pk_bf16_f32 v23, v24, v25
	v_lshl_add_u64 v[24:25], v[26:27], 0, v[28:29]
	global_store_dwordx4 v[24:25], v[20:23], off
	s_waitcnt lgkmcnt(0)

.LBB0_240:
	s_andn2_b64 vcc, exec, s[0:1]
	s_cbranch_vccnz .LBB0_213
	v_readlane_b32 s0, v255, 10
	v_readlane_b32 s1, v255, 11
	s_nop 1
	v_mov_b64_e32 v[20:21], s[0:1]
	flat_load_dwordx2 v[20:21], v[20:21] offset:96 sc0 sc1
	s_waitcnt vmcnt(0)
	s_ashr_i32 s0, s4, 31
	s_lshr_b32 s0, s0, 26
	s_add_i32 s0, s4, s0
	s_and_b32 s12, s0, 0xffffffc0
	s_lshl_b32 s1, s0, 5
	v_or_b32_e32 v22, s12, v4
	s_and_b32 s0, s1, 0xfffff800
	v_ashrrev_i32_e32 v23, 31, v22
	s_sub_i32 s10, s14, s0
	v_lshlrev_b64 v[22:23], 13, v[22:23]
	s_ashr_i32 s11, s10, 31
	s_ashr_i32 s13, s12, 31
	s_waitcnt lgkmcnt(0)
	v_readfirstlane_b32 s1, v21
	v_readfirstlane_b32 s0, v20
	s_nop 1
	v_lshl_add_u64 v[20:21], s[0:1], 0, v[22:23]
	v_lshl_add_u64 v[20:21], s[10:11], 2, v[20:21]
	v_lshl_add_u64 v[20:21], v[20:21], 0, v[0:1]
	v_add_co_u32_e32 v22, vcc, s28, v20
	s_nop 1
	v_addc_co_u32_e32 v23, vcc, 0, v21, vcc
	v_add_co_u32_e32 v24, vcc, s37, v20
	s_nop 1
	v_addc_co_u32_e32 v25, vcc, 0, v21, vcc
	v_add_co_u32_e32 v26, vcc, s43, v20
	s_nop 1
	v_addc_co_u32_e32 v27, vcc, 0, v21, vcc
	v_add_co_u32_e32 v28, vcc, s53, v20
	s_nop 1
	v_addc_co_u32_e32 v29, vcc, 0, v21, vcc
	v_add_co_u32_e32 v30, vcc, s54, v20
	s_nop 1
	v_addc_co_u32_e32 v31, vcc, 0, v21, vcc
	v_add_co_u32_e32 v32, vcc, s55, v20
	s_nop 1
	v_addc_co_u32_e32 v33, vcc, 0, v21, vcc
	v_add_co_u32_e32 v34, vcc, s56, v20
	s_nop 1
	v_addc_co_u32_e32 v35, vcc, 0, v21, vcc
	v_add_co_u32_e32 v36, vcc, s57, v20
	s_nop 1
	v_addc_co_u32_e32 v37, vcc, 0, v21, vcc
	v_add_co_u32_e32 v38, vcc, s58, v20
	s_nop 1
	v_addc_co_u32_e32 v39, vcc, 0, v21, vcc
	v_add_co_u32_e32 v40, vcc, s59, v20
	s_nop 1
	v_addc_co_u32_e32 v41, vcc, 0, v21, vcc
	v_add_co_u32_e32 v42, vcc, s60, v20
	s_nop 1
	v_addc_co_u32_e32 v43, vcc, 0, v21, vcc
	v_add_co_u32_e32 v44, vcc, s61, v20
	s_nop 1
	v_addc_co_u32_e32 v45, vcc, 0, v21, vcc
	v_add_co_u32_e32 v46, vcc, s62, v20
	s_nop 1
	v_addc_co_u32_e32 v47, vcc, 0, v21, vcc
	v_add_co_u32_e32 v48, vcc, s63, v20
	s_nop 1
	v_addc_co_u32_e32 v49, vcc, 0, v21, vcc
	v_add_co_u32_e32 v50, vcc, s64, v20
	s_nop 1
	v_addc_co_u32_e32 v51, vcc, 0, v21, vcc
	flat_load_dword v19, v[20:21] nt
	flat_load_dword v52, v[22:23] nt
	flat_load_dword v53, v[24:25] nt
	flat_load_dword v54, v[26:27] nt
	flat_load_dword v55, v[28:29] nt
	flat_load_dword v56, v[30:31] nt
	flat_load_dword v57, v[32:33] nt
	flat_load_dword v58, v[34:35] nt
	flat_load_dword v59, v[36:37] nt
	s_nop 0
	flat_load_dword v38, v[38:39] nt
	s_nop 0
	flat_load_dword v39, v[40:41] nt
	s_nop 0
	flat_load_dword v40, v[42:43] nt
	flat_load_dword v41, v[44:45] nt
	s_nop 0
	flat_load_dword v42, v[46:47] nt
	flat_load_dword v43, v[48:49] nt
	flat_load_dword v44, v[50:51] nt
	v_add_co_u32_e32 v22, vcc, s65, v20
	s_nop 1
	v_addc_co_u32_e32 v23, vcc, 0, v21, vcc
	v_add_co_u32_e32 v24, vcc, s66, v20
	s_nop 1
	v_addc_co_u32_e32 v25, vcc, 0, v21, vcc
	v_add_co_u32_e32 v26, vcc, s67, v20
	s_nop 1
	v_addc_co_u32_e32 v27, vcc, 0, v21, vcc
	v_add_co_u32_e32 v28, vcc, s68, v20
	s_nop 1
	v_addc_co_u32_e32 v29, vcc, 0, v21, vcc
	v_add_co_u32_e32 v30, vcc, s69, v20
	s_nop 1
	v_addc_co_u32_e32 v31, vcc, 0, v21, vcc
	v_add_co_u32_e32 v32, vcc, s70, v20
	s_nop 1
	v_addc_co_u32_e32 v33, vcc, 0, v21, vcc
	v_add_co_u32_e32 v34, vcc, s71, v20
	s_nop 1
	v_addc_co_u32_e32 v35, vcc, 0, v21, vcc
	v_add_co_u32_e32 v36, vcc, s72, v20
	s_nop 1
	v_addc_co_u32_e32 v37, vcc, 0, v21, vcc
	flat_load_dword v45, v[22:23] nt
	flat_load_dword v46, v[24:25] nt
	flat_load_dword v47, v[26:27] nt
	flat_load_dword v48, v[28:29] nt
	flat_load_dword v49, v[30:31] nt
	flat_load_dword v50, v[32:33] nt
	flat_load_dword v51, v[34:35] nt
	s_nop 0
	flat_load_dword v36, v[36:37] nt
	v_add_co_u32_e32 v22, vcc, s73, v20
	s_nop 1
	v_addc_co_u32_e32 v23, vcc, 0, v21, vcc
	v_add_co_u32_e32 v24, vcc, s74, v20
	s_nop 1
	v_addc_co_u32_e32 v25, vcc, 0, v21, vcc
	v_add_co_u32_e32 v26, vcc, s75, v20
	s_nop 1
	v_addc_co_u32_e32 v27, vcc, 0, v21, vcc
	v_add_co_u32_e32 v28, vcc, s76, v20
	s_nop 1
	v_addc_co_u32_e32 v29, vcc, 0, v21, vcc
	v_add_co_u32_e32 v30, vcc, s77, v20
	s_nop 1
	v_addc_co_u32_e32 v31, vcc, 0, v21, vcc
	v_add_co_u32_e32 v32, vcc, s78, v20
	s_nop 1
	v_addc_co_u32_e32 v33, vcc, 0, v21, vcc
	v_add_co_u32_e32 v34, vcc, s79, v20
	s_nop 1
	v_addc_co_u32_e32 v35, vcc, 0, v21, vcc
	v_add_co_u32_e32 v20, vcc, s80, v20
	s_nop 1
	v_addc_co_u32_e32 v21, vcc, 0, v21, vcc
	flat_load_dword v22, v[22:23] nt
	s_nop 0
	flat_load_dword v23, v[24:25] nt
	s_nop 0
	flat_load_dword v24, v[26:27] nt
	flat_load_dword v25, v[28:29] nt
	s_nop 0
	flat_load_dword v26, v[30:31] nt
	flat_load_dword v27, v[32:33] nt
	flat_load_dword v28, v[34:35] nt
	s_nop 0
	flat_load_dword v20, v[20:21] nt
	s_waitcnt vmcnt(0) lgkmcnt(0)
	ds_write2_b32 v5, v19, v52 offset1:66
	ds_write2_b32 v5, v53, v54 offset0:132 offset1:198
	ds_write2_b32 v12, v55, v56 offset0:8 offset1:74
	ds_write2_b32 v12, v57, v58 offset0:140 offset1:206
	ds_write2_b32 v13, v59, v38 offset0:16 offset1:82
	ds_write2_b32 v13, v39, v40 offset0:148 offset1:214
	ds_write2_b32 v14, v41, v42 offset0:24 offset1:90
	ds_write2_b32 v14, v43, v44 offset0:156 offset1:222
	ds_write2_b32 v15, v45, v46 offset0:32 offset1:98
	ds_write2_b32 v15, v47, v48 offset0:164 offset1:230
	ds_write2_b32 v16, v49, v50 offset0:40 offset1:106
	ds_write2_b32 v16, v51, v36 offset0:172 offset1:238
	ds_write2_b32 v17, v22, v23 offset0:48 offset1:114
	ds_write2_b32 v17, v24, v25 offset0:180 offset1:246
	ds_write2_b32 v18, v26, v27 offset0:56 offset1:122
	ds_write2_b32 v18, v28, v20 offset0:188 offset1:254
	s_waitcnt lgkmcnt(0)
	ds_read2_b32 v[20:21], v7 offset1:33
	s_waitcnt lgkmcnt(0)
	v_cvt_pk_bf16_f32 v20, v20, v21
	ds_read2_b32 v[22:23], v7 offset0:66 offset1:99
	s_waitcnt lgkmcnt(0)
	v_cvt_pk_bf16_f32 v21, v22, v23
	ds_read2_b32 v[22:23], v7 offset0:132 offset1:165
	s_waitcnt lgkmcnt(0)
	v_cvt_pk_bf16_f32 v22, v22, v23
	ds_read2_b32 v[24:25], v7 offset0:198 offset1:231
	s_waitcnt lgkmcnt(0)
	v_cvt_pk_bf16_f32 v23, v24, v25
	v_add_u32_e32 v24, s10, v6
	v_ashrrev_i32_e32 v25, 31, v24
	v_lshl_add_u64 v[26:27], s[12:13], 1, v[2:3]
	v_lshlrev_b64 v[30:31], 12, v[24:25]
	v_lshl_add_u64 v[30:31], v[26:27], 0, v[30:31]
	ds_read2_b32 v[28:29], v7 offset0:8 offset1:41
	global_store_dwordx4 v[30:31], v[20:23], off
	s_waitcnt lgkmcnt(0)
	s_nop 0
	v_cvt_pk_bf16_f32 v20, v28, v29
	ds_read2_b32 v[22:23], v7 offset0:74 offset1:107
	s_waitcnt lgkmcnt(0)
	v_cvt_pk_bf16_f32 v21, v22, v23
	ds_read2_b32 v[22:23], v7 offset0:140 offset1:173
	s_waitcnt lgkmcnt(0)
	v_cvt_pk_bf16_f32 v22, v22, v23
	ds_read2_b32 v[28:29], v7 offset0:206 offset1:239
	s_waitcnt lgkmcnt(0)
	v_cvt_pk_bf16_f32 v23, v28, v29
	v_add_u32_e32 v28, 8, v24
	v_ashrrev_i32_e32 v29, 31, v28
	v_lshlrev_b64 v[28:29], 12, v[28:29]
	ds_read2_b32 v[30:31], v7 offset0:16 offset1:49
	v_lshl_add_u64 v[28:29], v[26:27], 0, v[28:29]
	global_store_dwordx4 v[28:29], v[20:23], off
	s_waitcnt lgkmcnt(0)
	s_nop 0
	v_cvt_pk_bf16_f32 v20, v30, v31
	v_add_u32_e32 v30, 16, v24
	ds_read2_b32 v[22:23], v7 offset0:82 offset1:115
	v_ashrrev_i32_e32 v31, 31, v30
	s_waitcnt lgkmcnt(0)
	v_cvt_pk_bf16_f32 v21, v22, v23
	ds_read2_b32 v[22:23], v7 offset0:148 offset1:181
	v_lshlrev_b64 v[30:31], 12, v[30:31]
	v_add_u32_e32 v24, 24, v24
	s_waitcnt lgkmcnt(0)
	v_cvt_pk_bf16_f32 v22, v22, v23
	ds_read2_b32 v[28:29], v7 offset0:214 offset1:247
	s_waitcnt lgkmcnt(0)
	v_cvt_pk_bf16_f32 v23, v28, v29
	v_lshl_add_u64 v[30:31], v[26:27], 0, v[30:31]
	v_ashrrev_i32_e32 v25, 31, v24
	ds_read2_b32 v[28:29], v7 offset0:24 offset1:57
	global_store_dwordx4 v[30:31], v[20:23], off
	v_lshlrev_b64 v[24:25], 12, v[24:25]
	v_lshl_add_u64 v[24:25], v[26:27], 0, v[24:25]
	s_waitcnt lgkmcnt(0)
	v_cvt_pk_bf16_f32 v20, v28, v29
	ds_read2_b32 v[22:23], v7 offset0:90 offset1:123
	s_waitcnt lgkmcnt(0)
	v_cvt_pk_bf16_f32 v21, v22, v23
	ds_read2_b32 v[22:23], v7 offset0:156 offset1:189
	s_waitcnt lgkmcnt(0)
	v_cvt_pk_bf16_f32 v22, v22, v23
	ds_read2_b32 v[28:29], v7 offset0:222 offset1:255
	s_waitcnt lgkmcnt(0)
	v_cvt_pk_bf16_f32 v23, v28, v29
	global_store_dwordx4 v[24:25], v[20:23], off
	s_waitcnt lgkmcnt(0)
	s_branch .LBB0_213

.LBB0_326:
	s_sub_i32 s0, s10, 24
	v_ashrrev_i32_e32 v151, 31, v150
	v_mad_u64_u32 v[152:153], s[0:1], s0, v170, v[140:141]
	v_lshlrev_b64 v[154:155], 9, v[150:151]
	v_lshl_add_u64 v[154:155], v[152:153], 0, v[154:155]
	s_cmp_lt_i32 s10, 26
	s_mov_b64 s[0:1], -1
	v_cvt_pk_bf16_f32 v172, v158, v159
	v_cvt_pk_bf16_f32 v173, v162, v163
	v_cvt_pk_bf16_f32 v174, v156, v157
	v_cvt_pk_bf16_f32 v175, v160, v161
	global_store_dwordx4 v[154:155], v[172:175], off
	s_cbranch_scc1 .LBB0_330
	s_cmp_eq_u32 s10, 26
	v_mov_b32_e32 v161, v107
	v_mov_b32_e32 v160, v106
	v_mov_b32_e32 v157, v105
	v_mov_b32_e32 v156, v104
	v_mov_b32_e32 v163, v111
	v_mov_b32_e32 v162, v110
	v_mov_b32_e32 v159, v109
	v_mov_b32_e32 v158, v108
	s_cbranch_scc0 .LBB0_329
	v_mul_f32_e32 v138, 0xbfb8aa3b, v108
	v_exp_f32_e32 v138, v138
	v_mul_f32_e32 v157, 0xbfb8aa3b, v105
	v_exp_f32_e32 v157, v157
	v_mul_f32_e32 v156, 0xbfb8aa3b, v104
	v_add_f32_e32 v138, 1.0, v138
	v_rcp_f32_e32 v158, v138
	v_mul_f32_e32 v138, 0xbfb8aa3b, v109
	v_exp_f32_e32 v138, v138
	v_exp_f32_e32 v156, v156
	v_add_f32_e32 v138, 1.0, v138
	v_rcp_f32_e32 v159, v138
	v_add_f32_e32 v138, 1.0, v157
	v_mul_f32_e32 v157, 0xbfb8aa3b, v110
	v_exp_f32_e32 v160, v157
	v_mul_f32_e32 v157, 0xbfb8aa3b, v106
	v_exp_f32_e32 v161, v157
	v_rcp_f32_e32 v157, v138
	v_add_f32_e32 v138, 1.0, v160
	v_mul_f32_e32 v160, 0xbfb8aa3b, v111
	v_rcp_f32_e32 v162, v138
	v_add_f32_e32 v138, 1.0, v161
	v_exp_f32_e32 v161, v160
	v_mul_f32_e32 v160, 0xbfb8aa3b, v107
	v_exp_f32_e32 v171, v160
	v_rcp_f32_e32 v160, v138
	v_add_f32_e32 v138, 1.0, v161
	v_add_f32_e32 v156, 1.0, v156
	v_rcp_f32_e32 v163, v138
	v_add_f32_e32 v138, 1.0, v171
	v_rcp_f32_e32 v156, v156
	v_rcp_f32_e32 v161, v138

.LBB0_333:
	s_cmp_lt_i32 s10, 26
	s_mov_b64 s[0:1], -1
	v_cvt_pk_bf16_f32 v172, v158, v159
	v_cvt_pk_bf16_f32 v173, v162, v163
	v_cvt_pk_bf16_f32 v174, v156, v157
	v_cvt_pk_bf16_f32 v175, v160, v161
	global_store_dwordx4 v[154:155], v[172:175], off offset:256
	s_cbranch_scc1 .LBB0_337
	s_cmp_eq_u32 s10, 26
	v_mov_b32_e32 v161, v115
	v_mov_b32_e32 v160, v114
	v_mov_b32_e32 v157, v113
	v_mov_b32_e32 v156, v112
	v_mov_b32_e32 v163, v119
	v_mov_b32_e32 v162, v118
	v_mov_b32_e32 v159, v117
	v_mov_b32_e32 v158, v116
	s_cbranch_scc0 .LBB0_336
	v_mul_f32_e32 v138, 0xbfb8aa3b, v116
	v_exp_f32_e32 v138, v138
	v_mul_f32_e32 v154, 0xbfb8aa3b, v112
	v_exp_f32_e32 v154, v154
	v_mul_f32_e32 v155, 0xbfb8aa3b, v113
	v_add_f32_e32 v138, 1.0, v138
	v_rcp_f32_e32 v158, v138
	v_mul_f32_e32 v138, 0xbfb8aa3b, v117
	v_exp_f32_e32 v138, v138
	v_exp_f32_e32 v155, v155
	v_add_f32_e32 v154, 1.0, v154
	v_rcp_f32_e32 v156, v154
	v_add_f32_e32 v138, 1.0, v138
	v_mul_f32_e32 v154, 0xbfb8aa3b, v118
	v_rcp_f32_e32 v159, v138
	v_add_f32_e32 v138, 1.0, v155
	v_exp_f32_e32 v154, v154
	v_mul_f32_e32 v155, 0xbfb8aa3b, v114
	v_exp_f32_e32 v155, v155
	v_rcp_f32_e32 v157, v138
	v_add_f32_e32 v138, 1.0, v154
	v_mul_f32_e32 v154, 0xbfb8aa3b, v119
	v_rcp_f32_e32 v162, v138
	v_add_f32_e32 v138, 1.0, v155
	v_exp_f32_e32 v154, v154
	v_mul_f32_e32 v155, 0xbfb8aa3b, v115
	v_exp_f32_e32 v155, v155
	v_rcp_f32_e32 v160, v138
	v_add_f32_e32 v138, 1.0, v154
	v_rcp_f32_e32 v163, v138
	v_add_f32_e32 v138, 1.0, v155
	v_rcp_f32_e32 v161, v138

.LBB0_340:
	v_or_b32_e32 v154, 16, v150
	v_ashrrev_i32_e32 v155, 31, v154
	v_lshlrev_b64 v[154:155], 9, v[154:155]
	v_lshl_add_u64 v[154:155], v[152:153], 0, v[154:155]
	s_cmp_lt_i32 s10, 26
	s_mov_b64 s[0:1], -1
	v_cvt_pk_bf16_f32 v172, v158, v159
	v_cvt_pk_bf16_f32 v173, v162, v163
	v_cvt_pk_bf16_f32 v174, v156, v157
	v_cvt_pk_bf16_f32 v175, v160, v161
	global_store_dwordx4 v[154:155], v[172:175], off
	s_cbranch_scc1 .LBB0_344
	s_cmp_eq_u32 s10, 26
	v_mov_b32_e32 v161, v91
	v_mov_b32_e32 v160, v90
	v_mov_b32_e32 v157, v89
	v_mov_b32_e32 v156, v88
	v_mov_b32_e32 v163, v95
	v_mov_b32_e32 v162, v94
	v_mov_b32_e32 v159, v93
	v_mov_b32_e32 v158, v92
	s_cbranch_scc0 .LBB0_343
	v_mul_f32_e32 v138, 0xbfb8aa3b, v92
	v_exp_f32_e32 v138, v138
	v_mul_f32_e32 v157, 0xbfb8aa3b, v89
	v_exp_f32_e32 v157, v157
	v_mul_f32_e32 v156, 0xbfb8aa3b, v88
	v_add_f32_e32 v138, 1.0, v138
	v_rcp_f32_e32 v158, v138
	v_mul_f32_e32 v138, 0xbfb8aa3b, v93
	v_exp_f32_e32 v138, v138
	v_exp_f32_e32 v156, v156
	v_add_f32_e32 v138, 1.0, v138
	v_rcp_f32_e32 v159, v138
	v_add_f32_e32 v138, 1.0, v157
	v_mul_f32_e32 v157, 0xbfb8aa3b, v94
	v_exp_f32_e32 v160, v157
	v_mul_f32_e32 v157, 0xbfb8aa3b, v90
	v_exp_f32_e32 v161, v157
	v_rcp_f32_e32 v157, v138
	v_add_f32_e32 v138, 1.0, v160
	v_mul_f32_e32 v160, 0xbfb8aa3b, v95
	v_rcp_f32_e32 v162, v138
	v_add_f32_e32 v138, 1.0, v161
	v_exp_f32_e32 v161, v160
	v_mul_f32_e32 v160, 0xbfb8aa3b, v91
	v_exp_f32_e32 v171, v160
	v_rcp_f32_e32 v160, v138
	v_add_f32_e32 v138, 1.0, v161
	v_add_f32_e32 v156, 1.0, v156
	v_rcp_f32_e32 v163, v138
	v_add_f32_e32 v138, 1.0, v171
	v_rcp_f32_e32 v156, v156
	v_rcp_f32_e32 v161, v138

.LBB0_347:
	s_cmp_lt_i32 s10, 26
	s_mov_b64 s[0:1], -1
	v_cvt_pk_bf16_f32 v172, v158, v159
	v_cvt_pk_bf16_f32 v173, v162, v163
	v_cvt_pk_bf16_f32 v174, v156, v157
	v_cvt_pk_bf16_f32 v175, v160, v161
	global_store_dwordx4 v[154:155], v[172:175], off offset:256
	s_cbranch_scc1 .LBB0_351
	s_cmp_eq_u32 s10, 26
	v_mov_b32_e32 v161, v99
	v_mov_b32_e32 v160, v98
	v_mov_b32_e32 v157, v97
	v_mov_b32_e32 v156, v96
	v_mov_b32_e32 v163, v103
	v_mov_b32_e32 v162, v102
	v_mov_b32_e32 v159, v101
	v_mov_b32_e32 v158, v100
	s_cbranch_scc0 .LBB0_350
	v_mul_f32_e32 v138, 0xbfb8aa3b, v100
	v_exp_f32_e32 v138, v138
	v_mul_f32_e32 v154, 0xbfb8aa3b, v96
	v_exp_f32_e32 v154, v154
	v_mul_f32_e32 v155, 0xbfb8aa3b, v97
	v_add_f32_e32 v138, 1.0, v138
	v_rcp_f32_e32 v158, v138
	v_mul_f32_e32 v138, 0xbfb8aa3b, v101
	v_exp_f32_e32 v138, v138
	v_exp_f32_e32 v155, v155
	v_add_f32_e32 v154, 1.0, v154
	v_rcp_f32_e32 v156, v154
	v_add_f32_e32 v138, 1.0, v138
	v_mul_f32_e32 v154, 0xbfb8aa3b, v102
	v_rcp_f32_e32 v159, v138
	v_add_f32_e32 v138, 1.0, v155
	v_exp_f32_e32 v154, v154
	v_mul_f32_e32 v155, 0xbfb8aa3b, v98
	v_exp_f32_e32 v155, v155
	v_rcp_f32_e32 v157, v138
	v_add_f32_e32 v138, 1.0, v154
	v_mul_f32_e32 v154, 0xbfb8aa3b, v103
	v_rcp_f32_e32 v162, v138
	v_add_f32_e32 v138, 1.0, v155
	v_exp_f32_e32 v154, v154
	v_mul_f32_e32 v155, 0xbfb8aa3b, v99
	v_exp_f32_e32 v155, v155
	v_rcp_f32_e32 v160, v138
	v_add_f32_e32 v138, 1.0, v154
	v_rcp_f32_e32 v163, v138
	v_add_f32_e32 v138, 1.0, v155
	v_rcp_f32_e32 v161, v138

.LBB0_354:
	v_or_b32_e32 v154, 32, v150
	v_ashrrev_i32_e32 v155, 31, v154
	v_lshlrev_b64 v[154:155], 9, v[154:155]
	v_lshl_add_u64 v[154:155], v[152:153], 0, v[154:155]
	s_cmp_lt_i32 s10, 26
	s_mov_b64 s[0:1], -1
	v_cvt_pk_bf16_f32 v172, v158, v159
	v_cvt_pk_bf16_f32 v173, v162, v163
	v_cvt_pk_bf16_f32 v174, v156, v157
	v_cvt_pk_bf16_f32 v175, v160, v161
	global_store_dwordx4 v[154:155], v[172:175], off
	s_cbranch_scc1 .LBB0_358
	s_cmp_eq_u32 s10, 26
	v_mov_b32_e32 v161, v75
	v_mov_b32_e32 v160, v74
	v_mov_b32_e32 v157, v73
	v_mov_b32_e32 v156, v72
	v_mov_b32_e32 v163, v79
	v_mov_b32_e32 v162, v78
	v_mov_b32_e32 v159, v77
	v_mov_b32_e32 v158, v76
	s_cbranch_scc0 .LBB0_357
	v_mul_f32_e32 v138, 0xbfb8aa3b, v76
	v_exp_f32_e32 v138, v138
	v_mul_f32_e32 v157, 0xbfb8aa3b, v73
	v_exp_f32_e32 v157, v157
	v_mul_f32_e32 v156, 0xbfb8aa3b, v72
	v_add_f32_e32 v138, 1.0, v138
	v_rcp_f32_e32 v158, v138
	v_mul_f32_e32 v138, 0xbfb8aa3b, v77
	v_exp_f32_e32 v138, v138
	v_exp_f32_e32 v156, v156
	v_add_f32_e32 v138, 1.0, v138
	v_rcp_f32_e32 v159, v138
	v_add_f32_e32 v138, 1.0, v157
	v_mul_f32_e32 v157, 0xbfb8aa3b, v78
	v_exp_f32_e32 v160, v157
	v_mul_f32_e32 v157, 0xbfb8aa3b, v74
	v_exp_f32_e32 v161, v157
	v_rcp_f32_e32 v157, v138
	v_add_f32_e32 v138, 1.0, v160
	v_mul_f32_e32 v160, 0xbfb8aa3b, v79
	v_rcp_f32_e32 v162, v138
	v_add_f32_e32 v138, 1.0, v161
	v_exp_f32_e32 v161, v160
	v_mul_f32_e32 v160, 0xbfb8aa3b, v75
	v_exp_f32_e32 v171, v160
	v_rcp_f32_e32 v160, v138
	v_add_f32_e32 v138, 1.0, v161
	v_add_f32_e32 v156, 1.0, v156
	v_rcp_f32_e32 v163, v138
	v_add_f32_e32 v138, 1.0, v171
	v_rcp_f32_e32 v156, v156
	v_rcp_f32_e32 v161, v138

.LBB0_361:
	s_cmp_lt_i32 s10, 26
	s_mov_b64 s[0:1], -1
	v_cvt_pk_bf16_f32 v172, v158, v159
	v_cvt_pk_bf16_f32 v173, v162, v163
	v_cvt_pk_bf16_f32 v174, v156, v157
	v_cvt_pk_bf16_f32 v175, v160, v161
	global_store_dwordx4 v[154:155], v[172:175], off offset:256
	s_cbranch_scc1 .LBB0_365
	s_cmp_eq_u32 s10, 26
	v_mov_b32_e32 v161, v83
	v_mov_b32_e32 v160, v82
	v_mov_b32_e32 v157, v81
	v_mov_b32_e32 v156, v80
	v_mov_b32_e32 v163, v87
	v_mov_b32_e32 v162, v86
	v_mov_b32_e32 v159, v85
	v_mov_b32_e32 v158, v84
	s_cbranch_scc0 .LBB0_364
	v_mul_f32_e32 v138, 0xbfb8aa3b, v84
	v_exp_f32_e32 v138, v138
	v_mul_f32_e32 v154, 0xbfb8aa3b, v80
	v_exp_f32_e32 v154, v154
	v_mul_f32_e32 v155, 0xbfb8aa3b, v81
	v_add_f32_e32 v138, 1.0, v138
	v_rcp_f32_e32 v158, v138
	v_mul_f32_e32 v138, 0xbfb8aa3b, v85
	v_exp_f32_e32 v138, v138
	v_exp_f32_e32 v155, v155
	v_add_f32_e32 v154, 1.0, v154
	v_rcp_f32_e32 v156, v154
	v_add_f32_e32 v138, 1.0, v138
	v_mul_f32_e32 v154, 0xbfb8aa3b, v86
	v_rcp_f32_e32 v159, v138
	v_add_f32_e32 v138, 1.0, v155
	v_exp_f32_e32 v154, v154
	v_mul_f32_e32 v155, 0xbfb8aa3b, v82
	v_exp_f32_e32 v155, v155
	v_rcp_f32_e32 v157, v138
	v_add_f32_e32 v138, 1.0, v154
	v_mul_f32_e32 v154, 0xbfb8aa3b, v87
	v_rcp_f32_e32 v162, v138
	v_add_f32_e32 v138, 1.0, v155
	v_exp_f32_e32 v154, v154
	v_mul_f32_e32 v155, 0xbfb8aa3b, v83
	v_exp_f32_e32 v155, v155
	v_rcp_f32_e32 v160, v138
	v_add_f32_e32 v138, 1.0, v154
	v_rcp_f32_e32 v163, v138
	v_add_f32_e32 v138, 1.0, v155
	v_rcp_f32_e32 v161, v138

.LBB0_368:
	v_or_b32_e32 v154, 48, v150
	v_ashrrev_i32_e32 v155, 31, v154
	v_lshlrev_b64 v[154:155], 9, v[154:155]
	v_lshl_add_u64 v[154:155], v[152:153], 0, v[154:155]
	s_cmp_lt_i32 s10, 26
	s_mov_b64 s[0:1], -1
	v_cvt_pk_bf16_f32 v172, v158, v159
	v_cvt_pk_bf16_f32 v173, v162, v163
	v_cvt_pk_bf16_f32 v174, v156, v157
	v_cvt_pk_bf16_f32 v175, v160, v161
	global_store_dwordx4 v[154:155], v[172:175], off
	s_cbranch_scc1 .LBB0_372
	s_cmp_eq_u32 s10, 26
	v_mov_b32_e32 v161, v67
	v_mov_b32_e32 v160, v66
	v_mov_b32_e32 v157, v65
	v_mov_b32_e32 v156, v64
	v_mov_b32_e32 v163, v71
	v_mov_b32_e32 v162, v70
	v_mov_b32_e32 v159, v69
	v_mov_b32_e32 v158, v68
	s_cbranch_scc0 .LBB0_371
	v_mul_f32_e32 v138, 0xbfb8aa3b, v68
	v_exp_f32_e32 v138, v138
	v_mul_f32_e32 v157, 0xbfb8aa3b, v65
	v_exp_f32_e32 v157, v157
	v_mul_f32_e32 v156, 0xbfb8aa3b, v64
	v_add_f32_e32 v138, 1.0, v138
	v_rcp_f32_e32 v158, v138
	v_mul_f32_e32 v138, 0xbfb8aa3b, v69
	v_exp_f32_e32 v138, v138
	v_exp_f32_e32 v156, v156
	v_add_f32_e32 v138, 1.0, v138
	v_rcp_f32_e32 v159, v138
	v_add_f32_e32 v138, 1.0, v157
	v_mul_f32_e32 v157, 0xbfb8aa3b, v70
	v_exp_f32_e32 v160, v157
	v_mul_f32_e32 v157, 0xbfb8aa3b, v66
	v_exp_f32_e32 v161, v157
	v_rcp_f32_e32 v157, v138
	v_add_f32_e32 v138, 1.0, v160
	v_mul_f32_e32 v160, 0xbfb8aa3b, v71
	v_rcp_f32_e32 v162, v138
	v_add_f32_e32 v138, 1.0, v161
	v_exp_f32_e32 v161, v160
	v_mul_f32_e32 v160, 0xbfb8aa3b, v67
	v_exp_f32_e32 v171, v160
	v_rcp_f32_e32 v160, v138
	v_add_f32_e32 v138, 1.0, v161
	v_add_f32_e32 v156, 1.0, v156
	v_rcp_f32_e32 v163, v138
	v_add_f32_e32 v138, 1.0, v171
	v_rcp_f32_e32 v156, v156
	v_rcp_f32_e32 v161, v138

.LBB0_375:
	s_cmp_lt_i32 s10, 26
	s_mov_b64 s[0:1], -1
	v_cvt_pk_bf16_f32 v172, v158, v159
	v_cvt_pk_bf16_f32 v173, v162, v163
	v_cvt_pk_bf16_f32 v174, v156, v157
	v_cvt_pk_bf16_f32 v175, v160, v161
	global_store_dwordx4 v[154:155], v[172:175], off offset:256
	s_cbranch_scc1 .LBB0_379
	s_cmp_eq_u32 s10, 26
	v_mov_b32_e32 v161, v59
	v_mov_b32_e32 v160, v58
	v_mov_b32_e32 v157, v57
	v_mov_b32_e32 v156, v56
	v_mov_b32_e32 v163, v63
	v_mov_b32_e32 v162, v62
	v_mov_b32_e32 v159, v61
	v_mov_b32_e32 v158, v60
	s_cbranch_scc0 .LBB0_378
	v_mul_f32_e32 v138, 0xbfb8aa3b, v60
	v_exp_f32_e32 v138, v138
	v_mul_f32_e32 v154, 0xbfb8aa3b, v56
	v_exp_f32_e32 v154, v154
	v_mul_f32_e32 v155, 0xbfb8aa3b, v57
	v_add_f32_e32 v138, 1.0, v138
	v_rcp_f32_e32 v158, v138
	v_mul_f32_e32 v138, 0xbfb8aa3b, v61
	v_exp_f32_e32 v138, v138
	v_exp_f32_e32 v155, v155
	v_add_f32_e32 v154, 1.0, v154
	v_rcp_f32_e32 v156, v154
	v_add_f32_e32 v138, 1.0, v138
	v_mul_f32_e32 v154, 0xbfb8aa3b, v62
	v_rcp_f32_e32 v159, v138
	v_add_f32_e32 v138, 1.0, v155
	v_exp_f32_e32 v154, v154
	v_mul_f32_e32 v155, 0xbfb8aa3b, v58
	v_exp_f32_e32 v155, v155
	v_rcp_f32_e32 v157, v138
	v_add_f32_e32 v138, 1.0, v154
	v_mul_f32_e32 v154, 0xbfb8aa3b, v63
	v_rcp_f32_e32 v162, v138
	v_add_f32_e32 v138, 1.0, v155
	v_exp_f32_e32 v154, v154
	v_mul_f32_e32 v155, 0xbfb8aa3b, v59
	v_exp_f32_e32 v155, v155
	v_rcp_f32_e32 v160, v138
	v_add_f32_e32 v138, 1.0, v154
	v_rcp_f32_e32 v163, v138
	v_add_f32_e32 v138, 1.0, v155
	v_rcp_f32_e32 v161, v138

.LBB0_382:
	v_lshlrev_b64 v[154:155], 9, v[150:151]
	v_lshl_add_u64 v[176:177], v[152:153], 0, v[154:155]
	v_cvt_pk_bf16_f32 v172, v158, v159
	v_cvt_pk_bf16_f32 v173, v162, v163
	v_cvt_pk_bf16_f32 v174, v156, v157
	v_add_co_u32_e32 v156, vcc, 0x10000, v176
	v_lshl_add_u64 v[154:155], v[176:177], 0, s[40:41]
	s_nop 0
	v_addc_co_u32_e32 v157, vcc, 0, v177, vcc
	s_cmp_lt_i32 s10, 26
	s_mov_b64 s[0:1], -1
	v_cvt_pk_bf16_f32 v175, v160, v161
	global_store_dwordx4 v[156:157], v[172:175], off
	s_cbranch_scc1 .LBB0_386
	s_cmp_eq_u32 s10, 26
	v_mov_b32_e32 v161, v39
	v_mov_b32_e32 v160, v38
	v_mov_b32_e32 v157, v37
	v_mov_b32_e32 v156, v36
	v_mov_b32_e32 v163, v47
	v_mov_b32_e32 v162, v46
	v_mov_b32_e32 v159, v45
	v_mov_b32_e32 v158, v44
	s_cbranch_scc0 .LBB0_385
	v_mul_f32_e32 v138, 0xbfb8aa3b, v44
	v_exp_f32_e32 v138, v138
	v_mul_f32_e32 v157, 0xbfb8aa3b, v37
	v_exp_f32_e32 v157, v157
	v_mul_f32_e32 v156, 0xbfb8aa3b, v36
	v_add_f32_e32 v138, 1.0, v138
	v_rcp_f32_e32 v158, v138
	v_mul_f32_e32 v138, 0xbfb8aa3b, v45
	v_exp_f32_e32 v138, v138
	v_exp_f32_e32 v156, v156
	v_add_f32_e32 v138, 1.0, v138
	v_rcp_f32_e32 v159, v138
	v_add_f32_e32 v138, 1.0, v157
	v_mul_f32_e32 v157, 0xbfb8aa3b, v46
	v_exp_f32_e32 v160, v157
	v_mul_f32_e32 v157, 0xbfb8aa3b, v38
	v_exp_f32_e32 v161, v157
	v_rcp_f32_e32 v157, v138
	v_add_f32_e32 v138, 1.0, v160
	v_mul_f32_e32 v160, 0xbfb8aa3b, v47
	v_rcp_f32_e32 v162, v138
	v_add_f32_e32 v138, 1.0, v161
	v_exp_f32_e32 v161, v160
	v_mul_f32_e32 v160, 0xbfb8aa3b, v39
	v_exp_f32_e32 v171, v160
	v_rcp_f32_e32 v160, v138
	v_add_f32_e32 v138, 1.0, v161
	v_add_f32_e32 v156, 1.0, v156
	v_rcp_f32_e32 v163, v138
	v_add_f32_e32 v138, 1.0, v171
	v_rcp_f32_e32 v156, v156
	v_rcp_f32_e32 v161, v138

.LBB0_389:
	s_cmp_lt_i32 s10, 26
	s_mov_b64 s[0:1], -1
	v_cvt_pk_bf16_f32 v172, v158, v159
	v_cvt_pk_bf16_f32 v173, v162, v163
	v_cvt_pk_bf16_f32 v174, v156, v157
	v_cvt_pk_bf16_f32 v175, v160, v161
	global_store_dwordx4 v[154:155], v[172:175], off offset:256
	s_cbranch_scc1 .LBB0_393
	s_cmp_eq_u32 s10, 26
	v_mov_b32_e32 v161, v51
	v_mov_b32_e32 v160, v50
	v_mov_b32_e32 v157, v49
	v_mov_b32_e32 v156, v48
	v_mov_b32_e32 v163, v55
	v_mov_b32_e32 v162, v54
	v_mov_b32_e32 v159, v53
	v_mov_b32_e32 v158, v52
	s_cbranch_scc0 .LBB0_392
	v_mul_f32_e32 v138, 0xbfb8aa3b, v52
	v_exp_f32_e32 v138, v138
	v_mul_f32_e32 v154, 0xbfb8aa3b, v48
	v_exp_f32_e32 v154, v154
	v_mul_f32_e32 v155, 0xbfb8aa3b, v49
	v_add_f32_e32 v138, 1.0, v138
	v_rcp_f32_e32 v158, v138
	v_mul_f32_e32 v138, 0xbfb8aa3b, v53
	v_exp_f32_e32 v138, v138
	v_exp_f32_e32 v155, v155
	v_add_f32_e32 v154, 1.0, v154
	v_rcp_f32_e32 v156, v154
	v_add_f32_e32 v138, 1.0, v138
	v_mul_f32_e32 v154, 0xbfb8aa3b, v54
	v_rcp_f32_e32 v159, v138
	v_add_f32_e32 v138, 1.0, v155
	v_exp_f32_e32 v154, v154
	v_mul_f32_e32 v155, 0xbfb8aa3b, v50
	v_exp_f32_e32 v155, v155
	v_rcp_f32_e32 v157, v138
	v_add_f32_e32 v138, 1.0, v154
	v_mul_f32_e32 v154, 0xbfb8aa3b, v55
	v_rcp_f32_e32 v162, v138
	v_add_f32_e32 v138, 1.0, v155
	v_exp_f32_e32 v154, v154
	v_mul_f32_e32 v155, 0xbfb8aa3b, v51
	v_exp_f32_e32 v155, v155
	v_rcp_f32_e32 v160, v138
	v_add_f32_e32 v138, 1.0, v154
	v_rcp_f32_e32 v163, v138
	v_add_f32_e32 v138, 1.0, v155
	v_rcp_f32_e32 v161, v138

.LBB0_396:
	v_lshlrev_b64 v[154:155], 9, v[150:151]
	v_lshl_add_u64 v[176:177], v[152:153], 0, v[154:155]
	v_cvt_pk_bf16_f32 v172, v158, v159
	v_cvt_pk_bf16_f32 v173, v162, v163
	v_cvt_pk_bf16_f32 v174, v156, v157
	v_add_co_u32_e32 v156, vcc, 0x12000, v176
	v_lshl_add_u64 v[154:155], v[176:177], 0, s[42:43]
	s_nop 0
	v_addc_co_u32_e32 v157, vcc, 0, v177, vcc
	s_cmp_lt_i32 s10, 26
	s_mov_b64 s[0:1], -1
	v_cvt_pk_bf16_f32 v175, v160, v161
	global_store_dwordx4 v[156:157], v[172:175], off
	s_cbranch_scc1 .LBB0_400
	s_cmp_eq_u32 s10, 26
	v_mov_b32_e32 v161, v23
	v_mov_b32_e32 v160, v22
	v_mov_b32_e32 v157, v21
	v_mov_b32_e32 v156, v20
	v_mov_b32_e32 v163, v31
	v_mov_b32_e32 v162, v30
	v_mov_b32_e32 v159, v29
	v_mov_b32_e32 v158, v28
	s_cbranch_scc0 .LBB0_399
	v_mul_f32_e32 v138, 0xbfb8aa3b, v28
	v_exp_f32_e32 v138, v138
	v_mul_f32_e32 v157, 0xbfb8aa3b, v21
	v_exp_f32_e32 v157, v157
	v_mul_f32_e32 v156, 0xbfb8aa3b, v20
	v_add_f32_e32 v138, 1.0, v138
	v_rcp_f32_e32 v158, v138
	v_mul_f32_e32 v138, 0xbfb8aa3b, v29
	v_exp_f32_e32 v138, v138
	v_exp_f32_e32 v156, v156
	v_add_f32_e32 v138, 1.0, v138
	v_rcp_f32_e32 v159, v138
	v_add_f32_e32 v138, 1.0, v157
	v_mul_f32_e32 v157, 0xbfb8aa3b, v30
	v_exp_f32_e32 v160, v157
	v_mul_f32_e32 v157, 0xbfb8aa3b, v22
	v_exp_f32_e32 v161, v157
	v_rcp_f32_e32 v157, v138
	v_add_f32_e32 v138, 1.0, v160
	v_mul_f32_e32 v160, 0xbfb8aa3b, v31
	v_rcp_f32_e32 v162, v138
	v_add_f32_e32 v138, 1.0, v161
	v_exp_f32_e32 v161, v160
	v_mul_f32_e32 v160, 0xbfb8aa3b, v23
	v_exp_f32_e32 v171, v160
	v_rcp_f32_e32 v160, v138
	v_add_f32_e32 v138, 1.0, v161
	v_add_f32_e32 v156, 1.0, v156
	v_rcp_f32_e32 v163, v138
	v_add_f32_e32 v138, 1.0, v171
	v_rcp_f32_e32 v156, v156
	v_rcp_f32_e32 v161, v138

.LBB0_403:
	s_cmp_lt_i32 s10, 26
	s_mov_b64 s[0:1], -1
	v_cvt_pk_bf16_f32 v172, v158, v159
	v_cvt_pk_bf16_f32 v173, v162, v163
	v_cvt_pk_bf16_f32 v174, v156, v157
	v_cvt_pk_bf16_f32 v175, v160, v161
	global_store_dwordx4 v[154:155], v[172:175], off offset:256
	s_cbranch_scc1 .LBB0_407
	s_cmp_eq_u32 s10, 26
	v_mov_b32_e32 v161, v35
	v_mov_b32_e32 v160, v34
	v_mov_b32_e32 v157, v33
	v_mov_b32_e32 v156, v32
	v_mov_b32_e32 v163, v43
	v_mov_b32_e32 v162, v42
	v_mov_b32_e32 v159, v41
	v_mov_b32_e32 v158, v40
	s_cbranch_scc0 .LBB0_406
	v_mul_f32_e32 v138, 0xbfb8aa3b, v40
	v_exp_f32_e32 v138, v138
	v_mul_f32_e32 v154, 0xbfb8aa3b, v32
	v_exp_f32_e32 v154, v154
	v_mul_f32_e32 v155, 0xbfb8aa3b, v33
	v_add_f32_e32 v138, 1.0, v138
	v_rcp_f32_e32 v158, v138
	v_mul_f32_e32 v138, 0xbfb8aa3b, v41
	v_exp_f32_e32 v138, v138
	v_exp_f32_e32 v155, v155
	v_add_f32_e32 v154, 1.0, v154
	v_rcp_f32_e32 v156, v154
	v_add_f32_e32 v138, 1.0, v138
	v_mul_f32_e32 v154, 0xbfb8aa3b, v42
	v_rcp_f32_e32 v159, v138
	v_add_f32_e32 v138, 1.0, v155
	v_exp_f32_e32 v154, v154
	v_mul_f32_e32 v155, 0xbfb8aa3b, v34
	v_exp_f32_e32 v155, v155
	v_rcp_f32_e32 v157, v138
	v_add_f32_e32 v138, 1.0, v154
	v_mul_f32_e32 v154, 0xbfb8aa3b, v43
	v_rcp_f32_e32 v162, v138
	v_add_f32_e32 v138, 1.0, v155
	v_exp_f32_e32 v154, v154
	v_mul_f32_e32 v155, 0xbfb8aa3b, v35
	v_exp_f32_e32 v155, v155
	v_rcp_f32_e32 v160, v138
	v_add_f32_e32 v138, 1.0, v154
	v_rcp_f32_e32 v163, v138
	v_add_f32_e32 v138, 1.0, v155
	v_rcp_f32_e32 v161, v138

.LBB0_410:
	v_lshlrev_b64 v[154:155], 9, v[150:151]
	v_lshl_add_u64 v[176:177], v[152:153], 0, v[154:155]
	v_cvt_pk_bf16_f32 v172, v158, v159
	v_cvt_pk_bf16_f32 v173, v162, v163
	v_cvt_pk_bf16_f32 v174, v156, v157
	v_add_co_u32_e32 v156, vcc, 0x14000, v176
	v_lshl_add_u64 v[154:155], v[176:177], 0, s[44:45]
	s_nop 0
	v_addc_co_u32_e32 v157, vcc, 0, v177, vcc
	s_cmp_lt_i32 s10, 26
	s_mov_b64 s[0:1], -1
	v_cvt_pk_bf16_f32 v175, v160, v161
	global_store_dwordx4 v[156:157], v[172:175], off
	s_cbranch_scc1 .LBB0_414
	s_cmp_eq_u32 s10, 26
	v_mov_b32_e32 v161, v11
	v_mov_b32_e32 v160, v10
	v_mov_b32_e32 v157, v9
	v_mov_b32_e32 v156, v8
	v_mov_b32_e32 v163, v15
	v_mov_b32_e32 v162, v14
	v_mov_b32_e32 v159, v13
	v_mov_b32_e32 v158, v12
	s_cbranch_scc0 .LBB0_413
	v_mul_f32_e32 v138, 0xbfb8aa3b, v12
	v_exp_f32_e32 v138, v138
	v_mul_f32_e32 v157, 0xbfb8aa3b, v9
	v_exp_f32_e32 v157, v157
	v_mul_f32_e32 v156, 0xbfb8aa3b, v8
	v_add_f32_e32 v138, 1.0, v138
	v_rcp_f32_e32 v158, v138
	v_mul_f32_e32 v138, 0xbfb8aa3b, v13
	v_exp_f32_e32 v138, v138
	v_exp_f32_e32 v156, v156
	v_add_f32_e32 v138, 1.0, v138
	v_rcp_f32_e32 v159, v138
	v_add_f32_e32 v138, 1.0, v157
	v_mul_f32_e32 v157, 0xbfb8aa3b, v14
	v_exp_f32_e32 v160, v157
	v_mul_f32_e32 v157, 0xbfb8aa3b, v10
	v_exp_f32_e32 v161, v157
	v_rcp_f32_e32 v157, v138
	v_add_f32_e32 v138, 1.0, v160
	v_mul_f32_e32 v160, 0xbfb8aa3b, v15
	v_rcp_f32_e32 v162, v138
	v_add_f32_e32 v138, 1.0, v161
	v_exp_f32_e32 v161, v160
	v_mul_f32_e32 v160, 0xbfb8aa3b, v11
	v_exp_f32_e32 v171, v160
	v_rcp_f32_e32 v160, v138
	v_add_f32_e32 v138, 1.0, v161
	v_add_f32_e32 v156, 1.0, v156
	v_rcp_f32_e32 v163, v138
	v_add_f32_e32 v138, 1.0, v171
	v_rcp_f32_e32 v156, v156
	v_rcp_f32_e32 v161, v138

.LBB0_417:
	s_cmp_lt_i32 s10, 26
	s_mov_b64 s[0:1], -1
	v_cvt_pk_bf16_f32 v172, v158, v159
	v_cvt_pk_bf16_f32 v173, v162, v163
	v_cvt_pk_bf16_f32 v174, v156, v157
	v_cvt_pk_bf16_f32 v175, v160, v161
	global_store_dwordx4 v[154:155], v[172:175], off offset:256
	s_cbranch_scc1 .LBB0_421
	s_cmp_eq_u32 s10, 26
	v_mov_b32_e32 v159, v19
	v_mov_b32_e32 v158, v18
	v_mov_b32_e32 v155, v17
	v_mov_b32_e32 v154, v16
	v_mov_b32_e32 v161, v27
	v_mov_b32_e32 v160, v26
	v_mov_b32_e32 v157, v25
	v_mov_b32_e32 v156, v24
	s_cbranch_scc0 .LBB0_420
	v_mul_f32_e32 v138, 0xbfb8aa3b, v24
	v_exp_f32_e32 v138, v138
	v_mul_f32_e32 v155, 0xbfb8aa3b, v17
	v_exp_f32_e32 v155, v155
	v_mul_f32_e32 v154, 0xbfb8aa3b, v16
	v_add_f32_e32 v138, 1.0, v138
	v_rcp_f32_e32 v156, v138
	v_mul_f32_e32 v138, 0xbfb8aa3b, v25
	v_exp_f32_e32 v138, v138
	v_exp_f32_e32 v154, v154
	v_add_f32_e32 v138, 1.0, v138
	v_rcp_f32_e32 v157, v138
	v_add_f32_e32 v138, 1.0, v155
	v_mul_f32_e32 v155, 0xbfb8aa3b, v26
	v_exp_f32_e32 v158, v155
	v_mul_f32_e32 v155, 0xbfb8aa3b, v18
	v_exp_f32_e32 v159, v155
	v_rcp_f32_e32 v155, v138
	v_add_f32_e32 v138, 1.0, v158
	v_mul_f32_e32 v158, 0xbfb8aa3b, v27
	v_rcp_f32_e32 v160, v138
	v_add_f32_e32 v138, 1.0, v159
	v_exp_f32_e32 v159, v158
	v_mul_f32_e32 v158, 0xbfb8aa3b, v19
	v_exp_f32_e32 v162, v158
	v_rcp_f32_e32 v158, v138
	v_add_f32_e32 v138, 1.0, v159
	v_add_f32_e32 v154, 1.0, v154
	v_rcp_f32_e32 v161, v138
	v_add_f32_e32 v138, 1.0, v162
	v_rcp_f32_e32 v154, v154
	v_rcp_f32_e32 v159, v138

.LBB0_424:
	v_lshlrev_b64 v[162:163], 9, v[150:151]
	v_lshl_add_u64 v[162:163], v[152:153], 0, v[162:163]
	v_cvt_pk_bf16_f32 v172, v156, v157
	v_cvt_pk_bf16_f32 v173, v160, v161
	v_cvt_pk_bf16_f32 v174, v154, v155
	v_add_co_u32_e32 v154, vcc, 0x16000, v162
	v_lshl_add_u64 v[152:153], v[162:163], 0, s[46:47]
	s_nop 0
	v_addc_co_u32_e32 v155, vcc, 0, v163, vcc
	s_cmp_lt_i32 s10, 26
	s_mov_b64 s[0:1], -1
	v_cvt_pk_bf16_f32 v175, v158, v159
	global_store_dwordx4 v[154:155], v[172:175], off
	s_cbranch_scc1 .LBB0_428
	s_cmp_eq_u32 s10, 26
	v_mov_b32_e32 v159, v3
	v_mov_b32_e32 v158, v2
	v_mov_b32_e32 v155, v1
	v_mov_b32_e32 v154, v0
	v_mov_b32_e32 v161, v7
	v_mov_b32_e32 v160, v6
	v_mov_b32_e32 v157, v5
	v_mov_b32_e32 v156, v4
	s_cbranch_scc0 .LBB0_427
	v_mul_f32_e32 v138, 0xbfb8aa3b, v4
	v_exp_f32_e32 v138, v138
	v_mul_f32_e32 v151, 0xbfb8aa3b, v0
	v_exp_f32_e32 v151, v151
	v_mul_f32_e32 v154, 0xbfb8aa3b, v1
	v_add_f32_e32 v138, 1.0, v138
	v_rcp_f32_e32 v156, v138
	v_mul_f32_e32 v138, 0xbfb8aa3b, v5
	v_exp_f32_e32 v138, v138
	v_exp_f32_e32 v155, v154
	v_add_f32_e32 v151, 1.0, v151
	v_rcp_f32_e32 v154, v151
	v_add_f32_e32 v138, 1.0, v138
	v_mul_f32_e32 v151, 0xbfb8aa3b, v6
	v_rcp_f32_e32 v157, v138
	v_add_f32_e32 v138, 1.0, v155
	v_exp_f32_e32 v151, v151
	v_mul_f32_e32 v155, 0xbfb8aa3b, v2
	v_exp_f32_e32 v158, v155
	v_rcp_f32_e32 v155, v138
	v_add_f32_e32 v138, 1.0, v151
	v_mul_f32_e32 v151, 0xbfb8aa3b, v7
	v_rcp_f32_e32 v160, v138
	v_add_f32_e32 v138, 1.0, v158
	v_exp_f32_e32 v151, v151
	v_mul_f32_e32 v158, 0xbfb8aa3b, v3
	v_exp_f32_e32 v159, v158
	v_rcp_f32_e32 v158, v138
	v_add_f32_e32 v138, 1.0, v151
	v_rcp_f32_e32 v161, v138
	v_add_f32_e32 v138, 1.0, v159
	v_rcp_f32_e32 v159, v138

.LBB0_431:
	v_cvt_pk_bf16_f32 v172, v156, v157
	v_cvt_pk_bf16_f32 v173, v160, v161
	v_cvt_pk_bf16_f32 v174, v154, v155
	v_cvt_pk_bf16_f32 v175, v158, v159
	global_store_dwordx4 v[152:153], v[172:175], off offset:256
	s_mov_b64 s[0:1], 0
.LBB0_432:
	s_and_b64 vcc, exec, s[0:1]
	s_cbranch_vccz .LBB0_434
	s_cmp_lt_i32 s10, 8
	s_cselect_b32 s0, s82, 0x15900000
	s_add_u32 s0, s26, s0
	s_addc_u32 s1, s27, 0
	s_lshl_b32 s4, s10, 8
	s_and_b32 s4, s4, 0x700
	v_or_b32_e32 v138, s4, v165
	v_lshlrev_b32_e32 v138, 1, v138
	v_ashrrev_i32_e32 v151, 31, v150
	v_lshl_add_u64 v[158:159], s[0:1], 0, v[138:139]
	v_lshlrev_b64 v[152:153], 12, v[150:151]
	v_lshl_add_u64 v[152:153], v[158:159], 0, v[152:153]
	v_cvt_pk_bf16_f32 v154, v124, v125
	v_cvt_pk_bf16_f32 v155, v126, v127
	v_cvt_pk_bf16_f32 v156, v120, v121
	v_cvt_pk_bf16_f32 v157, v122, v123
	global_store_dwordx4 v[152:153], v[154:157], off
	s_mov_b64 s[0:1], 0x80000
	s_nop 0
	v_cvt_pk_bf16_f32 v154, v108, v109
	v_cvt_pk_bf16_f32 v155, v110, v111
	v_cvt_pk_bf16_f32 v156, v104, v105
	v_cvt_pk_bf16_f32 v157, v106, v107
	global_store_dwordx4 v[152:153], v[154:157], off offset:256
	s_nop 1
	v_or_b32_e32 v154, 16, v150
	v_ashrrev_i32_e32 v155, 31, v154
	v_lshlrev_b64 v[154:155], 12, v[154:155]
	v_lshl_add_u64 v[160:161], v[158:159], 0, v[154:155]
	v_cvt_pk_bf16_f32 v154, v116, v117
	v_cvt_pk_bf16_f32 v155, v118, v119
	v_cvt_pk_bf16_f32 v156, v112, v113
	v_cvt_pk_bf16_f32 v157, v114, v115
	global_store_dwordx4 v[160:161], v[154:157], off
	s_nop 1
	v_cvt_pk_bf16_f32 v154, v92, v93
	v_cvt_pk_bf16_f32 v155, v94, v95
	v_cvt_pk_bf16_f32 v156, v88, v89
	v_cvt_pk_bf16_f32 v157, v90, v91
	global_store_dwordx4 v[160:161], v[154:157], off offset:256
	s_nop 1
	v_or_b32_e32 v154, 32, v150
	v_ashrrev_i32_e32 v155, 31, v154
	v_lshlrev_b64 v[154:155], 12, v[154:155]
	v_lshl_add_u64 v[160:161], v[158:159], 0, v[154:155]
	v_cvt_pk_bf16_f32 v154, v100, v101
	v_cvt_pk_bf16_f32 v155, v102, v103
	v_cvt_pk_bf16_f32 v156, v96, v97
	v_cvt_pk_bf16_f32 v157, v98, v99
	global_store_dwordx4 v[160:161], v[154:157], off
	s_nop 1
	v_cvt_pk_bf16_f32 v154, v76, v77
	v_cvt_pk_bf16_f32 v155, v78, v79
	v_cvt_pk_bf16_f32 v156, v72, v73
	v_cvt_pk_bf16_f32 v157, v74, v75
	global_store_dwordx4 v[160:161], v[154:157], off offset:256
	v_add_co_u32_e32 v160, vcc, s83, v152
	s_nop 0
	v_or_b32_e32 v154, 48, v150
	v_ashrrev_i32_e32 v155, 31, v154
	v_lshlrev_b64 v[154:155], 12, v[154:155]
	v_lshl_add_u64 v[158:159], v[158:159], 0, v[154:155]
	v_cvt_pk_bf16_f32 v154, v84, v85
	v_cvt_pk_bf16_f32 v155, v86, v87
	v_cvt_pk_bf16_f32 v156, v80, v81
	v_cvt_pk_bf16_f32 v157, v82, v83
	global_store_dwordx4 v[158:159], v[154:157], off
	v_addc_co_u32_e32 v161, vcc, 0, v153, vcc
	s_nop 0
	v_cvt_pk_bf16_f32 v154, v68, v69
	v_cvt_pk_bf16_f32 v155, v70, v71
	v_cvt_pk_bf16_f32 v156, v64, v65
	v_cvt_pk_bf16_f32 v157, v66, v67
	global_store_dwordx4 v[158:159], v[154:157], off offset:256
	v_lshl_add_u64 v[158:159], v[152:153], 0, s[0:1]
	s_nop 0
	v_cvt_pk_bf16_f32 v154, v60, v61
	v_cvt_pk_bf16_f32 v155, v62, v63
	v_cvt_pk_bf16_f32 v156, v56, v57
	v_cvt_pk_bf16_f32 v157, v58, v59
	global_store_dwordx4 v[160:161], v[154:157], off
	v_add_co_u32_e32 v160, vcc, s84, v152
	s_nop 0
	v_cvt_pk_bf16_f32 v154, v44, v45
	v_cvt_pk_bf16_f32 v155, v46, v47
	v_cvt_pk_bf16_f32 v156, v36, v37
	v_cvt_pk_bf16_f32 v157, v38, v39
	global_store_dwordx4 v[158:159], v[154:157], off offset:256
	v_addc_co_u32_e32 v161, vcc, 0, v153, vcc
	s_nop 0
	v_cvt_pk_bf16_f32 v154, v52, v53
	v_cvt_pk_bf16_f32 v155, v54, v55
	v_cvt_pk_bf16_f32 v156, v48, v49
	v_cvt_pk_bf16_f32 v157, v50, v51
	v_lshl_add_u64 v[158:159], v[152:153], 0, s[50:51]
	global_store_dwordx4 v[160:161], v[154:157], off
	v_add_co_u32_e32 v160, vcc, s85, v152
	s_nop 0
	v_cvt_pk_bf16_f32 v154, v28, v29
	v_cvt_pk_bf16_f32 v155, v30, v31
	v_cvt_pk_bf16_f32 v156, v20, v21
	v_cvt_pk_bf16_f32 v157, v22, v23
	global_store_dwordx4 v[158:159], v[154:157], off offset:256
	v_lshl_add_u64 v[158:159], v[152:153], 0, s[52:53]
	v_addc_co_u32_e32 v161, vcc, 0, v153, vcc
	v_cvt_pk_bf16_f32 v154, v40, v41
	v_cvt_pk_bf16_f32 v155, v42, v43
	v_cvt_pk_bf16_f32 v156, v32, v33
	v_cvt_pk_bf16_f32 v157, v34, v35
	global_store_dwordx4 v[160:161], v[154:157], off
	s_nop 1
	v_cvt_pk_bf16_f32 v154, v12, v13
	v_cvt_pk_bf16_f32 v155, v14, v15
	v_cvt_pk_bf16_f32 v156, v8, v9
	v_cvt_pk_bf16_f32 v157, v10, v11
	global_store_dwordx4 v[158:159], v[154:157], off offset:256
	v_lshl_add_u64 v[158:159], v[152:153], 0, s[54:55]
	v_add_co_u32_e32 v152, vcc, s86, v152
	v_cvt_pk_bf16_f32 v154, v24, v25
	v_cvt_pk_bf16_f32 v155, v26, v27
	v_cvt_pk_bf16_f32 v156, v16, v17
	v_cvt_pk_bf16_f32 v157, v18, v19
	s_nop 1
	v_addc_co_u32_e32 v153, vcc, 0, v153, vcc
	global_store_dwordx4 v[152:153], v[154:157], off
	v_cvt_pk_bf16_f32 v152, v4, v5
	v_cvt_pk_bf16_f32 v153, v6, v7
	s_nop 1
	v_cvt_pk_bf16_f32 v154, v0, v1
	v_cvt_pk_bf16_f32 v155, v2, v3
	global_store_dwordx4 v[158:159], v[152:155], off offset:256

.LBB0_536:
	ds_read_b128 v[0:3], v173
	ds_read_b128 v[4:7], v173 offset:1024
	ds_read_b128 v[8:11], v173 offset:2048
	ds_read_b128 v[12:15], v173 offset:3072
	s_ashr_i32 s65, s64, 31
	s_lshl_b64 s[0:1], s[64:65], 17
	s_add_u32 s70, s18, s0
	s_addc_u32 s71, s19, s1
	s_and_b64 s[0:1], s[8:9], exec
	s_cselect_b32 s9, s71, s15
	s_cselect_b32 s8, s70, s14
	s_add_u32 s0, s12, 0x10080
	s_addc_u32 s1, s13, 0
	s_mov_b32 m0, s76
	v_lshl_add_u64 v[48:49], s[0:1], 0, v[142:143]
	ds_read_b128 v[16:19], v174
	ds_read_b128 v[20:23], v174 offset:1024
	ds_read_b128 v[24:27], v174 offset:2048
	ds_read_b128 v[28:31], v174 offset:3072
	ds_read_b128 v[32:35], v174 offset:4096
	ds_read_b128 v[36:39], v174 offset:5120
	ds_read_b128 v[40:43], v174 offset:6144
	ds_read_b128 v[44:47], v174 offset:7168
	global_load_lds_dwordx4 v[48:49], off
	v_lshl_add_u64 v[48:49], s[0:1], 0, v[138:139]
	s_mov_b32 m0, s77
	s_nop 0
	global_load_lds_dwordx4 v[48:49], off
	s_waitcnt lgkmcnt(8)
	s_barrier
	s_waitcnt lgkmcnt(0)
	s_waitcnt lgkmcnt(0)
	v_mfma_f32_16x16x32_bf16 v[48:51], v[0:3], v[16:19], 0
	v_mfma_f32_16x16x32_bf16 v[52:55], v[8:11], v[16:19], 0
	v_mfma_f32_16x16x32_bf16 v[56:59], v[0:3], v[24:27], 0
	v_mfma_f32_16x16x32_bf16 v[60:63], v[8:11], v[24:27], 0
	v_mfma_f32_16x16x32_bf16 v[64:67], v[0:3], v[32:35], 0
	v_mfma_f32_16x16x32_bf16 v[68:71], v[8:11], v[32:35], 0
	v_mfma_f32_16x16x32_bf16 v[72:75], v[0:3], v[40:43], 0
	v_mfma_f32_16x16x32_bf16 v[76:79], v[8:11], v[40:43], 0
	v_mfma_f32_16x16x32_bf16 v[48:51], v[4:7], v[20:23], v[48:51]
	v_mfma_f32_16x16x32_bf16 v[52:55], v[12:15], v[20:23], v[52:55]
	v_mfma_f32_16x16x32_bf16 v[56:59], v[4:7], v[28:31], v[56:59]
	v_mfma_f32_16x16x32_bf16 v[60:63], v[12:15], v[28:31], v[60:63]
	v_mfma_f32_16x16x32_bf16 v[64:67], v[4:7], v[36:39], v[64:67]
	v_mfma_f32_16x16x32_bf16 v[68:71], v[12:15], v[36:39], v[68:71]
	v_mfma_f32_16x16x32_bf16 v[72:75], v[4:7], v[44:47], v[72:75]
	v_mfma_f32_16x16x32_bf16 v[76:79], v[12:15], v[44:47], v[76:79]
	s_barrier
	v_lshl_add_u64 v[166:167], s[14:15], 0, v[140:141]
	s_add_i32 s11, s75, s5
	v_lshl_add_u64 v[96:97], v[166:167], 0, s[54:55]
	s_mov_b32 m0, s11
	v_lshl_add_u64 v[214:215], s[14:15], 0, v[136:137]
	s_add_i32 s0, s11, 0x2000
	ds_read_b128 v[80:83], v175
	ds_read_b128 v[84:87], v175 offset:1024
	ds_read_b128 v[88:91], v175 offset:2048
	ds_read_b128 v[92:95], v175 offset:3072
	global_load_lds_dwordx4 v[96:97], off
	v_lshl_add_u64 v[96:97], v[214:215], 0, s[54:55]
	s_mov_b32 m0, s0
	s_nop 0
	global_load_lds_dwordx4 v[96:97], off
	s_barrier
	s_waitcnt lgkmcnt(0)
	s_waitcnt lgkmcnt(0)
	v_mfma_f32_16x16x32_bf16 v[96:99], v[80:83], v[16:19], 0
	v_mfma_f32_16x16x32_bf16 v[16:19], v[88:91], v[16:19], 0
	v_mfma_f32_16x16x32_bf16 v[96:99], v[84:87], v[20:23], v[96:99]
	v_mfma_f32_16x16x32_bf16 v[16:19], v[92:95], v[20:23], v[16:19]
	v_mfma_f32_16x16x32_bf16 v[20:23], v[80:83], v[24:27], 0
	v_mfma_f32_16x16x32_bf16 v[24:27], v[88:91], v[24:27], 0
	v_mfma_f32_16x16x32_bf16 v[20:23], v[84:87], v[28:31], v[20:23]
	v_mfma_f32_16x16x32_bf16 v[24:27], v[92:95], v[28:31], v[24:27]
	v_mfma_f32_16x16x32_bf16 v[28:31], v[80:83], v[32:35], 0
	v_mfma_f32_16x16x32_bf16 v[32:35], v[88:91], v[32:35], 0
	v_mfma_f32_16x16x32_bf16 v[28:31], v[84:87], v[36:39], v[28:31]
	v_mfma_f32_16x16x32_bf16 v[32:35], v[92:95], v[36:39], v[32:35]
	v_mfma_f32_16x16x32_bf16 v[36:39], v[80:83], v[40:43], 0
	v_mfma_f32_16x16x32_bf16 v[40:43], v[88:91], v[40:43], 0
	v_mfma_f32_16x16x32_bf16 v[36:39], v[84:87], v[44:47], v[36:39]
	v_mfma_f32_16x16x32_bf16 v[40:43], v[92:95], v[44:47], v[40:43]
	v_lshl_add_u64 v[216:217], s[12:13], 0, v[142:143]
	s_mov_b32 m0, s36
	v_lshl_add_u64 v[128:129], v[216:217], 0, s[54:55]
	v_lshl_add_u64 v[222:223], s[12:13], 0, v[138:139]
	s_barrier
	ds_read_b128 v[44:47], v174 offset:16384
	ds_read_b128 v[100:103], v174 offset:17408
	ds_read_b128 v[104:107], v174 offset:18432
	ds_read_b128 v[108:111], v174 offset:19456
	ds_read_b128 v[112:115], v174 offset:20480
	ds_read_b128 v[116:119], v174 offset:21504
	ds_read_b128 v[120:123], v174 offset:22528
	ds_read_b128 v[124:127], v174 offset:23552
	global_load_lds_dwordx4 v[128:129], off
	v_lshl_add_u64 v[128:129], v[222:223], 0, s[54:55]
	s_mov_b32 m0, s37
	s_nop 0
	global_load_lds_dwordx4 v[128:129], off
	s_barrier
	s_waitcnt lgkmcnt(0)
	s_waitcnt lgkmcnt(0)
	v_mfma_f32_16x16x32_bf16 v[128:131], v[0:3], v[44:47], 0
	v_mfma_f32_16x16x32_bf16 v[150:153], v[0:3], v[104:107], 0
	v_mfma_f32_16x16x32_bf16 v[158:161], v[0:3], v[112:115], 0
	v_mfma_f32_16x16x32_bf16 v[0:3], v[0:3], v[120:123], 0
	v_mfma_f32_16x16x32_bf16 v[128:131], v[4:7], v[100:103], v[128:131]
	v_mfma_f32_16x16x32_bf16 v[150:153], v[4:7], v[108:111], v[150:153]
	v_mfma_f32_16x16x32_bf16 v[158:161], v[4:7], v[116:119], v[158:161]
	v_mfma_f32_16x16x32_bf16 v[0:3], v[4:7], v[124:127], v[0:3]
	v_mfma_f32_16x16x32_bf16 v[4:7], v[8:11], v[120:123], 0
	v_mfma_f32_16x16x32_bf16 v[132:135], v[8:11], v[44:47], 0
	v_mfma_f32_16x16x32_bf16 v[154:157], v[8:11], v[104:107], 0
	v_mfma_f32_16x16x32_bf16 v[162:165], v[8:11], v[112:115], 0
	v_mfma_f32_16x16x32_bf16 v[4:7], v[12:15], v[124:127], v[4:7]
	v_mfma_f32_16x16x32_bf16 v[132:135], v[12:15], v[100:103], v[132:135]
	v_mfma_f32_16x16x32_bf16 v[154:157], v[12:15], v[108:111], v[154:157]
	v_mfma_f32_16x16x32_bf16 v[162:165], v[12:15], v[116:119], v[162:165]
	s_barrier
	s_add_u32 s24, s14, 0x10100
	s_addc_u32 s25, s15, 0
	s_add_i32 s21, s78, s5
	v_lshl_add_u64 v[8:9], s[24:25], 0, v[140:141]
	s_mov_b32 m0, s21
	s_add_i32 s1, s21, 0x2000
	global_load_lds_dwordx4 v[8:9], off
	v_lshl_add_u64 v[8:9], s[24:25], 0, v[136:137]
	s_mov_b32 m0, s1
	s_nop 0
	global_load_lds_dwordx4 v[8:9], off
	s_waitcnt vmcnt(6)
	s_barrier
	v_mfma_f32_16x16x32_bf16 v[8:11], v[80:83], v[44:47], 0
	v_mfma_f32_16x16x32_bf16 v[12:15], v[88:91], v[44:47], 0
	v_mfma_f32_16x16x32_bf16 v[8:11], v[84:87], v[100:103], v[8:11]
	v_mfma_f32_16x16x32_bf16 v[12:15], v[92:95], v[100:103], v[12:15]
	v_mfma_f32_16x16x32_bf16 v[44:47], v[80:83], v[104:107], 0
	v_mfma_f32_16x16x32_bf16 v[100:103], v[88:91], v[104:107], 0
	v_mfma_f32_16x16x32_bf16 v[104:107], v[80:83], v[112:115], 0
	v_mfma_f32_16x16x32_bf16 v[80:83], v[80:83], v[120:123], 0
	v_mfma_f32_16x16x32_bf16 v[44:47], v[84:87], v[108:111], v[44:47]
	v_mfma_f32_16x16x32_bf16 v[100:103], v[92:95], v[108:111], v[100:103]
	v_mfma_f32_16x16x32_bf16 v[104:107], v[84:87], v[116:119], v[104:107]
	v_mfma_f32_16x16x32_bf16 v[108:111], v[88:91], v[112:115], 0
	v_mfma_f32_16x16x32_bf16 v[80:83], v[84:87], v[124:127], v[80:83]
	v_mfma_f32_16x16x32_bf16 v[84:87], v[88:91], v[120:123], 0
	v_mfma_f32_16x16x32_bf16 v[108:111], v[92:95], v[116:119], v[108:111]
	v_mfma_f32_16x16x32_bf16 v[84:87], v[92:95], v[124:127], v[84:87]
	s_add_i32 s23, 0, 0x18000
	v_add_u32_e32 v144, s23, v169
	s_barrier
	ds_read_b128 v[88:91], v144
	ds_read_b128 v[92:95], v144 offset:1024
	ds_read_b128 v[112:115], v144 offset:2048
	ds_read_b128 v[116:119], v144 offset:3072
	s_add_u32 s24, s12, 0x10100
	s_addc_u32 s25, s13, 0
	s_mov_b32 m0, s50
	v_lshl_add_u64 v[202:203], s[24:25], 0, v[142:143]
	ds_read_b128 v[120:123], v174 offset:32768
	ds_read_b128 v[124:127], v174 offset:33792
	ds_read_b128 v[178:181], v174 offset:34816
	ds_read_b128 v[182:185], v174 offset:35840
	ds_read_b128 v[186:189], v174 offset:36864
	ds_read_b128 v[190:193], v174 offset:37888
	ds_read_b128 v[194:197], v174 offset:38912
	ds_read_b128 v[198:201], v174 offset:39936
	global_load_lds_dwordx4 v[202:203], off
	v_lshl_add_u64 v[202:203], s[24:25], 0, v[138:139]
	s_mov_b32 m0, s51
	s_nop 0
	global_load_lds_dwordx4 v[202:203], off
	s_waitcnt lgkmcnt(8)
	s_barrier
	s_waitcnt lgkmcnt(0)
	s_waitcnt lgkmcnt(0)
	v_mfma_f32_16x16x32_bf16 v[48:51], v[88:91], v[120:123], v[48:51]
	v_mfma_f32_16x16x32_bf16 v[52:55], v[112:115], v[120:123], v[52:55]
	v_mfma_f32_16x16x32_bf16 v[56:59], v[88:91], v[178:181], v[56:59]
	v_mfma_f32_16x16x32_bf16 v[60:63], v[112:115], v[178:181], v[60:63]
	v_mfma_f32_16x16x32_bf16 v[64:67], v[88:91], v[186:189], v[64:67]
	v_mfma_f32_16x16x32_bf16 v[68:71], v[112:115], v[186:189], v[68:71]
	v_mfma_f32_16x16x32_bf16 v[72:75], v[88:91], v[194:197], v[72:75]
	v_mfma_f32_16x16x32_bf16 v[76:79], v[112:115], v[194:197], v[76:79]
	v_mfma_f32_16x16x32_bf16 v[48:51], v[92:95], v[124:127], v[48:51]
	v_mfma_f32_16x16x32_bf16 v[52:55], v[116:119], v[124:127], v[52:55]
	v_mfma_f32_16x16x32_bf16 v[56:59], v[92:95], v[182:185], v[56:59]
	v_mfma_f32_16x16x32_bf16 v[60:63], v[116:119], v[182:185], v[60:63]
	v_mfma_f32_16x16x32_bf16 v[64:67], v[92:95], v[190:193], v[64:67]
	v_mfma_f32_16x16x32_bf16 v[68:71], v[116:119], v[190:193], v[68:71]
	v_mfma_f32_16x16x32_bf16 v[72:75], v[92:95], v[198:201], v[72:75]
	v_mfma_f32_16x16x32_bf16 v[76:79], v[116:119], v[198:201], v[76:79]
	s_barrier
	s_add_i32 s25, 0, 0x1c000
	s_add_i32 s24, s23, s5
	v_add_u32_e32 v177, s25, v169
	v_lshl_add_u64 v[166:167], v[166:167], 0, s[58:59]
	s_mov_b32 m0, s24
	s_add_i32 s23, s24, 0x2000
	ds_read_b128 v[202:205], v177
	ds_read_b128 v[206:209], v177 offset:1024
	ds_read_b128 v[210:213], v177 offset:2048
	ds_read_b128 v[218:221], v177 offset:3072
	global_load_lds_dwordx4 v[166:167], off
	v_lshl_add_u64 v[166:167], v[214:215], 0, s[58:59]
	s_mov_b32 m0, s23
	s_nop 0
	global_load_lds_dwordx4 v[166:167], off
	s_barrier
	s_waitcnt lgkmcnt(0)
	s_waitcnt lgkmcnt(0)
	v_mfma_f32_16x16x32_bf16 v[96:99], v[202:205], v[120:123], v[96:99]
	v_mfma_f32_16x16x32_bf16 v[16:19], v[210:213], v[120:123], v[16:19]
	v_mfma_f32_16x16x32_bf16 v[20:23], v[202:205], v[178:181], v[20:23]
	v_mfma_f32_16x16x32_bf16 v[24:27], v[210:213], v[178:181], v[24:27]
	v_mfma_f32_16x16x32_bf16 v[28:31], v[202:205], v[186:189], v[28:31]
	v_mfma_f32_16x16x32_bf16 v[32:35], v[210:213], v[186:189], v[32:35]
	v_mfma_f32_16x16x32_bf16 v[36:39], v[202:205], v[194:197], v[36:39]
	v_mfma_f32_16x16x32_bf16 v[40:43], v[210:213], v[194:197], v[40:43]
	v_mfma_f32_16x16x32_bf16 v[96:99], v[206:209], v[124:127], v[96:99]
	v_mfma_f32_16x16x32_bf16 v[16:19], v[218:221], v[124:127], v[16:19]
	v_mfma_f32_16x16x32_bf16 v[20:23], v[206:209], v[182:185], v[20:23]
	v_mfma_f32_16x16x32_bf16 v[24:27], v[218:221], v[182:185], v[24:27]
	v_mfma_f32_16x16x32_bf16 v[28:31], v[206:209], v[190:193], v[28:31]
	v_mfma_f32_16x16x32_bf16 v[32:35], v[218:221], v[190:193], v[32:35]
	v_mfma_f32_16x16x32_bf16 v[36:39], v[206:209], v[198:201], v[36:39]
	v_mfma_f32_16x16x32_bf16 v[40:43], v[218:221], v[198:201], v[40:43]
	s_mov_b32 m0, s72
	v_lshl_add_u64 v[166:167], v[216:217], 0, s[58:59]
	s_barrier
	ds_read_b128 v[120:123], v174 offset:49152
	ds_read_b128 v[124:127], v174 offset:50176
	ds_read_b128 v[178:181], v174 offset:51200
	ds_read_b128 v[182:185], v174 offset:52224
	ds_read_b128 v[186:189], v174 offset:53248
	ds_read_b128 v[190:193], v174 offset:54272
	ds_read_b128 v[194:197], v174 offset:55296
	ds_read_b128 v[198:201], v174 offset:56320
	global_load_lds_dwordx4 v[166:167], off
	v_lshl_add_u64 v[166:167], v[222:223], 0, s[58:59]
	s_mov_b32 m0, s73
	s_nop 0
	global_load_lds_dwordx4 v[166:167], off
	s_barrier
	s_waitcnt lgkmcnt(0)
	s_waitcnt lgkmcnt(0)
	v_mfma_f32_16x16x32_bf16 v[128:131], v[88:91], v[120:123], v[128:131]
	v_mfma_f32_16x16x32_bf16 v[150:153], v[88:91], v[178:181], v[150:153]
	v_mfma_f32_16x16x32_bf16 v[0:3], v[88:91], v[194:197], v[0:3]
	v_mfma_f32_16x16x32_bf16 v[4:7], v[112:115], v[194:197], v[4:7]
	v_mfma_f32_16x16x32_bf16 v[128:131], v[92:95], v[124:127], v[128:131]
	v_mfma_f32_16x16x32_bf16 v[132:135], v[112:115], v[120:123], v[132:135]
	v_mfma_f32_16x16x32_bf16 v[150:153], v[92:95], v[182:185], v[150:153]
	v_mfma_f32_16x16x32_bf16 v[154:157], v[112:115], v[178:181], v[154:157]
	v_mfma_f32_16x16x32_bf16 v[158:161], v[88:91], v[186:189], v[158:161]
	v_mfma_f32_16x16x32_bf16 v[162:165], v[112:115], v[186:189], v[162:165]
	v_mfma_f32_16x16x32_bf16 v[0:3], v[92:95], v[198:201], v[0:3]
	v_mfma_f32_16x16x32_bf16 v[4:7], v[116:119], v[198:201], v[4:7]
	v_mfma_f32_16x16x32_bf16 v[132:135], v[116:119], v[124:127], v[132:135]
	v_mfma_f32_16x16x32_bf16 v[154:157], v[116:119], v[182:185], v[154:157]
	v_mfma_f32_16x16x32_bf16 v[158:161], v[92:95], v[190:193], v[158:161]
	v_mfma_f32_16x16x32_bf16 v[162:165], v[116:119], v[190:193], v[162:165]
	s_barrier
	s_add_u32 s46, s14, 0x10180
	s_addc_u32 s47, s15, 0
	s_add_i32 s15, s25, s5
	v_lshl_add_u64 v[88:89], s[46:47], 0, v[140:141]
	s_mov_b32 m0, s15
	s_add_i32 s14, s15, 0x2000
	global_load_lds_dwordx4 v[88:89], off
	v_lshl_add_u64 v[88:89], s[46:47], 0, v[136:137]
	s_mov_b32 m0, s14
	s_nop 0
	global_load_lds_dwordx4 v[88:89], off
	s_waitcnt vmcnt(6)
	s_barrier
	v_mfma_f32_16x16x32_bf16 v[8:11], v[202:205], v[120:123], v[8:11]
	v_mfma_f32_16x16x32_bf16 v[12:15], v[210:213], v[120:123], v[12:15]
	v_mfma_f32_16x16x32_bf16 v[44:47], v[202:205], v[178:181], v[44:47]
	v_mfma_f32_16x16x32_bf16 v[88:91], v[210:213], v[178:181], v[100:103]
	v_mfma_f32_16x16x32_bf16 v[92:95], v[202:205], v[186:189], v[104:107]
	v_mfma_f32_16x16x32_bf16 v[100:103], v[210:213], v[186:189], v[108:111]
	v_mfma_f32_16x16x32_bf16 v[80:83], v[202:205], v[194:197], v[80:83]
	v_mfma_f32_16x16x32_bf16 v[84:87], v[210:213], v[194:197], v[84:87]
	v_mfma_f32_16x16x32_bf16 v[8:11], v[206:209], v[124:127], v[8:11]
	v_mfma_f32_16x16x32_bf16 v[12:15], v[218:221], v[124:127], v[12:15]
	v_mfma_f32_16x16x32_bf16 v[44:47], v[206:209], v[182:185], v[44:47]
	v_mfma_f32_16x16x32_bf16 v[88:91], v[218:221], v[182:185], v[88:91]
	v_mfma_f32_16x16x32_bf16 v[92:95], v[206:209], v[190:193], v[92:95]
	v_mfma_f32_16x16x32_bf16 v[100:103], v[218:221], v[190:193], v[100:103]
	v_mfma_f32_16x16x32_bf16 v[80:83], v[206:209], v[198:201], v[80:83]
	v_mfma_f32_16x16x32_bf16 v[84:87], v[218:221], v[198:201], v[84:87]
	s_barrier
	ds_read_b128 v[104:107], v173
	ds_read_b128 v[108:111], v173 offset:1024
	ds_read_b128 v[112:115], v173 offset:2048
	ds_read_b128 v[116:119], v173 offset:3072
	s_add_u32 s12, s12, 0x10180
	s_addc_u32 s13, s13, 0
	s_mov_b32 m0, s76
	v_lshl_add_u64 v[166:167], s[12:13], 0, v[142:143]
	ds_read_b128 v[120:123], v174
	ds_read_b128 v[124:127], v174 offset:1024
	ds_read_b128 v[178:181], v174 offset:2048
	ds_read_b128 v[182:185], v174 offset:3072
	ds_read_b128 v[186:189], v174 offset:4096
	ds_read_b128 v[190:193], v174 offset:5120
	ds_read_b128 v[194:197], v174 offset:6144
	ds_read_b128 v[198:201], v174 offset:7168
	global_load_lds_dwordx4 v[166:167], off
	v_lshl_add_u64 v[166:167], s[12:13], 0, v[138:139]
	s_mov_b32 m0, s77
	s_nop 0
	global_load_lds_dwordx4 v[166:167], off
	s_waitcnt lgkmcnt(8)
	s_barrier
	s_waitcnt lgkmcnt(0)
	s_waitcnt lgkmcnt(0)
	v_mfma_f32_16x16x32_bf16 v[48:51], v[104:107], v[120:123], v[48:51]
	v_mfma_f32_16x16x32_bf16 v[52:55], v[112:115], v[120:123], v[52:55]
	v_mfma_f32_16x16x32_bf16 v[56:59], v[104:107], v[178:181], v[56:59]
	v_mfma_f32_16x16x32_bf16 v[60:63], v[112:115], v[178:181], v[60:63]
	v_mfma_f32_16x16x32_bf16 v[64:67], v[104:107], v[186:189], v[64:67]
	v_mfma_f32_16x16x32_bf16 v[68:71], v[112:115], v[186:189], v[68:71]
	v_mfma_f32_16x16x32_bf16 v[72:75], v[104:107], v[194:197], v[72:75]
	v_mfma_f32_16x16x32_bf16 v[76:79], v[112:115], v[194:197], v[76:79]
	v_mfma_f32_16x16x32_bf16 v[48:51], v[108:111], v[124:127], v[48:51]
	v_mfma_f32_16x16x32_bf16 v[52:55], v[116:119], v[124:127], v[52:55]
	v_mfma_f32_16x16x32_bf16 v[56:59], v[108:111], v[182:185], v[56:59]
	v_mfma_f32_16x16x32_bf16 v[60:63], v[116:119], v[182:185], v[60:63]
	v_mfma_f32_16x16x32_bf16 v[64:67], v[108:111], v[190:193], v[64:67]
	v_mfma_f32_16x16x32_bf16 v[68:71], v[116:119], v[190:193], v[68:71]
	v_mfma_f32_16x16x32_bf16 v[72:75], v[108:111], v[198:201], v[72:75]
	v_mfma_f32_16x16x32_bf16 v[76:79], v[116:119], v[198:201], v[76:79]
	s_barrier
	s_mov_b32 m0, s11
	v_lshl_add_u64 v[166:167], s[8:9], 0, v[140:141]
	ds_read_b128 v[202:205], v175
	ds_read_b128 v[206:209], v175 offset:1024
	ds_read_b128 v[210:213], v175 offset:2048
	ds_read_b128 v[218:221], v175 offset:3072
	global_load_lds_dwordx4 v[166:167], off
	v_lshl_add_u64 v[214:215], s[8:9], 0, v[136:137]
	s_mov_b32 m0, s0
	s_nop 0
	global_load_lds_dwordx4 v[214:215], off
	s_barrier
	s_waitcnt lgkmcnt(0)
	s_waitcnt lgkmcnt(0)
	v_mfma_f32_16x16x32_bf16 v[28:31], v[202:205], v[186:189], v[28:31]
	v_mfma_f32_16x16x32_bf16 v[96:99], v[202:205], v[120:123], v[96:99]
	v_mfma_f32_16x16x32_bf16 v[16:19], v[210:213], v[120:123], v[16:19]
	v_mfma_f32_16x16x32_bf16 v[120:123], v[206:209], v[190:193], v[28:31]
	v_mfma_f32_16x16x32_bf16 v[28:31], v[210:213], v[186:189], v[32:35]
	v_mfma_f32_16x16x32_bf16 v[32:35], v[218:221], v[190:193], v[28:31]
	v_mfma_f32_16x16x32_bf16 v[28:31], v[202:205], v[194:197], v[36:39]
	v_mfma_f32_16x16x32_bf16 v[20:23], v[202:205], v[178:181], v[20:23]
	v_mfma_f32_16x16x32_bf16 v[24:27], v[210:213], v[178:181], v[24:27]
	v_mfma_f32_16x16x32_bf16 v[36:39], v[206:209], v[198:201], v[28:31]
	v_mfma_f32_16x16x32_bf16 v[28:31], v[210:213], v[194:197], v[40:43]
	v_mfma_f32_16x16x32_bf16 v[96:99], v[206:209], v[124:127], v[96:99]
	v_mfma_f32_16x16x32_bf16 v[16:19], v[218:221], v[124:127], v[16:19]
	v_mfma_f32_16x16x32_bf16 v[20:23], v[206:209], v[182:185], v[20:23]
	v_mfma_f32_16x16x32_bf16 v[24:27], v[218:221], v[182:185], v[24:27]
	v_mfma_f32_16x16x32_bf16 v[40:43], v[218:221], v[198:201], v[28:31]
	s_mov_b32 m0, s36
	v_lshl_add_u64 v[146:147], s[68:69], 0, v[142:143]
	s_barrier
	ds_read_b128 v[28:31], v174 offset:16384
	ds_read_b128 v[124:127], v174 offset:17408
	ds_read_b128 v[178:181], v174 offset:18432
	ds_read_b128 v[182:185], v174 offset:19456
	ds_read_b128 v[186:189], v174 offset:20480
	ds_read_b128 v[190:193], v174 offset:21504
	ds_read_b128 v[194:197], v174 offset:22528
	ds_read_b128 v[198:201], v174 offset:23552
	global_load_lds_dwordx4 v[146:147], off
	v_lshl_add_u64 v[148:149], s[68:69], 0, v[138:139]
	s_mov_b32 m0, s37
	s_nop 0
	global_load_lds_dwordx4 v[148:149], off
	s_barrier
	s_waitcnt lgkmcnt(0)
	s_waitcnt lgkmcnt(0)
	v_mfma_f32_16x16x32_bf16 v[128:131], v[104:107], v[28:31], v[128:131]
	v_mfma_f32_16x16x32_bf16 v[222:225], v[108:111], v[124:127], v[128:131]
	v_mfma_f32_16x16x32_bf16 v[128:131], v[112:115], v[28:31], v[132:135]
	v_mfma_f32_16x16x32_bf16 v[132:135], v[116:119], v[124:127], v[128:131]
	v_mfma_f32_16x16x32_bf16 v[128:131], v[104:107], v[178:181], v[150:153]
	v_mfma_f32_16x16x32_bf16 v[150:153], v[108:111], v[182:185], v[128:131]
	v_mfma_f32_16x16x32_bf16 v[128:131], v[112:115], v[178:181], v[154:157]
	v_mfma_f32_16x16x32_bf16 v[154:157], v[116:119], v[182:185], v[128:131]
	v_mfma_f32_16x16x32_bf16 v[128:131], v[104:107], v[186:189], v[158:161]
	v_mfma_f32_16x16x32_bf16 v[0:3], v[104:107], v[194:197], v[0:3]
	v_mfma_f32_16x16x32_bf16 v[4:7], v[112:115], v[194:197], v[4:7]
	v_mfma_f32_16x16x32_bf16 v[158:161], v[108:111], v[190:193], v[128:131]
	v_mfma_f32_16x16x32_bf16 v[128:131], v[112:115], v[186:189], v[162:165]
	v_mfma_f32_16x16x32_bf16 v[0:3], v[108:111], v[198:201], v[0:3]
	v_mfma_f32_16x16x32_bf16 v[4:7], v[116:119], v[198:201], v[4:7]
	v_mfma_f32_16x16x32_bf16 v[162:165], v[116:119], v[190:193], v[128:131]
	s_barrier
	s_add_u32 s12, s8, 0x10000
	s_addc_u32 s13, s9, 0
	s_mov_b32 m0, s21
	v_lshl_add_u64 v[104:105], s[12:13], 0, v[140:141]
	global_load_lds_dwordx4 v[104:105], off
	v_lshl_add_u64 v[104:105], s[12:13], 0, v[136:137]
	s_mov_b32 m0, s1
	s_nop 0
	global_load_lds_dwordx4 v[104:105], off
	s_waitcnt vmcnt(6)
	s_barrier
	v_mfma_f32_16x16x32_bf16 v[8:11], v[202:205], v[28:31], v[8:11]
	v_mfma_f32_16x16x32_bf16 v[12:15], v[210:213], v[28:31], v[12:15]
	v_mfma_f32_16x16x32_bf16 v[28:31], v[202:205], v[178:181], v[44:47]
	v_mfma_f32_16x16x32_bf16 v[226:229], v[206:209], v[182:185], v[28:31]
	v_mfma_f32_16x16x32_bf16 v[28:31], v[210:213], v[178:181], v[88:91]
	v_mfma_f32_16x16x32_bf16 v[178:181], v[218:221], v[182:185], v[28:31]
	v_mfma_f32_16x16x32_bf16 v[28:31], v[202:205], v[186:189], v[92:95]
	v_mfma_f32_16x16x32_bf16 v[182:185], v[206:209], v[190:193], v[28:31]
	v_mfma_f32_16x16x32_bf16 v[28:31], v[210:213], v[186:189], v[100:103]
	v_mfma_f32_16x16x32_bf16 v[186:189], v[218:221], v[190:193], v[28:31]
	v_mfma_f32_16x16x32_bf16 v[28:31], v[202:205], v[194:197], v[80:83]
	v_mfma_f32_16x16x32_bf16 v[8:11], v[206:209], v[124:127], v[8:11]
	v_mfma_f32_16x16x32_bf16 v[12:15], v[218:221], v[124:127], v[12:15]
	v_mfma_f32_16x16x32_bf16 v[190:193], v[206:209], v[198:201], v[28:31]
	v_mfma_f32_16x16x32_bf16 v[28:31], v[210:213], v[194:197], v[84:87]
	v_mfma_f32_16x16x32_bf16 v[194:197], v[218:221], v[198:201], v[28:31]
	s_barrier
	ds_read_b128 v[44:47], v144
	ds_read_b128 v[198:201], v144 offset:1024
	ds_read_b128 v[202:205], v144 offset:2048
	ds_read_b128 v[206:209], v144 offset:3072
	s_add_u32 s0, s68, 0x10000
	s_addc_u32 s1, s69, 0
	s_mov_b32 m0, s50
	v_lshl_add_u64 v[80:81], s[0:1], 0, v[142:143]
	ds_read_b128 v[28:31], v174 offset:32768
	ds_read_b128 v[100:103], v174 offset:33792
	ds_read_b128 v[104:107], v174 offset:34816
	ds_read_b128 v[108:111], v174 offset:35840
	ds_read_b128 v[210:213], v174 offset:36864
	ds_read_b128 v[218:221], v174 offset:37888
	ds_read_b128 v[230:233], v174 offset:38912
	ds_read_b128 v[234:237], v174 offset:39936
	global_load_lds_dwordx4 v[80:81], off
	v_lshl_add_u64 v[80:81], s[0:1], 0, v[138:139]
	s_mov_b32 m0, s51
	s_nop 0
	global_load_lds_dwordx4 v[80:81], off
	s_waitcnt lgkmcnt(8)
	s_barrier
	s_waitcnt lgkmcnt(0)
	s_waitcnt lgkmcnt(0)
	v_mfma_f32_16x16x32_bf16 v[48:51], v[44:47], v[28:31], v[48:51]
	v_mfma_f32_16x16x32_bf16 v[128:131], v[198:201], v[100:103], v[48:51]
	v_mfma_f32_16x16x32_bf16 v[48:51], v[202:205], v[28:31], v[52:55]
	v_mfma_f32_16x16x32_bf16 v[92:95], v[206:209], v[100:103], v[48:51]
	v_mfma_f32_16x16x32_bf16 v[48:51], v[44:47], v[104:107], v[56:59]
	v_mfma_f32_16x16x32_bf16 v[124:127], v[198:201], v[108:111], v[48:51]
	v_mfma_f32_16x16x32_bf16 v[48:51], v[202:205], v[104:107], v[60:63]
	v_mfma_f32_16x16x32_bf16 v[88:91], v[206:209], v[108:111], v[48:51]
	v_mfma_f32_16x16x32_bf16 v[48:51], v[44:47], v[210:213], v[64:67]
	v_mfma_f32_16x16x32_bf16 v[116:119], v[198:201], v[218:221], v[48:51]
	v_mfma_f32_16x16x32_bf16 v[48:51], v[202:205], v[210:213], v[68:71]
	v_mfma_f32_16x16x32_bf16 v[84:87], v[206:209], v[218:221], v[48:51]
	v_mfma_f32_16x16x32_bf16 v[48:51], v[44:47], v[230:233], v[72:75]
	v_mfma_f32_16x16x32_bf16 v[112:115], v[198:201], v[234:237], v[48:51]
	v_mfma_f32_16x16x32_bf16 v[48:51], v[202:205], v[230:233], v[76:79]
	v_mfma_f32_16x16x32_bf16 v[80:83], v[206:209], v[234:237], v[48:51]
	s_barrier
	s_mov_b32 m0, s24
	s_nop 3
	v_lshl_add_u64 v[48:49], v[166:167], 0, s[44:45]
	ds_read_b128 v[238:241], v177
	ds_read_b128 v[242:245], v177 offset:1024
	ds_read_b128 v[246:249], v177 offset:2048
	ds_read_b128 v[250:253], v177 offset:3072
	global_load_lds_dwordx4 v[48:49], off
	v_lshl_add_u64 v[48:49], v[214:215], 0, s[44:45]
	s_mov_b32 m0, s23
	s_nop 0
	global_load_lds_dwordx4 v[48:49], off
	s_barrier
	s_waitcnt lgkmcnt(0)
	s_waitcnt lgkmcnt(0)
	v_mfma_f32_16x16x32_bf16 v[16:19], v[246:249], v[28:31], v[16:19]
	v_mfma_f32_16x16x32_bf16 v[48:51], v[238:241], v[28:31], v[96:99]
	v_mfma_f32_16x16x32_bf16 v[28:31], v[250:253], v[100:103], v[16:19]
	v_mfma_f32_16x16x32_bf16 v[16:19], v[238:241], v[104:107], v[20:23]
	v_mfma_f32_16x16x32_bf16 v[56:59], v[242:245], v[108:111], v[16:19]
	v_mfma_f32_16x16x32_bf16 v[16:19], v[246:249], v[104:107], v[24:27]
	v_mfma_f32_16x16x32_bf16 v[24:27], v[250:253], v[108:111], v[16:19]
	v_mfma_f32_16x16x32_bf16 v[16:19], v[238:241], v[210:213], v[120:123]
	v_mfma_f32_16x16x32_bf16 v[52:55], v[242:245], v[218:221], v[16:19]
	v_mfma_f32_16x16x32_bf16 v[16:19], v[246:249], v[210:213], v[32:35]
	v_mfma_f32_16x16x32_bf16 v[20:23], v[250:253], v[218:221], v[16:19]
	v_mfma_f32_16x16x32_bf16 v[16:19], v[238:241], v[230:233], v[36:39]
	v_mfma_f32_16x16x32_bf16 v[60:63], v[242:245], v[100:103], v[48:51]
	v_mfma_f32_16x16x32_bf16 v[48:51], v[242:245], v[234:237], v[16:19]
	v_mfma_f32_16x16x32_bf16 v[16:19], v[246:249], v[230:233], v[40:43]
	v_mfma_f32_16x16x32_bf16 v[16:19], v[250:253], v[234:237], v[16:19]
	s_mov_b32 m0, s72
	v_lshl_add_u64 v[40:41], v[146:147], 0, s[44:45]
	s_barrier
	ds_read_b128 v[32:35], v174 offset:49152
	ds_read_b128 v[36:39], v174 offset:50176
	ds_read_b128 v[120:123], v174 offset:51200
	ds_read_b128 v[210:213], v174 offset:52224
	ds_read_b128 v[218:221], v174 offset:53248
	ds_read_b128 v[230:233], v174 offset:54272
	ds_read_b128 v[234:237], v174 offset:55296
	ds_read_b128 v[214:217], v174 offset:56320
	global_load_lds_dwordx4 v[40:41], off
	v_lshl_add_u64 v[40:41], v[148:149], 0, s[44:45]
	s_mov_b32 m0, s73
	s_nop 0
	global_load_lds_dwordx4 v[40:41], off
	s_barrier
	s_waitcnt lgkmcnt(0)
	s_waitcnt lgkmcnt(0)
	v_mfma_f32_16x16x32_bf16 v[40:43], v[44:47], v[32:35], v[222:225]
	v_mfma_f32_16x16x32_bf16 v[108:111], v[198:201], v[36:39], v[40:43]
	v_mfma_f32_16x16x32_bf16 v[40:43], v[202:205], v[32:35], v[132:135]
	v_mfma_f32_16x16x32_bf16 v[76:79], v[206:209], v[36:39], v[40:43]
	v_mfma_f32_16x16x32_bf16 v[40:43], v[44:47], v[120:123], v[150:153]
	v_mfma_f32_16x16x32_bf16 v[104:107], v[198:201], v[210:213], v[40:43]
	v_mfma_f32_16x16x32_bf16 v[40:43], v[202:205], v[120:123], v[154:157]
	v_mfma_f32_16x16x32_bf16 v[72:75], v[206:209], v[210:213], v[40:43]
	v_mfma_f32_16x16x32_bf16 v[40:43], v[44:47], v[218:221], v[158:161]
	v_mfma_f32_16x16x32_bf16 v[0:3], v[44:47], v[234:237], v[0:3]
	v_mfma_f32_16x16x32_bf16 v[100:103], v[198:201], v[230:233], v[40:43]
	v_mfma_f32_16x16x32_bf16 v[40:43], v[202:205], v[218:221], v[162:165]
	v_mfma_f32_16x16x32_bf16 v[96:99], v[198:201], v[214:217], v[0:3]
	v_mfma_f32_16x16x32_bf16 v[0:3], v[202:205], v[234:237], v[4:7]
	v_mfma_f32_16x16x32_bf16 v[68:71], v[206:209], v[230:233], v[40:43]
	v_mfma_f32_16x16x32_bf16 v[64:67], v[206:209], v[214:217], v[0:3]
	s_barrier
	s_add_u32 s0, s8, 0x10080
	s_addc_u32 s1, s9, 0
	s_mov_b32 m0, s15
	s_nop 0
	v_lshl_add_u64 v[0:1], s[0:1], 0, v[140:141]
	global_load_lds_dwordx4 v[0:1], off
	v_lshl_add_u64 v[0:1], s[0:1], 0, v[136:137]
	s_mov_b32 m0, s14
	s_nop 0
	global_load_lds_dwordx4 v[0:1], off
	s_waitcnt vmcnt(6)
	s_barrier
	v_mfma_f32_16x16x32_bf16 v[0:3], v[238:241], v[32:35], v[8:11]
	v_mfma_f32_16x16x32_bf16 v[44:47], v[242:245], v[36:39], v[0:3]
	v_mfma_f32_16x16x32_bf16 v[0:3], v[246:249], v[32:35], v[12:15]
	v_mfma_f32_16x16x32_bf16 v[12:15], v[250:253], v[36:39], v[0:3]
	v_mfma_f32_16x16x32_bf16 v[0:3], v[238:241], v[120:123], v[226:229]
	v_mfma_f32_16x16x32_bf16 v[40:43], v[242:245], v[210:213], v[0:3]
	v_mfma_f32_16x16x32_bf16 v[0:3], v[246:249], v[120:123], v[178:181]
	v_mfma_f32_16x16x32_bf16 v[8:11], v[250:253], v[210:213], v[0:3]
	v_mfma_f32_16x16x32_bf16 v[0:3], v[238:241], v[218:221], v[182:185]
	v_mfma_f32_16x16x32_bf16 v[36:39], v[242:245], v[230:233], v[0:3]
	v_mfma_f32_16x16x32_bf16 v[0:3], v[246:249], v[218:221], v[186:189]
	v_mfma_f32_16x16x32_bf16 v[4:7], v[250:253], v[230:233], v[0:3]
	v_mfma_f32_16x16x32_bf16 v[0:3], v[238:241], v[234:237], v[190:193]
	v_mfma_f32_16x16x32_bf16 v[32:35], v[242:245], v[214:217], v[0:3]
	v_mfma_f32_16x16x32_bf16 v[0:3], v[246:249], v[234:237], v[194:197]
	v_mfma_f32_16x16x32_bf16 v[0:3], v[250:253], v[214:217], v[0:3]
	v_lshl_add_u32 v150, s10, 8, v168
	s_cmp_gt_i32 s20, 15
	s_mov_b64 s[0:1], -1
	s_barrier
	s_cbranch_scc0 .LBB0_542
	s_lshl_b32 s8, s20, 8
	s_cmp_gt_u32 s20, 31
	s_cbranch_scc0 .LBB0_539
	v_ashrrev_i32_e32 v151, 31, v150
	v_add_u32_e32 v144, s8, v171
	v_lshlrev_b64 v[120:121], 12, v[150:151]
	v_lshl_add_u64 v[120:121], s[56:57], 0, v[120:121]
	v_lshlrev_b64 v[122:123], 1, v[144:145]
	v_lshl_add_u64 v[120:121], v[120:121], 0, v[122:123]
	v_cvt_pk_bf16_f32 v132, v128, v129
	v_cvt_pk_bf16_f32 v133, v130, v131
	v_cvt_pk_bf16_f32 v134, v92, v93
	v_cvt_pk_bf16_f32 v135, v94, v95
	global_store_dwordx4 v[120:121], v[132:135], off
	s_mov_b64 s[0:1], 0x80000
	s_nop 0
	v_cvt_pk_bf16_f32 v132, v60, v61
	v_cvt_pk_bf16_f32 v133, v62, v63
	v_cvt_pk_bf16_f32 v134, v28, v29
	v_cvt_pk_bf16_f32 v135, v30, v31
	global_store_dwordx4 v[120:121], v[132:135], off offset:256
	s_nop 1
	v_or_b32_e32 v132, 16, v150
	v_ashrrev_i32_e32 v133, 31, v132
	v_lshlrev_b64 v[132:133], 12, v[132:133]
	v_lshl_add_u64 v[132:133], s[56:57], 0, v[132:133]
	v_lshl_add_u64 v[146:147], v[132:133], 0, v[122:123]
	v_cvt_pk_bf16_f32 v132, v124, v125
	v_cvt_pk_bf16_f32 v133, v126, v127
	v_cvt_pk_bf16_f32 v134, v88, v89
	v_cvt_pk_bf16_f32 v135, v90, v91
	global_store_dwordx4 v[146:147], v[132:135], off
	s_nop 1
	v_cvt_pk_bf16_f32 v132, v56, v57
	v_cvt_pk_bf16_f32 v133, v58, v59
	v_cvt_pk_bf16_f32 v134, v24, v25
	v_cvt_pk_bf16_f32 v135, v26, v27
	global_store_dwordx4 v[146:147], v[132:135], off offset:256
	s_nop 1
	v_or_b32_e32 v132, 32, v150
	v_ashrrev_i32_e32 v133, 31, v132
	v_lshlrev_b64 v[132:133], 12, v[132:133]
	v_lshl_add_u64 v[132:133], s[56:57], 0, v[132:133]
	v_lshl_add_u64 v[146:147], v[132:133], 0, v[122:123]
	v_cvt_pk_bf16_f32 v132, v116, v117
	v_cvt_pk_bf16_f32 v133, v118, v119
	v_cvt_pk_bf16_f32 v134, v84, v85
	v_cvt_pk_bf16_f32 v135, v86, v87
	global_store_dwordx4 v[146:147], v[132:135], off
	s_nop 1
	v_cvt_pk_bf16_f32 v132, v52, v53
	v_cvt_pk_bf16_f32 v133, v54, v55
	v_cvt_pk_bf16_f32 v134, v20, v21
	v_cvt_pk_bf16_f32 v135, v22, v23
	global_store_dwordx4 v[146:147], v[132:135], off offset:256
	s_nop 1
	v_or_b32_e32 v132, 48, v150
	v_ashrrev_i32_e32 v133, 31, v132
	v_lshlrev_b64 v[132:133], 12, v[132:133]
	v_lshl_add_u64 v[132:133], s[56:57], 0, v[132:133]
	v_lshl_add_u64 v[122:123], v[132:133], 0, v[122:123]
	v_cvt_pk_bf16_f32 v132, v112, v113
	v_cvt_pk_bf16_f32 v133, v114, v115
	v_cvt_pk_bf16_f32 v134, v80, v81
	v_cvt_pk_bf16_f32 v135, v82, v83
	global_store_dwordx4 v[122:123], v[132:135], off
	s_nop 1
	v_cvt_pk_bf16_f32 v132, v48, v49
	v_cvt_pk_bf16_f32 v133, v50, v51
	v_cvt_pk_bf16_f32 v134, v16, v17
	v_cvt_pk_bf16_f32 v135, v18, v19
	global_store_dwordx4 v[122:123], v[132:135], off offset:256
	v_lshl_add_u64 v[122:123], v[120:121], 0, s[0:1]
	s_mov_b32 s0, 0x80000
	v_add_co_u32_e32 v146, vcc, s0, v120
	v_cvt_pk_bf16_f32 v132, v108, v109
	v_cvt_pk_bf16_f32 v133, v110, v111
	v_cvt_pk_bf16_f32 v134, v76, v77
	v_cvt_pk_bf16_f32 v135, v78, v79
	s_nop 1
	v_addc_co_u32_e32 v147, vcc, 0, v121, vcc
	s_mov_b64 s[0:1], 0x90000
	global_store_dwordx4 v[146:147], v[132:135], off
	s_nop 1
	v_cvt_pk_bf16_f32 v132, v44, v45
	v_cvt_pk_bf16_f32 v133, v46, v47
	v_cvt_pk_bf16_f32 v134, v12, v13
	v_cvt_pk_bf16_f32 v135, v14, v15
	global_store_dwordx4 v[122:123], v[132:135], off offset:256
	v_lshl_add_u64 v[122:123], v[120:121], 0, s[0:1]
	s_mov_b32 s0, 0x90000
	v_add_co_u32_e32 v146, vcc, s0, v120
	v_cvt_pk_bf16_f32 v132, v104, v105
	v_cvt_pk_bf16_f32 v133, v106, v107
	v_cvt_pk_bf16_f32 v134, v72, v73
	v_cvt_pk_bf16_f32 v135, v74, v75
	s_nop 1
	v_addc_co_u32_e32 v147, vcc, 0, v121, vcc
	s_mov_b64 s[0:1], 0xa0000
	global_store_dwordx4 v[146:147], v[132:135], off
	s_nop 1
	v_cvt_pk_bf16_f32 v132, v40, v41
	v_cvt_pk_bf16_f32 v133, v42, v43
	v_cvt_pk_bf16_f32 v134, v8, v9
	v_cvt_pk_bf16_f32 v135, v10, v11
	global_store_dwordx4 v[122:123], v[132:135], off offset:256
	v_lshl_add_u64 v[122:123], v[120:121], 0, s[0:1]
	s_mov_b32 s0, 0xa0000
	v_add_co_u32_e32 v146, vcc, s0, v120
	s_mov_b64 s[0:1], 0xb0000
	s_nop 0
	v_addc_co_u32_e32 v147, vcc, 0, v121, vcc
	v_cvt_pk_bf16_f32 v132, v100, v101
	v_cvt_pk_bf16_f32 v133, v102, v103
	v_cvt_pk_bf16_f32 v134, v68, v69
	v_cvt_pk_bf16_f32 v135, v70, v71
	global_store_dwordx4 v[146:147], v[132:135], off
	v_lshl_add_u64 v[146:147], v[120:121], 0, s[0:1]
	s_mov_b32 s0, 0xb0000
	v_add_co_u32_e32 v120, vcc, s0, v120
	v_cvt_pk_bf16_f32 v132, v36, v37
	v_cvt_pk_bf16_f32 v133, v38, v39
	v_cvt_pk_bf16_f32 v134, v4, v5
	v_cvt_pk_bf16_f32 v135, v6, v7
	s_nop 1
	v_addc_co_u32_e32 v121, vcc, 0, v121, vcc
	global_store_dwordx4 v[122:123], v[132:135], off offset:256
	s_mov_b64 s[0:1], 0
	s_nop 0
	v_cvt_pk_bf16_f32 v132, v96, v97
	v_cvt_pk_bf16_f32 v133, v98, v99
	v_cvt_pk_bf16_f32 v134, v64, v65
	v_cvt_pk_bf16_f32 v135, v66, v67
	global_store_dwordx4 v[120:121], v[132:135], off
	v_cvt_pk_bf16_f32 v120, v32, v33
	v_cvt_pk_bf16_f32 v121, v34, v35
	v_cvt_pk_bf16_f32 v122, v0, v1
	v_cvt_pk_bf16_f32 v123, v2, v3
	global_store_dwordx4 v[146:147], v[120:123], off offset:256
.LBB0_539:
	s_andn2_b64 vcc, exec, s[0:1]
	s_cbranch_vccnz .LBB0_541
	v_add_u32_e32 v144, s8, v172
	v_lshl_add_u64 v[154:155], v[144:145], 2, s[42:43]
	flat_load_dwordx4 v[132:135], v[154:155]
	flat_load_dwordx4 v[120:123], v[154:155] offset:16
	v_or_b32_e32 v146, 16, v150
	v_ashrrev_i32_e32 v147, 31, v146
	v_ashrrev_i32_e32 v151, 31, v150
	v_lshlrev_b64 v[146:147], 13, v[146:147]
	v_lshlrev_b64 v[148:149], 13, v[150:151]
	v_lshlrev_b64 v[166:167], 1, v[144:145]
	v_lshl_add_u64 v[146:147], s[52:53], 0, v[146:147]
	v_lshl_add_u64 v[148:149], s[52:53], 0, v[148:149]
	v_lshl_add_u64 v[152:153], v[146:147], 0, v[166:167]
	v_lshl_add_u64 v[156:157], v[148:149], 0, v[166:167]
	s_mov_b32 s0, 0x100000
	s_waitcnt vmcnt(0) lgkmcnt(0)
	v_pk_add_f32 v[146:147], v[130:131], v[134:135]
	v_pk_add_f32 v[148:149], v[128:129], v[132:133]
	v_pk_add_f32 v[158:159], v[94:95], v[122:123]
	v_pk_add_f32 v[160:161], v[92:93], v[120:121]
	v_mul_f32_e32 v146, 0xbfb8aa3b, v146
	v_mul_f32_e32 v147, 0xbfb8aa3b, v147
	v_pk_add_f32 v[164:165], v[124:125], v[132:133]
	v_mul_f32_e32 v144, 0xbfb8aa3b, v148
	v_mul_f32_e32 v148, 0xbfb8aa3b, v160
	v_mul_f32_e32 v149, 0xbfb8aa3b, v149
	v_mul_f32_e32 v158, 0xbfb8aa3b, v158
	v_mul_f32_e32 v159, 0xbfb8aa3b, v159
	v_exp_f32_e32 v146, v146
	v_exp_f32_e32 v147, v147
	v_pk_add_f32 v[180:181], v[88:89], v[120:121]
	v_mul_f32_e32 v151, 0xbfb8aa3b, v161
	v_mul_f32_e32 v160, 0xbfb8aa3b, v164
	v_exp_f32_e32 v144, v144
	v_exp_f32_e32 v148, v148
	v_exp_f32_e32 v149, v149
	v_exp_f32_e32 v158, v158
	v_exp_f32_e32 v159, v159
	v_pk_add_f32 v[162:163], v[126:127], v[134:135]
	v_pk_add_f32 v[178:179], v[90:91], v[122:123]
	v_mul_f32_e32 v161, 0xbfb8aa3b, v180
	v_exp_f32_e32 v151, v151
	v_exp_f32_e32 v160, v160
	v_mul_f32_e32 v164, 0xbfb8aa3b, v165
	v_mul_f32_e32 v165, 0xbfb8aa3b, v181
	v_mul_f32_e32 v162, 0xbfb8aa3b, v162
	v_mul_f32_e32 v177, 0xbfb8aa3b, v178
	v_mul_f32_e32 v163, 0xbfb8aa3b, v163
	v_mul_f32_e32 v178, 0xbfb8aa3b, v179
	v_exp_f32_e32 v161, v161
	v_exp_f32_e32 v164, v164
	v_exp_f32_e32 v165, v165
	v_exp_f32_e32 v162, v162
	v_exp_f32_e32 v177, v177
	v_exp_f32_e32 v163, v163
	v_exp_f32_e32 v178, v178
	v_add_f32_e32 v146, 1.0, v146
	v_add_f32_e32 v147, 1.0, v147
	v_add_f32_e32 v144, 1.0, v144
	v_add_f32_e32 v148, 1.0, v148
	v_add_f32_e32 v149, 1.0, v149
	v_add_f32_e32 v158, 1.0, v158
	v_add_f32_e32 v159, 1.0, v159
	v_rcp_f32_e32 v146, v146
	v_rcp_f32_e32 v147, v147
	v_add_f32_e32 v151, 1.0, v151
	v_add_f32_e32 v160, 1.0, v160
	v_rcp_f32_e32 v144, v144
	v_rcp_f32_e32 v148, v148
	v_rcp_f32_e32 v149, v149
	v_rcp_f32_e32 v179, v158
	v_rcp_f32_e32 v180, v159
	v_cvt_pk_bf16_f32 v158, v144, v149
	v_cvt_pk_bf16_f32 v159, v146, v147
	v_pk_add_f32 v[146:147], v[118:119], v[134:135]
	v_add_f32_e32 v161, 1.0, v161
	v_rcp_f32_e32 v151, v151
	v_rcp_f32_e32 v181, v160
	v_cvt_pk_bf16_f32 v160, v148, v151
	v_pk_add_f32 v[148:149], v[116:117], v[132:133]
	v_mul_f32_e32 v146, 0xbfb8aa3b, v146
	v_add_f32_e32 v164, 1.0, v164
	v_add_f32_e32 v165, 1.0, v165
	v_add_f32_e32 v162, 1.0, v162
	v_add_f32_e32 v177, 1.0, v177
	v_add_f32_e32 v163, 1.0, v163
	v_add_f32_e32 v178, 1.0, v178
	v_rcp_f32_e32 v182, v161
	v_cvt_pk_bf16_f32 v161, v179, v180
	v_mul_f32_e32 v144, 0xbfb8aa3b, v148
	v_mul_f32_e32 v149, 0xbfb8aa3b, v149
	v_exp_f32_e32 v146, v146
	v_mul_f32_e32 v147, 0xbfb8aa3b, v147
	v_rcp_f32_e32 v164, v164
	v_rcp_f32_e32 v165, v165
	v_rcp_f32_e32 v162, v162
	v_rcp_f32_e32 v177, v177
	v_rcp_f32_e32 v163, v163
	v_rcp_f32_e32 v178, v178
	global_store_dwordx4 v[156:157], v[158:161], off
	v_exp_f32_e32 v144, v144
	v_exp_f32_e32 v149, v149
	v_cvt_pk_bf16_f32 v158, v181, v164
	v_cvt_pk_bf16_f32 v159, v162, v163
	v_cvt_pk_bf16_f32 v160, v182, v165
	v_cvt_pk_bf16_f32 v161, v177, v178
	v_exp_f32_e32 v147, v147
	global_store_dwordx4 v[152:153], v[158:161], off
	v_add_f32_e32 v146, 1.0, v146
	v_add_f32_e32 v144, 1.0, v144
	v_pk_add_f32 v[158:159], v[84:85], v[120:121]
	v_pk_add_f32 v[160:161], v[86:87], v[122:123]
	v_mul_f32_e32 v148, 0xbfb8aa3b, v158
	v_mul_f32_e32 v151, 0xbfb8aa3b, v159
	v_mul_f32_e32 v158, 0xbfb8aa3b, v160
	v_mul_f32_e32 v159, 0xbfb8aa3b, v161
	v_exp_f32_e32 v158, v158
	v_exp_f32_e32 v159, v159
	v_exp_f32_e32 v148, v148
	v_exp_f32_e32 v151, v151
	v_add_f32_e32 v149, 1.0, v149
	v_rcp_f32_e32 v146, v146
	v_add_f32_e32 v147, 1.0, v147
	v_rcp_f32_e32 v144, v144
	v_rcp_f32_e32 v149, v149
	v_rcp_f32_e32 v147, v147
	v_cvt_pk_bf16_f32 v160, v144, v149
	v_cvt_pk_bf16_f32 v161, v146, v147
	v_or_b32_e32 v146, 32, v150
	v_ashrrev_i32_e32 v147, 31, v146
	v_add_f32_e32 v158, 1.0, v158
	v_add_f32_e32 v159, 1.0, v159
	v_lshlrev_b64 v[146:147], 13, v[146:147]
	v_add_f32_e32 v148, 1.0, v148
	v_add_f32_e32 v151, 1.0, v151
	v_rcp_f32_e32 v158, v158
	v_rcp_f32_e32 v159, v159
	v_lshl_add_u64 v[146:147], s[52:53], 0, v[146:147]
	v_rcp_f32_e32 v148, v148
	v_rcp_f32_e32 v151, v151
	s_nop 0
	v_cvt_pk_bf16_f32 v162, v148, v151
	v_cvt_pk_bf16_f32 v163, v158, v159
	v_lshl_add_u64 v[158:159], v[146:147], 0, v[166:167]
	v_pk_add_f32 v[146:147], v[114:115], v[134:135]
	v_pk_add_f32 v[148:149], v[112:113], v[132:133]
	v_mul_f32_e32 v146, 0xbfb8aa3b, v146
	v_mul_f32_e32 v144, 0xbfb8aa3b, v148
	v_mul_f32_e32 v149, 0xbfb8aa3b, v149
	v_exp_f32_e32 v146, v146
	v_mul_f32_e32 v147, 0xbfb8aa3b, v147
	v_exp_f32_e32 v144, v144
	v_exp_f32_e32 v149, v149
	v_exp_f32_e32 v147, v147
	global_store_dwordx4 v[158:159], v[160:163], off
	v_add_f32_e32 v146, 1.0, v146
	v_add_f32_e32 v144, 1.0, v144
	v_pk_add_f32 v[160:161], v[80:81], v[120:121]
	v_pk_add_f32 v[162:163], v[82:83], v[122:123]
	v_mul_f32_e32 v148, 0xbfb8aa3b, v160
	v_mul_f32_e32 v151, 0xbfb8aa3b, v161
	v_mul_f32_e32 v160, 0xbfb8aa3b, v162
	v_mul_f32_e32 v161, 0xbfb8aa3b, v163
	v_exp_f32_e32 v160, v160
	v_exp_f32_e32 v161, v161
	v_exp_f32_e32 v148, v148
	v_exp_f32_e32 v151, v151
	v_add_f32_e32 v149, 1.0, v149
	v_rcp_f32_e32 v146, v146
	v_add_f32_e32 v147, 1.0, v147
	v_rcp_f32_e32 v144, v144
	v_rcp_f32_e32 v149, v149
	v_rcp_f32_e32 v147, v147
	v_cvt_pk_bf16_f32 v162, v144, v149
	v_cvt_pk_bf16_f32 v163, v146, v147
	v_or_b32_e32 v146, 48, v150
	v_ashrrev_i32_e32 v147, 31, v146
	v_add_f32_e32 v160, 1.0, v160
	v_add_f32_e32 v161, 1.0, v161
	v_lshlrev_b64 v[146:147], 13, v[146:147]
	v_add_f32_e32 v148, 1.0, v148
	v_add_f32_e32 v151, 1.0, v151
	v_rcp_f32_e32 v160, v160
	v_rcp_f32_e32 v161, v161
	v_lshl_add_u64 v[146:147], s[52:53], 0, v[146:147]
	v_rcp_f32_e32 v148, v148
	v_rcp_f32_e32 v151, v151
	s_nop 0
	v_cvt_pk_bf16_f32 v164, v148, v151
	v_cvt_pk_bf16_f32 v165, v160, v161
	v_lshl_add_u64 v[160:161], v[146:147], 0, v[166:167]
	global_store_dwordx4 v[160:161], v[162:165], off
	v_pk_add_f32 v[146:147], v[110:111], v[134:135]
	v_pk_add_f32 v[148:149], v[108:109], v[132:133]
	v_pk_add_f32 v[162:163], v[76:77], v[120:121]
	v_pk_add_f32 v[164:165], v[78:79], v[122:123]
	v_mul_f32_e32 v144, 0xbfb8aa3b, v148
	v_mul_f32_e32 v148, 0xbfb8aa3b, v162
	v_mul_f32_e32 v146, 0xbfb8aa3b, v146
	v_mul_f32_e32 v162, 0xbfb8aa3b, v164
	v_mul_f32_e32 v149, 0xbfb8aa3b, v149
	v_mul_f32_e32 v151, 0xbfb8aa3b, v163
	v_exp_f32_e32 v146, v146
	v_exp_f32_e32 v162, v162
	v_mul_f32_e32 v147, 0xbfb8aa3b, v147
	v_mul_f32_e32 v163, 0xbfb8aa3b, v165
	v_exp_f32_e32 v144, v144
	v_exp_f32_e32 v149, v149
	v_exp_f32_e32 v147, v147
	v_exp_f32_e32 v163, v163
	v_exp_f32_e32 v148, v148
	v_exp_f32_e32 v151, v151
	v_add_f32_e32 v146, 1.0, v146
	v_add_f32_e32 v162, 1.0, v162
	v_add_f32_e32 v144, 1.0, v144
	v_add_f32_e32 v149, 1.0, v149
	v_rcp_f32_e32 v146, v146
	v_rcp_f32_e32 v165, v162
	v_add_f32_e32 v147, 1.0, v147
	v_add_f32_e32 v162, 1.0, v163
	v_rcp_f32_e32 v144, v144
	v_add_f32_e32 v148, 1.0, v148
	v_rcp_f32_e32 v149, v149
	v_add_f32_e32 v151, 1.0, v151
	v_rcp_f32_e32 v147, v147
	v_rcp_f32_e32 v166, v162
	v_cvt_pk_bf16_f32 v162, v144, v149
	v_cvt_pk_bf16_f32 v163, v146, v147
	v_add_co_u32_e32 v146, vcc, s0, v156
	v_rcp_f32_e32 v148, v148
	v_rcp_f32_e32 v151, v151
	s_nop 0
	v_cvt_pk_bf16_f32 v164, v148, v151
	v_cvt_pk_bf16_f32 v165, v165, v166
	v_addc_co_u32_e32 v147, vcc, 0, v157, vcc
	global_store_dwordx4 v[146:147], v[162:165], off
	v_pk_add_f32 v[146:147], v[106:107], v[134:135]
	v_pk_add_f32 v[148:149], v[104:105], v[132:133]
	v_pk_add_f32 v[162:163], v[72:73], v[120:121]
	v_pk_add_f32 v[164:165], v[74:75], v[122:123]
	v_mul_f32_e32 v144, 0xbfb8aa3b, v148
	v_mul_f32_e32 v148, 0xbfb8aa3b, v162
	v_mul_f32_e32 v146, 0xbfb8aa3b, v146
	v_mul_f32_e32 v162, 0xbfb8aa3b, v164
	v_mul_f32_e32 v149, 0xbfb8aa3b, v149
	v_mul_f32_e32 v151, 0xbfb8aa3b, v163
	v_exp_f32_e32 v146, v146
	v_exp_f32_e32 v162, v162
	v_mul_f32_e32 v147, 0xbfb8aa3b, v147
	v_mul_f32_e32 v163, 0xbfb8aa3b, v165
	v_exp_f32_e32 v144, v144
	v_exp_f32_e32 v149, v149
	v_exp_f32_e32 v147, v147
	v_exp_f32_e32 v163, v163
	v_exp_f32_e32 v148, v148
	v_exp_f32_e32 v151, v151
	v_add_f32_e32 v146, 1.0, v146
	v_add_f32_e32 v162, 1.0, v162
	v_add_f32_e32 v144, 1.0, v144
	v_add_f32_e32 v149, 1.0, v149
	v_rcp_f32_e32 v146, v146
	v_rcp_f32_e32 v165, v162
	v_add_f32_e32 v147, 1.0, v147
	v_add_f32_e32 v162, 1.0, v163
	s_mov_b32 s0, 0x120000
	v_rcp_f32_e32 v144, v144
	v_add_f32_e32 v148, 1.0, v148
	v_rcp_f32_e32 v149, v149
	v_add_f32_e32 v151, 1.0, v151
	v_rcp_f32_e32 v147, v147
	v_rcp_f32_e32 v166, v162
	v_cvt_pk_bf16_f32 v162, v144, v149
	v_cvt_pk_bf16_f32 v163, v146, v147
	v_add_co_u32_e32 v146, vcc, s0, v156
	v_rcp_f32_e32 v148, v148
	v_rcp_f32_e32 v151, v151
	s_nop 0
	v_cvt_pk_bf16_f32 v164, v148, v151
	v_cvt_pk_bf16_f32 v165, v165, v166
	v_addc_co_u32_e32 v147, vcc, 0, v157, vcc
	global_store_dwordx4 v[146:147], v[162:165], off
	v_pk_add_f32 v[148:149], v[100:101], v[132:133]
	v_pk_add_f32 v[132:133], v[96:97], v[132:133]
	v_pk_add_f32 v[162:163], v[68:69], v[120:121]
	v_pk_add_f32 v[164:165], v[70:71], v[122:123]
	v_mul_f32_e32 v144, 0xbfb8aa3b, v148
	v_mul_f32_e32 v148, 0xbfb8aa3b, v162
	v_mul_f32_e32 v162, 0xbfb8aa3b, v164
	v_pk_add_f32 v[120:121], v[64:65], v[120:121]
	v_exp_f32_e32 v144, v144
	v_mul_f32_e32 v149, 0xbfb8aa3b, v149
	v_mul_f32_e32 v151, 0xbfb8aa3b, v163
	v_exp_f32_e32 v162, v162
	v_mul_f32_e32 v163, 0xbfb8aa3b, v165
	v_mul_f32_e32 v120, 0xbfb8aa3b, v120
	v_exp_f32_e32 v149, v149
	v_exp_f32_e32 v163, v163
	v_exp_f32_e32 v120, v120
	v_mul_f32_e32 v133, 0xbfb8aa3b, v133
	v_exp_f32_e32 v133, v133
	v_add_f32_e32 v144, 1.0, v144
	v_add_f32_e32 v162, 1.0, v162
	v_pk_add_f32 v[146:147], v[102:103], v[134:135]
	v_rcp_f32_e32 v144, v144
	v_add_f32_e32 v149, 1.0, v149
	v_rcp_f32_e32 v165, v162
	v_add_f32_e32 v162, 1.0, v163
	v_pk_add_f32 v[134:135], v[98:99], v[134:135]
	v_add_f32_e32 v120, 1.0, v120
	v_mul_f32_e32 v121, 0xbfb8aa3b, v121
	v_rcp_f32_e32 v149, v149
	v_rcp_f32_e32 v166, v162
	v_cvt_pk_bf16_f32 v162, v144, v149
	v_exp_f32_e32 v121, v121
	v_rcp_f32_e32 v144, v120
	v_add_f32_e32 v120, 1.0, v133
	v_mul_f32_e32 v133, 0xbfb8aa3b, v134
	v_mul_f32_e32 v146, 0xbfb8aa3b, v146
	v_exp_f32_e32 v133, v133
	v_exp_f32_e32 v146, v146
	v_mul_f32_e32 v147, 0xbfb8aa3b, v147
	v_exp_f32_e32 v147, v147
	v_mul_f32_e32 v132, 0xbfb8aa3b, v132
	v_pk_add_f32 v[122:123], v[66:67], v[122:123]
	v_exp_f32_e32 v132, v132
	v_add_f32_e32 v121, 1.0, v121
	v_mul_f32_e32 v122, 0xbfb8aa3b, v122
	v_exp_f32_e32 v148, v148
	v_exp_f32_e32 v151, v151
	v_exp_f32_e32 v122, v122
	v_rcp_f32_e32 v134, v121
	v_add_f32_e32 v121, 1.0, v133
	v_mul_f32_e32 v133, 0xbfb8aa3b, v135
	v_mul_f32_e32 v123, 0xbfb8aa3b, v123
	v_add_f32_e32 v146, 1.0, v146
	v_exp_f32_e32 v133, v133
	v_exp_f32_e32 v123, v123
	v_rcp_f32_e32 v146, v146
	v_add_f32_e32 v147, 1.0, v147
	s_mov_b32 s0, 0x140000
	v_rcp_f32_e32 v147, v147
	s_nop 0
	v_cvt_pk_bf16_f32 v163, v146, v147
	v_add_co_u32_e32 v146, vcc, s0, v156
	v_add_f32_e32 v132, 1.0, v132
	v_add_f32_e32 v148, 1.0, v148
	v_add_f32_e32 v151, 1.0, v151
	v_addc_co_u32_e32 v147, vcc, 0, v157, vcc
	v_rcp_f32_e32 v132, v132
	v_rcp_f32_e32 v120, v120
	v_add_f32_e32 v122, 1.0, v122
	s_mov_b32 s0, 0x160000
	v_rcp_f32_e32 v148, v148
	v_rcp_f32_e32 v151, v151
	s_nop 0
	v_cvt_pk_bf16_f32 v164, v148, v151
	v_cvt_pk_bf16_f32 v165, v165, v166
	global_store_dwordx4 v[146:147], v[162:165], off
	v_rcp_f32_e32 v135, v122
	v_add_f32_e32 v122, 1.0, v133
	v_add_f32_e32 v123, 1.0, v123
	v_cvt_pk_bf16_f32 v120, v132, v120
	v_add_co_u32_e32 v132, vcc, s0, v156
	v_rcp_f32_e32 v121, v121
	v_rcp_f32_e32 v122, v122
	v_rcp_f32_e32 v123, v123
	v_addc_co_u32_e32 v133, vcc, 0, v157, vcc
	v_cvt_pk_bf16_f32 v121, v121, v122
	v_cvt_pk_bf16_f32 v122, v144, v134
	v_cvt_pk_bf16_f32 v123, v135, v123
	global_store_dwordx4 v[132:133], v[120:123], off
	flat_load_dwordx4 v[132:135], v[154:155] offset:512
	s_nop 0
	flat_load_dwordx4 v[120:123], v[154:155] offset:528
	s_mov_b64 s[0:1], 0x100000
	v_lshl_add_u64 v[166:167], v[156:157], 0, s[0:1]
	s_mov_b64 s[0:1], 0x120000
	v_lshl_add_u64 v[164:165], v[156:157], 0, s[0:1]
	s_mov_b64 s[0:1], 0x140000
	v_lshl_add_u64 v[162:163], v[156:157], 0, s[0:1]
	s_mov_b64 s[0:1], 0x160000
	v_lshl_add_u64 v[154:155], v[156:157], 0, s[0:1]
	s_waitcnt vmcnt(0) lgkmcnt(0)
	v_pk_add_f32 v[146:147], v[62:63], v[134:135]
	v_pk_add_f32 v[148:149], v[60:61], v[132:133]
	v_pk_add_f32 v[178:179], v[28:29], v[120:121]
	v_pk_add_f32 v[180:181], v[30:31], v[122:123]
	v_mul_f32_e32 v144, 0xbfb8aa3b, v148
	v_mul_f32_e32 v148, 0xbfb8aa3b, v178
	v_mul_f32_e32 v149, 0xbfb8aa3b, v149
	v_mul_f32_e32 v146, 0xbfb8aa3b, v146
	v_mul_f32_e32 v147, 0xbfb8aa3b, v147
	v_mul_f32_e32 v178, 0xbfb8aa3b, v181
	v_exp_f32_e32 v144, v144
	v_exp_f32_e32 v148, v148
	v_exp_f32_e32 v149, v149
	v_mul_f32_e32 v151, 0xbfb8aa3b, v179
	v_exp_f32_e32 v146, v146
	v_mul_f32_e32 v177, 0xbfb8aa3b, v180
	v_exp_f32_e32 v147, v147
	v_exp_f32_e32 v178, v178
	v_exp_f32_e32 v151, v151
	v_exp_f32_e32 v177, v177
	v_add_f32_e32 v144, 1.0, v144
	v_add_f32_e32 v148, 1.0, v148
	v_add_f32_e32 v149, 1.0, v149
	v_add_f32_e32 v146, 1.0, v146
	v_add_f32_e32 v147, 1.0, v147
	v_add_f32_e32 v178, 1.0, v178
	v_rcp_f32_e32 v144, v144
	v_rcp_f32_e32 v148, v148
	v_rcp_f32_e32 v149, v149
	v_add_f32_e32 v151, 1.0, v151
	v_rcp_f32_e32 v146, v146
	v_add_f32_e32 v177, 1.0, v177
	v_rcp_f32_e32 v147, v147
	v_rcp_f32_e32 v181, v178
	v_cvt_pk_bf16_f32 v178, v144, v149
	v_cvt_pk_bf16_f32 v179, v146, v147
	v_rcp_f32_e32 v151, v151
	v_rcp_f32_e32 v177, v177
	v_cvt_pk_bf16_f32 v180, v148, v151
	v_cvt_pk_bf16_f32 v181, v177, v181
	global_store_dwordx4 v[156:157], v[178:181], off offset:256
	v_pk_add_f32 v[146:147], v[58:59], v[134:135]
	v_pk_add_f32 v[148:149], v[56:57], v[132:133]
	v_pk_add_f32 v[156:157], v[24:25], v[120:121]
	v_pk_add_f32 v[178:179], v[26:27], v[122:123]
	v_mul_f32_e32 v144, 0xbfb8aa3b, v148
	v_mul_f32_e32 v148, 0xbfb8aa3b, v156
	v_mul_f32_e32 v149, 0xbfb8aa3b, v149
	v_mul_f32_e32 v151, 0xbfb8aa3b, v157
	v_mul_f32_e32 v146, 0xbfb8aa3b, v146
	v_mul_f32_e32 v156, 0xbfb8aa3b, v178
	v_mul_f32_e32 v147, 0xbfb8aa3b, v147
	v_mul_f32_e32 v157, 0xbfb8aa3b, v179
	v_exp_f32_e32 v148, v148
	v_exp_f32_e32 v149, v149
	v_exp_f32_e32 v146, v146
	v_exp_f32_e32 v156, v156
	v_exp_f32_e32 v147, v147
	v_exp_f32_e32 v157, v157
	v_exp_f32_e32 v144, v144
	v_exp_f32_e32 v151, v151
	v_add_f32_e32 v148, 1.0, v148
	v_add_f32_e32 v149, 1.0, v149
	v_add_f32_e32 v146, 1.0, v146
	v_add_f32_e32 v156, 1.0, v156
	v_add_f32_e32 v147, 1.0, v147
	v_add_f32_e32 v157, 1.0, v157
	v_add_f32_e32 v144, 1.0, v144
	v_rcp_f32_e32 v148, v148
	v_rcp_f32_e32 v149, v149
	v_add_f32_e32 v151, 1.0, v151
	v_rcp_f32_e32 v146, v146
	v_rcp_f32_e32 v156, v156
	v_rcp_f32_e32 v147, v147
	v_rcp_f32_e32 v157, v157
	v_rcp_f32_e32 v144, v144
	v_rcp_f32_e32 v151, v151
	v_cvt_pk_bf16_f32 v178, v144, v149
	v_cvt_pk_bf16_f32 v179, v146, v147
	v_cvt_pk_bf16_f32 v180, v148, v151
	v_cvt_pk_bf16_f32 v181, v156, v157
	global_store_dwordx4 v[152:153], v[178:181], off offset:256
	v_pk_add_f32 v[146:147], v[54:55], v[134:135]
	v_pk_add_f32 v[148:149], v[52:53], v[132:133]
	v_pk_add_f32 v[152:153], v[20:21], v[120:121]
	v_pk_add_f32 v[156:157], v[22:23], v[122:123]
	v_mul_f32_e32 v144, 0xbfb8aa3b, v148
	v_mul_f32_e32 v148, 0xbfb8aa3b, v152
	v_mul_f32_e32 v149, 0xbfb8aa3b, v149
	v_mul_f32_e32 v151, 0xbfb8aa3b, v153
	v_mul_f32_e32 v146, 0xbfb8aa3b, v146
	v_mul_f32_e32 v152, 0xbfb8aa3b, v156
	v_mul_f32_e32 v147, 0xbfb8aa3b, v147
	v_mul_f32_e32 v153, 0xbfb8aa3b, v157
	v_exp_f32_e32 v148, v148
	v_exp_f32_e32 v149, v149
	v_exp_f32_e32 v146, v146
	v_exp_f32_e32 v152, v152
	v_exp_f32_e32 v147, v147
	v_exp_f32_e32 v153, v153
	v_exp_f32_e32 v144, v144
	v_exp_f32_e32 v151, v151
	v_add_f32_e32 v148, 1.0, v148
	v_add_f32_e32 v149, 1.0, v149
	v_add_f32_e32 v146, 1.0, v146
	v_add_f32_e32 v152, 1.0, v152
	v_add_f32_e32 v147, 1.0, v147
	v_add_f32_e32 v153, 1.0, v153
	v_add_f32_e32 v144, 1.0, v144
	v_rcp_f32_e32 v148, v148
	v_rcp_f32_e32 v149, v149
	v_add_f32_e32 v151, 1.0, v151
	v_rcp_f32_e32 v146, v146
	v_rcp_f32_e32 v152, v152
	v_rcp_f32_e32 v147, v147
	v_rcp_f32_e32 v153, v153
	v_rcp_f32_e32 v144, v144
	v_rcp_f32_e32 v151, v151
	v_cvt_pk_bf16_f32 v178, v144, v149
	v_cvt_pk_bf16_f32 v179, v146, v147
	v_cvt_pk_bf16_f32 v180, v148, v151
	v_cvt_pk_bf16_f32 v181, v152, v153
	v_pk_add_f32 v[146:147], v[50:51], v[134:135]
	v_pk_add_f32 v[148:149], v[48:49], v[132:133]
	v_pk_add_f32 v[152:153], v[16:17], v[120:121]
	v_pk_add_f32 v[156:157], v[18:19], v[122:123]
	v_mul_f32_e32 v144, 0xbfb8aa3b, v148
	v_mul_f32_e32 v148, 0xbfb8aa3b, v152
	v_mul_f32_e32 v149, 0xbfb8aa3b, v149
	v_mul_f32_e32 v151, 0xbfb8aa3b, v153
	v_mul_f32_e32 v146, 0xbfb8aa3b, v146
	v_mul_f32_e32 v152, 0xbfb8aa3b, v156
	v_mul_f32_e32 v147, 0xbfb8aa3b, v147
	v_mul_f32_e32 v153, 0xbfb8aa3b, v157
	v_exp_f32_e32 v144, v144
	v_exp_f32_e32 v148, v148
	v_exp_f32_e32 v149, v149
	v_exp_f32_e32 v146, v146
	v_exp_f32_e32 v152, v152
	v_exp_f32_e32 v147, v147
	v_exp_f32_e32 v153, v153
	v_exp_f32_e32 v151, v151
	v_add_f32_e32 v144, 1.0, v144
	v_add_f32_e32 v148, 1.0, v148
	v_add_f32_e32 v149, 1.0, v149
	v_add_f32_e32 v146, 1.0, v146
	v_add_f32_e32 v152, 1.0, v152
	v_add_f32_e32 v147, 1.0, v147
	v_add_f32_e32 v153, 1.0, v153
	global_store_dwordx4 v[158:159], v[178:181], off offset:256
	v_rcp_f32_e32 v144, v144
	v_rcp_f32_e32 v148, v148
	v_rcp_f32_e32 v149, v149
	v_add_f32_e32 v151, 1.0, v151
	v_rcp_f32_e32 v146, v146
	v_rcp_f32_e32 v152, v152
	v_rcp_f32_e32 v147, v147
	v_rcp_f32_e32 v153, v153
	v_cvt_pk_bf16_f32 v156, v144, v149
	v_cvt_pk_bf16_f32 v157, v146, v147
	v_rcp_f32_e32 v151, v151
	s_nop 0
	v_cvt_pk_bf16_f32 v158, v148, v151
	v_cvt_pk_bf16_f32 v159, v152, v153
	global_store_dwordx4 v[160:161], v[156:159], off offset:256
	v_pk_add_f32 v[148:149], v[44:45], v[132:133]
	v_pk_add_f32 v[152:153], v[12:13], v[120:121]
	v_pk_add_f32 v[156:157], v[14:15], v[122:123]
	v_pk_add_f32 v[146:147], v[46:47], v[134:135]
	v_mul_f32_e32 v144, 0xbfb8aa3b, v148
	v_mul_f32_e32 v148, 0xbfb8aa3b, v152
	v_mul_f32_e32 v149, 0xbfb8aa3b, v149
	v_mul_f32_e32 v151, 0xbfb8aa3b, v153
	v_mul_f32_e32 v152, 0xbfb8aa3b, v156
	v_mul_f32_e32 v153, 0xbfb8aa3b, v157
	v_exp_f32_e32 v148, v148
	v_exp_f32_e32 v149, v149
	v_mul_f32_e32 v146, 0xbfb8aa3b, v146
	v_exp_f32_e32 v152, v152
	v_mul_f32_e32 v147, 0xbfb8aa3b, v147
	v_exp_f32_e32 v153, v153
	v_exp_f32_e32 v144, v144
	v_exp_f32_e32 v151, v151
	v_exp_f32_e32 v146, v146
	v_exp_f32_e32 v147, v147
	v_add_f32_e32 v148, 1.0, v148
	v_add_f32_e32 v149, 1.0, v149
	v_add_f32_e32 v152, 1.0, v152
	v_add_f32_e32 v153, 1.0, v153
	v_add_f32_e32 v144, 1.0, v144
	v_rcp_f32_e32 v148, v148
	v_rcp_f32_e32 v149, v149
	v_add_f32_e32 v151, 1.0, v151
	v_add_f32_e32 v146, 1.0, v146
	v_rcp_f32_e32 v152, v152
	v_add_f32_e32 v147, 1.0, v147
	v_rcp_f32_e32 v153, v153
	v_rcp_f32_e32 v144, v144
	v_rcp_f32_e32 v151, v151
	v_rcp_f32_e32 v146, v146
	v_rcp_f32_e32 v147, v147
	v_cvt_pk_bf16_f32 v156, v144, v149
	v_cvt_pk_bf16_f32 v157, v146, v147
	v_cvt_pk_bf16_f32 v158, v148, v151
	v_cvt_pk_bf16_f32 v159, v152, v153
	v_pk_add_f32 v[148:149], v[40:41], v[132:133]
	v_pk_add_f32 v[152:153], v[8:9], v[120:121]
	global_store_dwordx4 v[166:167], v[156:159], off offset:256
	v_pk_add_f32 v[146:147], v[42:43], v[134:135]
	v_mul_f32_e32 v144, 0xbfb8aa3b, v148
	v_mul_f32_e32 v148, 0xbfb8aa3b, v152
	v_pk_add_f32 v[156:157], v[10:11], v[122:123]
	v_mul_f32_e32 v149, 0xbfb8aa3b, v149
	v_exp_f32_e32 v148, v148
	v_exp_f32_e32 v149, v149
	v_mul_f32_e32 v151, 0xbfb8aa3b, v153
	v_mul_f32_e32 v146, 0xbfb8aa3b, v146
	v_mul_f32_e32 v152, 0xbfb8aa3b, v156
	v_mul_f32_e32 v147, 0xbfb8aa3b, v147
	v_mul_f32_e32 v153, 0xbfb8aa3b, v157
	v_exp_f32_e32 v144, v144
	v_exp_f32_e32 v151, v151
	v_exp_f32_e32 v146, v146
	v_exp_f32_e32 v152, v152
	v_exp_f32_e32 v147, v147
	v_exp_f32_e32 v153, v153
	v_add_f32_e32 v148, 1.0, v148
	v_add_f32_e32 v149, 1.0, v149
	v_add_f32_e32 v144, 1.0, v144
	v_rcp_f32_e32 v148, v148
	v_rcp_f32_e32 v149, v149
	v_add_f32_e32 v151, 1.0, v151
	v_add_f32_e32 v146, 1.0, v146
	v_add_f32_e32 v152, 1.0, v152
	v_add_f32_e32 v147, 1.0, v147
	v_add_f32_e32 v153, 1.0, v153
	v_rcp_f32_e32 v144, v144
	v_rcp_f32_e32 v151, v151
	v_rcp_f32_e32 v146, v146
	v_rcp_f32_e32 v152, v152
	v_rcp_f32_e32 v147, v147
	v_rcp_f32_e32 v153, v153
	v_cvt_pk_bf16_f32 v156, v144, v149
	v_cvt_pk_bf16_f32 v157, v146, v147
	v_cvt_pk_bf16_f32 v158, v148, v151
	v_pk_add_f32 v[148:149], v[36:37], v[132:133]
	v_cvt_pk_bf16_f32 v159, v152, v153
	v_pk_add_f32 v[152:153], v[4:5], v[120:121]
	v_mul_f32_e32 v144, 0xbfb8aa3b, v148
	v_pk_add_f32 v[120:121], v[0:1], v[120:121]
	v_exp_f32_e32 v144, v144
	v_mul_f32_e32 v149, 0xbfb8aa3b, v149
	v_pk_add_f32 v[132:133], v[32:33], v[132:133]
	v_mul_f32_e32 v120, 0xbfb8aa3b, v120
	v_exp_f32_e32 v149, v149
	v_exp_f32_e32 v120, v120
	v_mul_f32_e32 v133, 0xbfb8aa3b, v133
	v_exp_f32_e32 v133, v133
	v_add_f32_e32 v144, 1.0, v144
	global_store_dwordx4 v[164:165], v[156:159], off offset:256
	v_pk_add_f32 v[146:147], v[38:39], v[134:135]
	v_rcp_f32_e32 v144, v144
	v_pk_add_f32 v[156:157], v[6:7], v[122:123]
	v_add_f32_e32 v149, 1.0, v149
	v_pk_add_f32 v[134:135], v[34:35], v[134:135]
	v_add_f32_e32 v120, 1.0, v120
	v_mul_f32_e32 v121, 0xbfb8aa3b, v121
	v_mul_f32_e32 v148, 0xbfb8aa3b, v152
	v_rcp_f32_e32 v149, v149
	v_mul_f32_e32 v152, 0xbfb8aa3b, v156
	v_cvt_pk_bf16_f32 v156, v144, v149
	v_exp_f32_e32 v121, v121
	v_rcp_f32_e32 v144, v120
	v_add_f32_e32 v120, 1.0, v133
	v_mul_f32_e32 v133, 0xbfb8aa3b, v134
	v_exp_f32_e32 v133, v133
	v_pk_add_f32 v[122:123], v[2:3], v[122:123]
	v_add_f32_e32 v121, 1.0, v121
	v_mul_f32_e32 v122, 0xbfb8aa3b, v122
	v_exp_f32_e32 v122, v122
	v_rcp_f32_e32 v134, v121
	v_add_f32_e32 v121, 1.0, v133
	v_mul_f32_e32 v133, 0xbfb8aa3b, v135
	v_mul_f32_e32 v123, 0xbfb8aa3b, v123
	v_mul_f32_e32 v151, 0xbfb8aa3b, v153
	v_mul_f32_e32 v146, 0xbfb8aa3b, v146
	v_mul_f32_e32 v147, 0xbfb8aa3b, v147
	v_mul_f32_e32 v153, 0xbfb8aa3b, v157
	v_mul_f32_e32 v132, 0xbfb8aa3b, v132
	v_exp_f32_e32 v133, v133
	v_exp_f32_e32 v123, v123
	v_exp_f32_e32 v148, v148
	v_exp_f32_e32 v151, v151
	v_exp_f32_e32 v146, v146
	v_exp_f32_e32 v152, v152
	v_exp_f32_e32 v147, v147
	v_exp_f32_e32 v153, v153
	v_exp_f32_e32 v132, v132
	v_add_f32_e32 v122, 1.0, v122
	v_rcp_f32_e32 v135, v122
	v_add_f32_e32 v122, 1.0, v133
	v_add_f32_e32 v123, 1.0, v123
	v_add_f32_e32 v148, 1.0, v148
	v_add_f32_e32 v151, 1.0, v151
	v_add_f32_e32 v146, 1.0, v146
	v_add_f32_e32 v152, 1.0, v152
	v_add_f32_e32 v147, 1.0, v147
	v_add_f32_e32 v153, 1.0, v153
	v_add_f32_e32 v132, 1.0, v132
	v_rcp_f32_e32 v120, v120
	v_rcp_f32_e32 v121, v121
	v_rcp_f32_e32 v122, v122
	v_rcp_f32_e32 v123, v123
	v_rcp_f32_e32 v148, v148
	v_rcp_f32_e32 v151, v151
	v_rcp_f32_e32 v146, v146
	v_rcp_f32_e32 v152, v152
	v_rcp_f32_e32 v147, v147
	v_rcp_f32_e32 v153, v153
	v_cvt_pk_bf16_f32 v157, v146, v147
	v_cvt_pk_bf16_f32 v158, v148, v151
	v_cvt_pk_bf16_f32 v159, v152, v153
	global_store_dwordx4 v[162:163], v[156:159], off offset:256
	v_rcp_f32_e32 v132, v132
	s_nop 0
	v_cvt_pk_bf16_f32 v120, v132, v120
	v_cvt_pk_bf16_f32 v121, v121, v122
	v_cvt_pk_bf16_f32 v122, v144, v134
	v_cvt_pk_bf16_f32 v123, v135, v123
	global_store_dwordx4 v[154:155], v[120:123], off offset:256

.LBB0_686:
	s_or_b64 exec, exec, s[18:19]
	s_waitcnt lgkmcnt(0)
	v_cvt_f32_u32_sdwa v63, v66 dst_sel:DWORD dst_unused:UNUSED_PAD src0_sel:WORD_0
	v_cvt_f32_u32_sdwa v62, v0 dst_sel:DWORD dst_unused:UNUSED_PAD src0_sel:WORD_0
	s_xor_b64 s[0:1], s[0:1], -1
	v_rcp_iflag_f32_e32 v67, v63
	s_nop 0
	v_mul_f32_e32 v67, v62, v67
	v_trunc_f32_e32 v67, v67
	v_fma_f32 v62, -v67, v63, v62
	v_cvt_u32_f32_e32 v67, v67
	v_cmp_ge_f32_e64 vcc, |v62|, v63
	s_nop 1
	v_addc_co_u32_e32 v63, vcc, 0, v67, vcc
	v_mul_lo_u16_e32 v62, v63, v66
	v_sub_u16_e32 v66, v0, v62
	v_lshlrev_b32_e32 v0, 5, v66
	s_and_saveexec_b64 s[4:5], s[0:1]
	s_xor_b64 s[0:1], exec, s[4:5]
	v_lshlrev_b32_e32 v62, 6, v66
	v_and_b32_e32 v62, 0x3f00, v62
	v_and_b32_e32 v0, 0x60, v0
	v_or3_b32 v62, v0, v62, v65
	s_andn2_saveexec_b64 s[0:1], s[0:1]
	v_add_u32_e32 v62, v0, v65
	s_or_b64 exec, exec, s[0:1]
	v_add_u32_e32 v0, 0x400, v164
	ds_write2_b32 v164, v2, v3 offset1:66
	ds_write2_b32 v164, v4, v5 offset0:132 offset1:198
	ds_write2_b32 v0, v6, v7 offset0:8 offset1:74
	ds_write2_b32 v0, v8, v9 offset0:140 offset1:206
	v_add_u32_e32 v0, 0x800, v164
	ds_write2_b32 v0, v10, v11 offset0:16 offset1:82
	ds_write2_b32 v0, v12, v13 offset0:148 offset1:214
	v_add_u32_e32 v0, 0xc00, v164
	ds_write2_b32 v0, v14, v15 offset0:24 offset1:90
	ds_write2_b32 v0, v16, v17 offset0:156 offset1:222
	v_add_u32_e32 v0, 0x1000, v164
	ds_write2_b32 v0, v18, v19 offset0:32 offset1:98
	ds_write2_b32 v0, v20, v21 offset0:164 offset1:230
	v_add_u32_e32 v0, 0x1400, v164
	ds_write2_b32 v0, v22, v23 offset0:40 offset1:106
	ds_write2_b32 v0, v24, v25 offset0:172 offset1:238
	v_add_u32_e32 v0, 0x1800, v164
	ds_write2_b32 v0, v26, v27 offset0:48 offset1:114
	ds_write2_b32 v0, v28, v29 offset0:180 offset1:246
	v_add_u32_e32 v0, 0x1c00, v164
	ds_write2_b32 v0, v30, v31 offset0:56 offset1:122
	ds_write2_b32 v0, v32, v33 offset0:188 offset1:254
	s_waitcnt lgkmcnt(0)
	ds_read2_b32 v[66:67], v149 offset1:33
	s_waitcnt lgkmcnt(0)
	v_cvt_pk_bf16_f32 v66, v66, v67
	ds_read2_b32 v[68:69], v149 offset0:66 offset1:99
	s_waitcnt lgkmcnt(0)
	v_cvt_pk_bf16_f32 v67, v68, v69
	ds_read2_b32 v[68:69], v149 offset0:132 offset1:165
	v_lshlrev_b32_sdwa v0, v166, v63 dst_sel:DWORD dst_unused:UNUSED_PAD src0_sel:DWORD src1_sel:WORD_0
	s_waitcnt lgkmcnt(0)
	v_cvt_pk_bf16_f32 v68, v68, v69
	ds_read2_b32 v[70:71], v149 offset0:198 offset1:231
	v_add_u32_e32 v63, v62, v148
	s_waitcnt lgkmcnt(0)
	v_cvt_pk_bf16_f32 v69, v70, v71
	v_mad_u64_u32 v[70:71], s[0:1], v58, v63, 0
	v_lshl_add_u64 v[60:61], v[60:61], 0, v[0:1]
	v_mov_b32_e32 v0, v71
	v_mov_b32_e32 v103, v1
	v_mad_u64_u32 v[72:73], s[0:1], v59, v63, v[0:1]
	v_lshl_add_u64 v[60:61], v[60:61], 0, v[102:103]
	v_mov_b32_e32 v71, v72
	v_lshl_add_u64 v[70:71], v[70:71], 1, v[60:61]
	global_store_dwordx4 v[70:71], v[66:69], off
	ds_read2_b32 v[66:67], v149 offset0:8 offset1:41
	v_add_u32_e32 v63, v62, v150
	s_waitcnt lgkmcnt(0)
	v_cvt_pk_bf16_f32 v66, v66, v67
	ds_read2_b32 v[68:69], v149 offset0:74 offset1:107
	s_waitcnt lgkmcnt(0)
	v_cvt_pk_bf16_f32 v67, v68, v69
	ds_read2_b32 v[68:69], v149 offset0:140 offset1:173
	s_waitcnt lgkmcnt(0)
	v_cvt_pk_bf16_f32 v68, v68, v69
	ds_read2_b32 v[70:71], v149 offset0:206 offset1:239
	s_waitcnt lgkmcnt(0)
	v_cvt_pk_bf16_f32 v69, v70, v71
	v_mad_u64_u32 v[70:71], s[0:1], v58, v63, 0
	v_mov_b32_e32 v0, v71
	v_mad_u64_u32 v[72:73], s[0:1], v59, v63, v[0:1]
	v_mov_b32_e32 v71, v72
	v_lshl_add_u64 v[70:71], v[70:71], 1, v[60:61]
	global_store_dwordx4 v[70:71], v[66:69], off
	ds_read2_b32 v[66:67], v149 offset0:16 offset1:49
	v_add_u32_e32 v63, v62, v151
	s_waitcnt lgkmcnt(0)
	v_cvt_pk_bf16_f32 v66, v66, v67
	ds_read2_b32 v[68:69], v149 offset0:82 offset1:115
	s_waitcnt lgkmcnt(0)
	v_cvt_pk_bf16_f32 v67, v68, v69
	ds_read2_b32 v[68:69], v149 offset0:148 offset1:181
	s_waitcnt lgkmcnt(0)
	v_cvt_pk_bf16_f32 v68, v68, v69
	ds_read2_b32 v[70:71], v149 offset0:214 offset1:247
	s_waitcnt lgkmcnt(0)
	v_cvt_pk_bf16_f32 v69, v70, v71
	v_mad_u64_u32 v[70:71], s[0:1], v58, v63, 0
	v_mov_b32_e32 v0, v71
	v_mad_u64_u32 v[72:73], s[0:1], v59, v63, v[0:1]
	v_add_u32_e32 v65, v62, v152
	v_mov_b32_e32 v71, v72
	v_mad_u64_u32 v[62:63], s[0:1], v58, v65, 0
	v_lshl_add_u64 v[70:71], v[70:71], 1, v[60:61]
	v_mov_b32_e32 v0, v63
	global_store_dwordx4 v[70:71], v[66:69], off
	ds_read2_b32 v[66:67], v149 offset0:24 offset1:57
	v_mad_u64_u32 v[58:59], s[0:1], v59, v65, v[0:1]
	s_waitcnt lgkmcnt(0)
	v_cvt_pk_bf16_f32 v66, v66, v67
	ds_read2_b32 v[68:69], v149 offset0:90 offset1:123
	v_mov_b32_e32 v63, v58
	s_waitcnt lgkmcnt(0)
	v_cvt_pk_bf16_f32 v67, v68, v69
	ds_read2_b32 v[68:69], v149 offset0:156 offset1:189
	v_lshl_add_u64 v[58:59], v[62:63], 1, v[60:61]
	s_waitcnt lgkmcnt(0)
	v_cvt_pk_bf16_f32 v68, v68, v69
	ds_read2_b32 v[70:71], v149 offset0:222 offset1:255
	s_waitcnt lgkmcnt(0)
	v_cvt_pk_bf16_f32 v69, v70, v71
	global_store_dwordx4 v[58:59], v[66:69], off
	s_waitcnt lgkmcnt(0)

.Lp6_loop:
	s_waitcnt vmcnt(6)
	v_mov_b64_e32 v[28:29], v[80:81]
	v_mov_b64_e32 v[30:31], v[82:83]
	v_mov_b64_e32 v[34:35], v[86:87]
	v_mov_b64_e32 v[36:37], v[88:89]
	v_mov_b64_e32 v[42:43], v[94:95]
	v_mov_b32_e32 v26, v98
	v_mov_b64_e32 v[6:7], v[60:61]
	v_mov_b64_e32 v[8:9], v[62:63]
	v_mov_b64_e32 v[10:11], v[64:65]
	v_mov_b64_e32 v[12:13], v[66:67]
	s_min_i32 s0, s20, 0xffff
	s_ashr_i32 s0, s0, 3
	s_lshl_b32 s1, s0, 11
	v_add_u32_e32 v121, s1, v124
	v_lshlrev_b32_e32 v98, 1, v121
	v_add_u32_e32 v121, 0x2000000, v121
	global_load_dwordx2 v[80:81], v98, s[38:39]
	global_load_dwordx2 v[82:83], v98, s[18:19]
	global_load_dwordx2 v[86:87], v98, s[68:69]
	global_load_dwordx2 v[88:89], v98, s[56:57]
	global_load_dword v94, v121, s[38:39]
	global_load_dword v95, v121, s[18:19]
	s_add_i32 s20, s20, s22
	v_lshlrev_b32_e32 v44, 16, v28
	v_and_b32_e32 v45, 0xffff0000, v28
	v_lshlrev_b32_e32 v28, 16, v29
	v_and_b32_e32 v29, 0xffff0000, v29
	v_lshlrev_b32_e32 v46, 16, v30
	v_and_b32_e32 v47, 0xffff0000, v30
	v_lshlrev_b32_e32 v30, 16, v31
	v_and_b32_e32 v31, 0xffff0000, v31
	v_pk_add_f32 v[28:29], v[28:29], v[30:31]
	v_pk_add_f32 v[30:31], v[44:45], v[46:47]
	v_add_f32_e32 v0, v30, v31
	v_add_f32_e32 v0, v28, v0
	v_add_f32_e32 v0, v29, v0
	s_nop 1
	v_add_f32_dpp v0, v0, v0 quad_perm:[1,0,3,2] row_mask:0xf bank_mask:0xf bound_ctrl:1
	s_nop 0
	v_add_f32_dpp v0, v0, v0 quad_perm:[2,3,0,1] row_mask:0xf bank_mask:0xf bound_ctrl:1
	s_nop 1
	v_add_f32_dpp v0, v0, v0 row_half_mirror row_mask:0xf bank_mask:0xf bound_ctrl:1
	s_nop 1
	v_add_f32_dpp v0, v0, v0 row_ror:8 row_mask:0xf bank_mask:0xf bound_ctrl:1
	v_fmamk_f32 v31, v0, 0xbc800000, v31
	v_fmac_f32_e32 v30, 0xbc800000, v0
	v_fmamk_f32 v29, v0, 0xbc800000, v29
	v_fmac_f32_e32 v28, 0xbc800000, v0
	v_pk_mul_f32 v[18:19], v[30:31], v[30:31]
	v_pk_mul_f32 v[14:15], v[28:29], v[28:29]
	v_add_f32_e32 v5, v18, v19
	v_add_f32_e32 v5, v14, v5
	v_add_f32_e32 v5, v15, v5
	v_add_f32_e32 v0, v42, v43
	v_lshlrev_b32_e32 v50, 16, v34
	v_add_f32_dpp v5, v5, v5 quad_perm:[1,0,3,2] row_mask:0xf bank_mask:0xf bound_ctrl:1
	v_add_f32_dpp v0, v0, v0 quad_perm:[1,0,3,2] row_mask:0xf bank_mask:0xf bound_ctrl:1
	v_and_b32_e32 v51, 0xffff0000, v34
	v_add_f32_dpp v5, v5, v5 quad_perm:[2,3,0,1] row_mask:0xf bank_mask:0xf bound_ctrl:1
	v_add_f32_dpp v0, v0, v0 quad_perm:[2,3,0,1] row_mask:0xf bank_mask:0xf bound_ctrl:1
	v_lshlrev_b32_e32 v34, 16, v35
	v_add_f32_dpp v5, v5, v5 row_half_mirror row_mask:0xf bank_mask:0xf bound_ctrl:1
	v_add_f32_dpp v0, v0, v0 row_half_mirror row_mask:0xf bank_mask:0xf bound_ctrl:1
	v_and_b32_e32 v35, 0xffff0000, v35
	v_add_f32_dpp v5, v5, v5 row_ror:8 row_mask:0xf bank_mask:0xf bound_ctrl:1
	v_fmamk_f32 v5, v5, 0x3c800000, v3
	v_mul_f32_e32 v14, 0x4f800000, v5
	v_cmp_gt_f32_e32 vcc, s24, v5
	v_add_f32_dpp v0, v0, v0 row_ror:8 row_mask:0xf bank_mask:0xf bound_ctrl:1
	v_lshlrev_b32_e32 v52, 16, v36
	v_cndmask_b32_e32 v5, v5, v14, vcc
	v_sqrt_f32_e32 v14, v5
	v_and_b32_e32 v53, 0xffff0000, v36
	v_lshlrev_b32_e32 v36, 16, v37
	v_and_b32_e32 v37, 0xffff0000, v37
	v_add_u32_e32 v15, -1, v14
	v_add_u32_e32 v16, 1, v14
	v_fma_f32 v17, -v15, v14, v5
	v_fma_f32 v18, -v16, v14, v5
	v_cmp_ge_f32_e64 s[6:7], 0, v17
	s_nop 1
	v_cndmask_b32_e64 v14, v14, v15, s[6:7]
	v_cmp_lt_f32_e64 s[6:7], 0, v18
	s_nop 1
	v_cndmask_b32_e64 v14, v14, v16, s[6:7]
	v_mul_f32_e32 v15, 0x37800000, v14
	v_cndmask_b32_e32 v14, v14, v15, vcc
	v_cmp_class_f32_e32 vcc, v5, v4
	s_nop 1
	v_cndmask_b32_e32 v5, v14, v5, vcc
	v_div_scale_f32 v14, s[0:1], v5, v5, 1.0
	v_rcp_f32_e32 v16, v14
	v_div_scale_f32 v15, vcc, 1.0, v5, 1.0
	v_fma_f32 v17, -v14, v16, 1.0
	v_fmac_f32_e32 v16, v17, v16
	v_mul_f32_e32 v17, v15, v16
	v_fma_f32 v18, -v14, v17, v15
	v_fmac_f32_e32 v17, v18, v16
	v_fma_f32 v14, -v14, v17, v15
	v_div_fmas_f32 v14, v14, v16, v17
	v_div_fixup_f32 v14, v14, v5, 1.0
	v_pk_mul_f32 v[16:17], v[30:31], v[14:15] op_sel_hi:[1,0]
	v_pk_mul_f32 v[14:15], v[28:29], v[14:15] op_sel_hi:[1,0]
	v_pk_fma_f32 v[6:7], v[6:7], v[16:17], v[10:11]
	v_pk_fma_f32 v[8:9], v[8:9], v[14:15], v[12:13]
	v_pk_fma_f32 v[6:7], v[0:1], v[50:51], v[6:7] op_sel_hi:[0,1,1]
	v_pk_fma_f32 v[8:9], v[0:1], v[34:35], v[8:9] op_sel_hi:[0,1,1]
	v_pk_mul_f32 v[6:7], v[6:7], v[52:53]
	v_pk_mul_f32 v[8:9], v[8:9], v[36:37]
	v_cvt_pk_bf16_f32 v6, v6, v7
	v_cvt_pk_bf16_f32 v7, v8, v9
	global_store_dwordx2 v26, v[6:7], s[8:9]
	s_waitcnt vmcnt(6)
	v_mov_b64_e32 v[28:29], v[100:101]
	v_mov_b64_e32 v[30:31], v[102:103]
	v_mov_b64_e32 v[34:35], v[106:107]
	v_mov_b64_e32 v[36:37], v[108:109]
	v_mov_b64_e32 v[42:43], v[114:115]
	v_mov_b32_e32 v26, v118
	v_mov_b64_e32 v[6:7], v[60:61]
	v_mov_b64_e32 v[8:9], v[62:63]
	v_mov_b64_e32 v[10:11], v[64:65]
	v_mov_b64_e32 v[12:13], v[66:67]
	s_min_i32 s0, s20, 0xffff
	s_ashr_i32 s0, s0, 3
	s_lshl_b32 s1, s0, 11
	v_add_u32_e32 v121, s1, v124
	v_lshlrev_b32_e32 v118, 1, v121
	v_add_u32_e32 v121, 0x2000000, v121
	global_load_dwordx2 v[100:101], v118, s[38:39]
	global_load_dwordx2 v[102:103], v118, s[18:19]
	global_load_dwordx2 v[106:107], v118, s[68:69]
	global_load_dwordx2 v[108:109], v118, s[56:57]
	global_load_dword v114, v121, s[38:39]
	global_load_dword v115, v121, s[18:19]
	s_add_i32 s20, s20, s22
	v_lshlrev_b32_e32 v44, 16, v28
	v_and_b32_e32 v45, 0xffff0000, v28
	v_lshlrev_b32_e32 v28, 16, v29
	v_and_b32_e32 v29, 0xffff0000, v29
	v_lshlrev_b32_e32 v46, 16, v30
	v_and_b32_e32 v47, 0xffff0000, v30
	v_lshlrev_b32_e32 v30, 16, v31
	v_and_b32_e32 v31, 0xffff0000, v31
	v_pk_add_f32 v[28:29], v[28:29], v[30:31]
	v_pk_add_f32 v[30:31], v[44:45], v[46:47]
	v_add_f32_e32 v0, v30, v31
	v_add_f32_e32 v0, v28, v0
	v_add_f32_e32 v0, v29, v0
	s_nop 1
	v_add_f32_dpp v0, v0, v0 quad_perm:[1,0,3,2] row_mask:0xf bank_mask:0xf bound_ctrl:1
	s_nop 0
	v_add_f32_dpp v0, v0, v0 quad_perm:[2,3,0,1] row_mask:0xf bank_mask:0xf bound_ctrl:1
	s_nop 1
	v_add_f32_dpp v0, v0, v0 row_half_mirror row_mask:0xf bank_mask:0xf bound_ctrl:1
	s_nop 1
	v_add_f32_dpp v0, v0, v0 row_ror:8 row_mask:0xf bank_mask:0xf bound_ctrl:1
	v_fmamk_f32 v31, v0, 0xbc800000, v31
	v_fmac_f32_e32 v30, 0xbc800000, v0
	v_fmamk_f32 v29, v0, 0xbc800000, v29
	v_fmac_f32_e32 v28, 0xbc800000, v0
	v_pk_mul_f32 v[18:19], v[30:31], v[30:31]
	v_pk_mul_f32 v[14:15], v[28:29], v[28:29]
	v_add_f32_e32 v5, v18, v19
	v_add_f32_e32 v5, v14, v5
	v_add_f32_e32 v5, v15, v5
	v_add_f32_e32 v0, v42, v43
	v_lshlrev_b32_e32 v50, 16, v34
	v_add_f32_dpp v5, v5, v5 quad_perm:[1,0,3,2] row_mask:0xf bank_mask:0xf bound_ctrl:1
	v_add_f32_dpp v0, v0, v0 quad_perm:[1,0,3,2] row_mask:0xf bank_mask:0xf bound_ctrl:1
	v_and_b32_e32 v51, 0xffff0000, v34
	v_add_f32_dpp v5, v5, v5 quad_perm:[2,3,0,1] row_mask:0xf bank_mask:0xf bound_ctrl:1
	v_add_f32_dpp v0, v0, v0 quad_perm:[2,3,0,1] row_mask:0xf bank_mask:0xf bound_ctrl:1
	v_lshlrev_b32_e32 v34, 16, v35
	v_add_f32_dpp v5, v5, v5 row_half_mirror row_mask:0xf bank_mask:0xf bound_ctrl:1
	v_add_f32_dpp v0, v0, v0 row_half_mirror row_mask:0xf bank_mask:0xf bound_ctrl:1
	v_and_b32_e32 v35, 0xffff0000, v35
	v_add_f32_dpp v5, v5, v5 row_ror:8 row_mask:0xf bank_mask:0xf bound_ctrl:1
	v_fmamk_f32 v5, v5, 0x3c800000, v3
	v_mul_f32_e32 v14, 0x4f800000, v5
	v_cmp_gt_f32_e32 vcc, s24, v5
	v_add_f32_dpp v0, v0, v0 row_ror:8 row_mask:0xf bank_mask:0xf bound_ctrl:1
	v_lshlrev_b32_e32 v52, 16, v36
	v_cndmask_b32_e32 v5, v5, v14, vcc
	v_sqrt_f32_e32 v14, v5
	v_and_b32_e32 v53, 0xffff0000, v36
	v_lshlrev_b32_e32 v36, 16, v37
	v_and_b32_e32 v37, 0xffff0000, v37
	v_add_u32_e32 v15, -1, v14
	v_add_u32_e32 v16, 1, v14
	v_fma_f32 v17, -v15, v14, v5
	v_fma_f32 v18, -v16, v14, v5
	v_cmp_ge_f32_e64 s[6:7], 0, v17
	s_nop 1
	v_cndmask_b32_e64 v14, v14, v15, s[6:7]
	v_cmp_lt_f32_e64 s[6:7], 0, v18
	s_nop 1
	v_cndmask_b32_e64 v14, v14, v16, s[6:7]
	v_mul_f32_e32 v15, 0x37800000, v14
	v_cndmask_b32_e32 v14, v14, v15, vcc
	v_cmp_class_f32_e32 vcc, v5, v4
	s_nop 1
	v_cndmask_b32_e32 v5, v14, v5, vcc
	v_div_scale_f32 v14, s[0:1], v5, v5, 1.0
	v_rcp_f32_e32 v16, v14
	v_div_scale_f32 v15, vcc, 1.0, v5, 1.0
	v_fma_f32 v17, -v14, v16, 1.0
	v_fmac_f32_e32 v16, v17, v16
	v_mul_f32_e32 v17, v15, v16
	v_fma_f32 v18, -v14, v17, v15
	v_fmac_f32_e32 v17, v18, v16
	v_fma_f32 v14, -v14, v17, v15
	v_div_fmas_f32 v14, v14, v16, v17
	v_div_fixup_f32 v14, v14, v5, 1.0
	v_pk_mul_f32 v[16:17], v[30:31], v[14:15] op_sel_hi:[1,0]
	v_pk_mul_f32 v[14:15], v[28:29], v[14:15] op_sel_hi:[1,0]
	v_pk_fma_f32 v[6:7], v[6:7], v[16:17], v[10:11]
	v_pk_fma_f32 v[8:9], v[8:9], v[14:15], v[12:13]
	v_pk_fma_f32 v[6:7], v[0:1], v[50:51], v[6:7] op_sel_hi:[0,1,1]
	v_pk_fma_f32 v[8:9], v[0:1], v[34:35], v[8:9] op_sel_hi:[0,1,1]
	v_pk_mul_f32 v[6:7], v[6:7], v[52:53]
	v_pk_mul_f32 v[8:9], v[8:9], v[36:37]
	v_cvt_pk_bf16_f32 v6, v6, v7
	v_cvt_pk_bf16_f32 v7, v8, v9
	global_store_dwordx2 v26, v[6:7], s[8:9]
	s_sub_u32 s4, s4, 1
	s_cmp_lg_u32 s4, 0
	s_cbranch_scc1 .Lp6_loop

.LBB0_911:
	v_add_co_u32_e32 v4, vcc, 0xfffff000, v110
	s_add_i32 s1, s22, s20
	s_nop 0
	v_addc_co_u32_e32 v5, vcc, -1, v111, vcc
	s_cmpk_lt_i32 s1, 0x2000
	global_load_dwordx4 v[32:35], v[110:111], off offset:-4096
	global_load_dwordx4 v[24:27], v[110:111], off offset:-3072
	global_load_dwordx4 v[16:19], v[110:111], off offset:-2048
	global_load_dwordx4 v[8:11], v[110:111], off offset:-1024
	global_load_dwordx4 v[0:3], v[110:111], off
	global_load_dwordx4 v[56:59], v[4:5], off offset:-3072
	global_load_dwordx4 v[48:51], v[4:5], off offset:-2048
	global_load_dwordx4 v[40:43], v[4:5], off offset:-1024
	s_cselect_b64 s[18:19], -1, 0
	s_and_b64 s[4:5], s[18:19], exec
	s_cselect_b32 s4, s1, s20
	s_ashr_i32 s5, s4, 31
	s_lshl_b64 s[4:5], s[4:5], 13
	v_lshl_add_u64 v[4:5], v[66:67], 0, s[4:5]
	global_load_dwordx4 v[60:63], v[4:5], off
	global_load_dwordx4 v[52:55], v[4:5], off offset:1024
	global_load_dwordx4 v[44:47], v[4:5], off offset:2048
	global_load_dwordx4 v[36:39], v[4:5], off offset:3072
	v_add_co_u32_e32 v4, vcc, s21, v4
	s_cmpk_gt_i32 s1, 0x1fff
	s_nop 0
	v_addc_co_u32_e32 v5, vcc, 0, v5, vcc
	global_load_dwordx4 v[28:31], v[4:5], off
	global_load_dwordx4 v[20:23], v[4:5], off offset:1024
	global_load_dwordx4 v[12:15], v[4:5], off offset:2048
	s_nop 0
	global_load_dwordx4 v[4:7], v[4:5], off offset:3072
	s_waitcnt vmcnt(15)
	v_mul_f32_e32 v124, v33, v33
	s_waitcnt vmcnt(14)
	v_mul_f32_e32 v125, v25, v25
	v_fmac_f32_e32 v124, v32, v32
	s_waitcnt vmcnt(10)
	v_mul_f32_e32 v127, v57, v57
	s_waitcnt vmcnt(9)
	v_mul_f32_e32 v128, v49, v49
	s_waitcnt vmcnt(8)
	v_mul_f32_e32 v129, v41, v41
	v_fmac_f32_e32 v127, v56, v56
	v_fmac_f32_e32 v128, v48, v48
	v_fmac_f32_e32 v129, v40, v40
	v_fmac_f32_e32 v127, v58, v58
	v_fmac_f32_e32 v128, v50, v50
	v_fmac_f32_e32 v129, v42, v42
	v_fmac_f32_e32 v127, v59, v59
	v_fmac_f32_e32 v128, v51, v51
	v_fmac_f32_e32 v129, v43, v43
	v_add_f32_e32 v127, v127, v128
	v_mul_f32_e32 v126, v17, v17
	v_fmac_f32_e32 v125, v24, v24
	v_fmac_f32_e32 v124, v34, v34
	v_add_f32_e32 v127, v127, v129
	s_waitcnt vmcnt(7)
	v_mul_f32_e32 v128, v61, v61
	s_waitcnt vmcnt(6)
	v_mul_f32_e32 v129, v53, v53
	v_mov_b32_e32 v114, v9
	v_mov_b32_e32 v115, v1
	v_fmac_f32_e32 v126, v16, v16
	v_fmac_f32_e32 v125, v26, v26
	v_fmac_f32_e32 v124, v35, v35
	s_waitcnt vmcnt(5)
	v_mul_f32_e32 v130, v45, v45
	v_fmac_f32_e32 v128, v60, v60
	v_fmac_f32_e32 v129, v52, v52
	v_mov_b32_e32 v112, v8
	v_mov_b32_e32 v113, v0
	v_pk_mul_f32 v[114:115], v[114:115], v[114:115]
	v_fmac_f32_e32 v126, v18, v18
	v_fmac_f32_e32 v125, v27, v27
	v_add_f32_e32 v124, v127, v124
	s_waitcnt vmcnt(4)
	v_mul_f32_e32 v127, v37, v37
	v_fmac_f32_e32 v130, v44, v44
	v_fmac_f32_e32 v128, v62, v62
	v_fmac_f32_e32 v129, v54, v54
	v_fmac_f32_e32 v126, v19, v19
	v_fmac_f32_e32 v127, v36, v36
	v_add_f32_e32 v124, v124, v125
	v_fmac_f32_e32 v130, v46, v46
	s_waitcnt vmcnt(3)
	v_mul_f32_e32 v125, v29, v29
	v_fmac_f32_e32 v128, v63, v63
	v_fmac_f32_e32 v129, v55, v55
	v_pk_fma_f32 v[112:113], v[112:113], v[112:113], v[114:115]
	v_mov_b32_e32 v114, v10
	v_mov_b32_e32 v115, v2
	v_fmac_f32_e32 v127, v38, v38
	v_add_f32_e32 v124, v124, v126
	s_waitcnt vmcnt(2)
	v_mul_f32_e32 v126, v21, v21
	v_fmac_f32_e32 v130, v47, v47
	v_fmac_f32_e32 v125, v28, v28
	v_add_f32_e32 v128, v128, v129
	v_pk_fma_f32 v[112:113], v[114:115], v[114:115], v[112:113]
	v_mov_b32_e32 v114, v11
	v_mov_b32_e32 v115, v3
	v_fmac_f32_e32 v127, v39, v39
	v_fmac_f32_e32 v126, v20, v20
	v_fmac_f32_e32 v125, v30, v30
	v_add_f32_e32 v128, v128, v130
	v_pk_fma_f32 v[112:113], v[114:115], v[114:115], v[112:113]
	v_fmac_f32_e32 v126, v22, v22
	v_fmac_f32_e32 v125, v31, v31
	v_add_f32_e32 v127, v128, v127
	v_add_f32_e32 v112, v124, v112
	v_fmac_f32_e32 v126, v23, v23
	v_add_f32_e32 v125, v127, v125
	v_add_f32_e32 v124, v112, v113
	v_add_f32_e32 v125, v125, v126
	ds_bpermute_b32 v126, v116, v124
	s_waitcnt vmcnt(1)
	v_mov_b32_e32 v114, v13
	s_waitcnt vmcnt(0)
	v_mov_b32_e32 v115, v5
	v_mov_b32_e32 v112, v12
	v_mov_b32_e32 v113, v4
	s_waitcnt lgkmcnt(0)
	v_add_f32_e32 v124, v124, v126
	ds_bpermute_b32 v126, v117, v124
	v_pk_mul_f32 v[114:115], v[114:115], v[114:115]
	v_mov_b64_e32 v[128:129], v[150:151]
	v_mov_b64_e32 v[130:131], v[152:153]
	v_pk_fma_f32 v[112:113], v[112:113], v[112:113], v[114:115]
	v_mov_b32_e32 v114, v14
	v_mov_b32_e32 v115, v6
	v_pk_fma_f32 v[112:113], v[114:115], v[114:115], v[112:113]
	v_mov_b32_e32 v114, v15
	v_mov_b32_e32 v115, v7
	v_pk_fma_f32 v[112:113], v[114:115], v[114:115], v[112:113]
	s_waitcnt lgkmcnt(0)
	v_add_f32_e32 v114, v124, v126
	v_add_f32_e32 v112, v125, v112
	v_mov_b64_e32 v[124:125], v[154:155]
	v_mov_b64_e32 v[126:127], v[156:157]
	v_mov_b64_e32 v[132:133], v[158:159]
	v_mov_b64_e32 v[134:135], v[160:161]
	ds_bpermute_b32 v115, v118, v114
	v_add_f32_e32 v112, v112, v113
	ds_bpermute_b32 v113, v116, v112
	s_waitcnt lgkmcnt(0)
	v_add_f32_e32 v114, v114, v115
	ds_bpermute_b32 v115, v119, v114
	v_add_f32_e32 v112, v112, v113
	ds_bpermute_b32 v113, v117, v112
	s_waitcnt lgkmcnt(0)
	v_add_f32_e32 v114, v114, v115
	ds_bpermute_b32 v115, v120, v114
	v_add_f32_e32 v112, v112, v113
	ds_bpermute_b32 v113, v118, v112
	s_waitcnt lgkmcnt(0)
	v_add_f32_e32 v114, v114, v115
	ds_bpermute_b32 v115, v121, v114
	v_add_f32_e32 v112, v112, v113
	ds_bpermute_b32 v113, v119, v112
	s_waitcnt lgkmcnt(0)
	v_add_f32_e32 v114, v114, v115
	v_fmamk_f32 v114, v114, 0x3a000000, v122
	v_mul_f32_e32 v115, 0x4f800000, v114
	v_cmp_gt_f32_e32 vcc, s0, v114
	v_add_f32_e32 v112, v112, v113
	ds_bpermute_b32 v113, v120, v112
	v_cndmask_b32_e32 v114, v114, v115, vcc
	v_sqrt_f32_e32 v115, v114
	s_waitcnt lgkmcnt(0)
	v_add_f32_e32 v112, v112, v113
	v_add_u32_e32 v136, -1, v115
	v_fma_f32 v137, -v136, v115, v114
	v_cmp_ge_f32_e64 s[6:7], 0, v137
	v_add_u32_e32 v137, 1, v115
	ds_bpermute_b32 v113, v121, v112
	v_cndmask_b32_e64 v136, v115, v136, s[6:7]
	v_fma_f32 v115, -v137, v115, v114
	v_cmp_lt_f32_e64 s[6:7], 0, v115
	s_waitcnt lgkmcnt(0)
	v_add_f32_e32 v112, v112, v113
	v_cndmask_b32_e64 v115, v136, v137, s[6:7]
	v_mul_f32_e32 v136, 0x37800000, v115
	v_cndmask_b32_e32 v115, v115, v136, vcc
	v_cmp_class_f32_e32 vcc, v114, v123
	v_fmamk_f32 v112, v112, 0x3a000000, v122
	v_mul_f32_e32 v138, 0x4f800000, v112
	v_cndmask_b32_e32 v114, v115, v114, vcc
	v_div_scale_f32 v115, s[4:5], v114, v114, 1.0
	v_rcp_f32_e32 v136, v115
	v_cmp_gt_f32_e64 s[6:7], s0, v112
	v_fma_f32 v113, -v115, v136, 1.0
	s_nop 0
	v_cndmask_b32_e64 v112, v112, v138, s[6:7]
	v_fmac_f32_e32 v136, v113, v136
	v_div_scale_f32 v113, vcc, 1.0, v114, 1.0
	v_sqrt_f32_e32 v138, v112
	v_mul_f32_e32 v137, v113, v136
	v_fma_f32 v139, -v115, v137, v113
	v_fmac_f32_e32 v137, v139, v136
	v_fma_f32 v113, -v115, v137, v113
	v_add_u32_e32 v115, -1, v138
	v_fma_f32 v139, -v115, v138, v112
	v_cmp_ge_f32_e64 s[8:9], 0, v139
	v_add_u32_e32 v139, 1, v138
	v_div_fmas_f32 v113, v113, v136, v137
	v_cndmask_b32_e64 v115, v138, v115, s[8:9]
	v_fma_f32 v138, -v139, v138, v112
	v_cmp_lt_f32_e64 s[8:9], 0, v138
	v_div_fixup_f32 v114, v113, v114, 1.0
	v_pk_add_f32 v[126:127], v[126:127], 1.0 op_sel_hi:[1,0]
	v_cndmask_b32_e64 v115, v115, v139, s[8:9]
	v_mul_f32_e32 v138, 0x37800000, v115
	v_cndmask_b32_e64 v115, v115, v138, s[6:7]
	v_cmp_class_f32_e64 s[6:7], v112, v123
	v_pk_add_f32 v[124:125], v[124:125], 1.0 op_sel_hi:[1,0]
	v_pk_mul_f32 v[126:127], v[130:131], v[126:127]
	v_cndmask_b32_e64 v112, v115, v112, s[6:7]
	v_div_scale_f32 v115, s[4:5], v112, v112, 1.0
	v_rcp_f32_e32 v138, v115
	v_pk_mul_f32 v[124:125], v[128:129], v[124:125]
	v_pk_mul_f32 v[56:57], v[114:115], v[56:57] op_sel_hi:[0,1]
	v_pk_mul_f32 v[58:59], v[114:115], v[58:59] op_sel_hi:[0,1]
	v_fma_f32 v113, -v115, v138, 1.0
	v_fmac_f32_e32 v138, v113, v138
	v_div_scale_f32 v113, vcc, 1.0, v112, 1.0
	v_mul_f32_e32 v136, v113, v138
	v_fma_f32 v137, -v115, v136, v113
	v_fmac_f32_e32 v136, v137, v138
	v_fma_f32 v113, -v115, v136, v113
	v_div_fmas_f32 v113, v113, v138, v136
	v_div_fixup_f32 v112, v113, v112, 1.0
	v_pk_fma_f32 v[58:59], v[126:127], v[58:59], v[134:135]
	v_pk_fma_f32 v[56:57], v[124:125], v[56:57], v[132:133]
	v_pk_mul_f32 v[60:61], v[112:113], v[60:61] op_sel_hi:[0,1]
	v_pk_mul_f32 v[62:63], v[112:113], v[62:63] op_sel_hi:[0,1]
	v_pk_fma_f32 v[60:61], v[124:125], v[60:61], v[132:133]
	v_cvt_pk_bf16_f32 v56, v56, v57
	v_cvt_pk_bf16_f32 v57, v58, v59
	v_lshl_add_u64 v[58:59], s[14:15], 0, v[64:65]
	v_pk_fma_f32 v[62:63], v[126:127], v[62:63], v[134:135]
	v_cvt_pk_bf16_f32 v60, v60, v61
	v_cvt_pk_bf16_f32 v61, v62, v63
	global_store_dwordx2 v[58:59], v[56:57], off offset:-2048
	v_lshl_add_u64 v[56:57], s[10:11], 0, v[64:65]
	s_cbranch_scc1 .LBB0_913
	v_add_co_u32_e32 v62, vcc, 0x7200000, v56
	s_nop 1
	v_addc_co_u32_e32 v63, vcc, 0, v57, vcc
	global_store_dwordx2 v[62:63], v[60:61], off
.LBB0_913:
	v_mov_b64_e32 v[124:125], v[162:163]
	v_mov_b64_e32 v[126:127], v[164:165]
	v_mov_b64_e32 v[128:129], v[166:167]
	v_mov_b64_e32 v[130:131], v[168:169]
	v_mov_b64_e32 v[132:133], v[170:171]
	v_mov_b64_e32 v[134:135], v[172:173]
	v_mov_b32_e32 v115, v114
	v_mov_b32_e32 v113, v112
	v_mov_b32_e32 v60, v114
	v_mov_b32_e32 v61, v114
	v_mov_b32_e32 v62, v112
	v_mov_b32_e32 v63, v112
	v_cndmask_b32_e64 v136, 0, 1, s[18:19]
	v_pk_mul_f32 v[48:49], v[114:115], v[48:49]
	v_pk_mul_f32 v[50:51], v[60:61], v[50:51]
	v_pk_mul_f32 v[54:55], v[62:63], v[54:55]
	v_pk_mul_f32 v[52:53], v[112:113], v[52:53]
	v_cmp_ne_u32_e64 s[6:7], 1, v136
	s_andn2_b64 vcc, exec, s[18:19]
	v_pk_add_f32 v[124:125], v[124:125], 1.0 op_sel_hi:[1,0]
	v_pk_add_f32 v[126:127], v[126:127], 1.0 op_sel_hi:[1,0]
	s_waitcnt lgkmcnt(0)
	v_pk_mul_f32 v[124:125], v[128:129], v[124:125]
	v_pk_mul_f32 v[126:127], v[130:131], v[126:127]
	v_pk_fma_f32 v[48:49], v[124:125], v[48:49], v[132:133]
	v_pk_fma_f32 v[50:51], v[126:127], v[50:51], v[134:135]
	v_pk_fma_f32 v[54:55], v[126:127], v[54:55], v[134:135]
	v_pk_fma_f32 v[52:53], v[124:125], v[52:53], v[132:133]
	v_cvt_pk_bf16_f32 v124, v48, v49
	v_cvt_pk_bf16_f32 v125, v50, v51
	v_cvt_pk_bf16_f32 v48, v52, v53
	v_cvt_pk_bf16_f32 v49, v54, v55
	global_store_dwordx2 v[58:59], v[124:125], off offset:-1536
	s_cbranch_vccnz .LBB0_915
	v_add_co_u32_e32 v50, vcc, 0x7200000, v56
	s_nop 1
	v_addc_co_u32_e32 v51, vcc, 0, v57, vcc
	global_store_dwordx2 v[50:51], v[48:49], off offset:512
.LBB0_915:
	v_mov_b64_e32 v[48:49], v[174:175]
	v_mov_b64_e32 v[50:51], v[176:177]
	s_nop 0
	v_mov_b64_e32 v[52:53], v[178:179]
	v_mov_b64_e32 v[54:55], v[180:181]
	v_mov_b64_e32 v[124:125], v[182:183]
	v_mov_b64_e32 v[126:127], v[184:185]
	v_pk_mul_f32 v[40:41], v[114:115], v[40:41]
	v_pk_mul_f32 v[42:43], v[60:61], v[42:43]
	v_pk_mul_f32 v[46:47], v[62:63], v[46:47]
	v_pk_mul_f32 v[44:45], v[112:113], v[44:45]
	s_and_b64 vcc, exec, s[6:7]
	v_pk_add_f32 v[48:49], v[48:49], 1.0 op_sel_hi:[1,0]
	v_pk_add_f32 v[50:51], v[50:51], 1.0 op_sel_hi:[1,0]
	s_waitcnt lgkmcnt(0)
	v_pk_mul_f32 v[48:49], v[52:53], v[48:49]
	v_pk_mul_f32 v[50:51], v[54:55], v[50:51]
	v_pk_fma_f32 v[40:41], v[48:49], v[40:41], v[124:125]
	v_pk_fma_f32 v[42:43], v[50:51], v[42:43], v[126:127]
	v_pk_fma_f32 v[46:47], v[50:51], v[46:47], v[126:127]
	v_pk_fma_f32 v[44:45], v[48:49], v[44:45], v[124:125]
	v_cvt_pk_bf16_f32 v48, v40, v41
	v_cvt_pk_bf16_f32 v49, v42, v43
	v_cvt_pk_bf16_f32 v40, v44, v45
	v_cvt_pk_bf16_f32 v41, v46, v47
	global_store_dwordx2 v[58:59], v[48:49], off offset:-1024
	s_cbranch_vccnz .LBB0_917
	v_add_co_u32_e32 v42, vcc, 0x7200000, v56
	s_nop 1
	v_addc_co_u32_e32 v43, vcc, 0, v57, vcc
	global_store_dwordx2 v[42:43], v[40:41], off offset:1024
.LBB0_917:
	v_mov_b64_e32 v[42:43], v[186:187]
	v_mov_b64_e32 v[44:45], v[188:189]
	s_nop 0
	v_mov_b64_e32 v[46:47], v[190:191]
	v_mov_b64_e32 v[48:49], v[192:193]
	v_mov_b64_e32 v[50:51], v[194:195]
	v_mov_b64_e32 v[52:53], v[196:197]
	v_mov_b32_e32 v40, v114
	v_mov_b32_e32 v41, v114
	v_pk_mul_f32 v[54:55], v[114:115], v[32:33]
	v_mov_b32_e32 v32, v112
	v_mov_b32_e32 v33, v112
	v_pk_mul_f32 v[34:35], v[40:41], v[34:35]
	v_pk_mul_f32 v[36:37], v[112:113], v[36:37]
	v_pk_mul_f32 v[38:39], v[32:33], v[38:39]
	s_and_b64 vcc, exec, s[6:7]
	v_pk_add_f32 v[44:45], v[44:45], 1.0 op_sel_hi:[1,0]
	v_pk_add_f32 v[42:43], v[42:43], 1.0 op_sel_hi:[1,0]
	s_waitcnt lgkmcnt(0)
	v_pk_mul_f32 v[44:45], v[48:49], v[44:45]
	v_pk_mul_f32 v[42:43], v[46:47], v[42:43]
	v_pk_fma_f32 v[34:35], v[44:45], v[34:35], v[52:53]
	v_pk_fma_f32 v[46:47], v[42:43], v[54:55], v[50:51]
	v_pk_fma_f32 v[38:39], v[44:45], v[38:39], v[52:53]
	v_pk_fma_f32 v[36:37], v[42:43], v[36:37], v[50:51]
	v_cvt_pk_bf16_f32 v42, v46, v47
	v_cvt_pk_bf16_f32 v43, v34, v35
	v_cvt_pk_bf16_f32 v34, v36, v37
	v_cvt_pk_bf16_f32 v35, v38, v39
	global_store_dwordx2 v[58:59], v[42:43], off offset:-512
	s_cbranch_vccnz .LBB0_919
	v_add_co_u32_e32 v36, vcc, 0x7200000, v56
	s_nop 1
	v_addc_co_u32_e32 v37, vcc, 0, v57, vcc
	global_store_dwordx2 v[36:37], v[34:35], off offset:1536
.LBB0_919:
	v_mov_b64_e32 v[34:35], v[198:199]
	v_mov_b64_e32 v[36:37], v[200:201]
	s_nop 0
	v_mov_b64_e32 v[42:43], v[202:203]
	v_mov_b64_e32 v[44:45], v[204:205]
	v_mov_b64_e32 v[46:47], v[206:207]
	v_mov_b64_e32 v[48:49], v[208:209]
	v_pk_mul_f32 v[24:25], v[114:115], v[24:25]
	v_pk_mul_f32 v[30:31], v[32:33], v[30:31]
	v_pk_mul_f32 v[26:27], v[40:41], v[26:27]
	v_pk_mul_f32 v[28:29], v[112:113], v[28:29]
	s_and_b64 vcc, exec, s[6:7]
	v_pk_add_f32 v[34:35], v[34:35], 1.0 op_sel_hi:[1,0]
	v_pk_add_f32 v[32:33], v[36:37], 1.0 op_sel_hi:[1,0]
	s_waitcnt lgkmcnt(0)
	v_pk_mul_f32 v[34:35], v[42:43], v[34:35]
	v_pk_mul_f32 v[32:33], v[44:45], v[32:33]
	v_pk_fma_f32 v[24:25], v[34:35], v[24:25], v[46:47]
	v_pk_fma_f32 v[26:27], v[32:33], v[26:27], v[48:49]
	v_pk_fma_f32 v[30:31], v[32:33], v[30:31], v[48:49]
	v_pk_fma_f32 v[28:29], v[34:35], v[28:29], v[46:47]
	v_cvt_pk_bf16_f32 v32, v24, v25
	v_cvt_pk_bf16_f32 v33, v26, v27
	v_cvt_pk_bf16_f32 v24, v28, v29
	v_cvt_pk_bf16_f32 v25, v30, v31
	global_store_dwordx2 v[58:59], v[32:33], off
	s_cbranch_vccnz .LBB0_921
	v_add_co_u32_e32 v26, vcc, 0x7200000, v56
	s_nop 1
	v_addc_co_u32_e32 v27, vcc, 0, v57, vcc
	global_store_dwordx2 v[26:27], v[24:25], off offset:2048
.LBB0_921:
	v_mov_b64_e32 v[26:27], v[210:211]
	v_mov_b64_e32 v[28:29], v[212:213]
	s_nop 0
	v_mov_b64_e32 v[30:31], v[214:215]
	v_mov_b64_e32 v[32:33], v[216:217]
	v_mov_b64_e32 v[34:35], v[218:219]
	v_mov_b64_e32 v[36:37], v[220:221]
	v_mov_b32_e32 v24, v114
	v_mov_b32_e32 v25, v114
	v_pk_mul_f32 v[38:39], v[114:115], v[16:17]
	v_mov_b32_e32 v16, v112
	v_mov_b32_e32 v17, v112
	v_pk_mul_f32 v[18:19], v[24:25], v[18:19]
	v_pk_mul_f32 v[20:21], v[112:113], v[20:21]
	v_pk_mul_f32 v[22:23], v[16:17], v[22:23]
	s_and_b64 vcc, exec, s[6:7]
	v_pk_add_f32 v[28:29], v[28:29], 1.0 op_sel_hi:[1,0]
	v_pk_add_f32 v[26:27], v[26:27], 1.0 op_sel_hi:[1,0]
	s_waitcnt lgkmcnt(0)
	v_pk_mul_f32 v[28:29], v[32:33], v[28:29]
	v_pk_mul_f32 v[26:27], v[30:31], v[26:27]
	v_pk_fma_f32 v[18:19], v[28:29], v[18:19], v[36:37]
	v_pk_fma_f32 v[30:31], v[26:27], v[38:39], v[34:35]
	v_pk_fma_f32 v[22:23], v[28:29], v[22:23], v[36:37]
	v_pk_fma_f32 v[20:21], v[26:27], v[20:21], v[34:35]
	v_cvt_pk_bf16_f32 v26, v30, v31
	v_cvt_pk_bf16_f32 v27, v18, v19
	v_cvt_pk_bf16_f32 v18, v20, v21
	v_cvt_pk_bf16_f32 v19, v22, v23
	global_store_dwordx2 v[58:59], v[26:27], off offset:512
	s_cbranch_vccnz .LBB0_923
	v_add_co_u32_e32 v20, vcc, 0x7200000, v56
	s_nop 1
	v_addc_co_u32_e32 v21, vcc, 0, v57, vcc
	global_store_dwordx2 v[20:21], v[18:19], off offset:2560
.LBB0_923:
	v_mov_b64_e32 v[18:19], v[222:223]
	v_mov_b64_e32 v[20:21], v[224:225]
	s_nop 0
	v_mov_b64_e32 v[26:27], v[226:227]
	v_mov_b64_e32 v[28:29], v[228:229]
	v_mov_b64_e32 v[30:31], v[230:231]
	v_mov_b64_e32 v[32:33], v[232:233]
	v_pk_mul_f32 v[8:9], v[114:115], v[8:9]
	v_pk_mul_f32 v[14:15], v[16:17], v[14:15]
	v_pk_mul_f32 v[10:11], v[24:25], v[10:11]
	v_pk_mul_f32 v[12:13], v[112:113], v[12:13]
	s_and_b64 vcc, exec, s[6:7]
	v_pk_add_f32 v[18:19], v[18:19], 1.0 op_sel_hi:[1,0]
	v_pk_add_f32 v[16:17], v[20:21], 1.0 op_sel_hi:[1,0]
	s_waitcnt lgkmcnt(0)
	v_pk_mul_f32 v[18:19], v[26:27], v[18:19]
	v_pk_mul_f32 v[16:17], v[28:29], v[16:17]
	v_pk_fma_f32 v[8:9], v[18:19], v[8:9], v[30:31]
	v_pk_fma_f32 v[10:11], v[16:17], v[10:11], v[32:33]
	v_pk_fma_f32 v[14:15], v[16:17], v[14:15], v[32:33]
	v_pk_fma_f32 v[12:13], v[18:19], v[12:13], v[30:31]
	v_cvt_pk_bf16_f32 v16, v8, v9
	v_cvt_pk_bf16_f32 v17, v10, v11
	v_cvt_pk_bf16_f32 v8, v12, v13
	v_cvt_pk_bf16_f32 v9, v14, v15
	global_store_dwordx2 v[58:59], v[16:17], off offset:1024
	s_cbranch_vccnz .LBB0_925
	v_add_co_u32_e32 v10, vcc, 0x7200000, v56
	s_nop 1
	v_addc_co_u32_e32 v11, vcc, 0, v57, vcc
	global_store_dwordx2 v[10:11], v[8:9], off offset:3072
.LBB0_925:
	v_mov_b64_e32 v[8:9], v[234:235]
	v_mov_b64_e32 v[10:11], v[236:237]
	s_nop 0
	v_mov_b64_e32 v[12:13], v[238:239]
	v_mov_b64_e32 v[14:15], v[240:241]
	v_mov_b64_e32 v[16:17], v[242:243]
	v_mov_b64_e32 v[18:19], v[244:245]
	v_mov_b32_e32 v20, v114
	v_mov_b32_e32 v21, v114
	v_pk_mul_f32 v[0:1], v[114:115], v[0:1]
	v_mov_b32_e32 v22, v112
	v_mov_b32_e32 v23, v112
	v_pk_mul_f32 v[4:5], v[112:113], v[4:5]
	v_pk_mul_f32 v[2:3], v[20:21], v[2:3]
	v_pk_mul_f32 v[6:7], v[22:23], v[6:7]
	s_and_b64 vcc, exec, s[6:7]
	v_pk_add_f32 v[8:9], v[8:9], 1.0 op_sel_hi:[1,0]
	v_pk_add_f32 v[10:11], v[10:11], 1.0 op_sel_hi:[1,0]
	s_waitcnt lgkmcnt(0)
	v_pk_mul_f32 v[8:9], v[12:13], v[8:9]
	v_pk_mul_f32 v[10:11], v[14:15], v[10:11]
	v_pk_fma_f32 v[0:1], v[8:9], v[0:1], v[16:17]
	v_pk_fma_f32 v[2:3], v[10:11], v[2:3], v[18:19]
	v_pk_fma_f32 v[6:7], v[10:11], v[6:7], v[18:19]
	v_pk_fma_f32 v[4:5], v[8:9], v[4:5], v[16:17]
	v_cvt_pk_bf16_f32 v8, v0, v1
	v_cvt_pk_bf16_f32 v9, v2, v3
	v_cvt_pk_bf16_f32 v0, v4, v5
	v_cvt_pk_bf16_f32 v1, v6, v7
	global_store_dwordx2 v[58:59], v[8:9], off offset:1536
	s_cbranch_vccnz .LBB0_910
	v_add_co_u32_e32 v2, vcc, 0x7200000, v56
	s_nop 1
	v_addc_co_u32_e32 v3, vcc, 0, v57, vcc
	global_store_dwordx2 v[2:3], v[0:1], off offset:3584
	s_branch .LBB0_910

.LBB0_986:
	ds_read_b128 v[152:155], v148
	ds_read_b128 v[156:159], v148 offset:1024
	ds_read_b128 v[160:163], v148 offset:2048
	ds_read_b128 v[164:167], v148 offset:3072
	s_add_u32 s4, s60, 0xfff80080
	s_addc_u32 s5, s61, -1
	s_cmp_eq_u32 s64, 28
	s_cselect_b32 s5, s0, s5
	s_cselect_b32 s4, s1, s4
	s_cselect_b32 s51, s11, s37
	s_cselect_b32 s50, s13, s36
	s_add_i32 m0, s19, 0xc000
	ds_read_b128 v[168:171], v149
	ds_read_b128 v[172:175], v149 offset:1024
	ds_read_b128 v[176:179], v149 offset:2048
	ds_read_b128 v[180:183], v149 offset:3072
	ds_read_b128 v[184:187], v149 offset:4096
	ds_read_b128 v[188:191], v149 offset:5120
	ds_read_b128 v[192:195], v149 offset:6144
	ds_read_b128 v[196:199], v149 offset:7168
	global_load_lds_dwordx4 v138, s[60:61]
	s_add_i32 m0, s19, 0xe000
	s_nop 0
	global_load_lds_dwordx4 v140, s[60:61]
	s_waitcnt lgkmcnt(8)
	s_barrier
	s_waitcnt lgkmcnt(0)
	s_waitcnt lgkmcnt(0)
	v_mfma_f32_16x16x32_bf16 v[124:127], v[152:155], v[168:171], v[124:127]
	v_mfma_f32_16x16x32_bf16 v[120:123], v[160:163], v[168:171], v[120:123]
	v_mfma_f32_16x16x32_bf16 v[108:111], v[152:155], v[176:179], v[108:111]
	v_mfma_f32_16x16x32_bf16 v[104:107], v[160:163], v[176:179], v[104:107]
	v_mfma_f32_16x16x32_bf16 v[92:95], v[152:155], v[184:187], v[92:95]
	v_mfma_f32_16x16x32_bf16 v[88:91], v[160:163], v[184:187], v[88:91]
	v_mfma_f32_16x16x32_bf16 v[76:79], v[152:155], v[192:195], v[76:79]
	v_mfma_f32_16x16x32_bf16 v[72:75], v[160:163], v[192:195], v[72:75]
	v_mfma_f32_16x16x32_bf16 v[124:127], v[156:159], v[172:175], v[124:127]
	v_mfma_f32_16x16x32_bf16 v[120:123], v[164:167], v[172:175], v[120:123]
	v_mfma_f32_16x16x32_bf16 v[108:111], v[156:159], v[180:183], v[108:111]
	v_mfma_f32_16x16x32_bf16 v[104:107], v[164:167], v[180:183], v[104:107]
	v_mfma_f32_16x16x32_bf16 v[92:95], v[156:159], v[188:191], v[92:95]
	v_mfma_f32_16x16x32_bf16 v[88:91], v[164:167], v[188:191], v[88:91]
	v_mfma_f32_16x16x32_bf16 v[76:79], v[156:159], v[196:199], v[76:79]
	v_mfma_f32_16x16x32_bf16 v[72:75], v[164:167], v[196:199], v[72:75]
	s_barrier
	s_add_i32 s42, s41, s21
	s_add_u32 s98, s50, s8
	s_addc_u32 s99, s51, s9
	s_mov_b32 m0, s42
	ds_read_b128 v[200:203], v150
	ds_read_b128 v[204:207], v150 offset:1024
	ds_read_b128 v[208:211], v150 offset:2048
	ds_read_b128 v[212:215], v150 offset:3072
	global_load_lds_dwordx4 v134, s[50:51]
	s_add_i32 m0, s42, 0x2000
	s_nop 0
	global_load_lds_dwordx4 v130, s[50:51]
	s_barrier
	s_waitcnt lgkmcnt(0)
	s_waitcnt lgkmcnt(0)
	v_mfma_f32_16x16x32_bf16 v[116:119], v[200:203], v[168:171], v[116:119]
	v_mfma_f32_16x16x32_bf16 v[112:115], v[208:211], v[168:171], v[112:115]
	v_mfma_f32_16x16x32_bf16 v[100:103], v[200:203], v[176:179], v[100:103]
	v_mfma_f32_16x16x32_bf16 v[96:99], v[208:211], v[176:179], v[96:99]
	v_mfma_f32_16x16x32_bf16 v[84:87], v[200:203], v[184:187], v[84:87]
	v_mfma_f32_16x16x32_bf16 v[80:83], v[208:211], v[184:187], v[80:83]
	v_mfma_f32_16x16x32_bf16 v[68:71], v[200:203], v[192:195], v[68:71]
	v_mfma_f32_16x16x32_bf16 v[64:67], v[208:211], v[192:195], v[64:67]
	v_mfma_f32_16x16x32_bf16 v[116:119], v[204:207], v[172:175], v[116:119]
	v_mfma_f32_16x16x32_bf16 v[112:115], v[212:215], v[172:175], v[112:115]
	v_mfma_f32_16x16x32_bf16 v[100:103], v[204:207], v[180:183], v[100:103]
	v_mfma_f32_16x16x32_bf16 v[96:99], v[212:215], v[180:183], v[96:99]
	v_mfma_f32_16x16x32_bf16 v[84:87], v[204:207], v[188:191], v[84:87]
	v_mfma_f32_16x16x32_bf16 v[80:83], v[212:215], v[188:191], v[80:83]
	v_mfma_f32_16x16x32_bf16 v[68:71], v[204:207], v[196:199], v[68:71]
	v_mfma_f32_16x16x32_bf16 v[64:67], v[212:215], v[196:199], v[64:67]
	s_mov_b32 m0, s19
	s_add_u32 s100, s4, s8
	s_addc_u32 s101, s5, s9
	s_barrier
	ds_read_b128 v[168:171], v149 offset:16384
	ds_read_b128 v[172:175], v149 offset:17408
	ds_read_b128 v[176:179], v149 offset:18432
	ds_read_b128 v[180:183], v149 offset:19456
	ds_read_b128 v[184:187], v149 offset:20480
	ds_read_b128 v[188:191], v149 offset:21504
	ds_read_b128 v[192:195], v149 offset:22528
	ds_read_b128 v[196:199], v149 offset:23552
	global_load_lds_dwordx4 v136, s[4:5]
	s_mov_b32 m0, s24
	s_nop 0
	global_load_lds_dwordx4 v132, s[4:5]
	s_barrier
	s_waitcnt lgkmcnt(0)
	s_waitcnt lgkmcnt(0)
	v_mfma_f32_16x16x32_bf16 v[60:63], v[152:155], v[168:171], v[60:63]
	v_mfma_f32_16x16x32_bf16 v[56:59], v[160:163], v[168:171], v[56:59]
	v_mfma_f32_16x16x32_bf16 v[44:47], v[152:155], v[176:179], v[44:47]
	v_mfma_f32_16x16x32_bf16 v[40:43], v[160:163], v[176:179], v[40:43]
	v_mfma_f32_16x16x32_bf16 v[28:31], v[152:155], v[184:187], v[28:31]
	v_mfma_f32_16x16x32_bf16 v[24:27], v[160:163], v[184:187], v[24:27]
	v_mfma_f32_16x16x32_bf16 v[12:15], v[152:155], v[192:195], v[12:15]
	v_mfma_f32_16x16x32_bf16 v[8:11], v[160:163], v[192:195], v[8:11]
	v_mfma_f32_16x16x32_bf16 v[60:63], v[156:159], v[172:175], v[60:63]
	v_mfma_f32_16x16x32_bf16 v[56:59], v[164:167], v[172:175], v[56:59]
	v_mfma_f32_16x16x32_bf16 v[44:47], v[156:159], v[180:183], v[44:47]
	v_mfma_f32_16x16x32_bf16 v[40:43], v[164:167], v[180:183], v[40:43]
	v_mfma_f32_16x16x32_bf16 v[28:31], v[156:159], v[188:191], v[28:31]
	v_mfma_f32_16x16x32_bf16 v[24:27], v[164:167], v[188:191], v[24:27]
	v_mfma_f32_16x16x32_bf16 v[12:15], v[156:159], v[196:199], v[12:15]
	v_mfma_f32_16x16x32_bf16 v[8:11], v[164:167], v[196:199], v[8:11]
	s_barrier
	s_add_u32 s42, s50, 0x80000
	s_addc_u32 s43, s51, 0
	s_add_i32 s44, s46, s21
	s_mov_b32 m0, s44
	s_nop 0
	global_load_lds_dwordx4 v134, s[42:43]
	s_add_i32 m0, s44, 0x2000
	s_nop 0
	global_load_lds_dwordx4 v130, s[42:43]
	s_waitcnt vmcnt(6)
	s_barrier
	v_mfma_f32_16x16x32_bf16 v[52:55], v[200:203], v[168:171], v[52:55]
	v_mfma_f32_16x16x32_bf16 v[48:51], v[208:211], v[168:171], v[48:51]
	v_mfma_f32_16x16x32_bf16 v[36:39], v[200:203], v[176:179], v[36:39]
	v_mfma_f32_16x16x32_bf16 v[32:35], v[208:211], v[176:179], v[32:35]
	v_mfma_f32_16x16x32_bf16 v[20:23], v[200:203], v[184:187], v[20:23]
	v_mfma_f32_16x16x32_bf16 v[16:19], v[208:211], v[184:187], v[16:19]
	v_mfma_f32_16x16x32_bf16 v[4:7], v[200:203], v[192:195], v[4:7]
	v_mfma_f32_16x16x32_bf16 v[0:3], v[208:211], v[192:195], v[0:3]
	v_mfma_f32_16x16x32_bf16 v[52:55], v[204:207], v[172:175], v[52:55]
	v_mfma_f32_16x16x32_bf16 v[48:51], v[212:215], v[172:175], v[48:51]
	v_mfma_f32_16x16x32_bf16 v[36:39], v[204:207], v[180:183], v[36:39]
	v_mfma_f32_16x16x32_bf16 v[32:35], v[212:215], v[180:183], v[32:35]
	v_mfma_f32_16x16x32_bf16 v[20:23], v[204:207], v[188:191], v[20:23]
	v_mfma_f32_16x16x32_bf16 v[16:19], v[212:215], v[188:191], v[16:19]
	v_mfma_f32_16x16x32_bf16 v[4:7], v[204:207], v[196:199], v[4:7]
	v_mfma_f32_16x16x32_bf16 v[0:3], v[212:215], v[196:199], v[0:3]
	s_add_i32 s42, 0, 0x18000
	v_add_u32_e32 v151, s42, v146
	s_barrier
	ds_read_b128 v[152:155], v151
	ds_read_b128 v[156:159], v151 offset:1024
	ds_read_b128 v[160:163], v151 offset:2048
	ds_read_b128 v[164:167], v151 offset:3072
	s_add_u32 s4, s4, 0x80000
	s_addc_u32 s5, s5, 0
	s_mov_b32 m0, s25
	ds_read_b128 v[168:171], v149 offset:32768
	ds_read_b128 v[172:175], v149 offset:33792
	ds_read_b128 v[176:179], v149 offset:34816
	ds_read_b128 v[180:183], v149 offset:35840
	ds_read_b128 v[184:187], v149 offset:36864
	ds_read_b128 v[188:191], v149 offset:37888
	ds_read_b128 v[192:195], v149 offset:38912
	ds_read_b128 v[196:199], v149 offset:39936
	global_load_lds_dwordx4 v136, s[4:5]
	s_mov_b32 m0, s28
	s_nop 0
	global_load_lds_dwordx4 v132, s[4:5]
	s_waitcnt lgkmcnt(8)
	s_barrier
	s_waitcnt lgkmcnt(0)
	s_waitcnt lgkmcnt(0)
	v_mfma_f32_16x16x32_bf16 v[124:127], v[152:155], v[168:171], v[124:127]
	v_mfma_f32_16x16x32_bf16 v[120:123], v[160:163], v[168:171], v[120:123]
	v_mfma_f32_16x16x32_bf16 v[108:111], v[152:155], v[176:179], v[108:111]
	v_mfma_f32_16x16x32_bf16 v[104:107], v[160:163], v[176:179], v[104:107]
	v_mfma_f32_16x16x32_bf16 v[92:95], v[152:155], v[184:187], v[92:95]
	v_mfma_f32_16x16x32_bf16 v[88:91], v[160:163], v[184:187], v[88:91]
	v_mfma_f32_16x16x32_bf16 v[76:79], v[152:155], v[192:195], v[76:79]
	v_mfma_f32_16x16x32_bf16 v[72:75], v[160:163], v[192:195], v[72:75]
	v_mfma_f32_16x16x32_bf16 v[124:127], v[156:159], v[172:175], v[124:127]
	v_mfma_f32_16x16x32_bf16 v[120:123], v[164:167], v[172:175], v[120:123]
	v_mfma_f32_16x16x32_bf16 v[108:111], v[156:159], v[180:183], v[108:111]
	v_mfma_f32_16x16x32_bf16 v[104:107], v[164:167], v[180:183], v[104:107]
	v_mfma_f32_16x16x32_bf16 v[92:95], v[156:159], v[188:191], v[92:95]
	v_mfma_f32_16x16x32_bf16 v[88:91], v[164:167], v[188:191], v[88:91]
	v_mfma_f32_16x16x32_bf16 v[76:79], v[156:159], v[196:199], v[76:79]
	v_mfma_f32_16x16x32_bf16 v[72:75], v[164:167], v[196:199], v[72:75]
	s_barrier
	s_add_i32 s43, 0, 0x1c000
	s_add_i32 s4, s42, s21
	v_add_u32_e32 v151, s43, v146
	s_mov_b32 m0, s4
	ds_read_b128 v[200:203], v151
	ds_read_b128 v[204:207], v151 offset:1024
	ds_read_b128 v[208:211], v151 offset:2048
	ds_read_b128 v[212:215], v151 offset:3072
	global_load_lds_dwordx4 v134, s[98:99]
	s_add_i32 m0, s4, 0x2000
	s_nop 0
	global_load_lds_dwordx4 v130, s[98:99]
	s_barrier
	s_waitcnt lgkmcnt(0)
	s_waitcnt lgkmcnt(0)
	v_mfma_f32_16x16x32_bf16 v[116:119], v[200:203], v[168:171], v[116:119]
	v_mfma_f32_16x16x32_bf16 v[112:115], v[208:211], v[168:171], v[112:115]
	v_mfma_f32_16x16x32_bf16 v[100:103], v[200:203], v[176:179], v[100:103]
	v_mfma_f32_16x16x32_bf16 v[96:99], v[208:211], v[176:179], v[96:99]
	v_mfma_f32_16x16x32_bf16 v[84:87], v[200:203], v[184:187], v[84:87]
	v_mfma_f32_16x16x32_bf16 v[80:83], v[208:211], v[184:187], v[80:83]
	v_mfma_f32_16x16x32_bf16 v[68:71], v[200:203], v[192:195], v[68:71]
	v_mfma_f32_16x16x32_bf16 v[64:67], v[208:211], v[192:195], v[64:67]
	v_mfma_f32_16x16x32_bf16 v[116:119], v[204:207], v[172:175], v[116:119]
	v_mfma_f32_16x16x32_bf16 v[112:115], v[212:215], v[172:175], v[112:115]
	v_mfma_f32_16x16x32_bf16 v[100:103], v[204:207], v[180:183], v[100:103]
	v_mfma_f32_16x16x32_bf16 v[96:99], v[212:215], v[180:183], v[96:99]
	v_mfma_f32_16x16x32_bf16 v[84:87], v[204:207], v[188:191], v[84:87]
	v_mfma_f32_16x16x32_bf16 v[80:83], v[212:215], v[188:191], v[80:83]
	v_mfma_f32_16x16x32_bf16 v[68:71], v[204:207], v[196:199], v[68:71]
	v_mfma_f32_16x16x32_bf16 v[64:67], v[212:215], v[196:199], v[64:67]
	s_mov_b32 m0, s33
	s_barrier
	ds_read_b128 v[168:171], v149 offset:49152
	ds_read_b128 v[172:175], v149 offset:50176
	ds_read_b128 v[176:179], v149 offset:51200
	ds_read_b128 v[180:183], v149 offset:52224
	ds_read_b128 v[184:187], v149 offset:53248
	ds_read_b128 v[188:191], v149 offset:54272
	ds_read_b128 v[192:195], v149 offset:55296
	ds_read_b128 v[196:199], v149 offset:56320
	global_load_lds_dwordx4 v136, s[100:101]
	s_mov_b32 m0, s40
	s_nop 0
	global_load_lds_dwordx4 v132, s[100:101]
	s_barrier
	s_waitcnt lgkmcnt(0)
	s_waitcnt lgkmcnt(0)
	v_mfma_f32_16x16x32_bf16 v[60:63], v[152:155], v[168:171], v[60:63]
	v_mfma_f32_16x16x32_bf16 v[56:59], v[160:163], v[168:171], v[56:59]
	v_mfma_f32_16x16x32_bf16 v[44:47], v[152:155], v[176:179], v[44:47]
	v_mfma_f32_16x16x32_bf16 v[40:43], v[160:163], v[176:179], v[40:43]
	v_mfma_f32_16x16x32_bf16 v[28:31], v[152:155], v[184:187], v[28:31]
	v_mfma_f32_16x16x32_bf16 v[24:27], v[160:163], v[184:187], v[24:27]
	v_mfma_f32_16x16x32_bf16 v[12:15], v[152:155], v[192:195], v[12:15]
	v_mfma_f32_16x16x32_bf16 v[8:11], v[160:163], v[192:195], v[8:11]
	v_mfma_f32_16x16x32_bf16 v[60:63], v[156:159], v[172:175], v[60:63]
	v_mfma_f32_16x16x32_bf16 v[56:59], v[164:167], v[172:175], v[56:59]
	v_mfma_f32_16x16x32_bf16 v[44:47], v[156:159], v[180:183], v[44:47]
	v_mfma_f32_16x16x32_bf16 v[40:43], v[164:167], v[180:183], v[40:43]
	v_mfma_f32_16x16x32_bf16 v[28:31], v[156:159], v[188:191], v[28:31]
	v_mfma_f32_16x16x32_bf16 v[24:27], v[164:167], v[188:191], v[24:27]
	v_mfma_f32_16x16x32_bf16 v[12:15], v[156:159], v[196:199], v[12:15]
	v_mfma_f32_16x16x32_bf16 v[8:11], v[164:167], v[196:199], v[8:11]
	s_barrier
	s_add_u32 s4, s50, 0x80080
	s_addc_u32 s5, s51, 0
	s_add_i32 s42, s43, s21
	s_mov_b32 m0, s42
	s_nop 0
	global_load_lds_dwordx4 v134, s[4:5]
	s_add_i32 m0, s42, 0x2000
	s_nop 0
	global_load_lds_dwordx4 v130, s[4:5]
	s_waitcnt vmcnt(6)
	s_barrier
	v_mfma_f32_16x16x32_bf16 v[52:55], v[200:203], v[168:171], v[52:55]
	v_mfma_f32_16x16x32_bf16 v[48:51], v[208:211], v[168:171], v[48:51]
	v_mfma_f32_16x16x32_bf16 v[36:39], v[200:203], v[176:179], v[36:39]
	v_mfma_f32_16x16x32_bf16 v[32:35], v[208:211], v[176:179], v[32:35]
	v_mfma_f32_16x16x32_bf16 v[20:23], v[200:203], v[184:187], v[20:23]
	v_mfma_f32_16x16x32_bf16 v[16:19], v[208:211], v[184:187], v[16:19]
	v_mfma_f32_16x16x32_bf16 v[4:7], v[200:203], v[192:195], v[4:7]
	v_mfma_f32_16x16x32_bf16 v[0:3], v[208:211], v[192:195], v[0:3]
	v_mfma_f32_16x16x32_bf16 v[52:55], v[204:207], v[172:175], v[52:55]
	v_mfma_f32_16x16x32_bf16 v[48:51], v[212:215], v[172:175], v[48:51]
	v_mfma_f32_16x16x32_bf16 v[36:39], v[204:207], v[180:183], v[36:39]
	v_mfma_f32_16x16x32_bf16 v[32:35], v[212:215], v[180:183], v[32:35]
	v_mfma_f32_16x16x32_bf16 v[20:23], v[204:207], v[188:191], v[20:23]
	v_mfma_f32_16x16x32_bf16 v[16:19], v[212:215], v[188:191], v[16:19]
	v_mfma_f32_16x16x32_bf16 v[4:7], v[204:207], v[196:199], v[4:7]
	v_mfma_f32_16x16x32_bf16 v[0:3], v[212:215], v[196:199], v[0:3]
	s_add_i32 s64, s64, 2
	s_add_u32 s60, s60, 0x100
	s_addc_u32 s61, s61, 0
	s_add_u32 s36, s36, 0x100
	s_addc_u32 s37, s37, 0
	s_cmp_gt_u32 s64, 29
	s_barrier
	s_cbranch_scc0 .LBB0_986
	v_mul_f32_e32 v152, 0xbfb8aa3b, v124
	v_exp_f32_e32 v153, v152
	v_mul_f32_e32 v152, 0xbfb8aa3b, v120
	v_exp_f32_e32 v154, v152
	v_lshl_or_b32 v152, s53, 7, v147
	v_add_f32_e32 v153, 1.0, v153
	v_rcp_f32_e32 v155, v153
	v_add_f32_e32 v153, 1.0, v154
	v_rcp_f32_e32 v154, v153
	v_lshl_add_u32 v151, s18, 8, v129
	v_mul_f32_e32 v124, v124, v155
	v_mul_f32_e32 v116, v124, v116
	v_mul_f32_e32 v124, 0xbfb8aa3b, v125
	v_mul_f32_e32 v120, v120, v154
	v_exp_f32_e32 v124, v124
	v_mul_f32_e32 v154, 0xbfb8aa3b, v121
	v_exp_f32_e32 v154, v154
	v_mul_f32_e32 v112, v120, v112
	v_add_f32_e32 v120, 1.0, v124
	v_rcp_f32_e32 v120, v120
	v_add_f32_e32 v124, 1.0, v154
	v_mul_f32_e32 v154, 0xbfb8aa3b, v126
	v_rcp_f32_e32 v124, v124
	v_exp_f32_e32 v154, v154
	v_mul_f32_e32 v120, v125, v120
	v_mul_f32_e32 v117, v120, v117
	v_mul_f32_e32 v120, v121, v124
	v_add_f32_e32 v121, 1.0, v154
	v_rcp_f32_e32 v121, v121
	v_mul_f32_e32 v124, 0xbfb8aa3b, v122
	v_exp_f32_e32 v124, v124
	v_mul_f32_e32 v113, v120, v113
	v_mul_f32_e32 v120, v126, v121
	v_mul_f32_e32 v121, 0xbfb8aa3b, v127
	v_mul_f32_e32 v118, v120, v118
	v_add_f32_e32 v120, 1.0, v124
	v_exp_f32_e32 v121, v121
	v_mul_f32_e32 v124, 0xbfb8aa3b, v123
	v_rcp_f32_e32 v120, v120
	v_exp_f32_e32 v124, v124
	v_add_f32_e32 v121, 1.0, v121
	v_rcp_f32_e32 v121, v121
	v_mul_f32_e32 v120, v122, v120
	v_add_f32_e32 v122, 1.0, v124
	v_rcp_f32_e32 v122, v122
	v_mul_f32_e32 v114, v120, v114
	v_mul_f32_e32 v120, v127, v121
	v_mul_f32_e32 v119, v120, v119
	v_mul_f32_e32 v120, v123, v122
	v_mul_f32_e32 v122, 0xbfb8aa3b, v108
	v_exp_f32_e32 v122, v122
	v_mul_f32_e32 v123, 0xbfb8aa3b, v104
	v_exp_f32_e32 v123, v123
	v_ashrrev_i32_e32 v153, 31, v152
	v_add_f32_e32 v122, 1.0, v122
	v_rcp_f32_e32 v122, v122
	v_mul_f32_e32 v115, v120, v115
	v_cvt_pk_bf16_f32 v116, v116, v117
	v_cvt_pk_bf16_f32 v117, v118, v119
	v_cvt_pk_bf16_f32 v118, v112, v113
	v_mov_b64_e32 v[112:113], s[48:49]
	v_cvt_pk_bf16_f32 v119, v114, v115
	v_mad_i64_i32 v[120:121], s[0:1], v151, s47, v[112:113]
	v_lshlrev_b64 v[114:115], 1, v[152:153]
	v_add_f32_e32 v123, 1.0, v123
	v_mul_f32_e32 v108, v108, v122
	v_lshl_add_u64 v[120:121], v[120:121], 0, v[114:115]
	v_rcp_f32_e32 v123, v123
	v_mul_f32_e32 v100, v108, v100
	v_mul_f32_e32 v108, 0xbfb8aa3b, v109
	global_store_dwordx4 v[120:121], v[116:119], off
	v_exp_f32_e32 v108, v108
	v_mul_f32_e32 v104, v104, v123
	v_mul_f32_e32 v116, 0xbfb8aa3b, v105
	v_exp_f32_e32 v116, v116
	v_mul_f32_e32 v104, v104, v96
	v_add_f32_e32 v96, 1.0, v108
	v_rcp_f32_e32 v96, v96
	v_add_f32_e32 v108, 1.0, v116
	v_mul_f32_e32 v116, 0xbfb8aa3b, v110
	v_rcp_f32_e32 v108, v108
	v_exp_f32_e32 v116, v116
	v_mul_f32_e32 v96, v109, v96
	v_mul_f32_e32 v96, v96, v101
	v_mul_f32_e32 v101, v105, v108
	v_add_f32_e32 v105, 1.0, v116
	v_rcp_f32_e32 v105, v105
	v_mul_f32_e32 v108, 0xbfb8aa3b, v106
	v_exp_f32_e32 v108, v108
	v_mul_f32_e32 v101, v101, v97
	v_mul_f32_e32 v97, v110, v105
	v_mul_f32_e32 v105, 0xbfb8aa3b, v111
	v_mul_f32_e32 v97, v97, v102
	v_add_f32_e32 v102, 1.0, v108
	v_exp_f32_e32 v105, v105
	v_mul_f32_e32 v108, 0xbfb8aa3b, v107
	v_rcp_f32_e32 v102, v102
	v_exp_f32_e32 v108, v108
	v_add_f32_e32 v105, 1.0, v105
	v_rcp_f32_e32 v105, v105
	v_mul_f32_e32 v102, v106, v102
	v_add_f32_e32 v106, 1.0, v108
	v_rcp_f32_e32 v106, v106
	v_mul_f32_e32 v102, v102, v98
	v_mul_f32_e32 v98, v111, v105
	v_mul_f32_e32 v98, v98, v103
	v_mul_f32_e32 v103, v107, v106
	v_mul_f32_e32 v99, v103, v99
	v_cvt_pk_bf16_f32 v96, v100, v96
	v_cvt_pk_bf16_f32 v97, v97, v98
	v_cvt_pk_bf16_f32 v98, v104, v101
	v_cvt_pk_bf16_f32 v99, v102, v99
	v_mul_f32_e32 v102, 0xbfb8aa3b, v92
	v_exp_f32_e32 v102, v102
	v_mul_f32_e32 v103, 0xbfb8aa3b, v88
	v_exp_f32_e32 v103, v103
	v_or_b32_e32 v100, 16, v151
	v_add_f32_e32 v102, 1.0, v102
	v_rcp_f32_e32 v102, v102
	v_mad_i64_i32 v[100:101], s[0:1], v100, s47, v[112:113]
	v_add_f32_e32 v103, 1.0, v103
	v_mul_f32_e32 v92, v92, v102
	v_lshl_add_u64 v[100:101], v[100:101], 0, v[114:115]
	v_rcp_f32_e32 v103, v103
	v_mul_f32_e32 v84, v92, v84
	v_mul_f32_e32 v92, 0xbfb8aa3b, v93
	global_store_dwordx4 v[100:101], v[96:99], off
	v_exp_f32_e32 v92, v92
	v_mul_f32_e32 v88, v88, v103
	v_mul_f32_e32 v96, 0xbfb8aa3b, v89
	v_exp_f32_e32 v96, v96
	v_mul_f32_e32 v88, v88, v80
	v_add_f32_e32 v80, 1.0, v92
	v_rcp_f32_e32 v80, v80
	v_add_f32_e32 v92, 1.0, v96
	v_mul_f32_e32 v96, 0xbfb8aa3b, v94
	v_rcp_f32_e32 v92, v92
	v_exp_f32_e32 v96, v96
	v_mul_f32_e32 v80, v93, v80
	v_mul_f32_e32 v80, v80, v85
	v_mul_f32_e32 v85, v89, v92
	v_add_f32_e32 v89, 1.0, v96
	v_rcp_f32_e32 v89, v89
	v_mul_f32_e32 v92, 0xbfb8aa3b, v90
	v_exp_f32_e32 v92, v92
	v_mul_f32_e32 v85, v85, v81
	v_mul_f32_e32 v81, v94, v89
	v_mul_f32_e32 v89, 0xbfb8aa3b, v95
	v_mul_f32_e32 v81, v81, v86
	v_add_f32_e32 v86, 1.0, v92
	v_exp_f32_e32 v89, v89
	v_mul_f32_e32 v92, 0xbfb8aa3b, v91
	v_rcp_f32_e32 v86, v86
	v_exp_f32_e32 v92, v92
	v_add_f32_e32 v89, 1.0, v89
	v_rcp_f32_e32 v89, v89
	v_mul_f32_e32 v86, v90, v86
	v_add_f32_e32 v90, 1.0, v92
	v_rcp_f32_e32 v90, v90
	v_mul_f32_e32 v86, v86, v82
	v_mul_f32_e32 v82, v95, v89
	v_mul_f32_e32 v82, v82, v87
	v_mul_f32_e32 v87, v91, v90
	v_mul_f32_e32 v83, v87, v83
	v_cvt_pk_bf16_f32 v80, v84, v80
	v_cvt_pk_bf16_f32 v81, v81, v82
	v_cvt_pk_bf16_f32 v82, v88, v85
	v_cvt_pk_bf16_f32 v83, v86, v83
	v_mul_f32_e32 v86, 0xbfb8aa3b, v76
	v_exp_f32_e32 v86, v86
	v_mul_f32_e32 v87, 0xbfb8aa3b, v72
	v_exp_f32_e32 v87, v87
	v_or_b32_e32 v84, 32, v151
	v_add_f32_e32 v86, 1.0, v86
	v_rcp_f32_e32 v86, v86
	v_mad_i64_i32 v[84:85], s[0:1], v84, s47, v[112:113]
	v_add_f32_e32 v87, 1.0, v87
	v_mul_f32_e32 v76, v76, v86
	v_lshl_add_u64 v[84:85], v[84:85], 0, v[114:115]
	v_rcp_f32_e32 v87, v87
	v_mul_f32_e32 v68, v76, v68
	v_mul_f32_e32 v76, 0xbfb8aa3b, v77
	global_store_dwordx4 v[84:85], v[80:83], off
	v_exp_f32_e32 v76, v76
	v_mul_f32_e32 v72, v72, v87
	v_mul_f32_e32 v80, 0xbfb8aa3b, v73
	v_exp_f32_e32 v80, v80
	v_mul_f32_e32 v72, v72, v64
	v_add_f32_e32 v64, 1.0, v76
	v_rcp_f32_e32 v64, v64
	v_add_f32_e32 v76, 1.0, v80
	v_mul_f32_e32 v80, 0xbfb8aa3b, v78
	v_rcp_f32_e32 v76, v76
	v_exp_f32_e32 v80, v80
	v_mul_f32_e32 v64, v77, v64
	v_mul_f32_e32 v64, v64, v69
	v_mul_f32_e32 v69, v73, v76
	v_add_f32_e32 v73, 1.0, v80
	v_rcp_f32_e32 v73, v73
	v_mul_f32_e32 v76, 0xbfb8aa3b, v74
	v_exp_f32_e32 v76, v76
	v_mul_f32_e32 v69, v69, v65
	v_mul_f32_e32 v65, v78, v73
	v_mul_f32_e32 v73, 0xbfb8aa3b, v79
	v_mul_f32_e32 v65, v65, v70
	v_add_f32_e32 v70, 1.0, v76
	v_exp_f32_e32 v73, v73
	v_mul_f32_e32 v76, 0xbfb8aa3b, v75
	v_rcp_f32_e32 v70, v70
	v_exp_f32_e32 v76, v76
	v_add_f32_e32 v73, 1.0, v73
	v_rcp_f32_e32 v73, v73
	v_mul_f32_e32 v70, v74, v70
	v_add_f32_e32 v74, 1.0, v76
	v_rcp_f32_e32 v74, v74
	v_mul_f32_e32 v70, v70, v66
	v_mul_f32_e32 v66, v79, v73
	v_mul_f32_e32 v66, v66, v71
	v_mul_f32_e32 v71, v75, v74
	v_mul_f32_e32 v67, v71, v67
	v_cvt_pk_bf16_f32 v64, v68, v64
	v_cvt_pk_bf16_f32 v65, v65, v66
	v_cvt_pk_bf16_f32 v66, v72, v69
	v_cvt_pk_bf16_f32 v67, v70, v67
	v_mul_f32_e32 v70, 0xbfb8aa3b, v60
	v_exp_f32_e32 v70, v70
	v_or_b32_e32 v68, 48, v151
	v_mad_i64_i32 v[68:69], s[0:1], v68, s47, v[112:113]
	v_lshl_add_u64 v[68:69], v[68:69], 0, v[114:115]
	v_mul_f32_e32 v71, 0xbfb8aa3b, v56
	global_store_dwordx4 v[68:69], v[64:67], off
	v_exp_f32_e32 v71, v71
	s_and_b64 vcc, exec, s[6:7]
	v_add_f32_e32 v64, 1.0, v70
	v_rcp_f32_e32 v64, v64
	v_add_f32_e32 v65, 1.0, v71
	v_rcp_f32_e32 v65, v65
	v_add_u32_e32 v66, 0x80, v151
	v_mul_f32_e32 v60, v60, v64
	v_mul_f32_e32 v52, v60, v52
	v_mul_f32_e32 v60, 0xbfb8aa3b, v61
	v_exp_f32_e32 v60, v60
	v_mul_f32_e32 v64, 0xbfb8aa3b, v57
	v_exp_f32_e32 v64, v64
	v_mul_f32_e32 v56, v56, v65
	v_mul_f32_e32 v56, v56, v48
	v_add_f32_e32 v48, 1.0, v60
	v_rcp_f32_e32 v48, v48
	v_add_f32_e32 v60, 1.0, v64
	v_mul_f32_e32 v64, 0xbfb8aa3b, v62
	v_rcp_f32_e32 v60, v60
	v_exp_f32_e32 v64, v64
	v_mul_f32_e32 v48, v61, v48
	v_mul_f32_e32 v48, v48, v53
	v_mul_f32_e32 v53, v57, v60
	v_add_f32_e32 v57, 1.0, v64
	v_rcp_f32_e32 v57, v57
	v_mul_f32_e32 v60, 0xbfb8aa3b, v58
	v_exp_f32_e32 v60, v60
	v_mul_f32_e32 v53, v53, v49
	v_mul_f32_e32 v49, v62, v57
	v_mul_f32_e32 v57, 0xbfb8aa3b, v63
	v_mul_f32_e32 v49, v49, v54
	v_add_f32_e32 v54, 1.0, v60
	v_exp_f32_e32 v57, v57
	v_mul_f32_e32 v60, 0xbfb8aa3b, v59
	v_rcp_f32_e32 v54, v54
	v_exp_f32_e32 v60, v60
	v_add_f32_e32 v57, 1.0, v57
	v_rcp_f32_e32 v57, v57
	v_mul_f32_e32 v54, v58, v54
	v_add_f32_e32 v58, 1.0, v60
	v_rcp_f32_e32 v58, v58
	v_mul_f32_e32 v54, v54, v50
	v_mul_f32_e32 v50, v63, v57
	v_mul_f32_e32 v50, v50, v55
	v_mul_f32_e32 v55, v59, v58
	v_mul_f32_e32 v51, v55, v51
	v_cvt_pk_bf16_f32 v48, v52, v48
	v_cvt_pk_bf16_f32 v49, v49, v50
	v_cvt_pk_bf16_f32 v50, v56, v53
	v_cvt_pk_bf16_f32 v51, v54, v51
	v_mul_f32_e32 v54, 0xbfb8aa3b, v44
	v_exp_f32_e32 v54, v54
	v_mul_f32_e32 v55, 0xbfb8aa3b, v40
	v_exp_f32_e32 v55, v55
	v_mad_i64_i32 v[52:53], s[0:1], v66, s47, v[112:113]
	v_add_f32_e32 v54, 1.0, v54
	v_rcp_f32_e32 v54, v54
	v_add_f32_e32 v55, 1.0, v55
	v_lshl_add_u64 v[52:53], v[52:53], 0, v[114:115]
	v_rcp_f32_e32 v55, v55
	v_mul_f32_e32 v44, v44, v54
	v_mul_f32_e32 v36, v44, v36
	v_mul_f32_e32 v44, 0xbfb8aa3b, v45
	global_store_dwordx4 v[52:53], v[48:51], off
	v_exp_f32_e32 v44, v44
	v_mul_f32_e32 v40, v40, v55
	v_mul_f32_e32 v48, 0xbfb8aa3b, v41
	v_exp_f32_e32 v48, v48
	v_mul_f32_e32 v40, v40, v32
	v_add_f32_e32 v32, 1.0, v44
	v_rcp_f32_e32 v32, v32
	v_add_f32_e32 v44, 1.0, v48
	v_mul_f32_e32 v48, 0xbfb8aa3b, v46
	v_rcp_f32_e32 v44, v44
	v_exp_f32_e32 v48, v48
	v_mul_f32_e32 v32, v45, v32
	v_mul_f32_e32 v32, v32, v37
	v_mul_f32_e32 v37, v41, v44
	v_add_f32_e32 v41, 1.0, v48
	v_rcp_f32_e32 v41, v41
	v_mul_f32_e32 v44, 0xbfb8aa3b, v42
	v_exp_f32_e32 v44, v44
	v_mul_f32_e32 v37, v37, v33
	v_mul_f32_e32 v33, v46, v41
	v_mul_f32_e32 v41, 0xbfb8aa3b, v47
	v_mul_f32_e32 v33, v33, v38
	v_add_f32_e32 v38, 1.0, v44
	v_exp_f32_e32 v41, v41
	v_mul_f32_e32 v44, 0xbfb8aa3b, v43
	v_rcp_f32_e32 v38, v38
	v_exp_f32_e32 v44, v44
	v_add_f32_e32 v41, 1.0, v41
	v_rcp_f32_e32 v41, v41
	v_mul_f32_e32 v38, v42, v38
	v_add_f32_e32 v42, 1.0, v44
	v_rcp_f32_e32 v42, v42
	v_mul_f32_e32 v38, v38, v34
	v_mul_f32_e32 v34, v47, v41
	v_mul_f32_e32 v34, v34, v39
	v_mul_f32_e32 v39, v43, v42
	v_mul_f32_e32 v35, v39, v35
	v_cvt_pk_bf16_f32 v32, v36, v32
	v_cvt_pk_bf16_f32 v33, v33, v34
	v_cvt_pk_bf16_f32 v34, v40, v37
	v_cvt_pk_bf16_f32 v35, v38, v35
	v_mul_f32_e32 v38, 0xbfb8aa3b, v28
	v_exp_f32_e32 v38, v38
	v_mul_f32_e32 v39, 0xbfb8aa3b, v24
	v_exp_f32_e32 v39, v39
	v_add_u32_e32 v36, 0x90, v151
	v_add_f32_e32 v38, 1.0, v38
	v_rcp_f32_e32 v38, v38
	v_mad_i64_i32 v[36:37], s[0:1], v36, s47, v[112:113]
	v_add_f32_e32 v39, 1.0, v39
	v_mul_f32_e32 v28, v28, v38
	v_lshl_add_u64 v[36:37], v[36:37], 0, v[114:115]
	v_rcp_f32_e32 v39, v39
	v_mul_f32_e32 v20, v28, v20
	v_mul_f32_e32 v28, 0xbfb8aa3b, v29
	global_store_dwordx4 v[36:37], v[32:35], off
	v_exp_f32_e32 v28, v28
	v_mul_f32_e32 v24, v24, v39
	v_mul_f32_e32 v32, 0xbfb8aa3b, v25
	v_exp_f32_e32 v32, v32
	v_mul_f32_e32 v24, v24, v16
	v_add_f32_e32 v16, 1.0, v28
	v_rcp_f32_e32 v16, v16
	v_add_f32_e32 v28, 1.0, v32
	v_mul_f32_e32 v32, 0xbfb8aa3b, v30
	v_rcp_f32_e32 v28, v28
	v_exp_f32_e32 v32, v32
	v_mul_f32_e32 v16, v29, v16
	v_mul_f32_e32 v16, v16, v21
	v_mul_f32_e32 v21, v25, v28
	v_add_f32_e32 v25, 1.0, v32
	v_rcp_f32_e32 v25, v25
	v_mul_f32_e32 v28, 0xbfb8aa3b, v26
	v_exp_f32_e32 v28, v28
	v_mul_f32_e32 v21, v21, v17
	v_mul_f32_e32 v17, v30, v25
	v_mul_f32_e32 v25, 0xbfb8aa3b, v31
	v_mul_f32_e32 v17, v17, v22
	v_add_f32_e32 v22, 1.0, v28
	v_exp_f32_e32 v25, v25
	v_mul_f32_e32 v28, 0xbfb8aa3b, v27
	v_rcp_f32_e32 v22, v22
	v_exp_f32_e32 v28, v28
	v_add_f32_e32 v25, 1.0, v25
	v_rcp_f32_e32 v25, v25
	v_mul_f32_e32 v22, v26, v22
	v_add_f32_e32 v26, 1.0, v28
	v_rcp_f32_e32 v26, v26
	v_mul_f32_e32 v22, v22, v18
	v_mul_f32_e32 v18, v31, v25
	v_mul_f32_e32 v18, v18, v23
	v_mul_f32_e32 v23, v27, v26
	v_mul_f32_e32 v19, v23, v19
	v_cvt_pk_bf16_f32 v16, v20, v16
	v_cvt_pk_bf16_f32 v17, v17, v18
	v_cvt_pk_bf16_f32 v18, v24, v21
	v_cvt_pk_bf16_f32 v19, v22, v19
	v_mul_f32_e32 v22, 0xbfb8aa3b, v12
	v_exp_f32_e32 v22, v22
	v_mul_f32_e32 v23, 0xbfb8aa3b, v8
	v_exp_f32_e32 v23, v23
	v_add_u32_e32 v20, 0xa0, v151
	v_add_f32_e32 v22, 1.0, v22
	v_rcp_f32_e32 v22, v22
	v_mad_i64_i32 v[20:21], s[0:1], v20, s47, v[112:113]
	v_add_f32_e32 v23, 1.0, v23
	v_mul_f32_e32 v12, v12, v22
	v_lshl_add_u64 v[20:21], v[20:21], 0, v[114:115]
	v_rcp_f32_e32 v23, v23
	v_mul_f32_e32 v4, v12, v4
	v_mul_f32_e32 v12, 0xbfb8aa3b, v13
	global_store_dwordx4 v[20:21], v[16:19], off
	v_exp_f32_e32 v12, v12
	v_mul_f32_e32 v8, v8, v23
	v_mul_f32_e32 v16, 0xbfb8aa3b, v9
	v_exp_f32_e32 v16, v16
	v_mul_f32_e32 v8, v8, v0
	v_add_f32_e32 v0, 1.0, v12
	v_rcp_f32_e32 v0, v0
	v_add_f32_e32 v12, 1.0, v16
	v_mul_f32_e32 v16, 0xbfb8aa3b, v14
	v_rcp_f32_e32 v12, v12
	v_exp_f32_e32 v16, v16
	v_mul_f32_e32 v0, v13, v0
	v_mul_f32_e32 v0, v0, v5
	v_mul_f32_e32 v5, v9, v12
	v_add_f32_e32 v9, 1.0, v16
	v_rcp_f32_e32 v9, v9
	v_mul_f32_e32 v12, 0xbfb8aa3b, v10
	v_exp_f32_e32 v12, v12
	v_mul_f32_e32 v5, v5, v1
	v_mul_f32_e32 v1, v14, v9
	v_mul_f32_e32 v9, 0xbfb8aa3b, v15
	v_exp_f32_e32 v9, v9
	v_mul_f32_e32 v1, v1, v6
	v_add_f32_e32 v6, 1.0, v12
	v_mul_f32_e32 v12, 0xbfb8aa3b, v11
	v_rcp_f32_e32 v6, v6
	v_exp_f32_e32 v12, v12
	v_add_f32_e32 v9, 1.0, v9
	v_rcp_f32_e32 v9, v9
	v_mul_f32_e32 v6, v10, v6
	v_add_f32_e32 v10, 1.0, v12
	v_rcp_f32_e32 v10, v10
	v_mul_f32_e32 v6, v6, v2
	v_mul_f32_e32 v2, v15, v9
	v_mul_f32_e32 v2, v2, v7
	v_cvt_pk_bf16_f32 v0, v4, v0
	v_add_u32_e32 v4, 0xb0, v151
	v_mul_f32_e32 v7, v11, v10
	v_cvt_pk_bf16_f32 v1, v1, v2
	v_cvt_pk_bf16_f32 v2, v8, v5
	v_mad_i64_i32 v[4:5], s[0:1], v4, s47, v[112:113]
	v_mul_f32_e32 v3, v7, v3
	v_lshl_add_u64 v[4:5], v[4:5], 0, v[114:115]
	s_mov_b32 s53, s10
	s_mov_b32 s18, s12
	s_mov_b64 s[50:51], s[16:17]
	s_mov_b64 s[36:37], s[14:15]
	v_cvt_pk_bf16_f32 v3, v6, v3
	global_store_dwordx4 v[4:5], v[0:3], off
	s_cbranch_vccz .LBB0_983
	s_waitcnt vmcnt(0)
	s_cmpk_gt_u32 s20, 0xff
	s_cbranch_scc1 .LBB0_990
	s_barrier

.LBB0_1159:
	v_add_co_u32_e32 v4, vcc, 0xfffff000, v116
	s_add_i32 s5, s22, s0
	s_nop 0
	v_addc_co_u32_e32 v5, vcc, -1, v117, vcc
	s_cmpk_lt_i32 s5, 0x2000
	global_load_dwordx4 v[32:35], v[116:117], off offset:-4096
	global_load_dwordx4 v[24:27], v[116:117], off offset:-3072
	global_load_dwordx4 v[16:19], v[116:117], off offset:-2048
	global_load_dwordx4 v[8:11], v[116:117], off offset:-1024
	global_load_dwordx4 v[0:3], v[116:117], off
	global_load_dwordx4 v[56:59], v[4:5], off offset:-3072
	global_load_dwordx4 v[48:51], v[4:5], off offset:-2048
	global_load_dwordx4 v[40:43], v[4:5], off offset:-1024
	s_cselect_b64 s[18:19], -1, 0
	s_and_b64 s[6:7], s[18:19], exec
	s_cselect_b32 s6, s5, s0
	s_ashr_i32 s7, s6, 31
	s_lshl_b64 s[6:7], s[6:7], 13
	v_lshl_add_u64 v[4:5], v[66:67], 0, s[6:7]
	global_load_dwordx4 v[60:63], v[4:5], off
	global_load_dwordx4 v[52:55], v[4:5], off offset:1024
	global_load_dwordx4 v[44:47], v[4:5], off offset:2048
	global_load_dwordx4 v[36:39], v[4:5], off offset:3072
	v_add_co_u32_e32 v4, vcc, s1, v4
	s_cmpk_gt_i32 s5, 0x1fff
	s_nop 0
	v_addc_co_u32_e32 v5, vcc, 0, v5, vcc
	global_load_dwordx4 v[28:31], v[4:5], off
	global_load_dwordx4 v[20:23], v[4:5], off offset:1024
	global_load_dwordx4 v[12:15], v[4:5], off offset:2048
	s_nop 0
	global_load_dwordx4 v[4:7], v[4:5], off offset:3072
	s_waitcnt vmcnt(15)
	v_mul_f32_e32 v130, v33, v33
	s_waitcnt vmcnt(14)
	v_mul_f32_e32 v131, v25, v25
	v_fmac_f32_e32 v130, v32, v32
	s_waitcnt vmcnt(10)
	v_mul_f32_e32 v133, v57, v57
	s_waitcnt vmcnt(9)
	v_mul_f32_e32 v134, v49, v49
	s_waitcnt vmcnt(8)
	v_mul_f32_e32 v135, v41, v41
	v_fmac_f32_e32 v133, v56, v56
	v_fmac_f32_e32 v134, v48, v48
	v_fmac_f32_e32 v135, v40, v40
	v_fmac_f32_e32 v133, v58, v58
	v_fmac_f32_e32 v134, v50, v50
	v_fmac_f32_e32 v135, v42, v42
	v_fmac_f32_e32 v133, v59, v59
	v_fmac_f32_e32 v134, v51, v51
	v_fmac_f32_e32 v135, v43, v43
	v_add_f32_e32 v133, v133, v134
	v_mul_f32_e32 v132, v17, v17
	v_fmac_f32_e32 v131, v24, v24
	v_fmac_f32_e32 v130, v34, v34
	v_add_f32_e32 v133, v133, v135
	s_waitcnt vmcnt(7)
	v_mul_f32_e32 v134, v61, v61
	s_waitcnt vmcnt(6)
	v_mul_f32_e32 v135, v53, v53
	v_mov_b32_e32 v120, v9
	v_mov_b32_e32 v121, v1
	v_fmac_f32_e32 v132, v16, v16
	v_fmac_f32_e32 v131, v26, v26
	v_fmac_f32_e32 v130, v35, v35
	s_waitcnt vmcnt(5)
	v_mul_f32_e32 v136, v45, v45
	v_fmac_f32_e32 v134, v60, v60
	v_fmac_f32_e32 v135, v52, v52
	v_mov_b32_e32 v118, v8
	v_mov_b32_e32 v119, v0
	v_pk_mul_f32 v[120:121], v[120:121], v[120:121]
	v_fmac_f32_e32 v132, v18, v18
	v_fmac_f32_e32 v131, v27, v27
	v_add_f32_e32 v130, v133, v130
	s_waitcnt vmcnt(4)
	v_mul_f32_e32 v133, v37, v37
	v_fmac_f32_e32 v136, v44, v44
	v_fmac_f32_e32 v134, v62, v62
	v_fmac_f32_e32 v135, v54, v54
	v_fmac_f32_e32 v132, v19, v19
	v_fmac_f32_e32 v133, v36, v36
	v_add_f32_e32 v130, v130, v131
	v_fmac_f32_e32 v136, v46, v46
	s_waitcnt vmcnt(3)
	v_mul_f32_e32 v131, v29, v29
	v_fmac_f32_e32 v134, v63, v63
	v_fmac_f32_e32 v135, v55, v55
	v_pk_fma_f32 v[118:119], v[118:119], v[118:119], v[120:121]
	v_mov_b32_e32 v120, v10
	v_mov_b32_e32 v121, v2
	v_fmac_f32_e32 v133, v38, v38
	v_add_f32_e32 v130, v130, v132
	s_waitcnt vmcnt(2)
	v_mul_f32_e32 v132, v21, v21
	v_fmac_f32_e32 v136, v47, v47
	v_fmac_f32_e32 v131, v28, v28
	v_add_f32_e32 v134, v134, v135
	v_pk_fma_f32 v[118:119], v[120:121], v[120:121], v[118:119]
	v_mov_b32_e32 v120, v11
	v_mov_b32_e32 v121, v3
	v_fmac_f32_e32 v133, v39, v39
	v_fmac_f32_e32 v132, v20, v20
	v_fmac_f32_e32 v131, v30, v30
	v_add_f32_e32 v134, v134, v136
	v_pk_fma_f32 v[118:119], v[120:121], v[120:121], v[118:119]
	v_fmac_f32_e32 v132, v22, v22
	v_fmac_f32_e32 v131, v31, v31
	v_add_f32_e32 v133, v134, v133
	v_add_f32_e32 v118, v130, v118
	v_fmac_f32_e32 v132, v23, v23
	v_add_f32_e32 v131, v133, v131
	v_add_f32_e32 v130, v118, v119
	v_add_f32_e32 v131, v131, v132
	ds_bpermute_b32 v132, v122, v130
	s_waitcnt vmcnt(1)
	v_mov_b32_e32 v120, v13
	s_waitcnt vmcnt(0)
	v_mov_b32_e32 v121, v5
	v_mov_b32_e32 v118, v12
	v_mov_b32_e32 v119, v4
	s_waitcnt lgkmcnt(0)
	v_add_f32_e32 v130, v130, v132
	ds_bpermute_b32 v132, v123, v130
	v_pk_mul_f32 v[120:121], v[120:121], v[120:121]
	v_mov_b64_e32 v[134:135], v[150:151]
	v_mov_b64_e32 v[136:137], v[152:153]
	v_pk_fma_f32 v[118:119], v[118:119], v[118:119], v[120:121]
	v_mov_b32_e32 v120, v14
	v_mov_b32_e32 v121, v6
	v_pk_fma_f32 v[118:119], v[120:121], v[120:121], v[118:119]
	v_mov_b32_e32 v120, v15
	v_mov_b32_e32 v121, v7
	v_pk_fma_f32 v[118:119], v[120:121], v[120:121], v[118:119]
	s_waitcnt lgkmcnt(0)
	v_add_f32_e32 v120, v130, v132
	v_add_f32_e32 v118, v131, v118
	v_mov_b64_e32 v[130:131], v[154:155]
	v_mov_b64_e32 v[132:133], v[156:157]
	v_mov_b64_e32 v[138:139], v[158:159]
	v_mov_b64_e32 v[140:141], v[160:161]
	ds_bpermute_b32 v121, v124, v120
	v_add_f32_e32 v118, v118, v119
	ds_bpermute_b32 v119, v122, v118
	s_waitcnt lgkmcnt(0)
	v_add_f32_e32 v120, v120, v121
	ds_bpermute_b32 v121, v125, v120
	v_add_f32_e32 v118, v118, v119
	ds_bpermute_b32 v119, v123, v118
	s_waitcnt lgkmcnt(0)
	v_add_f32_e32 v120, v120, v121
	ds_bpermute_b32 v121, v126, v120
	v_add_f32_e32 v118, v118, v119
	ds_bpermute_b32 v119, v124, v118
	s_waitcnt lgkmcnt(0)
	v_add_f32_e32 v120, v120, v121
	ds_bpermute_b32 v121, v127, v120
	v_add_f32_e32 v118, v118, v119
	ds_bpermute_b32 v119, v125, v118
	s_waitcnt lgkmcnt(0)
	v_add_f32_e32 v120, v120, v121
	v_fmamk_f32 v120, v120, 0x3a000000, v128
	v_mul_f32_e32 v121, 0x4f800000, v120
	v_cmp_gt_f32_e32 vcc, s4, v120
	v_add_f32_e32 v118, v118, v119
	ds_bpermute_b32 v119, v126, v118
	v_cndmask_b32_e32 v120, v120, v121, vcc
	v_sqrt_f32_e32 v121, v120
	s_waitcnt lgkmcnt(0)
	v_add_f32_e32 v118, v118, v119
	v_add_u32_e32 v142, -1, v121
	v_fma_f32 v143, -v142, v121, v120
	v_cmp_ge_f32_e64 s[6:7], 0, v143
	v_add_u32_e32 v143, 1, v121
	ds_bpermute_b32 v119, v127, v118
	v_cndmask_b32_e64 v142, v121, v142, s[6:7]
	v_fma_f32 v121, -v143, v121, v120
	v_cmp_lt_f32_e64 s[6:7], 0, v121
	s_waitcnt lgkmcnt(0)
	v_add_f32_e32 v118, v118, v119
	v_cndmask_b32_e64 v121, v142, v143, s[6:7]
	v_mul_f32_e32 v142, 0x37800000, v121
	v_cndmask_b32_e32 v121, v121, v142, vcc
	v_cmp_class_f32_e32 vcc, v120, v129
	v_fmamk_f32 v118, v118, 0x3a000000, v128
	v_mul_f32_e32 v144, 0x4f800000, v118
	v_cndmask_b32_e32 v120, v121, v120, vcc
	v_div_scale_f32 v121, s[6:7], v120, v120, 1.0
	v_rcp_f32_e32 v142, v121
	v_cmp_gt_f32_e64 s[6:7], s4, v118
	v_fma_f32 v119, -v121, v142, 1.0
	s_nop 0
	v_cndmask_b32_e64 v118, v118, v144, s[6:7]
	v_fmac_f32_e32 v142, v119, v142
	v_div_scale_f32 v119, vcc, 1.0, v120, 1.0
	v_sqrt_f32_e32 v144, v118
	v_mul_f32_e32 v143, v119, v142
	v_fma_f32 v145, -v121, v143, v119
	v_fmac_f32_e32 v143, v145, v142
	v_fma_f32 v119, -v121, v143, v119
	v_add_u32_e32 v121, -1, v144
	v_fma_f32 v145, -v121, v144, v118
	v_cmp_ge_f32_e64 s[8:9], 0, v145
	v_add_u32_e32 v145, 1, v144
	v_div_fmas_f32 v119, v119, v142, v143
	v_cndmask_b32_e64 v121, v144, v121, s[8:9]
	v_fma_f32 v144, -v145, v144, v118
	v_cmp_lt_f32_e64 s[8:9], 0, v144
	v_div_fixup_f32 v120, v119, v120, 1.0
	v_pk_add_f32 v[132:133], v[132:133], 1.0 op_sel_hi:[1,0]
	v_cndmask_b32_e64 v121, v121, v145, s[8:9]
	v_mul_f32_e32 v144, 0x37800000, v121
	v_cndmask_b32_e64 v121, v121, v144, s[6:7]
	v_cmp_class_f32_e64 s[6:7], v118, v129
	v_pk_add_f32 v[130:131], v[130:131], 1.0 op_sel_hi:[1,0]
	v_pk_mul_f32 v[132:133], v[136:137], v[132:133]
	v_cndmask_b32_e64 v118, v121, v118, s[6:7]
	v_div_scale_f32 v121, s[6:7], v118, v118, 1.0
	v_rcp_f32_e32 v144, v121
	v_pk_mul_f32 v[130:131], v[134:135], v[130:131]
	v_pk_mul_f32 v[56:57], v[120:121], v[56:57] op_sel_hi:[0,1]
	v_pk_mul_f32 v[58:59], v[120:121], v[58:59] op_sel_hi:[0,1]
	v_fma_f32 v119, -v121, v144, 1.0
	v_fmac_f32_e32 v144, v119, v144
	v_div_scale_f32 v119, vcc, 1.0, v118, 1.0
	v_mul_f32_e32 v142, v119, v144
	v_fma_f32 v143, -v121, v142, v119
	v_fmac_f32_e32 v142, v143, v144
	v_fma_f32 v119, -v121, v142, v119
	v_div_fmas_f32 v119, v119, v144, v142
	v_div_fixup_f32 v118, v119, v118, 1.0
	v_pk_fma_f32 v[58:59], v[132:133], v[58:59], v[140:141]
	v_pk_fma_f32 v[56:57], v[130:131], v[56:57], v[138:139]
	v_pk_mul_f32 v[60:61], v[118:119], v[60:61] op_sel_hi:[0,1]
	v_pk_mul_f32 v[62:63], v[118:119], v[62:63] op_sel_hi:[0,1]
	v_pk_fma_f32 v[60:61], v[130:131], v[60:61], v[138:139]
	v_cvt_pk_bf16_f32 v56, v56, v57
	v_cvt_pk_bf16_f32 v57, v58, v59
	v_lshl_add_u64 v[58:59], s[14:15], 0, v[64:65]
	v_pk_fma_f32 v[62:63], v[132:133], v[62:63], v[140:141]
	v_cvt_pk_bf16_f32 v60, v60, v61
	v_cvt_pk_bf16_f32 v61, v62, v63
	global_store_dwordx2 v[58:59], v[56:57], off offset:-2048
	v_lshl_add_u64 v[56:57], s[10:11], 0, v[64:65]
	s_cbranch_scc1 .LBB0_1161
	v_add_co_u32_e32 v62, vcc, 0x7200000, v56
	s_nop 1
	v_addc_co_u32_e32 v63, vcc, 0, v57, vcc
	global_store_dwordx2 v[62:63], v[60:61], off
.LBB0_1161:
	v_mov_b64_e32 v[130:131], v[162:163]
	v_mov_b64_e32 v[132:133], v[164:165]
	v_mov_b64_e32 v[134:135], v[166:167]
	v_mov_b64_e32 v[136:137], v[168:169]
	v_mov_b64_e32 v[138:139], v[170:171]
	v_mov_b64_e32 v[140:141], v[172:173]
	v_mov_b32_e32 v121, v120
	v_mov_b32_e32 v119, v118
	v_mov_b32_e32 v60, v120
	v_mov_b32_e32 v61, v120
	v_mov_b32_e32 v62, v118
	v_mov_b32_e32 v63, v118
	v_cndmask_b32_e64 v142, 0, 1, s[18:19]
	v_pk_mul_f32 v[48:49], v[120:121], v[48:49]
	v_pk_mul_f32 v[50:51], v[60:61], v[50:51]
	v_pk_mul_f32 v[54:55], v[62:63], v[54:55]
	v_pk_mul_f32 v[52:53], v[118:119], v[52:53]
	v_cmp_ne_u32_e64 s[6:7], 1, v142
	s_andn2_b64 vcc, exec, s[18:19]
	v_pk_add_f32 v[130:131], v[130:131], 1.0 op_sel_hi:[1,0]
	v_pk_add_f32 v[132:133], v[132:133], 1.0 op_sel_hi:[1,0]
	s_waitcnt lgkmcnt(0)
	v_pk_mul_f32 v[130:131], v[134:135], v[130:131]
	v_pk_mul_f32 v[132:133], v[136:137], v[132:133]
	v_pk_fma_f32 v[48:49], v[130:131], v[48:49], v[138:139]
	v_pk_fma_f32 v[50:51], v[132:133], v[50:51], v[140:141]
	v_pk_fma_f32 v[54:55], v[132:133], v[54:55], v[140:141]
	v_pk_fma_f32 v[52:53], v[130:131], v[52:53], v[138:139]
	v_cvt_pk_bf16_f32 v130, v48, v49
	v_cvt_pk_bf16_f32 v131, v50, v51
	v_cvt_pk_bf16_f32 v48, v52, v53
	v_cvt_pk_bf16_f32 v49, v54, v55
	global_store_dwordx2 v[58:59], v[130:131], off offset:-1536
	s_cbranch_vccnz .LBB0_1163
	v_add_co_u32_e32 v50, vcc, 0x7200000, v56
	s_nop 1
	v_addc_co_u32_e32 v51, vcc, 0, v57, vcc
	global_store_dwordx2 v[50:51], v[48:49], off offset:512
.LBB0_1163:
	v_mov_b64_e32 v[48:49], v[174:175]
	v_mov_b64_e32 v[50:51], v[176:177]
	s_nop 0
	v_mov_b64_e32 v[52:53], v[178:179]
	v_mov_b64_e32 v[54:55], v[180:181]
	v_mov_b64_e32 v[130:131], v[182:183]
	v_mov_b64_e32 v[132:133], v[184:185]
	v_pk_mul_f32 v[40:41], v[120:121], v[40:41]
	v_pk_mul_f32 v[42:43], v[60:61], v[42:43]
	v_pk_mul_f32 v[46:47], v[62:63], v[46:47]
	v_pk_mul_f32 v[44:45], v[118:119], v[44:45]
	s_and_b64 vcc, exec, s[6:7]
	v_pk_add_f32 v[48:49], v[48:49], 1.0 op_sel_hi:[1,0]
	v_pk_add_f32 v[50:51], v[50:51], 1.0 op_sel_hi:[1,0]
	s_waitcnt lgkmcnt(0)
	v_pk_mul_f32 v[48:49], v[52:53], v[48:49]
	v_pk_mul_f32 v[50:51], v[54:55], v[50:51]
	v_pk_fma_f32 v[40:41], v[48:49], v[40:41], v[130:131]
	v_pk_fma_f32 v[42:43], v[50:51], v[42:43], v[132:133]
	v_pk_fma_f32 v[46:47], v[50:51], v[46:47], v[132:133]
	v_pk_fma_f32 v[44:45], v[48:49], v[44:45], v[130:131]
	v_cvt_pk_bf16_f32 v48, v40, v41
	v_cvt_pk_bf16_f32 v49, v42, v43
	v_cvt_pk_bf16_f32 v40, v44, v45
	v_cvt_pk_bf16_f32 v41, v46, v47
	global_store_dwordx2 v[58:59], v[48:49], off offset:-1024
	s_cbranch_vccnz .LBB0_1165
	v_add_co_u32_e32 v42, vcc, 0x7200000, v56
	s_nop 1
	v_addc_co_u32_e32 v43, vcc, 0, v57, vcc
	global_store_dwordx2 v[42:43], v[40:41], off offset:1024
.LBB0_1165:
	v_mov_b64_e32 v[42:43], v[186:187]
	v_mov_b64_e32 v[44:45], v[188:189]
	s_nop 0
	v_mov_b64_e32 v[46:47], v[190:191]
	v_mov_b64_e32 v[48:49], v[192:193]
	v_mov_b64_e32 v[50:51], v[194:195]
	v_mov_b64_e32 v[52:53], v[196:197]
	v_mov_b32_e32 v40, v120
	v_mov_b32_e32 v41, v120
	v_pk_mul_f32 v[54:55], v[120:121], v[32:33]
	v_mov_b32_e32 v32, v118
	v_mov_b32_e32 v33, v118
	v_pk_mul_f32 v[34:35], v[40:41], v[34:35]
	v_pk_mul_f32 v[36:37], v[118:119], v[36:37]
	v_pk_mul_f32 v[38:39], v[32:33], v[38:39]
	s_and_b64 vcc, exec, s[6:7]
	v_pk_add_f32 v[44:45], v[44:45], 1.0 op_sel_hi:[1,0]
	v_pk_add_f32 v[42:43], v[42:43], 1.0 op_sel_hi:[1,0]
	s_waitcnt lgkmcnt(0)
	v_pk_mul_f32 v[44:45], v[48:49], v[44:45]
	v_pk_mul_f32 v[42:43], v[46:47], v[42:43]
	v_pk_fma_f32 v[34:35], v[44:45], v[34:35], v[52:53]
	v_pk_fma_f32 v[46:47], v[42:43], v[54:55], v[50:51]
	v_pk_fma_f32 v[38:39], v[44:45], v[38:39], v[52:53]
	v_pk_fma_f32 v[36:37], v[42:43], v[36:37], v[50:51]
	v_cvt_pk_bf16_f32 v42, v46, v47
	v_cvt_pk_bf16_f32 v43, v34, v35
	v_cvt_pk_bf16_f32 v34, v36, v37
	v_cvt_pk_bf16_f32 v35, v38, v39
	global_store_dwordx2 v[58:59], v[42:43], off offset:-512
	s_cbranch_vccnz .LBB0_1167
	v_add_co_u32_e32 v36, vcc, 0x7200000, v56
	s_nop 1
	v_addc_co_u32_e32 v37, vcc, 0, v57, vcc
	global_store_dwordx2 v[36:37], v[34:35], off offset:1536
.LBB0_1167:
	v_mov_b64_e32 v[34:35], v[198:199]
	v_mov_b64_e32 v[36:37], v[200:201]
	s_nop 0
	v_mov_b64_e32 v[42:43], v[202:203]
	v_mov_b64_e32 v[44:45], v[204:205]
	v_mov_b64_e32 v[46:47], v[206:207]
	v_mov_b64_e32 v[48:49], v[208:209]
	v_pk_mul_f32 v[24:25], v[120:121], v[24:25]
	v_pk_mul_f32 v[30:31], v[32:33], v[30:31]
	v_pk_mul_f32 v[26:27], v[40:41], v[26:27]
	v_pk_mul_f32 v[28:29], v[118:119], v[28:29]
	s_and_b64 vcc, exec, s[6:7]
	v_pk_add_f32 v[34:35], v[34:35], 1.0 op_sel_hi:[1,0]
	v_pk_add_f32 v[32:33], v[36:37], 1.0 op_sel_hi:[1,0]
	s_waitcnt lgkmcnt(0)
	v_pk_mul_f32 v[34:35], v[42:43], v[34:35]
	v_pk_mul_f32 v[32:33], v[44:45], v[32:33]
	v_pk_fma_f32 v[24:25], v[34:35], v[24:25], v[46:47]
	v_pk_fma_f32 v[26:27], v[32:33], v[26:27], v[48:49]
	v_pk_fma_f32 v[30:31], v[32:33], v[30:31], v[48:49]
	v_pk_fma_f32 v[28:29], v[34:35], v[28:29], v[46:47]
	v_cvt_pk_bf16_f32 v32, v24, v25
	v_cvt_pk_bf16_f32 v33, v26, v27
	v_cvt_pk_bf16_f32 v24, v28, v29
	v_cvt_pk_bf16_f32 v25, v30, v31
	global_store_dwordx2 v[58:59], v[32:33], off
	s_cbranch_vccnz .LBB0_1169
	v_add_co_u32_e32 v26, vcc, 0x7200000, v56
	s_nop 1
	v_addc_co_u32_e32 v27, vcc, 0, v57, vcc
	global_store_dwordx2 v[26:27], v[24:25], off offset:2048
.LBB0_1169:
	v_mov_b64_e32 v[26:27], v[210:211]
	v_mov_b64_e32 v[28:29], v[212:213]
	s_nop 0
	v_mov_b64_e32 v[30:31], v[214:215]
	v_mov_b64_e32 v[32:33], v[216:217]
	v_mov_b64_e32 v[34:35], v[218:219]
	v_mov_b64_e32 v[36:37], v[220:221]
	v_mov_b32_e32 v24, v120
	v_mov_b32_e32 v25, v120
	v_pk_mul_f32 v[38:39], v[120:121], v[16:17]
	v_mov_b32_e32 v16, v118
	v_mov_b32_e32 v17, v118
	v_pk_mul_f32 v[18:19], v[24:25], v[18:19]
	v_pk_mul_f32 v[20:21], v[118:119], v[20:21]
	v_pk_mul_f32 v[22:23], v[16:17], v[22:23]
	s_and_b64 vcc, exec, s[6:7]
	v_pk_add_f32 v[28:29], v[28:29], 1.0 op_sel_hi:[1,0]
	v_pk_add_f32 v[26:27], v[26:27], 1.0 op_sel_hi:[1,0]
	s_waitcnt lgkmcnt(0)
	v_pk_mul_f32 v[28:29], v[32:33], v[28:29]
	v_pk_mul_f32 v[26:27], v[30:31], v[26:27]
	v_pk_fma_f32 v[18:19], v[28:29], v[18:19], v[36:37]
	v_pk_fma_f32 v[30:31], v[26:27], v[38:39], v[34:35]
	v_pk_fma_f32 v[22:23], v[28:29], v[22:23], v[36:37]
	v_pk_fma_f32 v[20:21], v[26:27], v[20:21], v[34:35]
	v_cvt_pk_bf16_f32 v26, v30, v31
	v_cvt_pk_bf16_f32 v27, v18, v19
	v_cvt_pk_bf16_f32 v18, v20, v21
	v_cvt_pk_bf16_f32 v19, v22, v23
	global_store_dwordx2 v[58:59], v[26:27], off offset:512
	s_cbranch_vccnz .LBB0_1171
	v_add_co_u32_e32 v20, vcc, 0x7200000, v56
	s_nop 1
	v_addc_co_u32_e32 v21, vcc, 0, v57, vcc
	global_store_dwordx2 v[20:21], v[18:19], off offset:2560
.LBB0_1171:
	v_mov_b64_e32 v[18:19], v[222:223]
	v_mov_b64_e32 v[20:21], v[224:225]
	s_nop 0
	v_mov_b64_e32 v[26:27], v[226:227]
	v_mov_b64_e32 v[28:29], v[228:229]
	v_mov_b64_e32 v[30:31], v[230:231]
	v_mov_b64_e32 v[32:33], v[232:233]
	v_pk_mul_f32 v[8:9], v[120:121], v[8:9]
	v_pk_mul_f32 v[14:15], v[16:17], v[14:15]
	v_pk_mul_f32 v[10:11], v[24:25], v[10:11]
	v_pk_mul_f32 v[12:13], v[118:119], v[12:13]
	s_and_b64 vcc, exec, s[6:7]
	v_pk_add_f32 v[18:19], v[18:19], 1.0 op_sel_hi:[1,0]
	v_pk_add_f32 v[16:17], v[20:21], 1.0 op_sel_hi:[1,0]
	s_waitcnt lgkmcnt(0)
	v_pk_mul_f32 v[18:19], v[26:27], v[18:19]
	v_pk_mul_f32 v[16:17], v[28:29], v[16:17]
	v_pk_fma_f32 v[8:9], v[18:19], v[8:9], v[30:31]
	v_pk_fma_f32 v[10:11], v[16:17], v[10:11], v[32:33]
	v_pk_fma_f32 v[14:15], v[16:17], v[14:15], v[32:33]
	v_pk_fma_f32 v[12:13], v[18:19], v[12:13], v[30:31]
	v_cvt_pk_bf16_f32 v16, v8, v9
	v_cvt_pk_bf16_f32 v17, v10, v11
	v_cvt_pk_bf16_f32 v8, v12, v13
	v_cvt_pk_bf16_f32 v9, v14, v15
	global_store_dwordx2 v[58:59], v[16:17], off offset:1024
	s_cbranch_vccnz .LBB0_1173
	v_add_co_u32_e32 v10, vcc, 0x7200000, v56
	s_nop 1
	v_addc_co_u32_e32 v11, vcc, 0, v57, vcc
	global_store_dwordx2 v[10:11], v[8:9], off offset:3072
.LBB0_1173:
	v_mov_b64_e32 v[8:9], v[234:235]
	v_mov_b64_e32 v[10:11], v[236:237]
	s_nop 0
	v_mov_b64_e32 v[12:13], v[238:239]
	v_mov_b64_e32 v[14:15], v[240:241]
	v_mov_b64_e32 v[16:17], v[242:243]
	v_mov_b64_e32 v[18:19], v[244:245]
	v_mov_b32_e32 v20, v120
	v_mov_b32_e32 v21, v120
	v_pk_mul_f32 v[0:1], v[120:121], v[0:1]
	v_mov_b32_e32 v22, v118
	v_mov_b32_e32 v23, v118
	v_pk_mul_f32 v[4:5], v[118:119], v[4:5]
	v_pk_mul_f32 v[2:3], v[20:21], v[2:3]
	v_pk_mul_f32 v[6:7], v[22:23], v[6:7]
	s_and_b64 vcc, exec, s[6:7]
	v_pk_add_f32 v[8:9], v[8:9], 1.0 op_sel_hi:[1,0]
	v_pk_add_f32 v[10:11], v[10:11], 1.0 op_sel_hi:[1,0]
	s_waitcnt lgkmcnt(0)
	v_pk_mul_f32 v[8:9], v[12:13], v[8:9]
	v_pk_mul_f32 v[10:11], v[14:15], v[10:11]
	v_pk_fma_f32 v[0:1], v[8:9], v[0:1], v[16:17]
	v_pk_fma_f32 v[2:3], v[10:11], v[2:3], v[18:19]
	v_pk_fma_f32 v[6:7], v[10:11], v[6:7], v[18:19]
	v_pk_fma_f32 v[4:5], v[8:9], v[4:5], v[16:17]
	v_cvt_pk_bf16_f32 v8, v0, v1
	v_cvt_pk_bf16_f32 v9, v2, v3
	v_cvt_pk_bf16_f32 v0, v4, v5
	v_cvt_pk_bf16_f32 v1, v6, v7
	global_store_dwordx2 v[58:59], v[8:9], off offset:1536
	s_cbranch_vccnz .LBB0_1158
	v_add_co_u32_e32 v2, vcc, 0x7200000, v56
	s_nop 1
	v_addc_co_u32_e32 v3, vcc, 0, v57, vcc
	global_store_dwordx2 v[2:3], v[0:1], off offset:3584
	s_branch .LBB0_1158

.LBB0_1234:
	ds_read_b128 v[128:131], v171
	ds_read_b128 v[132:135], v171 offset:1024
	ds_read_b128 v[152:155], v171 offset:2048
	ds_read_b128 v[156:159], v171 offset:3072
	s_add_u32 s4, s46, 0xfff80080
	s_addc_u32 s5, s47, -1
	s_cmp_eq_u32 s64, 28
	s_cselect_b32 s5, s0, s5
	s_cselect_b32 s4, s1, s4
	s_cselect_b32 s59, s13, s37
	s_cselect_b32 s58, s15, s36
	s_add_i32 m0, s21, 0xc000
	ds_read_b128 v[160:163], v172
	ds_read_b128 v[164:167], v172 offset:1024
	ds_read_b128 v[174:177], v172 offset:2048
	ds_read_b128 v[178:181], v172 offset:3072
	ds_read_b128 v[182:185], v172 offset:4096
	ds_read_b128 v[186:189], v172 offset:5120
	ds_read_b128 v[190:193], v172 offset:6144
	ds_read_b128 v[194:197], v172 offset:7168
	global_load_lds_dwordx4 v144, s[46:47]
	s_add_i32 m0, s21, 0xe000
	s_nop 0
	global_load_lds_dwordx4 v146, s[46:47]
	s_waitcnt lgkmcnt(8)
	s_barrier
	s_waitcnt lgkmcnt(0)
	s_waitcnt lgkmcnt(0)
	v_mfma_f32_16x16x32_bf16 v[124:127], v[128:131], v[160:163], v[124:127]
	v_mfma_f32_16x16x32_bf16 v[120:123], v[152:155], v[160:163], v[120:123]
	v_mfma_f32_16x16x32_bf16 v[116:119], v[128:131], v[174:177], v[116:119]
	v_mfma_f32_16x16x32_bf16 v[112:115], v[152:155], v[174:177], v[112:115]
	v_mfma_f32_16x16x32_bf16 v[108:111], v[128:131], v[182:185], v[108:111]
	v_mfma_f32_16x16x32_bf16 v[104:107], v[152:155], v[182:185], v[104:107]
	v_mfma_f32_16x16x32_bf16 v[100:103], v[128:131], v[190:193], v[100:103]
	v_mfma_f32_16x16x32_bf16 v[96:99], v[152:155], v[190:193], v[96:99]
	v_mfma_f32_16x16x32_bf16 v[124:127], v[132:135], v[164:167], v[124:127]
	v_mfma_f32_16x16x32_bf16 v[120:123], v[156:159], v[164:167], v[120:123]
	v_mfma_f32_16x16x32_bf16 v[116:119], v[132:135], v[178:181], v[116:119]
	v_mfma_f32_16x16x32_bf16 v[112:115], v[156:159], v[178:181], v[112:115]
	v_mfma_f32_16x16x32_bf16 v[108:111], v[132:135], v[186:189], v[108:111]
	v_mfma_f32_16x16x32_bf16 v[104:107], v[156:159], v[186:189], v[104:107]
	v_mfma_f32_16x16x32_bf16 v[100:103], v[132:135], v[194:197], v[100:103]
	v_mfma_f32_16x16x32_bf16 v[96:99], v[156:159], v[194:197], v[96:99]
	s_barrier
	s_add_i32 s42, s60, s24
	s_add_u32 s98, s58, s10
	s_addc_u32 s99, s59, s11
	s_mov_b32 m0, s42
	ds_read_b128 v[198:201], v173
	ds_read_b128 v[202:205], v173 offset:1024
	ds_read_b128 v[206:209], v173 offset:2048
	ds_read_b128 v[210:213], v173 offset:3072
	global_load_lds_dwordx4 v140, s[58:59]
	s_add_i32 m0, s42, 0x2000
	s_nop 0
	global_load_lds_dwordx4 v136, s[58:59]
	s_barrier
	s_waitcnt lgkmcnt(0)
	s_waitcnt lgkmcnt(0)
	v_mfma_f32_16x16x32_bf16 v[68:71], v[198:201], v[160:163], v[68:71]
	v_mfma_f32_16x16x32_bf16 v[64:67], v[206:209], v[160:163], v[64:67]
	v_mfma_f32_16x16x32_bf16 v[52:55], v[198:201], v[174:177], v[52:55]
	v_mfma_f32_16x16x32_bf16 v[48:51], v[206:209], v[174:177], v[48:51]
	v_mfma_f32_16x16x32_bf16 v[44:47], v[198:201], v[182:185], v[44:47]
	v_mfma_f32_16x16x32_bf16 v[40:43], v[206:209], v[182:185], v[40:43]
	v_mfma_f32_16x16x32_bf16 v[36:39], v[198:201], v[190:193], v[36:39]
	v_mfma_f32_16x16x32_bf16 v[32:35], v[206:209], v[190:193], v[32:35]
	v_mfma_f32_16x16x32_bf16 v[68:71], v[202:205], v[164:167], v[68:71]
	v_mfma_f32_16x16x32_bf16 v[64:67], v[210:213], v[164:167], v[64:67]
	v_mfma_f32_16x16x32_bf16 v[52:55], v[202:205], v[178:181], v[52:55]
	v_mfma_f32_16x16x32_bf16 v[48:51], v[210:213], v[178:181], v[48:51]
	v_mfma_f32_16x16x32_bf16 v[44:47], v[202:205], v[186:189], v[44:47]
	v_mfma_f32_16x16x32_bf16 v[40:43], v[210:213], v[186:189], v[40:43]
	v_mfma_f32_16x16x32_bf16 v[36:39], v[202:205], v[194:197], v[36:39]
	v_mfma_f32_16x16x32_bf16 v[32:35], v[210:213], v[194:197], v[32:35]
	s_mov_b32 m0, s21
	s_add_u32 s100, s4, s10
	s_addc_u32 s101, s5, s11
	s_barrier
	ds_read_b128 v[160:163], v172 offset:16384
	ds_read_b128 v[164:167], v172 offset:17408
	ds_read_b128 v[174:177], v172 offset:18432
	ds_read_b128 v[178:181], v172 offset:19456
	ds_read_b128 v[182:185], v172 offset:20480
	ds_read_b128 v[186:189], v172 offset:21504
	ds_read_b128 v[190:193], v172 offset:22528
	ds_read_b128 v[194:197], v172 offset:23552
	global_load_lds_dwordx4 v142, s[4:5]
	s_mov_b32 m0, s28
	s_nop 0
	global_load_lds_dwordx4 v138, s[4:5]
	s_barrier
	s_waitcnt lgkmcnt(0)
	s_waitcnt lgkmcnt(0)
	v_mfma_f32_16x16x32_bf16 v[92:95], v[128:131], v[160:163], v[92:95]
	v_mfma_f32_16x16x32_bf16 v[88:91], v[152:155], v[160:163], v[88:91]
	v_mfma_f32_16x16x32_bf16 v[84:87], v[128:131], v[174:177], v[84:87]
	v_mfma_f32_16x16x32_bf16 v[80:83], v[152:155], v[174:177], v[80:83]
	v_mfma_f32_16x16x32_bf16 v[76:79], v[128:131], v[182:185], v[76:79]
	v_mfma_f32_16x16x32_bf16 v[72:75], v[152:155], v[182:185], v[72:75]
	v_mfma_f32_16x16x32_bf16 v[60:63], v[128:131], v[190:193], v[60:63]
	v_mfma_f32_16x16x32_bf16 v[56:59], v[152:155], v[190:193], v[56:59]
	v_mfma_f32_16x16x32_bf16 v[92:95], v[132:135], v[164:167], v[92:95]
	v_mfma_f32_16x16x32_bf16 v[88:91], v[156:159], v[164:167], v[88:91]
	v_mfma_f32_16x16x32_bf16 v[84:87], v[132:135], v[178:181], v[84:87]
	v_mfma_f32_16x16x32_bf16 v[80:83], v[156:159], v[178:181], v[80:83]
	v_mfma_f32_16x16x32_bf16 v[76:79], v[132:135], v[186:189], v[76:79]
	v_mfma_f32_16x16x32_bf16 v[72:75], v[156:159], v[186:189], v[72:75]
	v_mfma_f32_16x16x32_bf16 v[60:63], v[132:135], v[194:197], v[60:63]
	v_mfma_f32_16x16x32_bf16 v[56:59], v[156:159], v[194:197], v[56:59]
	s_barrier
	s_add_u32 s42, s58, 0x80000
	s_addc_u32 s43, s59, 0
	s_add_i32 s44, s61, s24
	s_mov_b32 m0, s44
	s_nop 0
	global_load_lds_dwordx4 v140, s[42:43]
	s_add_i32 m0, s44, 0x2000
	s_nop 0
	global_load_lds_dwordx4 v136, s[42:43]
	s_waitcnt vmcnt(6)
	s_barrier
	v_mfma_f32_16x16x32_bf16 v[28:31], v[198:201], v[160:163], v[28:31]
	v_mfma_f32_16x16x32_bf16 v[24:27], v[206:209], v[160:163], v[24:27]
	v_mfma_f32_16x16x32_bf16 v[20:23], v[198:201], v[174:177], v[20:23]
	v_mfma_f32_16x16x32_bf16 v[16:19], v[206:209], v[174:177], v[16:19]
	v_mfma_f32_16x16x32_bf16 v[12:15], v[198:201], v[182:185], v[12:15]
	v_mfma_f32_16x16x32_bf16 v[8:11], v[206:209], v[182:185], v[8:11]
	v_mfma_f32_16x16x32_bf16 v[4:7], v[198:201], v[190:193], v[4:7]
	v_mfma_f32_16x16x32_bf16 v[0:3], v[206:209], v[190:193], v[0:3]
	v_mfma_f32_16x16x32_bf16 v[28:31], v[202:205], v[164:167], v[28:31]
	v_mfma_f32_16x16x32_bf16 v[24:27], v[210:213], v[164:167], v[24:27]
	v_mfma_f32_16x16x32_bf16 v[20:23], v[202:205], v[178:181], v[20:23]
	v_mfma_f32_16x16x32_bf16 v[16:19], v[210:213], v[178:181], v[16:19]
	v_mfma_f32_16x16x32_bf16 v[12:15], v[202:205], v[186:189], v[12:15]
	v_mfma_f32_16x16x32_bf16 v[8:11], v[210:213], v[186:189], v[8:11]
	v_mfma_f32_16x16x32_bf16 v[4:7], v[202:205], v[194:197], v[4:7]
	v_mfma_f32_16x16x32_bf16 v[0:3], v[210:213], v[194:197], v[0:3]
	s_add_i32 s42, 0, 0x18000
	v_add_u32_e32 v156, s42, v169
	s_barrier
	ds_read_b128 v[128:131], v156
	ds_read_b128 v[132:135], v156 offset:1024
	ds_read_b128 v[152:155], v156 offset:2048
	ds_read_b128 v[156:159], v156 offset:3072
	s_add_u32 s4, s4, 0x80000
	s_addc_u32 s5, s5, 0
	s_mov_b32 m0, s29
	ds_read_b128 v[160:163], v172 offset:32768
	ds_read_b128 v[164:167], v172 offset:33792
	ds_read_b128 v[174:177], v172 offset:34816
	ds_read_b128 v[178:181], v172 offset:35840
	ds_read_b128 v[182:185], v172 offset:36864
	ds_read_b128 v[186:189], v172 offset:37888
	ds_read_b128 v[190:193], v172 offset:38912
	ds_read_b128 v[194:197], v172 offset:39936
	global_load_lds_dwordx4 v142, s[4:5]
	s_mov_b32 m0, s33
	s_nop 0
	global_load_lds_dwordx4 v138, s[4:5]
	s_waitcnt lgkmcnt(8)
	s_barrier
	s_waitcnt lgkmcnt(0)
	s_waitcnt lgkmcnt(0)
	v_mfma_f32_16x16x32_bf16 v[124:127], v[128:131], v[160:163], v[124:127]
	v_mfma_f32_16x16x32_bf16 v[120:123], v[152:155], v[160:163], v[120:123]
	v_mfma_f32_16x16x32_bf16 v[116:119], v[128:131], v[174:177], v[116:119]
	v_mfma_f32_16x16x32_bf16 v[112:115], v[152:155], v[174:177], v[112:115]
	v_mfma_f32_16x16x32_bf16 v[108:111], v[128:131], v[182:185], v[108:111]
	v_mfma_f32_16x16x32_bf16 v[104:107], v[152:155], v[182:185], v[104:107]
	v_mfma_f32_16x16x32_bf16 v[100:103], v[128:131], v[190:193], v[100:103]
	v_mfma_f32_16x16x32_bf16 v[96:99], v[152:155], v[190:193], v[96:99]
	v_mfma_f32_16x16x32_bf16 v[124:127], v[132:135], v[164:167], v[124:127]
	v_mfma_f32_16x16x32_bf16 v[120:123], v[156:159], v[164:167], v[120:123]
	v_mfma_f32_16x16x32_bf16 v[116:119], v[132:135], v[178:181], v[116:119]
	v_mfma_f32_16x16x32_bf16 v[112:115], v[156:159], v[178:181], v[112:115]
	v_mfma_f32_16x16x32_bf16 v[108:111], v[132:135], v[186:189], v[108:111]
	v_mfma_f32_16x16x32_bf16 v[104:107], v[156:159], v[186:189], v[104:107]
	v_mfma_f32_16x16x32_bf16 v[100:103], v[132:135], v[194:197], v[100:103]
	v_mfma_f32_16x16x32_bf16 v[96:99], v[156:159], v[194:197], v[96:99]
	s_barrier
	s_add_i32 s43, 0, 0x1c000
	s_add_i32 s4, s42, s24
	v_add_u32_e32 v210, s43, v169
	s_mov_b32 m0, s4
	ds_read_b128 v[198:201], v210
	ds_read_b128 v[202:205], v210 offset:1024
	ds_read_b128 v[206:209], v210 offset:2048
	ds_read_b128 v[210:213], v210 offset:3072
	global_load_lds_dwordx4 v140, s[98:99]
	s_add_i32 m0, s4, 0x2000
	s_nop 0
	global_load_lds_dwordx4 v136, s[98:99]
	s_barrier
	s_waitcnt lgkmcnt(0)
	s_waitcnt lgkmcnt(0)
	v_mfma_f32_16x16x32_bf16 v[68:71], v[198:201], v[160:163], v[68:71]
	v_mfma_f32_16x16x32_bf16 v[64:67], v[206:209], v[160:163], v[64:67]
	v_mfma_f32_16x16x32_bf16 v[52:55], v[198:201], v[174:177], v[52:55]
	v_mfma_f32_16x16x32_bf16 v[48:51], v[206:209], v[174:177], v[48:51]
	v_mfma_f32_16x16x32_bf16 v[44:47], v[198:201], v[182:185], v[44:47]
	v_mfma_f32_16x16x32_bf16 v[40:43], v[206:209], v[182:185], v[40:43]
	v_mfma_f32_16x16x32_bf16 v[36:39], v[198:201], v[190:193], v[36:39]
	v_mfma_f32_16x16x32_bf16 v[32:35], v[206:209], v[190:193], v[32:35]
	v_mfma_f32_16x16x32_bf16 v[68:71], v[202:205], v[164:167], v[68:71]
	v_mfma_f32_16x16x32_bf16 v[64:67], v[210:213], v[164:167], v[64:67]
	v_mfma_f32_16x16x32_bf16 v[52:55], v[202:205], v[178:181], v[52:55]
	v_mfma_f32_16x16x32_bf16 v[48:51], v[210:213], v[178:181], v[48:51]
	v_mfma_f32_16x16x32_bf16 v[44:47], v[202:205], v[186:189], v[44:47]
	v_mfma_f32_16x16x32_bf16 v[40:43], v[210:213], v[186:189], v[40:43]
	v_mfma_f32_16x16x32_bf16 v[36:39], v[202:205], v[194:197], v[36:39]
	v_mfma_f32_16x16x32_bf16 v[32:35], v[210:213], v[194:197], v[32:35]
	s_mov_b32 m0, s41
	s_barrier
	ds_read_b128 v[160:163], v172 offset:49152
	ds_read_b128 v[164:167], v172 offset:50176
	ds_read_b128 v[174:177], v172 offset:51200
	ds_read_b128 v[178:181], v172 offset:52224
	ds_read_b128 v[182:185], v172 offset:53248
	ds_read_b128 v[186:189], v172 offset:54272
	ds_read_b128 v[190:193], v172 offset:55296
	ds_read_b128 v[194:197], v172 offset:56320
	global_load_lds_dwordx4 v142, s[100:101]
	s_mov_b32 m0, s53
	s_nop 0
	global_load_lds_dwordx4 v138, s[100:101]
	s_barrier
	s_waitcnt lgkmcnt(0)
	s_waitcnt lgkmcnt(0)
	v_mfma_f32_16x16x32_bf16 v[92:95], v[128:131], v[160:163], v[92:95]
	v_mfma_f32_16x16x32_bf16 v[88:91], v[152:155], v[160:163], v[88:91]
	v_mfma_f32_16x16x32_bf16 v[84:87], v[128:131], v[174:177], v[84:87]
	v_mfma_f32_16x16x32_bf16 v[80:83], v[152:155], v[174:177], v[80:83]
	v_mfma_f32_16x16x32_bf16 v[76:79], v[128:131], v[182:185], v[76:79]
	v_mfma_f32_16x16x32_bf16 v[72:75], v[152:155], v[182:185], v[72:75]
	v_mfma_f32_16x16x32_bf16 v[60:63], v[128:131], v[190:193], v[60:63]
	v_mfma_f32_16x16x32_bf16 v[56:59], v[152:155], v[190:193], v[56:59]
	v_mfma_f32_16x16x32_bf16 v[92:95], v[132:135], v[164:167], v[92:95]
	v_mfma_f32_16x16x32_bf16 v[88:91], v[156:159], v[164:167], v[88:91]
	v_mfma_f32_16x16x32_bf16 v[84:87], v[132:135], v[178:181], v[84:87]
	v_mfma_f32_16x16x32_bf16 v[80:83], v[156:159], v[178:181], v[80:83]
	v_mfma_f32_16x16x32_bf16 v[76:79], v[132:135], v[186:189], v[76:79]
	v_mfma_f32_16x16x32_bf16 v[72:75], v[156:159], v[186:189], v[72:75]
	v_mfma_f32_16x16x32_bf16 v[60:63], v[132:135], v[194:197], v[60:63]
	v_mfma_f32_16x16x32_bf16 v[56:59], v[156:159], v[194:197], v[56:59]
	s_barrier
	s_add_u32 s4, s58, 0x80080
	s_addc_u32 s5, s59, 0
	s_add_i32 s42, s43, s24
	s_mov_b32 m0, s42
	s_nop 0
	global_load_lds_dwordx4 v140, s[4:5]
	s_add_i32 m0, s42, 0x2000
	s_nop 0
	global_load_lds_dwordx4 v136, s[4:5]
	s_waitcnt vmcnt(6)
	s_barrier
	v_mfma_f32_16x16x32_bf16 v[28:31], v[198:201], v[160:163], v[28:31]
	v_mfma_f32_16x16x32_bf16 v[24:27], v[206:209], v[160:163], v[24:27]
	v_mfma_f32_16x16x32_bf16 v[20:23], v[198:201], v[174:177], v[20:23]
	v_mfma_f32_16x16x32_bf16 v[16:19], v[206:209], v[174:177], v[16:19]
	v_mfma_f32_16x16x32_bf16 v[12:15], v[198:201], v[182:185], v[12:15]
	v_mfma_f32_16x16x32_bf16 v[8:11], v[206:209], v[182:185], v[8:11]
	v_mfma_f32_16x16x32_bf16 v[4:7], v[198:201], v[190:193], v[4:7]
	v_mfma_f32_16x16x32_bf16 v[0:3], v[206:209], v[190:193], v[0:3]
	v_mfma_f32_16x16x32_bf16 v[28:31], v[202:205], v[164:167], v[28:31]
	v_mfma_f32_16x16x32_bf16 v[24:27], v[210:213], v[164:167], v[24:27]
	v_mfma_f32_16x16x32_bf16 v[20:23], v[202:205], v[178:181], v[20:23]
	v_mfma_f32_16x16x32_bf16 v[16:19], v[210:213], v[178:181], v[16:19]
	v_mfma_f32_16x16x32_bf16 v[12:15], v[202:205], v[186:189], v[12:15]
	v_mfma_f32_16x16x32_bf16 v[8:11], v[210:213], v[186:189], v[8:11]
	v_mfma_f32_16x16x32_bf16 v[4:7], v[202:205], v[194:197], v[4:7]
	v_mfma_f32_16x16x32_bf16 v[0:3], v[210:213], v[194:197], v[0:3]
	s_add_i32 s64, s64, 2
	s_add_u32 s46, s46, 0x100
	s_addc_u32 s47, s47, 0
	s_add_u32 s36, s36, 0x100
	s_addc_u32 s37, s37, 0
	s_cmp_gt_u32 s64, 29
	s_barrier
	s_cbranch_scc0 .LBB0_1234
	v_lshl_or_b32 v152, s63, 8, v170
	v_ashrrev_i32_e32 v153, 31, v152
	v_lshl_add_u64 v[164:165], v[152:153], 2, s[8:9]
	flat_load_dwordx4 v[132:135], v[164:165]
	flat_load_dwordx4 v[128:131], v[164:165] offset:16
	v_lshl_add_u32 v182, s20, 8, v168
	v_mov_b64_e32 v[166:167], s[48:49]
	v_add_u32_e32 v159, 0x80, v182
	v_mad_i64_i32 v[154:155], s[0:1], v182, s62, v[166:167]
	v_or_b32_e32 v156, 16, v182
	v_or_b32_e32 v157, 32, v182
	v_or_b32_e32 v158, 48, v182
	v_lshlrev_b64 v[174:175], 1, v[152:153]
	v_mad_i64_i32 v[178:179], s[0:1], v159, s62, v[166:167]
	v_add_u32_e32 v160, 0x90, v182
	v_mad_i64_i32 v[152:153], s[0:1], v156, s62, v[166:167]
	v_mad_i64_i32 v[156:157], s[0:1], v157, s62, v[166:167]
	v_mad_i64_i32 v[176:177], s[0:1], v158, s62, v[166:167]
	v_lshl_add_u64 v[162:163], v[154:155], 0, v[174:175]
	v_lshl_add_u64 v[154:155], v[178:179], 0, v[174:175]
	v_mad_i64_i32 v[180:181], s[0:1], v160, s62, v[166:167]
	v_lshl_add_u64 v[160:161], v[152:153], 0, v[174:175]
	v_lshl_add_u64 v[158:159], v[156:157], 0, v[174:175]
	v_lshl_add_u64 v[156:157], v[176:177], 0, v[174:175]
	v_lshl_add_u64 v[152:153], v[180:181], 0, v[174:175]
	s_and_b64 vcc, exec, s[6:7]
	s_mov_b32 s63, s12
	s_mov_b32 s20, s14
	s_mov_b64 s[58:59], s[18:19]
	s_mov_b64 s[36:37], s[16:17]
	s_waitcnt vmcnt(0) lgkmcnt(0)
	v_pk_add_f32 v[124:125], v[124:125], v[132:133]
	v_pk_add_f32 v[178:179], v[72:73], v[128:129]
	v_cvt_pk_bf16_f32 v72, v124, v125
	v_pk_add_f32 v[126:127], v[126:127], v[134:135]
	v_pk_add_f32 v[122:123], v[122:123], v[130:131]
	v_pk_add_f32 v[120:121], v[120:121], v[128:129]
	v_pk_add_f32 v[116:117], v[116:117], v[132:133]
	v_pk_add_f32 v[176:177], v[74:75], v[130:131]
	v_cvt_pk_bf16_f32 v73, v126, v127
	v_cvt_pk_bf16_f32 v74, v120, v121
	v_cvt_pk_bf16_f32 v75, v122, v123
	global_store_dwordx4 v[162:163], v[72:75], off
	v_pk_add_f32 v[118:119], v[118:119], v[134:135]
	v_pk_add_f32 v[114:115], v[114:115], v[130:131]
	v_cvt_pk_bf16_f32 v72, v116, v117
	v_pk_add_f32 v[112:113], v[112:113], v[128:129]
	v_pk_add_f32 v[108:109], v[108:109], v[132:133]
	v_cvt_pk_bf16_f32 v73, v118, v119
	v_cvt_pk_bf16_f32 v74, v112, v113
	v_cvt_pk_bf16_f32 v75, v114, v115
	global_store_dwordx4 v[160:161], v[72:75], off
	v_pk_add_f32 v[110:111], v[110:111], v[134:135]
	v_pk_add_f32 v[106:107], v[106:107], v[130:131]
	v_cvt_pk_bf16_f32 v72, v108, v109
	v_pk_add_f32 v[104:105], v[104:105], v[128:129]
	v_pk_add_f32 v[100:101], v[100:101], v[132:133]
	v_cvt_pk_bf16_f32 v73, v110, v111
	v_cvt_pk_bf16_f32 v74, v104, v105
	v_cvt_pk_bf16_f32 v75, v106, v107
	global_store_dwordx4 v[158:159], v[72:75], off
	v_pk_add_f32 v[102:103], v[102:103], v[134:135]
	v_pk_add_f32 v[98:99], v[98:99], v[130:131]
	v_cvt_pk_bf16_f32 v72, v100, v101
	v_pk_add_f32 v[96:97], v[96:97], v[128:129]
	v_pk_add_f32 v[92:93], v[92:93], v[132:133]
	v_cvt_pk_bf16_f32 v73, v102, v103
	v_cvt_pk_bf16_f32 v74, v96, v97
	v_cvt_pk_bf16_f32 v75, v98, v99
	global_store_dwordx4 v[156:157], v[72:75], off
	v_pk_add_f32 v[94:95], v[94:95], v[134:135]
	v_pk_add_f32 v[90:91], v[90:91], v[130:131]
	v_cvt_pk_bf16_f32 v72, v92, v93
	v_pk_add_f32 v[88:89], v[88:89], v[128:129]
	v_pk_add_f32 v[84:85], v[84:85], v[132:133]
	v_pk_add_f32 v[76:77], v[76:77], v[132:133]
	v_cvt_pk_bf16_f32 v73, v94, v95
	v_cvt_pk_bf16_f32 v74, v88, v89
	v_cvt_pk_bf16_f32 v75, v90, v91
	global_store_dwordx4 v[154:155], v[72:75], off
	v_pk_add_f32 v[86:87], v[86:87], v[134:135]
	v_pk_add_f32 v[82:83], v[82:83], v[130:131]
	v_cvt_pk_bf16_f32 v72, v84, v85
	v_pk_add_f32 v[80:81], v[80:81], v[128:129]
	v_cvt_pk_bf16_f32 v73, v86, v87
	v_pk_add_f32 v[78:79], v[78:79], v[134:135]
	v_cvt_pk_bf16_f32 v74, v80, v81
	v_cvt_pk_bf16_f32 v75, v82, v83
	global_store_dwordx4 v[152:153], v[72:75], off
	v_pk_add_f32 v[60:61], v[60:61], v[132:133]
	v_pk_add_f32 v[62:63], v[62:63], v[134:135]
	v_cvt_pk_bf16_f32 v72, v76, v77
	v_add_u32_e32 v76, 0xa0, v182
	v_mad_i64_i32 v[76:77], s[0:1], v76, s62, v[166:167]
	v_cvt_pk_bf16_f32 v73, v78, v79
	v_lshl_add_u64 v[76:77], v[76:77], 0, v[174:175]
	v_cvt_pk_bf16_f32 v74, v178, v179
	v_cvt_pk_bf16_f32 v75, v176, v177
	global_store_dwordx4 v[76:77], v[72:75], off
	s_nop 1
	v_pk_add_f32 v[72:73], v[58:59], v[130:131]
	v_pk_add_f32 v[58:59], v[56:57], v[128:129]
	v_cvt_pk_bf16_f32 v56, v60, v61
	v_add_u32_e32 v60, 0xb0, v182
	v_mad_i64_i32 v[60:61], s[0:1], v60, s62, v[166:167]
	v_cvt_pk_bf16_f32 v57, v62, v63
	v_cvt_pk_bf16_f32 v58, v58, v59
	v_cvt_pk_bf16_f32 v59, v72, v73
	v_lshl_add_u64 v[72:73], v[60:61], 0, v[174:175]
	global_store_dwordx4 v[72:73], v[56:59], off
	flat_load_dwordx4 v[56:59], v[164:165] offset:512
	s_nop 0
	flat_load_dwordx4 v[60:63], v[164:165] offset:528
	s_waitcnt vmcnt(0) lgkmcnt(0)
	v_pk_add_f32 v[70:71], v[70:71], v[58:59]
	v_pk_add_f32 v[68:69], v[68:69], v[56:57]
	v_pk_add_f32 v[66:67], v[66:67], v[62:63]
	v_pk_add_f32 v[64:65], v[64:65], v[60:61]
	v_pk_add_f32 v[54:55], v[54:55], v[58:59]
	v_pk_add_f32 v[52:53], v[52:53], v[56:57]
	v_pk_add_f32 v[46:47], v[46:47], v[58:59]
	v_pk_add_f32 v[44:45], v[44:45], v[56:57]
	v_pk_add_f32 v[38:39], v[38:39], v[58:59]
	v_pk_add_f32 v[36:37], v[36:37], v[56:57]
	v_pk_add_f32 v[30:31], v[30:31], v[58:59]
	v_pk_add_f32 v[28:29], v[28:29], v[56:57]
	v_pk_add_f32 v[22:23], v[22:23], v[58:59]
	v_pk_add_f32 v[20:21], v[20:21], v[56:57]
	v_pk_add_f32 v[14:15], v[14:15], v[58:59]
	v_pk_add_f32 v[12:13], v[12:13], v[56:57]
	v_pk_add_f32 v[6:7], v[6:7], v[58:59]
	v_pk_add_f32 v[4:5], v[4:5], v[56:57]
	v_pk_add_f32 v[56:57], v[2:3], v[62:63]
	v_pk_add_f32 v[58:59], v[0:1], v[60:61]
	v_cvt_pk_bf16_f32 v0, v68, v69
	v_cvt_pk_bf16_f32 v1, v70, v71
	v_cvt_pk_bf16_f32 v2, v64, v65
	v_cvt_pk_bf16_f32 v3, v66, v67
	v_pk_add_f32 v[50:51], v[50:51], v[62:63]
	v_pk_add_f32 v[48:49], v[48:49], v[60:61]
	global_store_dwordx4 v[162:163], v[0:3], off offset:256
	v_pk_add_f32 v[42:43], v[42:43], v[62:63]
	v_pk_add_f32 v[40:41], v[40:41], v[60:61]
	v_cvt_pk_bf16_f32 v0, v52, v53
	v_cvt_pk_bf16_f32 v1, v54, v55
	v_cvt_pk_bf16_f32 v2, v48, v49
	v_cvt_pk_bf16_f32 v3, v50, v51
	global_store_dwordx4 v[160:161], v[0:3], off offset:256
	v_pk_add_f32 v[34:35], v[34:35], v[62:63]
	v_pk_add_f32 v[32:33], v[32:33], v[60:61]
	v_cvt_pk_bf16_f32 v0, v44, v45
	v_cvt_pk_bf16_f32 v1, v46, v47
	v_cvt_pk_bf16_f32 v2, v40, v41
	v_cvt_pk_bf16_f32 v3, v42, v43
	global_store_dwordx4 v[158:159], v[0:3], off offset:256
	v_pk_add_f32 v[26:27], v[26:27], v[62:63]
	v_pk_add_f32 v[24:25], v[24:25], v[60:61]
	v_cvt_pk_bf16_f32 v0, v36, v37
	v_cvt_pk_bf16_f32 v1, v38, v39
	v_cvt_pk_bf16_f32 v2, v32, v33
	v_cvt_pk_bf16_f32 v3, v34, v35
	global_store_dwordx4 v[156:157], v[0:3], off offset:256
	v_pk_add_f32 v[18:19], v[18:19], v[62:63]
	v_pk_add_f32 v[16:17], v[16:17], v[60:61]
	v_cvt_pk_bf16_f32 v0, v28, v29
	v_cvt_pk_bf16_f32 v1, v30, v31
	v_cvt_pk_bf16_f32 v2, v24, v25
	v_cvt_pk_bf16_f32 v3, v26, v27
	global_store_dwordx4 v[154:155], v[0:3], off offset:256
	v_pk_add_f32 v[10:11], v[10:11], v[62:63]
	v_pk_add_f32 v[8:9], v[8:9], v[60:61]
	v_cvt_pk_bf16_f32 v0, v20, v21
	v_cvt_pk_bf16_f32 v1, v22, v23
	v_cvt_pk_bf16_f32 v2, v16, v17
	v_cvt_pk_bf16_f32 v3, v18, v19
	global_store_dwordx4 v[152:153], v[0:3], off offset:256
	s_nop 1
	v_cvt_pk_bf16_f32 v0, v12, v13
	v_cvt_pk_bf16_f32 v1, v14, v15
	v_cvt_pk_bf16_f32 v2, v8, v9
	v_cvt_pk_bf16_f32 v3, v10, v11
	global_store_dwordx4 v[76:77], v[0:3], off offset:256
	s_nop 1
	v_cvt_pk_bf16_f32 v0, v4, v5
	v_cvt_pk_bf16_f32 v1, v6, v7
	v_cvt_pk_bf16_f32 v2, v58, v59
	v_cvt_pk_bf16_f32 v3, v56, v57
	global_store_dwordx4 v[72:73], v[0:3], off offset:256
	s_cbranch_vccz .LBB0_1231
	s_waitcnt vmcnt(0)
	s_cmpk_gt_u32 s23, 0xff
	s_cbranch_scc1 .LBB0_1238
	s_barrier

.LBB0_1468:
	s_and_b32 s6, s0, 0x7c0
	v_add_u32_e32 v6, s6, v1
	s_and_b32 s4, s9, 0xffffff00
	v_ashrrev_i32_e32 v7, 31, v6
	s_ashr_i32 s5, s4, 31
	v_lshlrev_b64 v[6:7], 13, v[6:7]
	v_lshl_add_u64 v[6:7], v[6:7], 0, s[4:5]
	v_or_b32_e32 v6, v6, v0
	v_lshlrev_b64 v[10:11], 2, v[6:7]
	v_lshl_add_u64 v[12:13], s[26:27], 0, v[10:11]
	v_add_co_u32_e32 v38, vcc, s8, v12
	v_lshl_add_u64 v[6:7], s[48:49], 0, v[10:11]
	v_or_b32_e32 v14, 0x100, v10
	v_mov_b32_e32 v15, v11
	v_or_b32_e32 v16, 0x200, v10
	v_mov_b32_e32 v17, v11
	v_or_b32_e32 v10, 0x300, v10
	v_addc_co_u32_e32 v39, vcc, 0, v13, vcc
	global_load_dwordx4 v[6:9], v[6:7], off
	v_lshl_add_u64 v[40:41], s[48:49], 0, v[14:15]
	v_lshl_add_u64 v[42:43], s[48:49], 0, v[16:17]
	v_lshl_add_u64 v[44:45], s[48:49], 0, v[10:11]
	global_load_dwordx4 v[10:13], v[38:39], off offset:16
	global_load_dwordx4 v[14:17], v[40:41], off
	global_load_dwordx4 v[18:21], v[38:39], off offset:272
	global_load_dwordx4 v[22:25], v[42:43], off
	global_load_dwordx4 v[26:29], v[38:39], off offset:528
	global_load_dwordx4 v[30:33], v[44:45], off
	global_load_dwordx4 v[34:37], v[38:39], off offset:784
	v_add_u32_e32 v38, s4, v1
	s_lshl_b32 s6, s6, 1
	v_ashrrev_i32_e32 v39, 31, v38
	v_lshl_add_u64 v[40:41], v[2:3], 0, s[6:7]
	v_add_u32_e32 v42, 64, v38
	v_add_u32_e32 v44, 0x80, v38
	v_add_u32_e32 v46, 0xc0, v38
	v_lshlrev_b64 v[38:39], 12, v[38:39]
	v_lshl_add_u64 v[38:39], v[40:41], 0, v[38:39]
	v_ashrrev_i32_e32 v43, 31, v42
	v_lshlrev_b64 v[42:43], 12, v[42:43]
	v_lshl_add_u64 v[42:43], v[40:41], 0, v[42:43]
	v_ashrrev_i32_e32 v45, 31, v44
	v_lshlrev_b64 v[44:45], 12, v[44:45]
	v_lshl_add_u64 v[44:45], v[40:41], 0, v[44:45]
	v_ashrrev_i32_e32 v47, 31, v46
	s_add_i32 s10, s10, s30
	s_add_i32 s9, s9, s22
	s_add_i32 s0, s0, s1
	v_lshlrev_b64 v[46:47], 12, v[46:47]
	s_cmpk_gt_i32 s10, 0x3ff
	s_waitcnt vmcnt(7)
	ds_write2_b32 v4, v6, v7 offset1:1
	ds_write2_b32 v4, v8, v9 offset0:2 offset1:3
	s_waitcnt vmcnt(6)
	ds_write2_b32 v4, v10, v11 offset0:4 offset1:5
	ds_write2_b32 v4, v12, v13 offset0:6 offset1:7
	s_waitcnt vmcnt(5)
	ds_write2_b32 v4, v14, v15 offset0:64 offset1:65
	s_waitcnt vmcnt(4)
	ds_write2_b32 v4, v18, v19 offset0:68 offset1:69
	ds_write2_b32 v4, v16, v17 offset0:66 offset1:67
	ds_write2_b32 v4, v20, v21 offset0:70 offset1:71
	s_waitcnt vmcnt(3)
	ds_write2_b32 v4, v22, v23 offset0:128 offset1:129
	s_waitcnt vmcnt(2)
	ds_write2_b32 v4, v26, v27 offset0:132 offset1:133
	ds_write2_b32 v4, v24, v25 offset0:130 offset1:131
	ds_write2_b32 v4, v28, v29 offset0:134 offset1:135
	s_waitcnt vmcnt(1)
	ds_write2_b32 v4, v30, v31 offset0:192 offset1:193
	s_waitcnt vmcnt(0)
	ds_write2_b32 v4, v34, v35 offset0:196 offset1:197
	ds_write2_b32 v4, v32, v33 offset0:194 offset1:195
	ds_write2_b32 v4, v36, v37 offset0:198 offset1:199
	s_waitcnt lgkmcnt(0)
	s_barrier
	ds_read_b32 v6, v5 offset:1028
	ds_read_b32 v7, v5
	s_waitcnt lgkmcnt(0)
	v_cvt_pk_bf16_f32 v6, v7, v6
	ds_read_b32 v7, v5 offset:3084
	ds_read_b32 v8, v5 offset:2056
	s_waitcnt lgkmcnt(0)
	v_cvt_pk_bf16_f32 v7, v8, v7
	ds_read_b32 v8, v5 offset:5140
	ds_read_b32 v9, v5 offset:4112
	s_waitcnt lgkmcnt(0)
	v_cvt_pk_bf16_f32 v8, v9, v8
	ds_read_b32 v9, v5 offset:7196
	ds_read_b32 v10, v5 offset:6168
	s_waitcnt lgkmcnt(0)
	v_cvt_pk_bf16_f32 v9, v10, v9
	ds_read_b32 v10, v5 offset:1284
	ds_read_b32 v11, v5 offset:256
	global_store_dwordx4 v[38:39], v[6:9], off
	s_waitcnt lgkmcnt(0)
	s_nop 0
	v_cvt_pk_bf16_f32 v6, v11, v10
	ds_read_b32 v7, v5 offset:3340
	ds_read_b32 v8, v5 offset:2312
	s_waitcnt lgkmcnt(0)
	v_cvt_pk_bf16_f32 v7, v8, v7
	ds_read_b32 v8, v5 offset:5396
	ds_read_b32 v9, v5 offset:4368
	s_waitcnt lgkmcnt(0)
	v_cvt_pk_bf16_f32 v8, v9, v8
	ds_read_b32 v9, v5 offset:7452
	ds_read_b32 v10, v5 offset:6424
	s_waitcnt lgkmcnt(0)
	v_cvt_pk_bf16_f32 v9, v10, v9
	ds_read_b32 v10, v5 offset:1540
	ds_read_b32 v11, v5 offset:512
	global_store_dwordx4 v[42:43], v[6:9], off
	s_waitcnt lgkmcnt(0)
	s_nop 0
	v_cvt_pk_bf16_f32 v6, v11, v10
	ds_read_b32 v7, v5 offset:3596
	ds_read_b32 v8, v5 offset:2568
	s_waitcnt lgkmcnt(0)
	v_cvt_pk_bf16_f32 v7, v8, v7
	ds_read_b32 v8, v5 offset:5652
	ds_read_b32 v9, v5 offset:4624
	s_waitcnt lgkmcnt(0)
	v_cvt_pk_bf16_f32 v8, v9, v8
	ds_read_b32 v9, v5 offset:7708
	ds_read_b32 v10, v5 offset:6680
	s_waitcnt lgkmcnt(0)
	v_cvt_pk_bf16_f32 v9, v10, v9
	ds_read_b32 v10, v5 offset:1796
	ds_read_b32 v11, v5 offset:768
	global_store_dwordx4 v[44:45], v[6:9], off
	s_waitcnt lgkmcnt(0)
	s_nop 0
	v_cvt_pk_bf16_f32 v6, v11, v10
	ds_read_b32 v7, v5 offset:3852
	ds_read_b32 v8, v5 offset:2824
	s_waitcnt lgkmcnt(0)
	v_cvt_pk_bf16_f32 v7, v8, v7
	ds_read_b32 v8, v5 offset:5908
	ds_read_b32 v9, v5 offset:4880
	s_waitcnt lgkmcnt(0)
	v_cvt_pk_bf16_f32 v8, v9, v8
	ds_read_b32 v9, v5 offset:7964
	ds_read_b32 v12, v5 offset:6936
	v_lshl_add_u64 v[10:11], v[40:41], 0, v[46:47]
	s_waitcnt lgkmcnt(0)
	v_cvt_pk_bf16_f32 v9, v12, v9
	global_store_dwordx4 v[10:11], v[6:9], off
	s_barrier
	s_cbranch_scc0 .LBB0_1468

.LBB0_1676:
	ds_read_b128 v[150:153], v147
	ds_read_b128 v[154:157], v147 offset:1024
	ds_read_b128 v[158:161], v147 offset:2048
	ds_read_b128 v[162:165], v147 offset:3072
	s_add_u32 s4, s20, 0xfff80080
	s_addc_u32 s5, s21, -1
	s_cmp_eq_u32 s53, 28
	s_cselect_b32 s5, s0, s5
	s_cselect_b32 s4, s1, s4
	s_cselect_b32 s45, s11, s52
	s_cselect_b32 s44, s13, s51
	s_add_i32 m0, s19, 0xc000
	ds_read_b128 v[166:169], v148
	ds_read_b128 v[170:173], v148 offset:1024
	ds_read_b128 v[174:177], v148 offset:2048
	ds_read_b128 v[178:181], v148 offset:3072
	ds_read_b128 v[182:185], v148 offset:4096
	ds_read_b128 v[186:189], v148 offset:5120
	ds_read_b128 v[190:193], v148 offset:6144
	ds_read_b128 v[194:197], v148 offset:7168
	global_load_lds_dwordx4 v136, s[20:21]
	s_add_i32 m0, s19, 0xe000
	s_nop 0
	global_load_lds_dwordx4 v138, s[20:21]
	s_waitcnt lgkmcnt(8)
	s_barrier
	s_waitcnt lgkmcnt(0)
	s_waitcnt lgkmcnt(0)
	v_mfma_f32_16x16x32_bf16 v[124:127], v[150:153], v[166:169], v[124:127]
	v_mfma_f32_16x16x32_bf16 v[120:123], v[158:161], v[166:169], v[120:123]
	v_mfma_f32_16x16x32_bf16 v[108:111], v[150:153], v[174:177], v[108:111]
	v_mfma_f32_16x16x32_bf16 v[104:107], v[158:161], v[174:177], v[104:107]
	v_mfma_f32_16x16x32_bf16 v[92:95], v[150:153], v[182:185], v[92:95]
	v_mfma_f32_16x16x32_bf16 v[88:91], v[158:161], v[182:185], v[88:91]
	v_mfma_f32_16x16x32_bf16 v[76:79], v[150:153], v[190:193], v[76:79]
	v_mfma_f32_16x16x32_bf16 v[72:75], v[158:161], v[190:193], v[72:75]
	v_mfma_f32_16x16x32_bf16 v[124:127], v[154:157], v[170:173], v[124:127]
	v_mfma_f32_16x16x32_bf16 v[120:123], v[162:165], v[170:173], v[120:123]
	v_mfma_f32_16x16x32_bf16 v[108:111], v[154:157], v[178:181], v[108:111]
	v_mfma_f32_16x16x32_bf16 v[104:107], v[162:165], v[178:181], v[104:107]
	v_mfma_f32_16x16x32_bf16 v[92:95], v[154:157], v[186:189], v[92:95]
	v_mfma_f32_16x16x32_bf16 v[88:91], v[162:165], v[186:189], v[88:91]
	v_mfma_f32_16x16x32_bf16 v[76:79], v[154:157], v[194:197], v[76:79]
	v_mfma_f32_16x16x32_bf16 v[72:75], v[162:165], v[194:197], v[72:75]
	s_barrier
	s_add_i32 s42, s41, s24
	s_add_u32 s98, s44, s8
	s_addc_u32 s99, s45, s9
	s_mov_b32 m0, s42
	ds_read_b128 v[198:201], v149
	ds_read_b128 v[202:205], v149 offset:1024
	ds_read_b128 v[206:209], v149 offset:2048
	ds_read_b128 v[210:213], v149 offset:3072
	global_load_lds_dwordx4 v132, s[44:45]
	s_add_i32 m0, s42, 0x2000
	s_nop 0
	global_load_lds_dwordx4 v128, s[44:45]
	s_barrier
	s_waitcnt lgkmcnt(0)
	s_waitcnt lgkmcnt(0)
	v_mfma_f32_16x16x32_bf16 v[116:119], v[198:201], v[166:169], v[116:119]
	v_mfma_f32_16x16x32_bf16 v[112:115], v[206:209], v[166:169], v[112:115]
	v_mfma_f32_16x16x32_bf16 v[100:103], v[198:201], v[174:177], v[100:103]
	v_mfma_f32_16x16x32_bf16 v[96:99], v[206:209], v[174:177], v[96:99]
	v_mfma_f32_16x16x32_bf16 v[84:87], v[198:201], v[182:185], v[84:87]
	v_mfma_f32_16x16x32_bf16 v[80:83], v[206:209], v[182:185], v[80:83]
	v_mfma_f32_16x16x32_bf16 v[68:71], v[198:201], v[190:193], v[68:71]
	v_mfma_f32_16x16x32_bf16 v[64:67], v[206:209], v[190:193], v[64:67]
	v_mfma_f32_16x16x32_bf16 v[116:119], v[202:205], v[170:173], v[116:119]
	v_mfma_f32_16x16x32_bf16 v[112:115], v[210:213], v[170:173], v[112:115]
	v_mfma_f32_16x16x32_bf16 v[100:103], v[202:205], v[178:181], v[100:103]
	v_mfma_f32_16x16x32_bf16 v[96:99], v[210:213], v[178:181], v[96:99]
	v_mfma_f32_16x16x32_bf16 v[84:87], v[202:205], v[186:189], v[84:87]
	v_mfma_f32_16x16x32_bf16 v[80:83], v[210:213], v[186:189], v[80:83]
	v_mfma_f32_16x16x32_bf16 v[68:71], v[202:205], v[194:197], v[68:71]
	v_mfma_f32_16x16x32_bf16 v[64:67], v[210:213], v[194:197], v[64:67]
	s_mov_b32 m0, s19
	s_add_u32 s100, s4, s8
	s_addc_u32 s101, s5, s9
	s_barrier
	ds_read_b128 v[166:169], v148 offset:16384
	ds_read_b128 v[170:173], v148 offset:17408
	ds_read_b128 v[174:177], v148 offset:18432
	ds_read_b128 v[178:181], v148 offset:19456
	ds_read_b128 v[182:185], v148 offset:20480
	ds_read_b128 v[186:189], v148 offset:21504
	ds_read_b128 v[190:193], v148 offset:22528
	ds_read_b128 v[194:197], v148 offset:23552
	global_load_lds_dwordx4 v134, s[4:5]
	s_mov_b32 m0, s28
	s_nop 0
	global_load_lds_dwordx4 v130, s[4:5]
	s_barrier
	s_waitcnt lgkmcnt(0)
	s_waitcnt lgkmcnt(0)
	v_mfma_f32_16x16x32_bf16 v[60:63], v[150:153], v[166:169], v[60:63]
	v_mfma_f32_16x16x32_bf16 v[56:59], v[158:161], v[166:169], v[56:59]
	v_mfma_f32_16x16x32_bf16 v[44:47], v[150:153], v[174:177], v[44:47]
	v_mfma_f32_16x16x32_bf16 v[40:43], v[158:161], v[174:177], v[40:43]
	v_mfma_f32_16x16x32_bf16 v[28:31], v[150:153], v[182:185], v[28:31]
	v_mfma_f32_16x16x32_bf16 v[24:27], v[158:161], v[182:185], v[24:27]
	v_mfma_f32_16x16x32_bf16 v[12:15], v[150:153], v[190:193], v[12:15]
	v_mfma_f32_16x16x32_bf16 v[8:11], v[158:161], v[190:193], v[8:11]
	v_mfma_f32_16x16x32_bf16 v[60:63], v[154:157], v[170:173], v[60:63]
	v_mfma_f32_16x16x32_bf16 v[56:59], v[162:165], v[170:173], v[56:59]
	v_mfma_f32_16x16x32_bf16 v[44:47], v[154:157], v[178:181], v[44:47]
	v_mfma_f32_16x16x32_bf16 v[40:43], v[162:165], v[178:181], v[40:43]
	v_mfma_f32_16x16x32_bf16 v[28:31], v[154:157], v[186:189], v[28:31]
	v_mfma_f32_16x16x32_bf16 v[24:27], v[162:165], v[186:189], v[24:27]
	v_mfma_f32_16x16x32_bf16 v[12:15], v[154:157], v[194:197], v[12:15]
	v_mfma_f32_16x16x32_bf16 v[8:11], v[162:165], v[194:197], v[8:11]
	s_barrier
	s_add_u32 s42, s44, 0x80000
	s_addc_u32 s43, s45, 0
	s_add_i32 s54, s46, s24
	s_mov_b32 m0, s54
	s_nop 0
	global_load_lds_dwordx4 v132, s[42:43]
	s_add_i32 m0, s54, 0x2000
	s_nop 0
	global_load_lds_dwordx4 v128, s[42:43]
	s_waitcnt vmcnt(6)
	s_barrier
	v_mfma_f32_16x16x32_bf16 v[52:55], v[198:201], v[166:169], v[52:55]
	v_mfma_f32_16x16x32_bf16 v[48:51], v[206:209], v[166:169], v[48:51]
	v_mfma_f32_16x16x32_bf16 v[36:39], v[198:201], v[174:177], v[36:39]
	v_mfma_f32_16x16x32_bf16 v[32:35], v[206:209], v[174:177], v[32:35]
	v_mfma_f32_16x16x32_bf16 v[20:23], v[198:201], v[182:185], v[20:23]
	v_mfma_f32_16x16x32_bf16 v[16:19], v[206:209], v[182:185], v[16:19]
	v_mfma_f32_16x16x32_bf16 v[4:7], v[198:201], v[190:193], v[4:7]
	v_mfma_f32_16x16x32_bf16 v[0:3], v[206:209], v[190:193], v[0:3]
	v_mfma_f32_16x16x32_bf16 v[52:55], v[202:205], v[170:173], v[52:55]
	v_mfma_f32_16x16x32_bf16 v[48:51], v[210:213], v[170:173], v[48:51]
	v_mfma_f32_16x16x32_bf16 v[36:39], v[202:205], v[178:181], v[36:39]
	v_mfma_f32_16x16x32_bf16 v[32:35], v[210:213], v[178:181], v[32:35]
	v_mfma_f32_16x16x32_bf16 v[20:23], v[202:205], v[186:189], v[20:23]
	v_mfma_f32_16x16x32_bf16 v[16:19], v[210:213], v[186:189], v[16:19]
	v_mfma_f32_16x16x32_bf16 v[4:7], v[202:205], v[194:197], v[4:7]
	v_mfma_f32_16x16x32_bf16 v[0:3], v[210:213], v[194:197], v[0:3]
	s_add_i32 s42, 0, 0x18000
	v_add_u32_e32 v162, s42, v145
	s_barrier
	ds_read_b128 v[150:153], v162
	ds_read_b128 v[154:157], v162 offset:1024
	ds_read_b128 v[158:161], v162 offset:2048
	ds_read_b128 v[162:165], v162 offset:3072
	s_add_u32 s4, s4, 0x80000
	s_addc_u32 s5, s5, 0
	s_mov_b32 m0, s29
	ds_read_b128 v[166:169], v148 offset:32768
	ds_read_b128 v[170:173], v148 offset:33792
	ds_read_b128 v[174:177], v148 offset:34816
	ds_read_b128 v[178:181], v148 offset:35840
	ds_read_b128 v[182:185], v148 offset:36864
	ds_read_b128 v[186:189], v148 offset:37888
	ds_read_b128 v[190:193], v148 offset:38912
	ds_read_b128 v[194:197], v148 offset:39936
	global_load_lds_dwordx4 v134, s[4:5]
	s_mov_b32 m0, s33
	s_nop 0
	global_load_lds_dwordx4 v130, s[4:5]
	s_waitcnt lgkmcnt(8)
	s_barrier
	s_waitcnt lgkmcnt(0)
	s_waitcnt lgkmcnt(0)
	v_mfma_f32_16x16x32_bf16 v[124:127], v[150:153], v[166:169], v[124:127]
	v_mfma_f32_16x16x32_bf16 v[120:123], v[158:161], v[166:169], v[120:123]
	v_mfma_f32_16x16x32_bf16 v[108:111], v[150:153], v[174:177], v[108:111]
	v_mfma_f32_16x16x32_bf16 v[104:107], v[158:161], v[174:177], v[104:107]
	v_mfma_f32_16x16x32_bf16 v[92:95], v[150:153], v[182:185], v[92:95]
	v_mfma_f32_16x16x32_bf16 v[88:91], v[158:161], v[182:185], v[88:91]
	v_mfma_f32_16x16x32_bf16 v[76:79], v[150:153], v[190:193], v[76:79]
	v_mfma_f32_16x16x32_bf16 v[72:75], v[158:161], v[190:193], v[72:75]
	v_mfma_f32_16x16x32_bf16 v[124:127], v[154:157], v[170:173], v[124:127]
	v_mfma_f32_16x16x32_bf16 v[120:123], v[162:165], v[170:173], v[120:123]
	v_mfma_f32_16x16x32_bf16 v[108:111], v[154:157], v[178:181], v[108:111]
	v_mfma_f32_16x16x32_bf16 v[104:107], v[162:165], v[178:181], v[104:107]
	v_mfma_f32_16x16x32_bf16 v[92:95], v[154:157], v[186:189], v[92:95]
	v_mfma_f32_16x16x32_bf16 v[88:91], v[162:165], v[186:189], v[88:91]
	v_mfma_f32_16x16x32_bf16 v[76:79], v[154:157], v[194:197], v[76:79]
	v_mfma_f32_16x16x32_bf16 v[72:75], v[162:165], v[194:197], v[72:75]
	s_barrier
	s_add_i32 s43, 0, 0x1c000
	s_add_i32 s4, s42, s24
	v_add_u32_e32 v210, s43, v145
	s_mov_b32 m0, s4
	ds_read_b128 v[198:201], v210
	ds_read_b128 v[202:205], v210 offset:1024
	ds_read_b128 v[206:209], v210 offset:2048
	ds_read_b128 v[210:213], v210 offset:3072
	global_load_lds_dwordx4 v132, s[98:99]
	s_add_i32 m0, s4, 0x2000
	s_nop 0
	global_load_lds_dwordx4 v128, s[98:99]
	s_barrier
	s_waitcnt lgkmcnt(0)
	s_waitcnt lgkmcnt(0)
	v_mfma_f32_16x16x32_bf16 v[116:119], v[198:201], v[166:169], v[116:119]
	v_mfma_f32_16x16x32_bf16 v[112:115], v[206:209], v[166:169], v[112:115]
	v_mfma_f32_16x16x32_bf16 v[100:103], v[198:201], v[174:177], v[100:103]
	v_mfma_f32_16x16x32_bf16 v[96:99], v[206:209], v[174:177], v[96:99]
	v_mfma_f32_16x16x32_bf16 v[84:87], v[198:201], v[182:185], v[84:87]
	v_mfma_f32_16x16x32_bf16 v[80:83], v[206:209], v[182:185], v[80:83]
	v_mfma_f32_16x16x32_bf16 v[68:71], v[198:201], v[190:193], v[68:71]
	v_mfma_f32_16x16x32_bf16 v[64:67], v[206:209], v[190:193], v[64:67]
	v_mfma_f32_16x16x32_bf16 v[116:119], v[202:205], v[170:173], v[116:119]
	v_mfma_f32_16x16x32_bf16 v[112:115], v[210:213], v[170:173], v[112:115]
	v_mfma_f32_16x16x32_bf16 v[100:103], v[202:205], v[178:181], v[100:103]
	v_mfma_f32_16x16x32_bf16 v[96:99], v[210:213], v[178:181], v[96:99]
	v_mfma_f32_16x16x32_bf16 v[84:87], v[202:205], v[186:189], v[84:87]
	v_mfma_f32_16x16x32_bf16 v[80:83], v[210:213], v[186:189], v[80:83]
	v_mfma_f32_16x16x32_bf16 v[68:71], v[202:205], v[194:197], v[68:71]
	v_mfma_f32_16x16x32_bf16 v[64:67], v[210:213], v[194:197], v[64:67]
	s_mov_b32 m0, s37
	s_barrier
	ds_read_b128 v[166:169], v148 offset:49152
	ds_read_b128 v[170:173], v148 offset:50176
	ds_read_b128 v[174:177], v148 offset:51200
	ds_read_b128 v[178:181], v148 offset:52224
	ds_read_b128 v[182:185], v148 offset:53248
	ds_read_b128 v[186:189], v148 offset:54272
	ds_read_b128 v[190:193], v148 offset:55296
	ds_read_b128 v[194:197], v148 offset:56320
	global_load_lds_dwordx4 v134, s[100:101]
	s_mov_b32 m0, s40
	s_nop 0
	global_load_lds_dwordx4 v130, s[100:101]
	s_barrier
	s_waitcnt lgkmcnt(0)
	s_waitcnt lgkmcnt(0)
	v_mfma_f32_16x16x32_bf16 v[60:63], v[150:153], v[166:169], v[60:63]
	v_mfma_f32_16x16x32_bf16 v[56:59], v[158:161], v[166:169], v[56:59]
	v_mfma_f32_16x16x32_bf16 v[44:47], v[150:153], v[174:177], v[44:47]
	v_mfma_f32_16x16x32_bf16 v[40:43], v[158:161], v[174:177], v[40:43]
	v_mfma_f32_16x16x32_bf16 v[28:31], v[150:153], v[182:185], v[28:31]
	v_mfma_f32_16x16x32_bf16 v[24:27], v[158:161], v[182:185], v[24:27]
	v_mfma_f32_16x16x32_bf16 v[12:15], v[150:153], v[190:193], v[12:15]
	v_mfma_f32_16x16x32_bf16 v[8:11], v[158:161], v[190:193], v[8:11]
	v_mfma_f32_16x16x32_bf16 v[60:63], v[154:157], v[170:173], v[60:63]
	v_mfma_f32_16x16x32_bf16 v[56:59], v[162:165], v[170:173], v[56:59]
	v_mfma_f32_16x16x32_bf16 v[44:47], v[154:157], v[178:181], v[44:47]
	v_mfma_f32_16x16x32_bf16 v[40:43], v[162:165], v[178:181], v[40:43]
	v_mfma_f32_16x16x32_bf16 v[28:31], v[154:157], v[186:189], v[28:31]
	v_mfma_f32_16x16x32_bf16 v[24:27], v[162:165], v[186:189], v[24:27]
	v_mfma_f32_16x16x32_bf16 v[12:15], v[154:157], v[194:197], v[12:15]
	v_mfma_f32_16x16x32_bf16 v[8:11], v[162:165], v[194:197], v[8:11]
	s_barrier
	s_add_u32 s4, s44, 0x80080
	s_addc_u32 s5, s45, 0
	s_add_i32 s42, s43, s24
	s_mov_b32 m0, s42
	s_nop 0
	global_load_lds_dwordx4 v132, s[4:5]
	s_add_i32 m0, s42, 0x2000
	s_nop 0
	global_load_lds_dwordx4 v128, s[4:5]
	s_waitcnt vmcnt(6)
	s_barrier
	v_mfma_f32_16x16x32_bf16 v[52:55], v[198:201], v[166:169], v[52:55]
	v_mfma_f32_16x16x32_bf16 v[48:51], v[206:209], v[166:169], v[48:51]
	v_mfma_f32_16x16x32_bf16 v[36:39], v[198:201], v[174:177], v[36:39]
	v_mfma_f32_16x16x32_bf16 v[32:35], v[206:209], v[174:177], v[32:35]
	v_mfma_f32_16x16x32_bf16 v[20:23], v[198:201], v[182:185], v[20:23]
	v_mfma_f32_16x16x32_bf16 v[16:19], v[206:209], v[182:185], v[16:19]
	v_mfma_f32_16x16x32_bf16 v[4:7], v[198:201], v[190:193], v[4:7]
	v_mfma_f32_16x16x32_bf16 v[0:3], v[206:209], v[190:193], v[0:3]
	v_mfma_f32_16x16x32_bf16 v[52:55], v[202:205], v[170:173], v[52:55]
	v_mfma_f32_16x16x32_bf16 v[48:51], v[210:213], v[170:173], v[48:51]
	v_mfma_f32_16x16x32_bf16 v[36:39], v[202:205], v[178:181], v[36:39]
	v_mfma_f32_16x16x32_bf16 v[32:35], v[210:213], v[178:181], v[32:35]
	v_mfma_f32_16x16x32_bf16 v[20:23], v[202:205], v[186:189], v[20:23]
	v_mfma_f32_16x16x32_bf16 v[16:19], v[210:213], v[186:189], v[16:19]
	v_mfma_f32_16x16x32_bf16 v[4:7], v[202:205], v[194:197], v[4:7]
	v_mfma_f32_16x16x32_bf16 v[0:3], v[210:213], v[194:197], v[0:3]
	s_add_i32 s53, s53, 2
	s_add_u32 s20, s20, 0x100
	s_addc_u32 s21, s21, 0
	s_add_u32 s51, s51, 0x100
	s_addc_u32 s52, s52, 0
	s_cmp_gt_u32 s53, 29
	s_barrier
	s_cbranch_scc0 .LBB0_1676
	v_mul_f32_e32 v151, 0xbfb8aa3b, v124
	v_exp_f32_e32 v151, v151
	v_mul_f32_e32 v152, 0xbfb8aa3b, v120
	v_exp_f32_e32 v153, v152
	v_lshl_or_b32 v152, s50, 7, v146
	v_add_f32_e32 v151, 1.0, v151
	v_rcp_f32_e32 v151, v151
	v_add_f32_e32 v153, 1.0, v153
	v_rcp_f32_e32 v154, v153
	v_lshl_add_u32 v150, s18, 8, v144
	v_mul_f32_e32 v124, v124, v151
	v_mul_f32_e32 v116, v124, v116
	v_mul_f32_e32 v124, 0xbfb8aa3b, v125
	v_exp_f32_e32 v124, v124
	v_mul_f32_e32 v151, 0xbfb8aa3b, v121
	v_exp_f32_e32 v151, v151
	v_mul_f32_e32 v120, v120, v154
	v_mul_f32_e32 v112, v120, v112
	v_add_f32_e32 v120, 1.0, v124
	v_rcp_f32_e32 v120, v120
	v_add_f32_e32 v124, 1.0, v151
	v_mul_f32_e32 v151, 0xbfb8aa3b, v126
	v_rcp_f32_e32 v124, v124
	v_exp_f32_e32 v151, v151
	v_mul_f32_e32 v120, v125, v120
	v_mul_f32_e32 v117, v120, v117
	v_mul_f32_e32 v120, v121, v124
	v_add_f32_e32 v121, 1.0, v151
	v_rcp_f32_e32 v121, v121
	v_mul_f32_e32 v124, 0xbfb8aa3b, v122
	v_exp_f32_e32 v124, v124
	v_mul_f32_e32 v113, v120, v113
	v_mul_f32_e32 v120, v126, v121
	v_mul_f32_e32 v121, 0xbfb8aa3b, v127
	v_mul_f32_e32 v118, v120, v118
	v_add_f32_e32 v120, 1.0, v124
	v_exp_f32_e32 v121, v121
	v_mul_f32_e32 v124, 0xbfb8aa3b, v123
	v_rcp_f32_e32 v120, v120
	v_exp_f32_e32 v124, v124
	v_add_f32_e32 v121, 1.0, v121
	v_rcp_f32_e32 v121, v121
	v_mul_f32_e32 v120, v122, v120
	v_add_f32_e32 v122, 1.0, v124
	v_rcp_f32_e32 v122, v122
	v_mul_f32_e32 v114, v120, v114
	v_mul_f32_e32 v120, v127, v121
	v_mul_f32_e32 v119, v120, v119
	v_mul_f32_e32 v120, v123, v122
	v_mul_f32_e32 v122, 0xbfb8aa3b, v108
	v_exp_f32_e32 v122, v122
	v_mul_f32_e32 v123, 0xbfb8aa3b, v104
	v_exp_f32_e32 v123, v123
	v_ashrrev_i32_e32 v153, 31, v152
	v_add_f32_e32 v122, 1.0, v122
	v_rcp_f32_e32 v122, v122
	v_mul_f32_e32 v115, v120, v115
	v_cvt_pk_bf16_f32 v116, v116, v117
	v_cvt_pk_bf16_f32 v117, v118, v119
	v_cvt_pk_bf16_f32 v118, v112, v113
	v_mov_b64_e32 v[112:113], s[48:49]
	v_cvt_pk_bf16_f32 v119, v114, v115
	v_mad_i64_i32 v[120:121], s[0:1], v150, s47, v[112:113]
	v_lshlrev_b64 v[114:115], 1, v[152:153]
	v_add_f32_e32 v123, 1.0, v123
	v_mul_f32_e32 v108, v108, v122
	v_lshl_add_u64 v[120:121], v[120:121], 0, v[114:115]
	v_rcp_f32_e32 v123, v123
	v_mul_f32_e32 v100, v108, v100
	v_mul_f32_e32 v108, 0xbfb8aa3b, v109
	global_store_dwordx4 v[120:121], v[116:119], off
	v_exp_f32_e32 v108, v108
	v_mul_f32_e32 v104, v104, v123
	v_mul_f32_e32 v116, 0xbfb8aa3b, v105
	v_exp_f32_e32 v116, v116
	v_mul_f32_e32 v104, v104, v96
	v_add_f32_e32 v96, 1.0, v108
	v_rcp_f32_e32 v96, v96
	v_add_f32_e32 v108, 1.0, v116
	v_mul_f32_e32 v116, 0xbfb8aa3b, v110
	v_rcp_f32_e32 v108, v108
	v_exp_f32_e32 v116, v116
	v_mul_f32_e32 v96, v109, v96
	v_mul_f32_e32 v96, v96, v101
	v_mul_f32_e32 v101, v105, v108
	v_add_f32_e32 v105, 1.0, v116
	v_rcp_f32_e32 v105, v105
	v_mul_f32_e32 v108, 0xbfb8aa3b, v106
	v_exp_f32_e32 v108, v108
	v_mul_f32_e32 v101, v101, v97
	v_mul_f32_e32 v97, v110, v105
	v_mul_f32_e32 v105, 0xbfb8aa3b, v111
	v_mul_f32_e32 v97, v97, v102
	v_add_f32_e32 v102, 1.0, v108
	v_exp_f32_e32 v105, v105
	v_mul_f32_e32 v108, 0xbfb8aa3b, v107
	v_rcp_f32_e32 v102, v102
	v_exp_f32_e32 v108, v108
	v_add_f32_e32 v105, 1.0, v105
	v_rcp_f32_e32 v105, v105
	v_mul_f32_e32 v102, v106, v102
	v_add_f32_e32 v106, 1.0, v108
	v_rcp_f32_e32 v106, v106
	v_mul_f32_e32 v102, v102, v98
	v_mul_f32_e32 v98, v111, v105
	v_mul_f32_e32 v98, v98, v103
	v_mul_f32_e32 v103, v107, v106
	v_mul_f32_e32 v99, v103, v99
	v_cvt_pk_bf16_f32 v96, v100, v96
	v_cvt_pk_bf16_f32 v97, v97, v98
	v_cvt_pk_bf16_f32 v98, v104, v101
	v_cvt_pk_bf16_f32 v99, v102, v99
	v_mul_f32_e32 v102, 0xbfb8aa3b, v92
	v_exp_f32_e32 v102, v102
	v_mul_f32_e32 v103, 0xbfb8aa3b, v88
	v_exp_f32_e32 v103, v103
	v_or_b32_e32 v100, 16, v150
	v_add_f32_e32 v102, 1.0, v102
	v_rcp_f32_e32 v102, v102
	v_mad_i64_i32 v[100:101], s[0:1], v100, s47, v[112:113]
	v_add_f32_e32 v103, 1.0, v103
	v_mul_f32_e32 v92, v92, v102
	v_lshl_add_u64 v[100:101], v[100:101], 0, v[114:115]
	v_rcp_f32_e32 v103, v103
	v_mul_f32_e32 v84, v92, v84
	v_mul_f32_e32 v92, 0xbfb8aa3b, v93
	global_store_dwordx4 v[100:101], v[96:99], off
	v_exp_f32_e32 v92, v92
	v_mul_f32_e32 v88, v88, v103
	v_mul_f32_e32 v96, 0xbfb8aa3b, v89
	v_exp_f32_e32 v96, v96
	v_mul_f32_e32 v88, v88, v80
	v_add_f32_e32 v80, 1.0, v92
	v_rcp_f32_e32 v80, v80
	v_add_f32_e32 v92, 1.0, v96
	v_mul_f32_e32 v96, 0xbfb8aa3b, v94
	v_rcp_f32_e32 v92, v92
	v_exp_f32_e32 v96, v96
	v_mul_f32_e32 v80, v93, v80
	v_mul_f32_e32 v80, v80, v85
	v_mul_f32_e32 v85, v89, v92
	v_add_f32_e32 v89, 1.0, v96
	v_rcp_f32_e32 v89, v89
	v_mul_f32_e32 v92, 0xbfb8aa3b, v90
	v_exp_f32_e32 v92, v92
	v_mul_f32_e32 v85, v85, v81
	v_mul_f32_e32 v81, v94, v89
	v_mul_f32_e32 v89, 0xbfb8aa3b, v95
	v_mul_f32_e32 v81, v81, v86
	v_add_f32_e32 v86, 1.0, v92
	v_exp_f32_e32 v89, v89
	v_mul_f32_e32 v92, 0xbfb8aa3b, v91
	v_rcp_f32_e32 v86, v86
	v_exp_f32_e32 v92, v92
	v_add_f32_e32 v89, 1.0, v89
	v_rcp_f32_e32 v89, v89
	v_mul_f32_e32 v86, v90, v86
	v_add_f32_e32 v90, 1.0, v92
	v_rcp_f32_e32 v90, v90
	v_mul_f32_e32 v86, v86, v82
	v_mul_f32_e32 v82, v95, v89
	v_mul_f32_e32 v82, v82, v87
	v_mul_f32_e32 v87, v91, v90
	v_mul_f32_e32 v83, v87, v83
	v_cvt_pk_bf16_f32 v80, v84, v80
	v_cvt_pk_bf16_f32 v81, v81, v82
	v_cvt_pk_bf16_f32 v82, v88, v85
	v_cvt_pk_bf16_f32 v83, v86, v83
	v_mul_f32_e32 v86, 0xbfb8aa3b, v76
	v_exp_f32_e32 v86, v86
	v_mul_f32_e32 v87, 0xbfb8aa3b, v72
	v_exp_f32_e32 v87, v87
	v_or_b32_e32 v84, 32, v150
	v_add_f32_e32 v86, 1.0, v86
	v_rcp_f32_e32 v86, v86
	v_mad_i64_i32 v[84:85], s[0:1], v84, s47, v[112:113]
	v_add_f32_e32 v87, 1.0, v87
	v_mul_f32_e32 v76, v76, v86
	v_lshl_add_u64 v[84:85], v[84:85], 0, v[114:115]
	v_rcp_f32_e32 v87, v87
	v_mul_f32_e32 v68, v76, v68
	v_mul_f32_e32 v76, 0xbfb8aa3b, v77
	global_store_dwordx4 v[84:85], v[80:83], off
	v_exp_f32_e32 v76, v76
	v_mul_f32_e32 v72, v72, v87
	v_mul_f32_e32 v80, 0xbfb8aa3b, v73
	v_exp_f32_e32 v80, v80
	v_mul_f32_e32 v72, v72, v64
	v_add_f32_e32 v64, 1.0, v76
	v_rcp_f32_e32 v64, v64
	v_add_f32_e32 v76, 1.0, v80
	v_mul_f32_e32 v80, 0xbfb8aa3b, v78
	v_rcp_f32_e32 v76, v76
	v_exp_f32_e32 v80, v80
	v_mul_f32_e32 v64, v77, v64
	v_mul_f32_e32 v64, v64, v69
	v_mul_f32_e32 v69, v73, v76
	v_add_f32_e32 v73, 1.0, v80
	v_rcp_f32_e32 v73, v73
	v_mul_f32_e32 v76, 0xbfb8aa3b, v74
	v_exp_f32_e32 v76, v76
	v_mul_f32_e32 v69, v69, v65
	v_mul_f32_e32 v65, v78, v73
	v_mul_f32_e32 v73, 0xbfb8aa3b, v79
	v_mul_f32_e32 v65, v65, v70
	v_add_f32_e32 v70, 1.0, v76
	v_exp_f32_e32 v73, v73
	v_mul_f32_e32 v76, 0xbfb8aa3b, v75
	v_rcp_f32_e32 v70, v70
	v_exp_f32_e32 v76, v76
	v_add_f32_e32 v73, 1.0, v73
	v_rcp_f32_e32 v73, v73
	v_mul_f32_e32 v70, v74, v70
	v_add_f32_e32 v74, 1.0, v76
	v_rcp_f32_e32 v74, v74
	v_mul_f32_e32 v70, v70, v66
	v_mul_f32_e32 v66, v79, v73
	v_mul_f32_e32 v66, v66, v71
	v_mul_f32_e32 v71, v75, v74
	v_mul_f32_e32 v67, v71, v67
	v_cvt_pk_bf16_f32 v64, v68, v64
	v_cvt_pk_bf16_f32 v65, v65, v66
	v_cvt_pk_bf16_f32 v66, v72, v69
	v_cvt_pk_bf16_f32 v67, v70, v67
	v_mul_f32_e32 v70, 0xbfb8aa3b, v60
	v_exp_f32_e32 v70, v70
	v_or_b32_e32 v68, 48, v150
	v_mad_i64_i32 v[68:69], s[0:1], v68, s47, v[112:113]
	v_lshl_add_u64 v[68:69], v[68:69], 0, v[114:115]
	v_mul_f32_e32 v71, 0xbfb8aa3b, v56
	global_store_dwordx4 v[68:69], v[64:67], off
	v_exp_f32_e32 v71, v71
	s_and_b64 vcc, exec, s[6:7]
	v_add_f32_e32 v64, 1.0, v70
	v_rcp_f32_e32 v64, v64
	v_add_f32_e32 v65, 1.0, v71
	v_rcp_f32_e32 v65, v65
	v_add_u32_e32 v66, 0x80, v150
	v_mul_f32_e32 v60, v60, v64
	v_mul_f32_e32 v52, v60, v52
	v_mul_f32_e32 v60, 0xbfb8aa3b, v61
	v_exp_f32_e32 v60, v60
	v_mul_f32_e32 v64, 0xbfb8aa3b, v57
	v_exp_f32_e32 v64, v64
	v_mul_f32_e32 v56, v56, v65
	v_mul_f32_e32 v56, v56, v48
	v_add_f32_e32 v48, 1.0, v60
	v_rcp_f32_e32 v48, v48
	v_add_f32_e32 v60, 1.0, v64
	v_mul_f32_e32 v64, 0xbfb8aa3b, v62
	v_rcp_f32_e32 v60, v60
	v_exp_f32_e32 v64, v64
	v_mul_f32_e32 v48, v61, v48
	v_mul_f32_e32 v48, v48, v53
	v_mul_f32_e32 v53, v57, v60
	v_add_f32_e32 v57, 1.0, v64
	v_rcp_f32_e32 v57, v57
	v_mul_f32_e32 v60, 0xbfb8aa3b, v58
	v_exp_f32_e32 v60, v60
	v_mul_f32_e32 v53, v53, v49
	v_mul_f32_e32 v49, v62, v57
	v_mul_f32_e32 v57, 0xbfb8aa3b, v63
	v_mul_f32_e32 v49, v49, v54
	v_add_f32_e32 v54, 1.0, v60
	v_exp_f32_e32 v57, v57
	v_mul_f32_e32 v60, 0xbfb8aa3b, v59
	v_rcp_f32_e32 v54, v54
	v_exp_f32_e32 v60, v60
	v_add_f32_e32 v57, 1.0, v57
	v_rcp_f32_e32 v57, v57
	v_mul_f32_e32 v54, v58, v54
	v_add_f32_e32 v58, 1.0, v60
	v_rcp_f32_e32 v58, v58
	v_mul_f32_e32 v54, v54, v50
	v_mul_f32_e32 v50, v63, v57
	v_mul_f32_e32 v50, v50, v55
	v_mul_f32_e32 v55, v59, v58
	v_mul_f32_e32 v51, v55, v51
	v_cvt_pk_bf16_f32 v48, v52, v48
	v_cvt_pk_bf16_f32 v49, v49, v50
	v_cvt_pk_bf16_f32 v50, v56, v53
	v_cvt_pk_bf16_f32 v51, v54, v51
	v_mul_f32_e32 v54, 0xbfb8aa3b, v44
	v_exp_f32_e32 v54, v54
	v_mul_f32_e32 v55, 0xbfb8aa3b, v40
	v_exp_f32_e32 v55, v55
	v_mad_i64_i32 v[52:53], s[0:1], v66, s47, v[112:113]
	v_add_f32_e32 v54, 1.0, v54
	v_rcp_f32_e32 v54, v54
	v_add_f32_e32 v55, 1.0, v55
	v_lshl_add_u64 v[52:53], v[52:53], 0, v[114:115]
	v_rcp_f32_e32 v55, v55
	v_mul_f32_e32 v44, v44, v54
	v_mul_f32_e32 v36, v44, v36
	v_mul_f32_e32 v44, 0xbfb8aa3b, v45
	global_store_dwordx4 v[52:53], v[48:51], off
	v_exp_f32_e32 v44, v44
	v_mul_f32_e32 v40, v40, v55
	v_mul_f32_e32 v48, 0xbfb8aa3b, v41
	v_exp_f32_e32 v48, v48
	v_mul_f32_e32 v40, v40, v32
	v_add_f32_e32 v32, 1.0, v44
	v_rcp_f32_e32 v32, v32
	v_add_f32_e32 v44, 1.0, v48
	v_mul_f32_e32 v48, 0xbfb8aa3b, v46
	v_rcp_f32_e32 v44, v44
	v_exp_f32_e32 v48, v48
	v_mul_f32_e32 v32, v45, v32
	v_mul_f32_e32 v32, v32, v37
	v_mul_f32_e32 v37, v41, v44
	v_add_f32_e32 v41, 1.0, v48
	v_rcp_f32_e32 v41, v41
	v_mul_f32_e32 v44, 0xbfb8aa3b, v42
	v_exp_f32_e32 v44, v44
	v_mul_f32_e32 v37, v37, v33
	v_mul_f32_e32 v33, v46, v41
	v_mul_f32_e32 v41, 0xbfb8aa3b, v47
	v_mul_f32_e32 v33, v33, v38
	v_add_f32_e32 v38, 1.0, v44
	v_exp_f32_e32 v41, v41
	v_mul_f32_e32 v44, 0xbfb8aa3b, v43
	v_rcp_f32_e32 v38, v38
	v_exp_f32_e32 v44, v44
	v_add_f32_e32 v41, 1.0, v41
	v_rcp_f32_e32 v41, v41
	v_mul_f32_e32 v38, v42, v38
	v_add_f32_e32 v42, 1.0, v44
	v_rcp_f32_e32 v42, v42
	v_mul_f32_e32 v38, v38, v34
	v_mul_f32_e32 v34, v47, v41
	v_mul_f32_e32 v34, v34, v39
	v_mul_f32_e32 v39, v43, v42
	v_mul_f32_e32 v35, v39, v35
	v_cvt_pk_bf16_f32 v32, v36, v32
	v_cvt_pk_bf16_f32 v33, v33, v34
	v_cvt_pk_bf16_f32 v34, v40, v37
	v_cvt_pk_bf16_f32 v35, v38, v35
	v_mul_f32_e32 v38, 0xbfb8aa3b, v28
	v_exp_f32_e32 v38, v38
	v_mul_f32_e32 v39, 0xbfb8aa3b, v24
	v_exp_f32_e32 v39, v39
	v_add_u32_e32 v36, 0x90, v150
	v_add_f32_e32 v38, 1.0, v38
	v_rcp_f32_e32 v38, v38
	v_mad_i64_i32 v[36:37], s[0:1], v36, s47, v[112:113]
	v_add_f32_e32 v39, 1.0, v39
	v_mul_f32_e32 v28, v28, v38
	v_lshl_add_u64 v[36:37], v[36:37], 0, v[114:115]
	v_rcp_f32_e32 v39, v39
	v_mul_f32_e32 v20, v28, v20
	v_mul_f32_e32 v28, 0xbfb8aa3b, v29
	global_store_dwordx4 v[36:37], v[32:35], off
	v_exp_f32_e32 v28, v28
	v_mul_f32_e32 v24, v24, v39
	v_mul_f32_e32 v32, 0xbfb8aa3b, v25
	v_exp_f32_e32 v32, v32
	v_mul_f32_e32 v24, v24, v16
	v_add_f32_e32 v16, 1.0, v28
	v_rcp_f32_e32 v16, v16
	v_add_f32_e32 v28, 1.0, v32
	v_mul_f32_e32 v32, 0xbfb8aa3b, v30
	v_rcp_f32_e32 v28, v28
	v_exp_f32_e32 v32, v32
	v_mul_f32_e32 v16, v29, v16
	v_mul_f32_e32 v16, v16, v21
	v_mul_f32_e32 v21, v25, v28
	v_add_f32_e32 v25, 1.0, v32
	v_rcp_f32_e32 v25, v25
	v_mul_f32_e32 v28, 0xbfb8aa3b, v26
	v_exp_f32_e32 v28, v28
	v_mul_f32_e32 v21, v21, v17
	v_mul_f32_e32 v17, v30, v25
	v_mul_f32_e32 v25, 0xbfb8aa3b, v31
	v_mul_f32_e32 v17, v17, v22
	v_add_f32_e32 v22, 1.0, v28
	v_exp_f32_e32 v25, v25
	v_mul_f32_e32 v28, 0xbfb8aa3b, v27
	v_rcp_f32_e32 v22, v22
	v_exp_f32_e32 v28, v28
	v_add_f32_e32 v25, 1.0, v25
	v_rcp_f32_e32 v25, v25
	v_mul_f32_e32 v22, v26, v22
	v_add_f32_e32 v26, 1.0, v28
	v_rcp_f32_e32 v26, v26
	v_mul_f32_e32 v22, v22, v18
	v_mul_f32_e32 v18, v31, v25
	v_mul_f32_e32 v18, v18, v23
	v_mul_f32_e32 v23, v27, v26
	v_mul_f32_e32 v19, v23, v19
	v_cvt_pk_bf16_f32 v16, v20, v16
	v_cvt_pk_bf16_f32 v17, v17, v18
	v_cvt_pk_bf16_f32 v18, v24, v21
	v_cvt_pk_bf16_f32 v19, v22, v19
	v_mul_f32_e32 v22, 0xbfb8aa3b, v12
	v_exp_f32_e32 v22, v22
	v_mul_f32_e32 v23, 0xbfb8aa3b, v8
	v_exp_f32_e32 v23, v23
	v_add_u32_e32 v20, 0xa0, v150
	v_add_f32_e32 v22, 1.0, v22
	v_rcp_f32_e32 v22, v22
	v_mad_i64_i32 v[20:21], s[0:1], v20, s47, v[112:113]
	v_add_f32_e32 v23, 1.0, v23
	v_mul_f32_e32 v12, v12, v22
	v_lshl_add_u64 v[20:21], v[20:21], 0, v[114:115]
	v_rcp_f32_e32 v23, v23
	v_mul_f32_e32 v4, v12, v4
	v_mul_f32_e32 v12, 0xbfb8aa3b, v13
	global_store_dwordx4 v[20:21], v[16:19], off
	v_exp_f32_e32 v12, v12
	v_mul_f32_e32 v8, v8, v23
	v_mul_f32_e32 v16, 0xbfb8aa3b, v9
	v_exp_f32_e32 v16, v16
	v_mul_f32_e32 v8, v8, v0
	v_add_f32_e32 v0, 1.0, v12
	v_rcp_f32_e32 v0, v0
	v_add_f32_e32 v12, 1.0, v16
	v_mul_f32_e32 v16, 0xbfb8aa3b, v14
	v_rcp_f32_e32 v12, v12
	v_exp_f32_e32 v16, v16
	v_mul_f32_e32 v0, v13, v0
	v_mul_f32_e32 v0, v0, v5
	v_mul_f32_e32 v5, v9, v12
	v_add_f32_e32 v9, 1.0, v16
	v_rcp_f32_e32 v9, v9
	v_mul_f32_e32 v12, 0xbfb8aa3b, v10
	v_exp_f32_e32 v12, v12
	v_mul_f32_e32 v5, v5, v1
	v_mul_f32_e32 v1, v14, v9
	v_mul_f32_e32 v9, 0xbfb8aa3b, v15
	v_exp_f32_e32 v9, v9
	v_mul_f32_e32 v1, v1, v6
	v_add_f32_e32 v6, 1.0, v12
	v_mul_f32_e32 v12, 0xbfb8aa3b, v11
	v_rcp_f32_e32 v6, v6
	v_exp_f32_e32 v12, v12
	v_add_f32_e32 v9, 1.0, v9
	v_rcp_f32_e32 v9, v9
	v_mul_f32_e32 v6, v10, v6
	v_add_f32_e32 v10, 1.0, v12
	v_rcp_f32_e32 v10, v10
	v_mul_f32_e32 v6, v6, v2
	v_mul_f32_e32 v2, v15, v9
	v_mul_f32_e32 v2, v2, v7
	v_cvt_pk_bf16_f32 v0, v4, v0
	v_add_u32_e32 v4, 0xb0, v150
	v_mul_f32_e32 v7, v11, v10
	v_cvt_pk_bf16_f32 v1, v1, v2
	v_cvt_pk_bf16_f32 v2, v8, v5
	v_mad_i64_i32 v[4:5], s[0:1], v4, s47, v[112:113]
	v_mul_f32_e32 v3, v7, v3
	v_lshl_add_u64 v[4:5], v[4:5], 0, v[114:115]
	s_mov_b32 s50, s10
	s_mov_b32 s18, s12
	s_mov_b64 s[44:45], s[16:17]
	s_mov_b64 s[20:21], s[14:15]
	v_cvt_pk_bf16_f32 v3, v6, v3
	global_store_dwordx4 v[4:5], v[0:3], off
	s_cbranch_vccz .LBB0_1673
	s_waitcnt vmcnt(0)
	s_cmpk_gt_u32 s23, 0xff
	s_cbranch_scc1 .LBB0_1680
	s_barrier
